# gemm_loops_duplicate_lgkmcnt0_wait_removed
# speedup vs baseline: 1.0083x; 1.0083x over previous
.LBB0_150:
	ds_read_b128 v[152:155], v148
	ds_read_b128 v[156:159], v148 offset:1024
	ds_read_b128 v[160:163], v148 offset:2048
	ds_read_b128 v[164:167], v148 offset:3072
	s_add_u32 s40, s38, 0xfffc0080
	s_addc_u32 s41, s39, -1
	s_cmp_eq_u32 s75, 12
	s_cselect_b32 s43, s13, s41
	s_cselect_b32 s42, s37, s40
	s_cselect_b32 s41, s9, s74
	s_cselect_b32 s40, s72, s73
	v_lshl_add_u64 v[200:201], s[38:39], 0, v[136:137]
	s_add_i32 m0, s51, 0xc000
	ds_read_b128 v[168:171], v149
	ds_read_b128 v[172:175], v149 offset:1024
	ds_read_b128 v[176:179], v149 offset:2048
	ds_read_b128 v[180:183], v149 offset:3072
	ds_read_b128 v[184:187], v149 offset:4096
	ds_read_b128 v[188:191], v149 offset:5120
	ds_read_b128 v[192:195], v149 offset:6144
	ds_read_b128 v[196:199], v149 offset:7168
	global_load_lds_dwordx4 v[200:201], off
	v_lshl_add_u64 v[200:201], s[38:39], 0, v[138:139]
	s_add_i32 m0, s51, 0xe000
	s_nop 0
	global_load_lds_dwordx4 v[200:201], off
	s_waitcnt lgkmcnt(8)
	s_barrier
	s_waitcnt lgkmcnt(0)
	s_setprio 1
	v_mfma_f32_16x16x32_bf16 v[124:127], v[152:155], v[168:171], v[124:127]
	v_mfma_f32_16x16x32_bf16 v[120:123], v[160:163], v[168:171], v[120:123]
	v_mfma_f32_16x16x32_bf16 v[116:119], v[152:155], v[176:179], v[116:119]
	v_mfma_f32_16x16x32_bf16 v[112:115], v[160:163], v[176:179], v[112:115]
	v_mfma_f32_16x16x32_bf16 v[108:111], v[152:155], v[184:187], v[108:111]
	v_mfma_f32_16x16x32_bf16 v[104:107], v[160:163], v[184:187], v[104:107]
	v_mfma_f32_16x16x32_bf16 v[100:103], v[152:155], v[192:195], v[100:103]
	v_mfma_f32_16x16x32_bf16 v[96:99], v[160:163], v[192:195], v[96:99]
	v_mfma_f32_16x16x32_bf16 v[124:127], v[156:159], v[172:175], v[124:127]
	v_mfma_f32_16x16x32_bf16 v[120:123], v[164:167], v[172:175], v[120:123]
	v_mfma_f32_16x16x32_bf16 v[116:119], v[156:159], v[180:183], v[116:119]
	v_mfma_f32_16x16x32_bf16 v[112:115], v[164:167], v[180:183], v[112:115]
	v_mfma_f32_16x16x32_bf16 v[108:111], v[156:159], v[188:191], v[108:111]
	v_mfma_f32_16x16x32_bf16 v[104:107], v[164:167], v[188:191], v[104:107]
	v_mfma_f32_16x16x32_bf16 v[100:103], v[156:159], v[196:199], v[100:103]
	v_mfma_f32_16x16x32_bf16 v[96:99], v[164:167], v[196:199], v[96:99]
	s_setprio 0
	s_barrier
	s_add_i32 s76, s69, s48
	v_lshl_add_u64 v[208:209], s[40:41], 0, v[132:133]
	s_mov_b32 m0, s76
	ds_read_b128 v[200:203], v150
	ds_read_b128 v[204:207], v150 offset:1024
	ds_read_b128 v[212:215], v150 offset:2048
	ds_read_b128 v[216:219], v150 offset:3072
	global_load_lds_dwordx4 v[208:209], off
	v_lshl_add_u64 v[220:221], s[40:41], 0, v[128:129]
	s_add_i32 m0, s76, 0x2000
	s_nop 0
	global_load_lds_dwordx4 v[220:221], off
	s_barrier
	s_waitcnt lgkmcnt(0)
	s_setprio 1
	v_mfma_f32_16x16x32_bf16 v[76:79], v[200:203], v[168:171], v[76:79]
	v_mfma_f32_16x16x32_bf16 v[72:75], v[212:215], v[168:171], v[72:75]
	v_mfma_f32_16x16x32_bf16 v[60:63], v[200:203], v[176:179], v[60:63]
	v_mfma_f32_16x16x32_bf16 v[56:59], v[212:215], v[176:179], v[56:59]
	v_mfma_f32_16x16x32_bf16 v[44:47], v[200:203], v[184:187], v[44:47]
	v_mfma_f32_16x16x32_bf16 v[40:43], v[212:215], v[184:187], v[40:43]
	v_mfma_f32_16x16x32_bf16 v[36:39], v[200:203], v[192:195], v[36:39]
	v_mfma_f32_16x16x32_bf16 v[32:35], v[212:215], v[192:195], v[32:35]
	v_mfma_f32_16x16x32_bf16 v[76:79], v[204:207], v[172:175], v[76:79]
	v_mfma_f32_16x16x32_bf16 v[72:75], v[216:219], v[172:175], v[72:75]
	v_mfma_f32_16x16x32_bf16 v[60:63], v[204:207], v[180:183], v[60:63]
	v_mfma_f32_16x16x32_bf16 v[56:59], v[216:219], v[180:183], v[56:59]
	v_mfma_f32_16x16x32_bf16 v[44:47], v[204:207], v[188:191], v[44:47]
	v_mfma_f32_16x16x32_bf16 v[40:43], v[216:219], v[188:191], v[40:43]
	v_mfma_f32_16x16x32_bf16 v[36:39], v[204:207], v[196:199], v[36:39]
	v_mfma_f32_16x16x32_bf16 v[32:35], v[216:219], v[196:199], v[32:35]
	s_setprio 0
	s_mov_b32 m0, s51
	v_lshl_add_u64 v[222:223], s[42:43], 0, v[134:135]
	s_barrier
	ds_read_b128 v[168:171], v149 offset:16384
	ds_read_b128 v[172:175], v149 offset:17408
	ds_read_b128 v[176:179], v149 offset:18432
	ds_read_b128 v[180:183], v149 offset:19456
	ds_read_b128 v[184:187], v149 offset:20480
	ds_read_b128 v[188:191], v149 offset:21504
	ds_read_b128 v[192:195], v149 offset:22528
	ds_read_b128 v[196:199], v149 offset:23552
	global_load_lds_dwordx4 v[222:223], off
	v_lshl_add_u64 v[224:225], s[42:43], 0, v[130:131]
	s_mov_b32 m0, s54
	s_nop 0
	global_load_lds_dwordx4 v[224:225], off
	s_barrier
	s_waitcnt lgkmcnt(0)
	s_setprio 1
	v_mfma_f32_16x16x32_bf16 v[92:95], v[152:155], v[168:171], v[92:95]
	v_mfma_f32_16x16x32_bf16 v[88:91], v[160:163], v[168:171], v[88:91]
	v_mfma_f32_16x16x32_bf16 v[84:87], v[152:155], v[176:179], v[84:87]
	v_mfma_f32_16x16x32_bf16 v[80:83], v[160:163], v[176:179], v[80:83]
	v_mfma_f32_16x16x32_bf16 v[68:71], v[152:155], v[184:187], v[68:71]
	v_mfma_f32_16x16x32_bf16 v[64:67], v[160:163], v[184:187], v[64:67]
	v_mfma_f32_16x16x32_bf16 v[52:55], v[152:155], v[192:195], v[52:55]
	v_mfma_f32_16x16x32_bf16 v[48:51], v[160:163], v[192:195], v[48:51]
	v_mfma_f32_16x16x32_bf16 v[92:95], v[156:159], v[172:175], v[92:95]
	v_mfma_f32_16x16x32_bf16 v[88:91], v[164:167], v[172:175], v[88:91]
	v_mfma_f32_16x16x32_bf16 v[84:87], v[156:159], v[180:183], v[84:87]
	v_mfma_f32_16x16x32_bf16 v[80:83], v[164:167], v[180:183], v[80:83]
	v_mfma_f32_16x16x32_bf16 v[68:71], v[156:159], v[188:191], v[68:71]
	v_mfma_f32_16x16x32_bf16 v[64:67], v[164:167], v[188:191], v[64:67]
	v_mfma_f32_16x16x32_bf16 v[52:55], v[156:159], v[196:199], v[52:55]
	v_mfma_f32_16x16x32_bf16 v[48:51], v[164:167], v[196:199], v[48:51]
	s_setprio 0
	s_barrier
	s_add_u32 s76, s40, 0x40000
	s_addc_u32 s77, s41, 0
	s_add_i32 s78, s70, s48
	v_lshl_add_u64 v[152:153], s[76:77], 0, v[132:133]
	s_mov_b32 m0, s78
	s_nop 0
	global_load_lds_dwordx4 v[152:153], off
	v_lshl_add_u64 v[152:153], s[76:77], 0, v[128:129]
	s_add_i32 m0, s78, 0x2000
	s_nop 0
	global_load_lds_dwordx4 v[152:153], off
	s_waitcnt vmcnt(6)
	s_barrier
	s_setprio 1
	v_mfma_f32_16x16x32_bf16 v[28:31], v[200:203], v[168:171], v[28:31]
	v_mfma_f32_16x16x32_bf16 v[24:27], v[212:215], v[168:171], v[24:27]
	v_mfma_f32_16x16x32_bf16 v[20:23], v[200:203], v[176:179], v[20:23]
	v_mfma_f32_16x16x32_bf16 v[16:19], v[212:215], v[176:179], v[16:19]
	v_mfma_f32_16x16x32_bf16 v[12:15], v[200:203], v[184:187], v[12:15]
	v_mfma_f32_16x16x32_bf16 v[8:11], v[212:215], v[184:187], v[8:11]
	v_mfma_f32_16x16x32_bf16 v[4:7], v[200:203], v[192:195], v[4:7]
	v_mfma_f32_16x16x32_bf16 v[0:3], v[212:215], v[192:195], v[0:3]
	v_mfma_f32_16x16x32_bf16 v[28:31], v[204:207], v[172:175], v[28:31]
	v_mfma_f32_16x16x32_bf16 v[24:27], v[216:219], v[172:175], v[24:27]
	v_mfma_f32_16x16x32_bf16 v[20:23], v[204:207], v[180:183], v[20:23]
	v_mfma_f32_16x16x32_bf16 v[16:19], v[216:219], v[180:183], v[16:19]
	v_mfma_f32_16x16x32_bf16 v[12:15], v[204:207], v[188:191], v[12:15]
	v_mfma_f32_16x16x32_bf16 v[8:11], v[216:219], v[188:191], v[8:11]
	v_mfma_f32_16x16x32_bf16 v[4:7], v[204:207], v[196:199], v[4:7]
	v_mfma_f32_16x16x32_bf16 v[0:3], v[216:219], v[196:199], v[0:3]
	s_setprio 0
	s_add_i32 s76, 0, 0x18000
	v_add_u32_e32 v151, s76, v146
	s_barrier
	ds_read_b128 v[152:155], v151
	ds_read_b128 v[156:159], v151 offset:1024
	ds_read_b128 v[160:163], v151 offset:2048
	ds_read_b128 v[164:167], v151 offset:3072
	s_add_u32 s42, s42, 0x40000
	s_addc_u32 s43, s43, 0
	s_mov_b32 m0, s55
	v_lshl_add_u64 v[200:201], s[42:43], 0, v[134:135]
	ds_read_b128 v[168:171], v149 offset:32768
	ds_read_b128 v[172:175], v149 offset:33792
	ds_read_b128 v[176:179], v149 offset:34816
	ds_read_b128 v[180:183], v149 offset:35840
	ds_read_b128 v[184:187], v149 offset:36864
	ds_read_b128 v[188:191], v149 offset:37888
	ds_read_b128 v[192:195], v149 offset:38912
	ds_read_b128 v[196:199], v149 offset:39936
	global_load_lds_dwordx4 v[200:201], off
	v_lshl_add_u64 v[200:201], s[42:43], 0, v[130:131]
	s_mov_b32 m0, s62
	s_nop 0
	global_load_lds_dwordx4 v[200:201], off
	s_waitcnt lgkmcnt(8)
	s_barrier
	s_waitcnt lgkmcnt(0)
	s_setprio 1
	v_mfma_f32_16x16x32_bf16 v[124:127], v[152:155], v[168:171], v[124:127]
	v_mfma_f32_16x16x32_bf16 v[120:123], v[160:163], v[168:171], v[120:123]
	v_mfma_f32_16x16x32_bf16 v[116:119], v[152:155], v[176:179], v[116:119]
	v_mfma_f32_16x16x32_bf16 v[112:115], v[160:163], v[176:179], v[112:115]
	v_mfma_f32_16x16x32_bf16 v[108:111], v[152:155], v[184:187], v[108:111]
	v_mfma_f32_16x16x32_bf16 v[104:107], v[160:163], v[184:187], v[104:107]
	v_mfma_f32_16x16x32_bf16 v[100:103], v[152:155], v[192:195], v[100:103]
	v_mfma_f32_16x16x32_bf16 v[96:99], v[160:163], v[192:195], v[96:99]
	v_mfma_f32_16x16x32_bf16 v[124:127], v[156:159], v[172:175], v[124:127]
	v_mfma_f32_16x16x32_bf16 v[120:123], v[164:167], v[172:175], v[120:123]
	v_mfma_f32_16x16x32_bf16 v[116:119], v[156:159], v[180:183], v[116:119]
	v_mfma_f32_16x16x32_bf16 v[112:115], v[164:167], v[180:183], v[112:115]
	v_mfma_f32_16x16x32_bf16 v[108:111], v[156:159], v[188:191], v[108:111]
	v_mfma_f32_16x16x32_bf16 v[104:107], v[164:167], v[188:191], v[104:107]
	v_mfma_f32_16x16x32_bf16 v[100:103], v[156:159], v[196:199], v[100:103]
	v_mfma_f32_16x16x32_bf16 v[96:99], v[164:167], v[196:199], v[96:99]
	s_setprio 0
	s_barrier
	s_add_i32 s42, 0, 0x1c000
	s_add_i32 s43, s76, s48
	v_add_u32_e32 v151, s42, v146
	v_lshl_add_u64 v[208:209], v[208:209], 0, s[0:1]
	s_mov_b32 m0, s43
	ds_read_b128 v[200:203], v151
	ds_read_b128 v[204:207], v151 offset:1024
	ds_read_b128 v[212:215], v151 offset:2048
	ds_read_b128 v[216:219], v151 offset:3072
	global_load_lds_dwordx4 v[208:209], off
	v_lshl_add_u64 v[208:209], v[220:221], 0, s[0:1]
	s_add_i32 m0, s43, 0x2000
	s_nop 0
	global_load_lds_dwordx4 v[208:209], off
	s_barrier
	s_waitcnt lgkmcnt(0)
	s_setprio 1
	v_mfma_f32_16x16x32_bf16 v[76:79], v[200:203], v[168:171], v[76:79]
	v_mfma_f32_16x16x32_bf16 v[72:75], v[212:215], v[168:171], v[72:75]
	v_mfma_f32_16x16x32_bf16 v[60:63], v[200:203], v[176:179], v[60:63]
	v_mfma_f32_16x16x32_bf16 v[56:59], v[212:215], v[176:179], v[56:59]
	v_mfma_f32_16x16x32_bf16 v[44:47], v[200:203], v[184:187], v[44:47]
	v_mfma_f32_16x16x32_bf16 v[40:43], v[212:215], v[184:187], v[40:43]
	v_mfma_f32_16x16x32_bf16 v[36:39], v[200:203], v[192:195], v[36:39]
	v_mfma_f32_16x16x32_bf16 v[32:35], v[212:215], v[192:195], v[32:35]
	v_mfma_f32_16x16x32_bf16 v[76:79], v[204:207], v[172:175], v[76:79]
	v_mfma_f32_16x16x32_bf16 v[72:75], v[216:219], v[172:175], v[72:75]
	v_mfma_f32_16x16x32_bf16 v[60:63], v[204:207], v[180:183], v[60:63]
	v_mfma_f32_16x16x32_bf16 v[56:59], v[216:219], v[180:183], v[56:59]
	v_mfma_f32_16x16x32_bf16 v[44:47], v[204:207], v[188:191], v[44:47]
	v_mfma_f32_16x16x32_bf16 v[40:43], v[216:219], v[188:191], v[40:43]
	v_mfma_f32_16x16x32_bf16 v[36:39], v[204:207], v[196:199], v[36:39]
	v_mfma_f32_16x16x32_bf16 v[32:35], v[216:219], v[196:199], v[32:35]
	s_setprio 0
	s_mov_b32 m0, s63
	v_lshl_add_u64 v[208:209], v[222:223], 0, s[0:1]
	s_barrier
	ds_read_b128 v[168:171], v149 offset:49152
	ds_read_b128 v[172:175], v149 offset:50176
	ds_read_b128 v[176:179], v149 offset:51200
	ds_read_b128 v[180:183], v149 offset:52224
	ds_read_b128 v[184:187], v149 offset:53248
	ds_read_b128 v[188:191], v149 offset:54272
	ds_read_b128 v[192:195], v149 offset:55296
	ds_read_b128 v[196:199], v149 offset:56320
	global_load_lds_dwordx4 v[208:209], off
	v_lshl_add_u64 v[208:209], v[224:225], 0, s[0:1]
	s_mov_b32 m0, s64
	s_nop 0
	global_load_lds_dwordx4 v[208:209], off
	s_barrier
	s_waitcnt lgkmcnt(0)
	s_setprio 1
	v_mfma_f32_16x16x32_bf16 v[92:95], v[152:155], v[168:171], v[92:95]
	v_mfma_f32_16x16x32_bf16 v[88:91], v[160:163], v[168:171], v[88:91]
	v_mfma_f32_16x16x32_bf16 v[84:87], v[152:155], v[176:179], v[84:87]
	v_mfma_f32_16x16x32_bf16 v[80:83], v[160:163], v[176:179], v[80:83]
	v_mfma_f32_16x16x32_bf16 v[68:71], v[152:155], v[184:187], v[68:71]
	v_mfma_f32_16x16x32_bf16 v[64:67], v[160:163], v[184:187], v[64:67]
	v_mfma_f32_16x16x32_bf16 v[52:55], v[152:155], v[192:195], v[52:55]
	v_mfma_f32_16x16x32_bf16 v[48:51], v[160:163], v[192:195], v[48:51]
	v_mfma_f32_16x16x32_bf16 v[92:95], v[156:159], v[172:175], v[92:95]
	v_mfma_f32_16x16x32_bf16 v[88:91], v[164:167], v[172:175], v[88:91]
	v_mfma_f32_16x16x32_bf16 v[84:87], v[156:159], v[180:183], v[84:87]
	v_mfma_f32_16x16x32_bf16 v[80:83], v[164:167], v[180:183], v[80:83]
	v_mfma_f32_16x16x32_bf16 v[68:71], v[156:159], v[188:191], v[68:71]
	v_mfma_f32_16x16x32_bf16 v[64:67], v[164:167], v[188:191], v[64:67]
	v_mfma_f32_16x16x32_bf16 v[52:55], v[156:159], v[196:199], v[52:55]
	v_mfma_f32_16x16x32_bf16 v[48:51], v[164:167], v[196:199], v[48:51]
	s_setprio 0
	s_barrier
	s_add_u32 s40, s40, 0x40080
	s_addc_u32 s41, s41, 0
	s_add_i32 s42, s42, s48
	v_lshl_add_u64 v[152:153], s[40:41], 0, v[132:133]
	s_mov_b32 m0, s42
	s_nop 0
	global_load_lds_dwordx4 v[152:153], off
	v_lshl_add_u64 v[152:153], s[40:41], 0, v[128:129]
	s_add_i32 m0, s42, 0x2000
	s_nop 0
	global_load_lds_dwordx4 v[152:153], off
	s_waitcnt vmcnt(6)
	s_barrier
	s_setprio 1
	v_mfma_f32_16x16x32_bf16 v[28:31], v[200:203], v[168:171], v[28:31]
	v_mfma_f32_16x16x32_bf16 v[24:27], v[212:215], v[168:171], v[24:27]
	v_mfma_f32_16x16x32_bf16 v[20:23], v[200:203], v[176:179], v[20:23]
	v_mfma_f32_16x16x32_bf16 v[16:19], v[212:215], v[176:179], v[16:19]
	v_mfma_f32_16x16x32_bf16 v[12:15], v[200:203], v[184:187], v[12:15]
	v_mfma_f32_16x16x32_bf16 v[8:11], v[212:215], v[184:187], v[8:11]
	v_mfma_f32_16x16x32_bf16 v[4:7], v[200:203], v[192:195], v[4:7]
	v_mfma_f32_16x16x32_bf16 v[0:3], v[212:215], v[192:195], v[0:3]
	v_mfma_f32_16x16x32_bf16 v[28:31], v[204:207], v[172:175], v[28:31]
	v_mfma_f32_16x16x32_bf16 v[24:27], v[216:219], v[172:175], v[24:27]
	v_mfma_f32_16x16x32_bf16 v[20:23], v[204:207], v[180:183], v[20:23]
	v_mfma_f32_16x16x32_bf16 v[16:19], v[216:219], v[180:183], v[16:19]
	v_mfma_f32_16x16x32_bf16 v[12:15], v[204:207], v[188:191], v[12:15]
	v_mfma_f32_16x16x32_bf16 v[8:11], v[216:219], v[188:191], v[8:11]
	v_mfma_f32_16x16x32_bf16 v[4:7], v[204:207], v[196:199], v[4:7]
	v_mfma_f32_16x16x32_bf16 v[0:3], v[216:219], v[196:199], v[0:3]
	s_setprio 0
	s_add_i32 s75, s75, 2
	s_add_u32 s38, s38, 0x100
	s_addc_u32 s39, s39, 0
	s_add_u32 s73, s73, 0x100
	s_addc_u32 s74, s74, 0
	s_cmp_gt_u32 s75, 13
	s_barrier
	s_cbranch_scc0 .LBB0_150
	v_lshl_add_u32 v151, s36, 8, v144
	s_cmp_gt_i32 s71, 11
	s_mov_b64 s[36:37], -1
	s_cbranch_scc0 .LBB0_155
	s_and_saveexec_b64 s[36:37], s[2:3]
	s_cbranch_execz .LBB0_154
	v_lshl_or_b32 v152, v151, 8, v147
	v_readlane_b32 s38, v253, 59
	v_readlane_b32 s39, v253, 60
	v_or_b32_e32 v153, 0x1000, v152
	s_nop 3
	global_store_dwordx4 v153, v[116:119], s[38:39] nt
	v_or_b32_e32 v153, 0x2000, v152
	global_store_dwordx4 v153, v[108:111], s[38:39] nt
	v_or_b32_e32 v153, 0x3000, v152
	global_store_dwordx4 v153, v[100:103], s[38:39] nt
	v_add_u32_e32 v153, 0x8000, v152
	global_store_dwordx4 v153, v[92:95], s[38:39] nt
	v_add_u32_e32 v153, 0x9000, v152
	global_store_dwordx4 v153, v[84:87], s[38:39] nt
	v_add_u32_e32 v153, 0xa000, v152
	global_store_dwordx4 v153, v[68:71], s[38:39] nt
	v_add_u32_e32 v153, 0xb000, v152
	global_store_dwordx4 v153, v[52:55], s[38:39] nt
	v_or_b32_e32 v153, 16, v152
	global_store_dwordx4 v153, v[120:123], s[38:39] nt
	v_or_b32_e32 v153, 0x1010, v152
	global_store_dwordx4 v153, v[112:115], s[38:39] nt
	v_or_b32_e32 v153, 0x2010, v152
	global_store_dwordx4 v153, v[104:107], s[38:39] nt
	v_or_b32_e32 v153, 0x3010, v152
	global_store_dwordx4 v153, v[96:99], s[38:39] nt
	v_add_u32_e32 v153, 0x8010, v152
	global_store_dwordx4 v153, v[88:91], s[38:39] nt
	v_add_u32_e32 v153, 0x9010, v152
	global_store_dwordx4 v152, v[124:127], s[38:39] nt
	global_store_dwordx4 v153, v[80:83], s[38:39] nt
	v_add_u32_e32 v153, 0xa010, v152
	v_add_u32_e32 v152, 0xb010, v152
	global_store_dwordx4 v153, v[64:67], s[38:39] nt
	global_store_dwordx4 v152, v[48:51], s[38:39] nt

.LBB0_177:
	ds_read_b128 v[152:155], v149
	ds_read_b128 v[156:159], v149 offset:1024
	ds_read_b128 v[160:163], v149 offset:2048
	ds_read_b128 v[164:167], v149 offset:3072
	s_add_u32 s36, s34, 0xfffc0080
	s_addc_u32 s37, s35, -1
	s_cmp_eq_u32 s68, 12
	s_cselect_b32 s39, s9, s37
	s_cselect_b32 s38, s64, s36
	s_cselect_b32 s37, s3, s67
	s_cselect_b32 s36, s65, s66
	v_lshl_add_u64 v[144:145], s[34:35], 0, v[136:137]
	s_add_i32 m0, s13, 0xc000
	ds_read_b128 v[168:171], v150
	ds_read_b128 v[172:175], v150 offset:1024
	ds_read_b128 v[176:179], v150 offset:2048
	ds_read_b128 v[180:183], v150 offset:3072
	ds_read_b128 v[184:187], v150 offset:4096
	ds_read_b128 v[188:191], v150 offset:5120
	ds_read_b128 v[192:195], v150 offset:6144
	ds_read_b128 v[196:199], v150 offset:7168
	global_load_lds_dwordx4 v[144:145], off
	v_lshl_add_u64 v[144:145], s[34:35], 0, v[138:139]
	s_add_i32 m0, s13, 0xe000
	s_nop 0
	global_load_lds_dwordx4 v[144:145], off
	s_waitcnt lgkmcnt(8)
	s_barrier
	s_waitcnt lgkmcnt(0)
	s_setprio 1
	v_mfma_f32_16x16x32_bf16 v[124:127], v[152:155], v[168:171], v[124:127]
	v_mfma_f32_16x16x32_bf16 v[120:123], v[160:163], v[168:171], v[120:123]
	v_mfma_f32_16x16x32_bf16 v[112:115], v[152:155], v[176:179], v[112:115]
	v_mfma_f32_16x16x32_bf16 v[104:107], v[160:163], v[176:179], v[104:107]
	v_mfma_f32_16x16x32_bf16 v[96:99], v[152:155], v[184:187], v[96:99]
	v_mfma_f32_16x16x32_bf16 v[88:91], v[160:163], v[184:187], v[88:91]
	v_mfma_f32_16x16x32_bf16 v[80:83], v[152:155], v[192:195], v[80:83]
	v_mfma_f32_16x16x32_bf16 v[72:75], v[160:163], v[192:195], v[72:75]
	v_mfma_f32_16x16x32_bf16 v[124:127], v[156:159], v[172:175], v[124:127]
	v_mfma_f32_16x16x32_bf16 v[120:123], v[164:167], v[172:175], v[120:123]
	v_mfma_f32_16x16x32_bf16 v[112:115], v[156:159], v[180:183], v[112:115]
	v_mfma_f32_16x16x32_bf16 v[104:107], v[164:167], v[180:183], v[104:107]
	v_mfma_f32_16x16x32_bf16 v[96:99], v[156:159], v[188:191], v[96:99]
	v_mfma_f32_16x16x32_bf16 v[88:91], v[164:167], v[188:191], v[88:91]
	v_mfma_f32_16x16x32_bf16 v[80:83], v[156:159], v[196:199], v[80:83]
	v_mfma_f32_16x16x32_bf16 v[72:75], v[164:167], v[196:199], v[72:75]
	s_setprio 0
	s_barrier
	s_add_i32 s69, s55, s42
	v_lshl_add_u64 v[144:145], s[36:37], 0, v[130:131]
	s_mov_b32 m0, s69
	ds_read_b128 v[200:203], v151
	ds_read_b128 v[204:207], v151 offset:1024
	ds_read_b128 v[212:215], v151 offset:2048
	ds_read_b128 v[216:219], v151 offset:3072
	global_load_lds_dwordx4 v[144:145], off
	v_lshl_add_u64 v[208:209], s[36:37], 0, v[134:135]
	s_add_i32 m0, s69, 0x2000
	s_nop 0
	global_load_lds_dwordx4 v[208:209], off
	s_barrier
	s_waitcnt lgkmcnt(0)
	s_setprio 1
	v_mfma_f32_16x16x32_bf16 v[116:119], v[200:203], v[168:171], v[116:119]
	v_mfma_f32_16x16x32_bf16 v[108:111], v[212:215], v[168:171], v[108:111]
	v_mfma_f32_16x16x32_bf16 v[100:103], v[200:203], v[176:179], v[100:103]
	v_mfma_f32_16x16x32_bf16 v[92:95], v[212:215], v[176:179], v[92:95]
	v_mfma_f32_16x16x32_bf16 v[84:87], v[200:203], v[184:187], v[84:87]
	v_mfma_f32_16x16x32_bf16 v[76:79], v[212:215], v[184:187], v[76:79]
	v_mfma_f32_16x16x32_bf16 v[68:71], v[200:203], v[192:195], v[68:71]
	v_mfma_f32_16x16x32_bf16 v[64:67], v[212:215], v[192:195], v[64:67]
	v_mfma_f32_16x16x32_bf16 v[116:119], v[204:207], v[172:175], v[116:119]
	v_mfma_f32_16x16x32_bf16 v[108:111], v[216:219], v[172:175], v[108:111]
	v_mfma_f32_16x16x32_bf16 v[100:103], v[204:207], v[180:183], v[100:103]
	v_mfma_f32_16x16x32_bf16 v[92:95], v[216:219], v[180:183], v[92:95]
	v_mfma_f32_16x16x32_bf16 v[84:87], v[204:207], v[188:191], v[84:87]
	v_mfma_f32_16x16x32_bf16 v[76:79], v[216:219], v[188:191], v[76:79]
	v_mfma_f32_16x16x32_bf16 v[68:71], v[204:207], v[196:199], v[68:71]
	v_mfma_f32_16x16x32_bf16 v[64:67], v[216:219], v[196:199], v[64:67]
	s_setprio 0
	s_mov_b32 m0, s13
	v_lshl_add_u64 v[220:221], s[38:39], 0, v[128:129]
	s_barrier
	ds_read_b128 v[168:171], v150 offset:16384
	ds_read_b128 v[172:175], v150 offset:17408
	ds_read_b128 v[176:179], v150 offset:18432
	ds_read_b128 v[180:183], v150 offset:19456
	ds_read_b128 v[184:187], v150 offset:20480
	ds_read_b128 v[188:191], v150 offset:21504
	ds_read_b128 v[192:195], v150 offset:22528
	ds_read_b128 v[196:199], v150 offset:23552
	global_load_lds_dwordx4 v[220:221], off
	v_lshl_add_u64 v[222:223], s[38:39], 0, v[132:133]
	s_mov_b32 m0, s43
	s_nop 0
	global_load_lds_dwordx4 v[222:223], off
	s_barrier
	s_waitcnt lgkmcnt(0)
	s_setprio 1
	v_mfma_f32_16x16x32_bf16 v[60:63], v[152:155], v[168:171], v[60:63]
	v_mfma_f32_16x16x32_bf16 v[56:59], v[160:163], v[168:171], v[56:59]
	v_mfma_f32_16x16x32_bf16 v[52:55], v[152:155], v[176:179], v[52:55]
	v_mfma_f32_16x16x32_bf16 v[44:47], v[160:163], v[176:179], v[44:47]
	v_mfma_f32_16x16x32_bf16 v[36:39], v[152:155], v[184:187], v[36:39]
	v_mfma_f32_16x16x32_bf16 v[28:31], v[160:163], v[184:187], v[28:31]
	v_mfma_f32_16x16x32_bf16 v[20:23], v[152:155], v[192:195], v[20:23]
	v_mfma_f32_16x16x32_bf16 v[12:15], v[160:163], v[192:195], v[12:15]
	v_mfma_f32_16x16x32_bf16 v[60:63], v[156:159], v[172:175], v[60:63]
	v_mfma_f32_16x16x32_bf16 v[56:59], v[164:167], v[172:175], v[56:59]
	v_mfma_f32_16x16x32_bf16 v[52:55], v[156:159], v[180:183], v[52:55]
	v_mfma_f32_16x16x32_bf16 v[44:47], v[164:167], v[180:183], v[44:47]
	v_mfma_f32_16x16x32_bf16 v[36:39], v[156:159], v[188:191], v[36:39]
	v_mfma_f32_16x16x32_bf16 v[28:31], v[164:167], v[188:191], v[28:31]
	v_mfma_f32_16x16x32_bf16 v[20:23], v[156:159], v[196:199], v[20:23]
	v_mfma_f32_16x16x32_bf16 v[12:15], v[164:167], v[196:199], v[12:15]
	s_setprio 0
	s_barrier
	s_add_u32 s70, s36, 0x40000
	s_addc_u32 s71, s37, 0
	s_add_i32 s69, s62, s42
	v_lshl_add_u64 v[152:153], s[70:71], 0, v[130:131]
	s_mov_b32 m0, s69
	s_nop 0
	global_load_lds_dwordx4 v[152:153], off
	v_lshl_add_u64 v[152:153], s[70:71], 0, v[134:135]
	s_add_i32 m0, s69, 0x2000
	s_nop 0
	global_load_lds_dwordx4 v[152:153], off
	s_waitcnt vmcnt(6)
	s_barrier
	s_setprio 1
	v_mfma_f32_16x16x32_bf16 v[48:51], v[200:203], v[168:171], v[48:51]
	v_mfma_f32_16x16x32_bf16 v[40:43], v[212:215], v[168:171], v[40:43]
	v_mfma_f32_16x16x32_bf16 v[32:35], v[200:203], v[176:179], v[32:35]
	v_mfma_f32_16x16x32_bf16 v[24:27], v[212:215], v[176:179], v[24:27]
	v_mfma_f32_16x16x32_bf16 v[16:19], v[200:203], v[184:187], v[16:19]
	v_mfma_f32_16x16x32_bf16 v[8:11], v[212:215], v[184:187], v[8:11]
	v_mfma_f32_16x16x32_bf16 v[4:7], v[200:203], v[192:195], v[4:7]
	v_mfma_f32_16x16x32_bf16 v[0:3], v[212:215], v[192:195], v[0:3]
	v_mfma_f32_16x16x32_bf16 v[48:51], v[204:207], v[172:175], v[48:51]
	v_mfma_f32_16x16x32_bf16 v[40:43], v[216:219], v[172:175], v[40:43]
	v_mfma_f32_16x16x32_bf16 v[32:35], v[204:207], v[180:183], v[32:35]
	v_mfma_f32_16x16x32_bf16 v[24:27], v[216:219], v[180:183], v[24:27]
	v_mfma_f32_16x16x32_bf16 v[16:19], v[204:207], v[188:191], v[16:19]
	v_mfma_f32_16x16x32_bf16 v[8:11], v[216:219], v[188:191], v[8:11]
	v_mfma_f32_16x16x32_bf16 v[4:7], v[204:207], v[196:199], v[4:7]
	v_mfma_f32_16x16x32_bf16 v[0:3], v[216:219], v[196:199], v[0:3]
	s_setprio 0
	s_add_i32 s69, 0, 0x18000
	v_add_u32_e32 v164, s69, v147
	s_barrier
	ds_read_b128 v[152:155], v164
	ds_read_b128 v[156:159], v164 offset:1024
	ds_read_b128 v[160:163], v164 offset:2048
	ds_read_b128 v[164:167], v164 offset:3072
	s_add_u32 s38, s38, 0x40000
	s_addc_u32 s39, s39, 0
	s_mov_b32 m0, s48
	v_lshl_add_u64 v[200:201], s[38:39], 0, v[128:129]
	ds_read_b128 v[168:171], v150 offset:32768
	ds_read_b128 v[172:175], v150 offset:33792
	ds_read_b128 v[176:179], v150 offset:34816
	ds_read_b128 v[180:183], v150 offset:35840
	ds_read_b128 v[184:187], v150 offset:36864
	ds_read_b128 v[188:191], v150 offset:37888
	ds_read_b128 v[192:195], v150 offset:38912
	ds_read_b128 v[196:199], v150 offset:39936
	global_load_lds_dwordx4 v[200:201], off
	v_lshl_add_u64 v[200:201], s[38:39], 0, v[132:133]
	s_mov_b32 m0, s49
	s_nop 0
	global_load_lds_dwordx4 v[200:201], off
	s_waitcnt lgkmcnt(8)
	s_barrier
	s_waitcnt lgkmcnt(0)
	s_setprio 1
	v_mfma_f32_16x16x32_bf16 v[124:127], v[152:155], v[168:171], v[124:127]
	v_mfma_f32_16x16x32_bf16 v[120:123], v[160:163], v[168:171], v[120:123]
	v_mfma_f32_16x16x32_bf16 v[112:115], v[152:155], v[176:179], v[112:115]
	v_mfma_f32_16x16x32_bf16 v[104:107], v[160:163], v[176:179], v[104:107]
	v_mfma_f32_16x16x32_bf16 v[96:99], v[152:155], v[184:187], v[96:99]
	v_mfma_f32_16x16x32_bf16 v[88:91], v[160:163], v[184:187], v[88:91]
	v_mfma_f32_16x16x32_bf16 v[80:83], v[152:155], v[192:195], v[80:83]
	v_mfma_f32_16x16x32_bf16 v[72:75], v[160:163], v[192:195], v[72:75]
	v_mfma_f32_16x16x32_bf16 v[124:127], v[156:159], v[172:175], v[124:127]
	v_mfma_f32_16x16x32_bf16 v[120:123], v[164:167], v[172:175], v[120:123]
	v_mfma_f32_16x16x32_bf16 v[112:115], v[156:159], v[180:183], v[112:115]
	v_mfma_f32_16x16x32_bf16 v[104:107], v[164:167], v[180:183], v[104:107]
	v_mfma_f32_16x16x32_bf16 v[96:99], v[156:159], v[188:191], v[96:99]
	v_mfma_f32_16x16x32_bf16 v[88:91], v[164:167], v[188:191], v[88:91]
	v_mfma_f32_16x16x32_bf16 v[80:83], v[156:159], v[196:199], v[80:83]
	v_mfma_f32_16x16x32_bf16 v[72:75], v[164:167], v[196:199], v[72:75]
	s_setprio 0
	s_barrier
	s_add_i32 s38, 0, 0x1c000
	s_add_i32 s39, s69, s42
	v_add_u32_e32 v211, s38, v147
	v_lshl_add_u64 v[144:145], v[144:145], 0, s[0:1]
	s_mov_b32 m0, s39
	ds_read_b128 v[200:203], v211
	ds_read_b128 v[204:207], v211 offset:1024
	ds_read_b128 v[212:215], v211 offset:2048
	ds_read_b128 v[216:219], v211 offset:3072
	global_load_lds_dwordx4 v[144:145], off
	v_lshl_add_u64 v[144:145], v[208:209], 0, s[0:1]
	s_add_i32 m0, s39, 0x2000
	s_nop 0
	global_load_lds_dwordx4 v[144:145], off
	s_barrier
	s_waitcnt lgkmcnt(0)
	s_setprio 1
	v_mfma_f32_16x16x32_bf16 v[116:119], v[200:203], v[168:171], v[116:119]
	v_mfma_f32_16x16x32_bf16 v[108:111], v[212:215], v[168:171], v[108:111]
	v_mfma_f32_16x16x32_bf16 v[100:103], v[200:203], v[176:179], v[100:103]
	v_mfma_f32_16x16x32_bf16 v[92:95], v[212:215], v[176:179], v[92:95]
	v_mfma_f32_16x16x32_bf16 v[84:87], v[200:203], v[184:187], v[84:87]
	v_mfma_f32_16x16x32_bf16 v[76:79], v[212:215], v[184:187], v[76:79]
	v_mfma_f32_16x16x32_bf16 v[68:71], v[200:203], v[192:195], v[68:71]
	v_mfma_f32_16x16x32_bf16 v[64:67], v[212:215], v[192:195], v[64:67]
	v_mfma_f32_16x16x32_bf16 v[116:119], v[204:207], v[172:175], v[116:119]
	v_mfma_f32_16x16x32_bf16 v[108:111], v[216:219], v[172:175], v[108:111]
	v_mfma_f32_16x16x32_bf16 v[100:103], v[204:207], v[180:183], v[100:103]
	v_mfma_f32_16x16x32_bf16 v[92:95], v[216:219], v[180:183], v[92:95]
	v_mfma_f32_16x16x32_bf16 v[84:87], v[204:207], v[188:191], v[84:87]
	v_mfma_f32_16x16x32_bf16 v[76:79], v[216:219], v[188:191], v[76:79]
	v_mfma_f32_16x16x32_bf16 v[68:71], v[204:207], v[196:199], v[68:71]
	v_mfma_f32_16x16x32_bf16 v[64:67], v[216:219], v[196:199], v[64:67]
	s_setprio 0
	s_mov_b32 m0, s51
	v_lshl_add_u64 v[144:145], v[220:221], 0, s[0:1]
	s_barrier
	ds_read_b128 v[168:171], v150 offset:49152
	ds_read_b128 v[172:175], v150 offset:50176
	ds_read_b128 v[176:179], v150 offset:51200
	ds_read_b128 v[180:183], v150 offset:52224
	ds_read_b128 v[184:187], v150 offset:53248
	ds_read_b128 v[188:191], v150 offset:54272
	ds_read_b128 v[192:195], v150 offset:55296
	ds_read_b128 v[196:199], v150 offset:56320
	global_load_lds_dwordx4 v[144:145], off
	v_lshl_add_u64 v[144:145], v[222:223], 0, s[0:1]
	s_mov_b32 m0, s54
	s_nop 0
	global_load_lds_dwordx4 v[144:145], off
	s_barrier
	s_waitcnt lgkmcnt(0)
	s_setprio 1
	v_mfma_f32_16x16x32_bf16 v[60:63], v[152:155], v[168:171], v[60:63]
	v_mfma_f32_16x16x32_bf16 v[56:59], v[160:163], v[168:171], v[56:59]
	v_mfma_f32_16x16x32_bf16 v[52:55], v[152:155], v[176:179], v[52:55]
	v_mfma_f32_16x16x32_bf16 v[44:47], v[160:163], v[176:179], v[44:47]
	v_mfma_f32_16x16x32_bf16 v[36:39], v[152:155], v[184:187], v[36:39]
	v_mfma_f32_16x16x32_bf16 v[28:31], v[160:163], v[184:187], v[28:31]
	v_mfma_f32_16x16x32_bf16 v[20:23], v[152:155], v[192:195], v[20:23]
	v_mfma_f32_16x16x32_bf16 v[12:15], v[160:163], v[192:195], v[12:15]
	v_mfma_f32_16x16x32_bf16 v[60:63], v[156:159], v[172:175], v[60:63]
	v_mfma_f32_16x16x32_bf16 v[56:59], v[164:167], v[172:175], v[56:59]
	v_mfma_f32_16x16x32_bf16 v[52:55], v[156:159], v[180:183], v[52:55]
	v_mfma_f32_16x16x32_bf16 v[44:47], v[164:167], v[180:183], v[44:47]
	v_mfma_f32_16x16x32_bf16 v[36:39], v[156:159], v[188:191], v[36:39]
	v_mfma_f32_16x16x32_bf16 v[28:31], v[164:167], v[188:191], v[28:31]
	v_mfma_f32_16x16x32_bf16 v[20:23], v[156:159], v[196:199], v[20:23]
	v_mfma_f32_16x16x32_bf16 v[12:15], v[164:167], v[196:199], v[12:15]
	s_setprio 0
	s_barrier
	s_add_u32 s36, s36, 0x40080
	s_addc_u32 s37, s37, 0
	s_add_i32 s38, s38, s42
	v_lshl_add_u64 v[144:145], s[36:37], 0, v[130:131]
	s_mov_b32 m0, s38
	s_nop 0
	global_load_lds_dwordx4 v[144:145], off
	v_lshl_add_u64 v[144:145], s[36:37], 0, v[134:135]
	s_add_i32 m0, s38, 0x2000
	s_nop 0
	global_load_lds_dwordx4 v[144:145], off
	s_waitcnt vmcnt(6)
	s_barrier
	s_setprio 1
	v_mfma_f32_16x16x32_bf16 v[48:51], v[200:203], v[168:171], v[48:51]
	v_mfma_f32_16x16x32_bf16 v[40:43], v[212:215], v[168:171], v[40:43]
	v_mfma_f32_16x16x32_bf16 v[32:35], v[200:203], v[176:179], v[32:35]
	v_mfma_f32_16x16x32_bf16 v[24:27], v[212:215], v[176:179], v[24:27]
	v_mfma_f32_16x16x32_bf16 v[16:19], v[200:203], v[184:187], v[16:19]
	v_mfma_f32_16x16x32_bf16 v[8:11], v[212:215], v[184:187], v[8:11]
	v_mfma_f32_16x16x32_bf16 v[4:7], v[200:203], v[192:195], v[4:7]
	v_mfma_f32_16x16x32_bf16 v[0:3], v[212:215], v[192:195], v[0:3]
	v_mfma_f32_16x16x32_bf16 v[48:51], v[204:207], v[172:175], v[48:51]
	v_mfma_f32_16x16x32_bf16 v[40:43], v[216:219], v[172:175], v[40:43]
	v_mfma_f32_16x16x32_bf16 v[32:35], v[204:207], v[180:183], v[32:35]
	v_mfma_f32_16x16x32_bf16 v[24:27], v[216:219], v[180:183], v[24:27]
	v_mfma_f32_16x16x32_bf16 v[16:19], v[204:207], v[188:191], v[16:19]
	v_mfma_f32_16x16x32_bf16 v[8:11], v[216:219], v[188:191], v[8:11]
	v_mfma_f32_16x16x32_bf16 v[4:7], v[204:207], v[196:199], v[4:7]
	v_mfma_f32_16x16x32_bf16 v[0:3], v[216:219], v[196:199], v[0:3]
	s_setprio 0
	s_add_i32 s68, s68, 2
	s_add_u32 s34, s34, 0x100
	s_addc_u32 s35, s35, 0
	s_add_u32 s66, s66, 0x100
	s_addc_u32 s67, s67, 0
	s_cmp_gt_u32 s68, 13
	s_barrier
	s_cbranch_scc0 .LBB0_177
	v_lshl_add_u32 v152, s12, 8, v146
	v_ashrrev_i32_e32 v153, 31, v152
	v_lshl_or_b32 v144, s63, 8, v148
	v_readlane_b32 s34, v253, 61
	v_ashrrev_i32_e32 v145, 31, v144
	v_lshlrev_b64 v[154:155], 17, v[152:153]
	v_readlane_b32 s35, v253, 62
	v_lshlrev_b64 v[156:157], 1, v[144:145]
	v_cvt_pk_bf16_f32 v124, v124, v125
	v_cvt_pk_bf16_f32 v125, v126, v127
	v_cvt_pk_bf16_f32 v126, v120, v121
	s_nop 0
	v_lshl_add_u64 v[154:155], s[34:35], 0, v[154:155]
	v_lshl_add_u64 v[144:145], v[154:155], 0, v[156:157]
	v_cvt_pk_bf16_f32 v127, v122, v123
	global_store_dwordx4 v[144:145], v[124:127], off nt
	v_cvt_pk_bf16_f32 v116, v116, v117
	v_cvt_pk_bf16_f32 v117, v118, v119
	v_cvt_pk_bf16_f32 v118, v108, v109
	v_or_b32_e32 v108, 16, v152
	v_ashrrev_i32_e32 v109, 31, v108
	v_lshlrev_b64 v[108:109], 17, v[108:109]
	v_lshl_add_u64 v[108:109], s[34:35], 0, v[108:109]
	v_cvt_pk_bf16_f32 v119, v110, v111
	global_store_dwordx4 v[144:145], v[116:119], off offset:256 nt
	s_mov_b32 s3, 0x1000000
	s_mov_b32 s63, s2
	v_lshl_add_u64 v[116:117], v[108:109], 0, v[156:157]
	v_cvt_pk_bf16_f32 v108, v112, v113
	v_cvt_pk_bf16_f32 v109, v114, v115
	v_cvt_pk_bf16_f32 v110, v104, v105
	v_cvt_pk_bf16_f32 v111, v106, v107
	global_store_dwordx4 v[116:117], v[108:111], off nt
	v_cvt_pk_bf16_f32 v100, v100, v101
	v_cvt_pk_bf16_f32 v101, v102, v103
	v_cvt_pk_bf16_f32 v102, v92, v93
	v_or_b32_e32 v92, 32, v152
	v_ashrrev_i32_e32 v93, 31, v92
	v_lshlrev_b64 v[92:93], 17, v[92:93]
	v_lshl_add_u64 v[92:93], s[34:35], 0, v[92:93]
	v_cvt_pk_bf16_f32 v103, v94, v95
	global_store_dwordx4 v[116:117], v[100:103], off offset:256 nt
	s_mov_b32 s12, s8
	s_mov_b64 s[36:37], s[30:31]
	v_lshl_add_u64 v[100:101], v[92:93], 0, v[156:157]
	v_cvt_pk_bf16_f32 v92, v96, v97
	v_cvt_pk_bf16_f32 v93, v98, v99
	v_cvt_pk_bf16_f32 v94, v88, v89
	v_cvt_pk_bf16_f32 v95, v90, v91
	global_store_dwordx4 v[100:101], v[92:95], off nt
	v_cvt_pk_bf16_f32 v84, v84, v85
	v_cvt_pk_bf16_f32 v85, v86, v87
	v_cvt_pk_bf16_f32 v86, v76, v77
	v_or_b32_e32 v76, 48, v152
	v_ashrrev_i32_e32 v77, 31, v76
	v_lshlrev_b64 v[76:77], 17, v[76:77]
	v_lshl_add_u64 v[76:77], s[34:35], 0, v[76:77]
	v_cvt_pk_bf16_f32 v87, v78, v79
	global_store_dwordx4 v[100:101], v[84:87], off offset:256 nt
	s_mov_b64 s[34:35], 0x1000000
	s_nop 0
	v_lshl_add_u64 v[84:85], v[76:77], 0, v[156:157]
	v_cvt_pk_bf16_f32 v76, v80, v81
	v_cvt_pk_bf16_f32 v77, v82, v83
	v_cvt_pk_bf16_f32 v78, v72, v73
	v_cvt_pk_bf16_f32 v79, v74, v75
	global_store_dwordx4 v[84:85], v[76:79], off nt
	v_cvt_pk_bf16_f32 v68, v68, v69
	v_cvt_pk_bf16_f32 v69, v70, v71
	v_cvt_pk_bf16_f32 v70, v64, v65
	v_cvt_pk_bf16_f32 v71, v66, v67
	global_store_dwordx4 v[84:85], v[68:71], off offset:256 nt
	v_cvt_pk_bf16_f32 v60, v60, v61
	v_cvt_pk_bf16_f32 v61, v62, v63
	v_cvt_pk_bf16_f32 v62, v56, v57
	v_add_co_u32_e32 v56, vcc, s3, v144
	v_lshl_add_u64 v[64:65], v[144:145], 0, s[34:35]
	s_nop 0
	v_addc_co_u32_e32 v57, vcc, 0, v145, vcc
	s_mov_b32 s3, 0x1200000
	v_cvt_pk_bf16_f32 v63, v58, v59
	global_store_dwordx4 v[56:57], v[60:63], off nt
	v_cvt_pk_bf16_f32 v48, v48, v49
	v_cvt_pk_bf16_f32 v49, v50, v51
	v_cvt_pk_bf16_f32 v50, v40, v41
	v_cvt_pk_bf16_f32 v51, v42, v43
	global_store_dwordx4 v[64:65], v[48:51], off offset:256 nt
	s_mov_b64 s[34:35], 0x1200000
	v_cvt_pk_bf16_f32 v40, v52, v53
	v_cvt_pk_bf16_f32 v41, v54, v55
	v_cvt_pk_bf16_f32 v42, v44, v45
	v_add_co_u32_e32 v44, vcc, s3, v144
	v_lshl_add_u64 v[48:49], v[144:145], 0, s[34:35]
	s_nop 0
	v_addc_co_u32_e32 v45, vcc, 0, v145, vcc
	s_mov_b32 s3, 0x1400000
	v_cvt_pk_bf16_f32 v43, v46, v47
	global_store_dwordx4 v[44:45], v[40:43], off nt
	v_cvt_pk_bf16_f32 v32, v32, v33
	v_cvt_pk_bf16_f32 v33, v34, v35
	v_cvt_pk_bf16_f32 v34, v24, v25
	v_cvt_pk_bf16_f32 v35, v26, v27
	global_store_dwordx4 v[48:49], v[32:35], off offset:256 nt
	s_mov_b64 s[34:35], 0x1400000
	v_cvt_pk_bf16_f32 v24, v36, v37
	v_cvt_pk_bf16_f32 v25, v38, v39
	v_cvt_pk_bf16_f32 v26, v28, v29
	v_add_co_u32_e32 v28, vcc, s3, v144
	v_lshl_add_u64 v[32:33], v[144:145], 0, s[34:35]
	s_nop 0
	v_addc_co_u32_e32 v29, vcc, 0, v145, vcc
	s_mov_b32 s3, 0x1600000
	v_cvt_pk_bf16_f32 v27, v30, v31
	global_store_dwordx4 v[28:29], v[24:27], off nt
	v_cvt_pk_bf16_f32 v16, v16, v17
	v_cvt_pk_bf16_f32 v17, v18, v19
	v_cvt_pk_bf16_f32 v18, v8, v9
	v_cvt_pk_bf16_f32 v19, v10, v11
	global_store_dwordx4 v[32:33], v[16:19], off offset:256 nt
	v_cvt_pk_bf16_f32 v8, v20, v21
	v_cvt_pk_bf16_f32 v9, v22, v23
	v_cvt_pk_bf16_f32 v10, v12, v13
	v_add_co_u32_e32 v12, vcc, s3, v144
	s_mov_b64 s[34:35], 0x1600000
	s_nop 0
	v_addc_co_u32_e32 v13, vcc, 0, v145, vcc
	v_lshl_add_u64 v[16:17], v[144:145], 0, s[34:35]
	s_and_b64 vcc, exec, s[4:5]
	s_mov_b64 s[34:35], s[14:15]
	v_cvt_pk_bf16_f32 v11, v14, v15
	global_store_dwordx4 v[12:13], v[8:11], off nt
	v_cvt_pk_bf16_f32 v4, v4, v5
	v_cvt_pk_bf16_f32 v5, v6, v7
	v_cvt_pk_bf16_f32 v6, v0, v1
	v_cvt_pk_bf16_f32 v7, v2, v3
	global_store_dwordx4 v[16:17], v[4:7], off offset:256 nt
	s_cbranch_vccz .LBB0_170
	s_waitcnt vmcnt(0)
	s_cmpk_gt_u32 s40, 0xff
	s_cbranch_scc1 .LBB0_181
	s_barrier

.LBB0_200:
	s_add_u32 s48, s42, 0xfffc0080
	s_addc_u32 s49, s43, -1
	s_add_i32 s81, 0, 0x10000
	v_add_u32_e32 v140, s81, v144
	ds_read_b128 v[148:151], v140
	ds_read_b128 v[152:155], v140 offset:1024
	ds_read_b128 v[156:159], v140 offset:2048
	ds_read_b128 v[160:163], v140 offset:3072
	s_cmp_eq_u32 s80, 12
	s_cselect_b32 s51, s35, s49
	s_cselect_b32 s50, s76, s48
	s_cselect_b32 s49, s31, s79
	s_cselect_b32 s48, s77, s78
	v_lshl_add_u64 v[140:141], s[42:43], 0, v[136:137]
	s_add_i32 m0, s37, 0xc000
	ds_read_b128 v[164:167], v146
	ds_read_b128 v[168:171], v146 offset:1024
	ds_read_b128 v[172:175], v146 offset:2048
	ds_read_b128 v[176:179], v146 offset:3072
	ds_read_b128 v[180:183], v146 offset:4096
	ds_read_b128 v[184:187], v146 offset:5120
	ds_read_b128 v[188:191], v146 offset:6144
	ds_read_b128 v[192:195], v146 offset:7168
	global_load_lds_dwordx4 v[140:141], off
	v_lshl_add_u64 v[140:141], s[42:43], 0, v[138:139]
	s_add_i32 m0, s37, 0xe000
	s_nop 0
	global_load_lds_dwordx4 v[140:141], off
	s_waitcnt lgkmcnt(8)
	s_barrier
	s_waitcnt lgkmcnt(0)
	s_setprio 1
	v_mfma_f32_16x16x32_bf16 v[124:127], v[148:151], v[164:167], v[124:127]
	v_mfma_f32_16x16x32_bf16 v[120:123], v[156:159], v[164:167], v[120:123]
	v_mfma_f32_16x16x32_bf16 v[116:119], v[148:151], v[172:175], v[116:119]
	v_mfma_f32_16x16x32_bf16 v[108:111], v[156:159], v[172:175], v[108:111]
	v_mfma_f32_16x16x32_bf16 v[100:103], v[148:151], v[180:183], v[100:103]
	v_mfma_f32_16x16x32_bf16 v[92:95], v[156:159], v[180:183], v[92:95]
	v_mfma_f32_16x16x32_bf16 v[84:87], v[148:151], v[188:191], v[84:87]
	v_mfma_f32_16x16x32_bf16 v[76:79], v[156:159], v[188:191], v[76:79]
	v_mfma_f32_16x16x32_bf16 v[124:127], v[152:155], v[168:171], v[124:127]
	v_mfma_f32_16x16x32_bf16 v[120:123], v[160:163], v[168:171], v[120:123]
	v_mfma_f32_16x16x32_bf16 v[116:119], v[152:155], v[176:179], v[116:119]
	v_mfma_f32_16x16x32_bf16 v[108:111], v[160:163], v[176:179], v[108:111]
	v_mfma_f32_16x16x32_bf16 v[100:103], v[152:155], v[184:187], v[100:103]
	v_mfma_f32_16x16x32_bf16 v[92:95], v[160:163], v[184:187], v[92:95]
	v_mfma_f32_16x16x32_bf16 v[84:87], v[152:155], v[192:195], v[84:87]
	v_mfma_f32_16x16x32_bf16 v[76:79], v[160:163], v[192:195], v[76:79]
	s_setprio 0
	s_barrier
	s_add_i32 s84, 0, 0x14000
	v_add_u32_e32 v140, s84, v144
	s_add_i32 s81, s81, s69
	ds_read_b128 v[196:199], v140
	ds_read_b128 v[200:203], v140 offset:1024
	ds_read_b128 v[204:207], v140 offset:2048
	ds_read_b128 v[212:215], v140 offset:3072
	v_lshl_add_u64 v[140:141], s[48:49], 0, v[128:129]
	s_mov_b32 m0, s81
	v_lshl_add_u64 v[208:209], s[48:49], 0, v[134:135]
	global_load_lds_dwordx4 v[140:141], off
	s_add_i32 m0, s81, 0x2000
	s_nop 0
	global_load_lds_dwordx4 v[208:209], off
	s_barrier
	s_waitcnt lgkmcnt(0)
	s_setprio 1
	v_mfma_f32_16x16x32_bf16 v[112:115], v[196:199], v[164:167], v[112:115]
	v_mfma_f32_16x16x32_bf16 v[104:107], v[204:207], v[164:167], v[104:107]
	v_mfma_f32_16x16x32_bf16 v[96:99], v[196:199], v[172:175], v[96:99]
	v_mfma_f32_16x16x32_bf16 v[88:91], v[204:207], v[172:175], v[88:91]
	v_mfma_f32_16x16x32_bf16 v[80:83], v[196:199], v[180:183], v[80:83]
	v_mfma_f32_16x16x32_bf16 v[72:75], v[204:207], v[180:183], v[72:75]
	v_mfma_f32_16x16x32_bf16 v[68:71], v[196:199], v[188:191], v[68:71]
	v_mfma_f32_16x16x32_bf16 v[64:67], v[204:207], v[188:191], v[64:67]
	v_mfma_f32_16x16x32_bf16 v[112:115], v[200:203], v[168:171], v[112:115]
	v_mfma_f32_16x16x32_bf16 v[104:107], v[212:215], v[168:171], v[104:107]
	v_mfma_f32_16x16x32_bf16 v[96:99], v[200:203], v[176:179], v[96:99]
	v_mfma_f32_16x16x32_bf16 v[88:91], v[212:215], v[176:179], v[88:91]
	v_mfma_f32_16x16x32_bf16 v[80:83], v[200:203], v[184:187], v[80:83]
	v_mfma_f32_16x16x32_bf16 v[72:75], v[212:215], v[184:187], v[72:75]
	v_mfma_f32_16x16x32_bf16 v[68:71], v[200:203], v[192:195], v[68:71]
	v_mfma_f32_16x16x32_bf16 v[64:67], v[212:215], v[192:195], v[64:67]
	s_setprio 0
	s_mov_b32 m0, s37
	v_lshl_add_u64 v[216:217], s[50:51], 0, v[130:131]
	s_barrier
	ds_read_b128 v[164:167], v146 offset:16384
	ds_read_b128 v[168:171], v146 offset:17408
	ds_read_b128 v[172:175], v146 offset:18432
	ds_read_b128 v[176:179], v146 offset:19456
	ds_read_b128 v[180:183], v146 offset:20480
	ds_read_b128 v[184:187], v146 offset:21504
	ds_read_b128 v[188:191], v146 offset:22528
	ds_read_b128 v[192:195], v146 offset:23552
	global_load_lds_dwordx4 v[216:217], off
	v_lshl_add_u64 v[218:219], s[50:51], 0, v[132:133]
	s_mov_b32 m0, s70
	s_nop 0
	global_load_lds_dwordx4 v[218:219], off
	s_barrier
	s_waitcnt lgkmcnt(0)
	s_setprio 1
	v_mfma_f32_16x16x32_bf16 v[60:63], v[148:151], v[164:167], v[60:63]
	v_mfma_f32_16x16x32_bf16 v[56:59], v[156:159], v[164:167], v[56:59]
	v_mfma_f32_16x16x32_bf16 v[52:55], v[148:151], v[172:175], v[52:55]
	v_mfma_f32_16x16x32_bf16 v[44:47], v[156:159], v[172:175], v[44:47]
	v_mfma_f32_16x16x32_bf16 v[36:39], v[148:151], v[180:183], v[36:39]
	v_mfma_f32_16x16x32_bf16 v[28:31], v[156:159], v[180:183], v[28:31]
	v_mfma_f32_16x16x32_bf16 v[20:23], v[148:151], v[188:191], v[20:23]
	v_mfma_f32_16x16x32_bf16 v[12:15], v[156:159], v[188:191], v[12:15]
	v_mfma_f32_16x16x32_bf16 v[60:63], v[152:155], v[168:171], v[60:63]
	v_mfma_f32_16x16x32_bf16 v[56:59], v[160:163], v[168:171], v[56:59]
	v_mfma_f32_16x16x32_bf16 v[52:55], v[152:155], v[176:179], v[52:55]
	v_mfma_f32_16x16x32_bf16 v[44:47], v[160:163], v[176:179], v[44:47]
	v_mfma_f32_16x16x32_bf16 v[36:39], v[152:155], v[184:187], v[36:39]
	v_mfma_f32_16x16x32_bf16 v[28:31], v[160:163], v[184:187], v[28:31]
	v_mfma_f32_16x16x32_bf16 v[20:23], v[152:155], v[192:195], v[20:23]
	v_mfma_f32_16x16x32_bf16 v[12:15], v[160:163], v[192:195], v[12:15]
	s_setprio 0
	s_barrier
	s_add_u32 s82, s48, 0x40000
	s_addc_u32 s83, s49, 0
	s_add_i32 s81, s84, s69
	v_lshl_add_u64 v[148:149], s[82:83], 0, v[128:129]
	s_mov_b32 m0, s81
	s_nop 0
	global_load_lds_dwordx4 v[148:149], off
	v_lshl_add_u64 v[148:149], s[82:83], 0, v[134:135]
	s_add_i32 m0, s81, 0x2000
	s_nop 0
	global_load_lds_dwordx4 v[148:149], off
	s_waitcnt vmcnt(6)
	s_barrier
	s_setprio 1
	v_mfma_f32_16x16x32_bf16 v[48:51], v[196:199], v[164:167], v[48:51]
	v_mfma_f32_16x16x32_bf16 v[40:43], v[204:207], v[164:167], v[40:43]
	v_mfma_f32_16x16x32_bf16 v[32:35], v[196:199], v[172:175], v[32:35]
	v_mfma_f32_16x16x32_bf16 v[24:27], v[204:207], v[172:175], v[24:27]
	v_mfma_f32_16x16x32_bf16 v[16:19], v[196:199], v[180:183], v[16:19]
	v_mfma_f32_16x16x32_bf16 v[8:11], v[204:207], v[180:183], v[8:11]
	v_mfma_f32_16x16x32_bf16 v[4:7], v[196:199], v[188:191], v[4:7]
	v_mfma_f32_16x16x32_bf16 v[0:3], v[204:207], v[188:191], v[0:3]
	v_mfma_f32_16x16x32_bf16 v[48:51], v[200:203], v[168:171], v[48:51]
	v_mfma_f32_16x16x32_bf16 v[40:43], v[212:215], v[168:171], v[40:43]
	v_mfma_f32_16x16x32_bf16 v[32:35], v[200:203], v[176:179], v[32:35]
	v_mfma_f32_16x16x32_bf16 v[24:27], v[212:215], v[176:179], v[24:27]
	v_mfma_f32_16x16x32_bf16 v[16:19], v[200:203], v[184:187], v[16:19]
	v_mfma_f32_16x16x32_bf16 v[8:11], v[212:215], v[184:187], v[8:11]
	v_mfma_f32_16x16x32_bf16 v[4:7], v[200:203], v[192:195], v[4:7]
	v_mfma_f32_16x16x32_bf16 v[0:3], v[212:215], v[192:195], v[0:3]
	s_setprio 0
	s_add_i32 s81, 0, 0x18000
	v_add_u32_e32 v147, s81, v144
	s_barrier
	ds_read_b128 v[148:151], v147
	ds_read_b128 v[152:155], v147 offset:1024
	ds_read_b128 v[156:159], v147 offset:2048
	ds_read_b128 v[160:163], v147 offset:3072
	s_add_u32 s50, s50, 0x40000
	s_addc_u32 s51, s51, 0
	s_mov_b32 m0, s71
	v_lshl_add_u64 v[196:197], s[50:51], 0, v[130:131]
	ds_read_b128 v[164:167], v146 offset:32768
	ds_read_b128 v[168:171], v146 offset:33792
	ds_read_b128 v[172:175], v146 offset:34816
	ds_read_b128 v[176:179], v146 offset:35840
	ds_read_b128 v[180:183], v146 offset:36864
	ds_read_b128 v[184:187], v146 offset:37888
	ds_read_b128 v[188:191], v146 offset:38912
	ds_read_b128 v[192:195], v146 offset:39936
	global_load_lds_dwordx4 v[196:197], off
	v_lshl_add_u64 v[196:197], s[50:51], 0, v[132:133]
	s_mov_b32 m0, s72
	s_nop 0
	global_load_lds_dwordx4 v[196:197], off
	s_waitcnt lgkmcnt(8)
	s_barrier
	s_waitcnt lgkmcnt(0)
	s_setprio 1
	v_mfma_f32_16x16x32_bf16 v[124:127], v[148:151], v[164:167], v[124:127]
	v_mfma_f32_16x16x32_bf16 v[120:123], v[156:159], v[164:167], v[120:123]
	v_mfma_f32_16x16x32_bf16 v[116:119], v[148:151], v[172:175], v[116:119]
	v_mfma_f32_16x16x32_bf16 v[108:111], v[156:159], v[172:175], v[108:111]
	v_mfma_f32_16x16x32_bf16 v[100:103], v[148:151], v[180:183], v[100:103]
	v_mfma_f32_16x16x32_bf16 v[92:95], v[156:159], v[180:183], v[92:95]
	v_mfma_f32_16x16x32_bf16 v[84:87], v[148:151], v[188:191], v[84:87]
	v_mfma_f32_16x16x32_bf16 v[76:79], v[156:159], v[188:191], v[76:79]
	v_mfma_f32_16x16x32_bf16 v[124:127], v[152:155], v[168:171], v[124:127]
	v_mfma_f32_16x16x32_bf16 v[120:123], v[160:163], v[168:171], v[120:123]
	v_mfma_f32_16x16x32_bf16 v[116:119], v[152:155], v[176:179], v[116:119]
	v_mfma_f32_16x16x32_bf16 v[108:111], v[160:163], v[176:179], v[108:111]
	v_mfma_f32_16x16x32_bf16 v[100:103], v[152:155], v[184:187], v[100:103]
	v_mfma_f32_16x16x32_bf16 v[92:95], v[160:163], v[184:187], v[92:95]
	v_mfma_f32_16x16x32_bf16 v[84:87], v[152:155], v[192:195], v[84:87]
	v_mfma_f32_16x16x32_bf16 v[76:79], v[160:163], v[192:195], v[76:79]
	s_setprio 0
	s_barrier
	s_add_i32 s50, 0, 0x1c000
	s_add_i32 s51, s81, s69
	v_add_u32_e32 v147, s50, v144
	v_lshl_add_u64 v[140:141], v[140:141], 0, s[2:3]
	s_mov_b32 m0, s51
	ds_read_b128 v[196:199], v147
	ds_read_b128 v[200:203], v147 offset:1024
	ds_read_b128 v[204:207], v147 offset:2048
	ds_read_b128 v[212:215], v147 offset:3072
	global_load_lds_dwordx4 v[140:141], off
	v_lshl_add_u64 v[140:141], v[208:209], 0, s[2:3]
	s_add_i32 m0, s51, 0x2000
	s_nop 0
	global_load_lds_dwordx4 v[140:141], off
	s_barrier
	s_waitcnt lgkmcnt(0)
	s_setprio 1
	v_mfma_f32_16x16x32_bf16 v[112:115], v[196:199], v[164:167], v[112:115]
	v_mfma_f32_16x16x32_bf16 v[104:107], v[204:207], v[164:167], v[104:107]
	v_mfma_f32_16x16x32_bf16 v[96:99], v[196:199], v[172:175], v[96:99]
	v_mfma_f32_16x16x32_bf16 v[88:91], v[204:207], v[172:175], v[88:91]
	v_mfma_f32_16x16x32_bf16 v[80:83], v[196:199], v[180:183], v[80:83]
	v_mfma_f32_16x16x32_bf16 v[72:75], v[204:207], v[180:183], v[72:75]
	v_mfma_f32_16x16x32_bf16 v[68:71], v[196:199], v[188:191], v[68:71]
	v_mfma_f32_16x16x32_bf16 v[64:67], v[204:207], v[188:191], v[64:67]
	v_mfma_f32_16x16x32_bf16 v[112:115], v[200:203], v[168:171], v[112:115]
	v_mfma_f32_16x16x32_bf16 v[104:107], v[212:215], v[168:171], v[104:107]
	v_mfma_f32_16x16x32_bf16 v[96:99], v[200:203], v[176:179], v[96:99]
	v_mfma_f32_16x16x32_bf16 v[88:91], v[212:215], v[176:179], v[88:91]
	v_mfma_f32_16x16x32_bf16 v[80:83], v[200:203], v[184:187], v[80:83]
	v_mfma_f32_16x16x32_bf16 v[72:75], v[212:215], v[184:187], v[72:75]
	v_mfma_f32_16x16x32_bf16 v[68:71], v[200:203], v[192:195], v[68:71]
	v_mfma_f32_16x16x32_bf16 v[64:67], v[212:215], v[192:195], v[64:67]
	s_setprio 0
	s_mov_b32 m0, s0
	v_lshl_add_u64 v[140:141], v[216:217], 0, s[2:3]
	s_barrier
	ds_read_b128 v[164:167], v146 offset:49152
	ds_read_b128 v[168:171], v146 offset:50176
	ds_read_b128 v[172:175], v146 offset:51200
	ds_read_b128 v[176:179], v146 offset:52224
	ds_read_b128 v[180:183], v146 offset:53248
	ds_read_b128 v[184:187], v146 offset:54272
	ds_read_b128 v[188:191], v146 offset:55296
	ds_read_b128 v[192:195], v146 offset:56320
	global_load_lds_dwordx4 v[140:141], off
	v_lshl_add_u64 v[140:141], v[218:219], 0, s[2:3]
	s_mov_b32 m0, s73
	s_nop 0
	global_load_lds_dwordx4 v[140:141], off
	s_barrier
	s_waitcnt lgkmcnt(0)
	s_setprio 1
	v_mfma_f32_16x16x32_bf16 v[60:63], v[148:151], v[164:167], v[60:63]
	v_mfma_f32_16x16x32_bf16 v[56:59], v[156:159], v[164:167], v[56:59]
	v_mfma_f32_16x16x32_bf16 v[52:55], v[148:151], v[172:175], v[52:55]
	v_mfma_f32_16x16x32_bf16 v[44:47], v[156:159], v[172:175], v[44:47]
	v_mfma_f32_16x16x32_bf16 v[36:39], v[148:151], v[180:183], v[36:39]
	v_mfma_f32_16x16x32_bf16 v[28:31], v[156:159], v[180:183], v[28:31]
	v_mfma_f32_16x16x32_bf16 v[20:23], v[148:151], v[188:191], v[20:23]
	v_mfma_f32_16x16x32_bf16 v[12:15], v[156:159], v[188:191], v[12:15]
	v_mfma_f32_16x16x32_bf16 v[60:63], v[152:155], v[168:171], v[60:63]
	v_mfma_f32_16x16x32_bf16 v[56:59], v[160:163], v[168:171], v[56:59]
	v_mfma_f32_16x16x32_bf16 v[52:55], v[152:155], v[176:179], v[52:55]
	v_mfma_f32_16x16x32_bf16 v[44:47], v[160:163], v[176:179], v[44:47]
	v_mfma_f32_16x16x32_bf16 v[36:39], v[152:155], v[184:187], v[36:39]
	v_mfma_f32_16x16x32_bf16 v[28:31], v[160:163], v[184:187], v[28:31]
	v_mfma_f32_16x16x32_bf16 v[20:23], v[152:155], v[192:195], v[20:23]
	v_mfma_f32_16x16x32_bf16 v[12:15], v[160:163], v[192:195], v[12:15]
	s_setprio 0
	s_barrier
	s_add_u32 s48, s48, 0x40080
	s_addc_u32 s49, s49, 0
	s_add_i32 s50, s50, s69
	v_lshl_add_u64 v[140:141], s[48:49], 0, v[128:129]
	s_mov_b32 m0, s50
	s_nop 0
	global_load_lds_dwordx4 v[140:141], off
	v_lshl_add_u64 v[140:141], s[48:49], 0, v[134:135]
	s_add_i32 m0, s50, 0x2000
	s_nop 0
	global_load_lds_dwordx4 v[140:141], off
	s_waitcnt vmcnt(6)
	s_barrier
	s_setprio 1
	v_mfma_f32_16x16x32_bf16 v[48:51], v[196:199], v[164:167], v[48:51]
	v_mfma_f32_16x16x32_bf16 v[40:43], v[204:207], v[164:167], v[40:43]
	v_mfma_f32_16x16x32_bf16 v[32:35], v[196:199], v[172:175], v[32:35]
	v_mfma_f32_16x16x32_bf16 v[24:27], v[204:207], v[172:175], v[24:27]
	v_mfma_f32_16x16x32_bf16 v[16:19], v[196:199], v[180:183], v[16:19]
	v_mfma_f32_16x16x32_bf16 v[8:11], v[204:207], v[180:183], v[8:11]
	v_mfma_f32_16x16x32_bf16 v[4:7], v[196:199], v[188:191], v[4:7]
	v_mfma_f32_16x16x32_bf16 v[0:3], v[204:207], v[188:191], v[0:3]
	v_mfma_f32_16x16x32_bf16 v[48:51], v[200:203], v[168:171], v[48:51]
	v_mfma_f32_16x16x32_bf16 v[40:43], v[212:215], v[168:171], v[40:43]
	v_mfma_f32_16x16x32_bf16 v[32:35], v[200:203], v[176:179], v[32:35]
	v_mfma_f32_16x16x32_bf16 v[24:27], v[212:215], v[176:179], v[24:27]
	v_mfma_f32_16x16x32_bf16 v[16:19], v[200:203], v[184:187], v[16:19]
	v_mfma_f32_16x16x32_bf16 v[8:11], v[212:215], v[184:187], v[8:11]
	v_mfma_f32_16x16x32_bf16 v[4:7], v[200:203], v[192:195], v[4:7]
	v_mfma_f32_16x16x32_bf16 v[0:3], v[212:215], v[192:195], v[0:3]
	s_setprio 0
	s_add_i32 s80, s80, 2
	s_add_u32 s42, s42, 0x100
	s_addc_u32 s43, s43, 0
	s_add_u32 s78, s78, 0x100
	s_addc_u32 s79, s79, 0
	s_cmp_gt_u32 s80, 13
	s_barrier
	s_cbranch_scc0 .LBB0_200
	v_lshl_add_u32 v148, s36, 8, v143
	v_ashrrev_i32_e32 v149, 31, v148
	v_lshl_or_b32 v140, s75, 8, v145
	v_ashrrev_i32_e32 v141, 31, v140
	v_lshlrev_b64 v[150:151], 10, v[148:149]
	v_lshl_add_u64 v[150:151], s[14:15], 0, v[150:151]
	v_lshlrev_b64 v[152:153], 1, v[140:141]
	v_lshl_add_u64 v[140:141], v[150:151], 0, v[152:153]
	v_cvt_pk_bf16_f32 v124, v124, v125
	v_cvt_pk_bf16_f32 v125, v126, v127
	v_cvt_pk_bf16_f32 v126, v120, v121
	v_cvt_pk_bf16_f32 v127, v122, v123
	global_store_dwordx4 v[140:141], v[124:127], off nt
	v_cvt_pk_bf16_f32 v112, v112, v113
	v_cvt_pk_bf16_f32 v113, v114, v115
	v_cvt_pk_bf16_f32 v114, v104, v105
	v_or_b32_e32 v104, 16, v148
	v_ashrrev_i32_e32 v105, 31, v104
	v_lshlrev_b64 v[104:105], 10, v[104:105]
	v_lshl_add_u64 v[104:105], s[14:15], 0, v[104:105]
	v_cvt_pk_bf16_f32 v115, v106, v107
	global_store_dwordx4 v[140:141], v[112:115], off offset:256 nt
	s_mov_b32 s31, 0x20000
	s_mov_b64 s[42:43], 0x20000
	v_lshl_add_u64 v[112:113], v[104:105], 0, v[152:153]
	v_cvt_pk_bf16_f32 v104, v116, v117
	v_cvt_pk_bf16_f32 v105, v118, v119
	v_cvt_pk_bf16_f32 v106, v108, v109
	v_cvt_pk_bf16_f32 v107, v110, v111
	global_store_dwordx4 v[112:113], v[104:107], off nt
	v_cvt_pk_bf16_f32 v96, v96, v97
	v_cvt_pk_bf16_f32 v97, v98, v99
	v_cvt_pk_bf16_f32 v98, v88, v89
	v_or_b32_e32 v88, 32, v148
	v_ashrrev_i32_e32 v89, 31, v88
	v_lshlrev_b64 v[88:89], 10, v[88:89]
	v_lshl_add_u64 v[88:89], s[14:15], 0, v[88:89]
	v_cvt_pk_bf16_f32 v99, v90, v91
	global_store_dwordx4 v[112:113], v[96:99], off offset:256 nt
	s_mov_b32 s75, s30
	s_mov_b32 s36, s34
	v_lshl_add_u64 v[96:97], v[88:89], 0, v[152:153]
	v_cvt_pk_bf16_f32 v88, v100, v101
	v_cvt_pk_bf16_f32 v89, v102, v103
	v_cvt_pk_bf16_f32 v90, v92, v93
	v_cvt_pk_bf16_f32 v91, v94, v95
	global_store_dwordx4 v[96:97], v[88:91], off nt
	v_cvt_pk_bf16_f32 v80, v80, v81
	v_cvt_pk_bf16_f32 v81, v82, v83
	v_cvt_pk_bf16_f32 v82, v72, v73
	v_or_b32_e32 v72, 48, v148
	v_ashrrev_i32_e32 v73, 31, v72
	v_lshlrev_b64 v[72:73], 10, v[72:73]
	v_lshl_add_u64 v[72:73], s[14:15], 0, v[72:73]
	v_cvt_pk_bf16_f32 v83, v74, v75
	global_store_dwordx4 v[96:97], v[80:83], off offset:256 nt
	s_mov_b64 s[48:49], s[40:41]
	s_nop 0
	v_lshl_add_u64 v[80:81], v[72:73], 0, v[152:153]
	v_cvt_pk_bf16_f32 v72, v84, v85
	v_cvt_pk_bf16_f32 v73, v86, v87
	v_cvt_pk_bf16_f32 v74, v76, v77
	v_cvt_pk_bf16_f32 v75, v78, v79
	global_store_dwordx4 v[80:81], v[72:75], off nt
	v_cvt_pk_bf16_f32 v68, v68, v69
	v_cvt_pk_bf16_f32 v69, v70, v71
	v_cvt_pk_bf16_f32 v70, v64, v65
	v_cvt_pk_bf16_f32 v71, v66, v67
	global_store_dwordx4 v[80:81], v[68:71], off offset:256 nt
	v_cvt_pk_bf16_f32 v60, v60, v61
	v_cvt_pk_bf16_f32 v61, v62, v63
	v_cvt_pk_bf16_f32 v62, v56, v57
	v_add_co_u32_e32 v56, vcc, s31, v140
	v_lshl_add_u64 v[64:65], v[140:141], 0, s[42:43]
	s_nop 0
	v_addc_co_u32_e32 v57, vcc, 0, v141, vcc
	s_mov_b32 s31, 0x24000
	v_cvt_pk_bf16_f32 v63, v58, v59
	global_store_dwordx4 v[56:57], v[60:63], off nt
	v_cvt_pk_bf16_f32 v48, v48, v49
	v_cvt_pk_bf16_f32 v49, v50, v51
	v_cvt_pk_bf16_f32 v50, v40, v41
	v_cvt_pk_bf16_f32 v51, v42, v43
	global_store_dwordx4 v[64:65], v[48:51], off offset:256 nt
	s_mov_b64 s[42:43], 0x24000
	v_cvt_pk_bf16_f32 v40, v52, v53
	v_cvt_pk_bf16_f32 v41, v54, v55
	v_cvt_pk_bf16_f32 v42, v44, v45
	v_add_co_u32_e32 v44, vcc, s31, v140
	v_lshl_add_u64 v[48:49], v[140:141], 0, s[42:43]
	s_nop 0
	v_addc_co_u32_e32 v45, vcc, 0, v141, vcc
	s_mov_b32 s31, 0x28000
	v_cvt_pk_bf16_f32 v43, v46, v47
	global_store_dwordx4 v[44:45], v[40:43], off nt
	v_cvt_pk_bf16_f32 v32, v32, v33
	v_cvt_pk_bf16_f32 v33, v34, v35
	v_cvt_pk_bf16_f32 v34, v24, v25
	v_cvt_pk_bf16_f32 v35, v26, v27
	global_store_dwordx4 v[48:49], v[32:35], off offset:256 nt
	s_mov_b64 s[42:43], 0x28000
	v_cvt_pk_bf16_f32 v24, v36, v37
	v_cvt_pk_bf16_f32 v25, v38, v39
	v_cvt_pk_bf16_f32 v26, v28, v29
	v_add_co_u32_e32 v28, vcc, s31, v140
	v_lshl_add_u64 v[32:33], v[140:141], 0, s[42:43]
	s_nop 0
	v_addc_co_u32_e32 v29, vcc, 0, v141, vcc
	s_mov_b32 s31, 0x2c000
	v_cvt_pk_bf16_f32 v27, v30, v31
	global_store_dwordx4 v[28:29], v[24:27], off nt
	v_cvt_pk_bf16_f32 v16, v16, v17
	v_cvt_pk_bf16_f32 v17, v18, v19
	v_cvt_pk_bf16_f32 v18, v8, v9
	v_cvt_pk_bf16_f32 v19, v10, v11
	global_store_dwordx4 v[32:33], v[16:19], off offset:256 nt
	v_cvt_pk_bf16_f32 v8, v20, v21
	v_cvt_pk_bf16_f32 v9, v22, v23
	v_cvt_pk_bf16_f32 v10, v12, v13
	v_add_co_u32_e32 v12, vcc, s31, v140
	s_mov_b64 s[42:43], 0x2c000
	s_nop 0
	v_addc_co_u32_e32 v13, vcc, 0, v141, vcc
	v_lshl_add_u64 v[16:17], v[140:141], 0, s[42:43]
	s_and_b64 vcc, exec, s[28:29]
	s_mov_b64 s[42:43], s[38:39]
	v_cvt_pk_bf16_f32 v11, v14, v15
	global_store_dwordx4 v[12:13], v[8:11], off nt
	v_cvt_pk_bf16_f32 v4, v4, v5
	v_cvt_pk_bf16_f32 v5, v6, v7
	v_cvt_pk_bf16_f32 v6, v0, v1
	v_cvt_pk_bf16_f32 v7, v2, v3
	global_store_dwordx4 v[16:17], v[4:7], off offset:256 nt
	s_cbranch_vccz .LBB0_193
	s_waitcnt vmcnt(0)
	s_cmpk_gt_u32 s65, 0xff
	s_cbranch_scc1 .LBB0_204
	s_barrier

.LBB0_220:
	s_add_u32 s40, s38, 0xfffc0080
	s_addc_u32 s41, s39, -1
	s_add_i32 s76, 0, 0x10000
	v_add_u32_e32 v140, s76, v144
	ds_read_b128 v[148:151], v140
	ds_read_b128 v[152:155], v140 offset:1024
	ds_read_b128 v[156:159], v140 offset:2048
	ds_read_b128 v[160:163], v140 offset:3072
	s_cmp_eq_u32 s75, 12
	s_cselect_b32 s43, s29, s41
	s_cselect_b32 s42, s71, s40
	s_cselect_b32 s41, s15, s74
	s_cselect_b32 s40, s72, s73
	v_lshl_add_u64 v[140:141], s[38:39], 0, v[136:137]
	s_add_i32 m0, s31, 0xc000
	ds_read_b128 v[164:167], v146
	ds_read_b128 v[168:171], v146 offset:1024
	ds_read_b128 v[172:175], v146 offset:2048
	ds_read_b128 v[176:179], v146 offset:3072
	ds_read_b128 v[180:183], v146 offset:4096
	ds_read_b128 v[184:187], v146 offset:5120
	ds_read_b128 v[188:191], v146 offset:6144
	ds_read_b128 v[192:195], v146 offset:7168
	global_load_lds_dwordx4 v[140:141], off
	v_lshl_add_u64 v[140:141], s[38:39], 0, v[138:139]
	s_add_i32 m0, s31, 0xe000
	s_nop 0
	global_load_lds_dwordx4 v[140:141], off
	s_waitcnt lgkmcnt(8)
	s_barrier
	s_waitcnt lgkmcnt(0)
	s_setprio 1
	v_mfma_f32_16x16x32_bf16 v[124:127], v[148:151], v[164:167], v[124:127]
	v_mfma_f32_16x16x32_bf16 v[120:123], v[156:159], v[164:167], v[120:123]
	v_mfma_f32_16x16x32_bf16 v[116:119], v[148:151], v[172:175], v[116:119]
	v_mfma_f32_16x16x32_bf16 v[108:111], v[156:159], v[172:175], v[108:111]
	v_mfma_f32_16x16x32_bf16 v[100:103], v[148:151], v[180:183], v[100:103]
	v_mfma_f32_16x16x32_bf16 v[92:95], v[156:159], v[180:183], v[92:95]
	v_mfma_f32_16x16x32_bf16 v[84:87], v[148:151], v[188:191], v[84:87]
	v_mfma_f32_16x16x32_bf16 v[76:79], v[156:159], v[188:191], v[76:79]
	v_mfma_f32_16x16x32_bf16 v[124:127], v[152:155], v[168:171], v[124:127]
	v_mfma_f32_16x16x32_bf16 v[120:123], v[160:163], v[168:171], v[120:123]
	v_mfma_f32_16x16x32_bf16 v[116:119], v[152:155], v[176:179], v[116:119]
	v_mfma_f32_16x16x32_bf16 v[108:111], v[160:163], v[176:179], v[108:111]
	v_mfma_f32_16x16x32_bf16 v[100:103], v[152:155], v[184:187], v[100:103]
	v_mfma_f32_16x16x32_bf16 v[92:95], v[160:163], v[184:187], v[92:95]
	v_mfma_f32_16x16x32_bf16 v[84:87], v[152:155], v[192:195], v[84:87]
	v_mfma_f32_16x16x32_bf16 v[76:79], v[160:163], v[192:195], v[76:79]
	s_setprio 0
	s_barrier
	s_add_i32 s78, 0, 0x14000
	v_add_u32_e32 v140, s78, v144
	s_add_i32 s76, s76, s64
	ds_read_b128 v[196:199], v140
	ds_read_b128 v[200:203], v140 offset:1024
	ds_read_b128 v[204:207], v140 offset:2048
	ds_read_b128 v[212:215], v140 offset:3072
	v_lshl_add_u64 v[140:141], s[40:41], 0, v[128:129]
	s_mov_b32 m0, s76
	v_lshl_add_u64 v[208:209], s[40:41], 0, v[134:135]
	global_load_lds_dwordx4 v[140:141], off
	s_add_i32 m0, s76, 0x2000
	s_nop 0
	global_load_lds_dwordx4 v[208:209], off
	s_barrier
	s_waitcnt lgkmcnt(0)
	s_setprio 1
	v_mfma_f32_16x16x32_bf16 v[112:115], v[196:199], v[164:167], v[112:115]
	v_mfma_f32_16x16x32_bf16 v[104:107], v[204:207], v[164:167], v[104:107]
	v_mfma_f32_16x16x32_bf16 v[96:99], v[196:199], v[172:175], v[96:99]
	v_mfma_f32_16x16x32_bf16 v[88:91], v[204:207], v[172:175], v[88:91]
	v_mfma_f32_16x16x32_bf16 v[80:83], v[196:199], v[180:183], v[80:83]
	v_mfma_f32_16x16x32_bf16 v[72:75], v[204:207], v[180:183], v[72:75]
	v_mfma_f32_16x16x32_bf16 v[68:71], v[196:199], v[188:191], v[68:71]
	v_mfma_f32_16x16x32_bf16 v[64:67], v[204:207], v[188:191], v[64:67]
	v_mfma_f32_16x16x32_bf16 v[112:115], v[200:203], v[168:171], v[112:115]
	v_mfma_f32_16x16x32_bf16 v[104:107], v[212:215], v[168:171], v[104:107]
	v_mfma_f32_16x16x32_bf16 v[96:99], v[200:203], v[176:179], v[96:99]
	v_mfma_f32_16x16x32_bf16 v[88:91], v[212:215], v[176:179], v[88:91]
	v_mfma_f32_16x16x32_bf16 v[80:83], v[200:203], v[184:187], v[80:83]
	v_mfma_f32_16x16x32_bf16 v[72:75], v[212:215], v[184:187], v[72:75]
	v_mfma_f32_16x16x32_bf16 v[68:71], v[200:203], v[192:195], v[68:71]
	v_mfma_f32_16x16x32_bf16 v[64:67], v[212:215], v[192:195], v[64:67]
	s_setprio 0
	s_mov_b32 m0, s31
	v_lshl_add_u64 v[216:217], s[42:43], 0, v[130:131]
	s_barrier
	ds_read_b128 v[164:167], v146 offset:16384
	ds_read_b128 v[168:171], v146 offset:17408
	ds_read_b128 v[172:175], v146 offset:18432
	ds_read_b128 v[176:179], v146 offset:19456
	ds_read_b128 v[180:183], v146 offset:20480
	ds_read_b128 v[184:187], v146 offset:21504
	ds_read_b128 v[188:191], v146 offset:22528
	ds_read_b128 v[192:195], v146 offset:23552
	global_load_lds_dwordx4 v[216:217], off
	v_lshl_add_u64 v[218:219], s[42:43], 0, v[132:133]
	s_mov_b32 m0, s65
	s_nop 0
	global_load_lds_dwordx4 v[218:219], off
	s_barrier
	s_waitcnt lgkmcnt(0)
	s_setprio 1
	v_mfma_f32_16x16x32_bf16 v[60:63], v[148:151], v[164:167], v[60:63]
	v_mfma_f32_16x16x32_bf16 v[56:59], v[156:159], v[164:167], v[56:59]
	v_mfma_f32_16x16x32_bf16 v[52:55], v[148:151], v[172:175], v[52:55]
	v_mfma_f32_16x16x32_bf16 v[44:47], v[156:159], v[172:175], v[44:47]
	v_mfma_f32_16x16x32_bf16 v[36:39], v[148:151], v[180:183], v[36:39]
	v_mfma_f32_16x16x32_bf16 v[28:31], v[156:159], v[180:183], v[28:31]
	v_mfma_f32_16x16x32_bf16 v[20:23], v[148:151], v[188:191], v[20:23]
	v_mfma_f32_16x16x32_bf16 v[12:15], v[156:159], v[188:191], v[12:15]
	v_mfma_f32_16x16x32_bf16 v[60:63], v[152:155], v[168:171], v[60:63]
	v_mfma_f32_16x16x32_bf16 v[56:59], v[160:163], v[168:171], v[56:59]
	v_mfma_f32_16x16x32_bf16 v[52:55], v[152:155], v[176:179], v[52:55]
	v_mfma_f32_16x16x32_bf16 v[44:47], v[160:163], v[176:179], v[44:47]
	v_mfma_f32_16x16x32_bf16 v[36:39], v[152:155], v[184:187], v[36:39]
	v_mfma_f32_16x16x32_bf16 v[28:31], v[160:163], v[184:187], v[28:31]
	v_mfma_f32_16x16x32_bf16 v[20:23], v[152:155], v[192:195], v[20:23]
	v_mfma_f32_16x16x32_bf16 v[12:15], v[160:163], v[192:195], v[12:15]
	s_setprio 0
	s_barrier
	s_add_u32 s76, s40, 0x40000
	s_addc_u32 s77, s41, 0
	s_add_i32 s78, s78, s64
	v_lshl_add_u64 v[148:149], s[76:77], 0, v[128:129]
	s_mov_b32 m0, s78
	s_nop 0
	global_load_lds_dwordx4 v[148:149], off
	v_lshl_add_u64 v[148:149], s[76:77], 0, v[134:135]
	s_add_i32 m0, s78, 0x2000
	s_nop 0
	global_load_lds_dwordx4 v[148:149], off
	s_waitcnt vmcnt(6)
	s_barrier
	s_setprio 1
	v_mfma_f32_16x16x32_bf16 v[48:51], v[196:199], v[164:167], v[48:51]
	v_mfma_f32_16x16x32_bf16 v[40:43], v[204:207], v[164:167], v[40:43]
	v_mfma_f32_16x16x32_bf16 v[32:35], v[196:199], v[172:175], v[32:35]
	v_mfma_f32_16x16x32_bf16 v[24:27], v[204:207], v[172:175], v[24:27]
	v_mfma_f32_16x16x32_bf16 v[16:19], v[196:199], v[180:183], v[16:19]
	v_mfma_f32_16x16x32_bf16 v[8:11], v[204:207], v[180:183], v[8:11]
	v_mfma_f32_16x16x32_bf16 v[4:7], v[196:199], v[188:191], v[4:7]
	v_mfma_f32_16x16x32_bf16 v[0:3], v[204:207], v[188:191], v[0:3]
	v_mfma_f32_16x16x32_bf16 v[48:51], v[200:203], v[168:171], v[48:51]
	v_mfma_f32_16x16x32_bf16 v[40:43], v[212:215], v[168:171], v[40:43]
	v_mfma_f32_16x16x32_bf16 v[32:35], v[200:203], v[176:179], v[32:35]
	v_mfma_f32_16x16x32_bf16 v[24:27], v[212:215], v[176:179], v[24:27]
	v_mfma_f32_16x16x32_bf16 v[16:19], v[200:203], v[184:187], v[16:19]
	v_mfma_f32_16x16x32_bf16 v[8:11], v[212:215], v[184:187], v[8:11]
	v_mfma_f32_16x16x32_bf16 v[4:7], v[200:203], v[192:195], v[4:7]
	v_mfma_f32_16x16x32_bf16 v[0:3], v[212:215], v[192:195], v[0:3]
	s_setprio 0
	s_add_i32 s76, 0, 0x18000
	v_add_u32_e32 v147, s76, v144
	s_barrier
	ds_read_b128 v[148:151], v147
	ds_read_b128 v[152:155], v147 offset:1024
	ds_read_b128 v[156:159], v147 offset:2048
	ds_read_b128 v[160:163], v147 offset:3072
	s_add_u32 s42, s42, 0x40000
	s_addc_u32 s43, s43, 0
	s_mov_b32 m0, s66
	v_lshl_add_u64 v[196:197], s[42:43], 0, v[130:131]
	ds_read_b128 v[164:167], v146 offset:32768
	ds_read_b128 v[168:171], v146 offset:33792
	ds_read_b128 v[172:175], v146 offset:34816
	ds_read_b128 v[176:179], v146 offset:35840
	ds_read_b128 v[180:183], v146 offset:36864
	ds_read_b128 v[184:187], v146 offset:37888
	ds_read_b128 v[188:191], v146 offset:38912
	ds_read_b128 v[192:195], v146 offset:39936
	global_load_lds_dwordx4 v[196:197], off
	v_lshl_add_u64 v[196:197], s[42:43], 0, v[132:133]
	s_mov_b32 m0, s67
	s_nop 0
	global_load_lds_dwordx4 v[196:197], off
	s_waitcnt lgkmcnt(8)
	s_barrier
	s_waitcnt lgkmcnt(0)
	s_setprio 1
	v_mfma_f32_16x16x32_bf16 v[124:127], v[148:151], v[164:167], v[124:127]
	v_mfma_f32_16x16x32_bf16 v[120:123], v[156:159], v[164:167], v[120:123]
	v_mfma_f32_16x16x32_bf16 v[116:119], v[148:151], v[172:175], v[116:119]
	v_mfma_f32_16x16x32_bf16 v[108:111], v[156:159], v[172:175], v[108:111]
	v_mfma_f32_16x16x32_bf16 v[100:103], v[148:151], v[180:183], v[100:103]
	v_mfma_f32_16x16x32_bf16 v[92:95], v[156:159], v[180:183], v[92:95]
	v_mfma_f32_16x16x32_bf16 v[84:87], v[148:151], v[188:191], v[84:87]
	v_mfma_f32_16x16x32_bf16 v[76:79], v[156:159], v[188:191], v[76:79]
	v_mfma_f32_16x16x32_bf16 v[124:127], v[152:155], v[168:171], v[124:127]
	v_mfma_f32_16x16x32_bf16 v[120:123], v[160:163], v[168:171], v[120:123]
	v_mfma_f32_16x16x32_bf16 v[116:119], v[152:155], v[176:179], v[116:119]
	v_mfma_f32_16x16x32_bf16 v[108:111], v[160:163], v[176:179], v[108:111]
	v_mfma_f32_16x16x32_bf16 v[100:103], v[152:155], v[184:187], v[100:103]
	v_mfma_f32_16x16x32_bf16 v[92:95], v[160:163], v[184:187], v[92:95]
	v_mfma_f32_16x16x32_bf16 v[84:87], v[152:155], v[192:195], v[84:87]
	v_mfma_f32_16x16x32_bf16 v[76:79], v[160:163], v[192:195], v[76:79]
	s_setprio 0
	s_barrier
	s_add_i32 s42, 0, 0x1c000
	s_add_i32 s43, s76, s64
	v_add_u32_e32 v147, s42, v144
	v_lshl_add_u64 v[140:141], v[140:141], 0, s[2:3]
	s_mov_b32 m0, s43
	ds_read_b128 v[196:199], v147
	ds_read_b128 v[200:203], v147 offset:1024
	ds_read_b128 v[204:207], v147 offset:2048
	ds_read_b128 v[212:215], v147 offset:3072
	global_load_lds_dwordx4 v[140:141], off
	v_lshl_add_u64 v[140:141], v[208:209], 0, s[2:3]
	s_add_i32 m0, s43, 0x2000
	s_nop 0
	global_load_lds_dwordx4 v[140:141], off
	s_barrier
	s_waitcnt lgkmcnt(0)
	s_setprio 1
	v_mfma_f32_16x16x32_bf16 v[112:115], v[196:199], v[164:167], v[112:115]
	v_mfma_f32_16x16x32_bf16 v[104:107], v[204:207], v[164:167], v[104:107]
	v_mfma_f32_16x16x32_bf16 v[96:99], v[196:199], v[172:175], v[96:99]
	v_mfma_f32_16x16x32_bf16 v[88:91], v[204:207], v[172:175], v[88:91]
	v_mfma_f32_16x16x32_bf16 v[80:83], v[196:199], v[180:183], v[80:83]
	v_mfma_f32_16x16x32_bf16 v[72:75], v[204:207], v[180:183], v[72:75]
	v_mfma_f32_16x16x32_bf16 v[68:71], v[196:199], v[188:191], v[68:71]
	v_mfma_f32_16x16x32_bf16 v[64:67], v[204:207], v[188:191], v[64:67]
	v_mfma_f32_16x16x32_bf16 v[112:115], v[200:203], v[168:171], v[112:115]
	v_mfma_f32_16x16x32_bf16 v[104:107], v[212:215], v[168:171], v[104:107]
	v_mfma_f32_16x16x32_bf16 v[96:99], v[200:203], v[176:179], v[96:99]
	v_mfma_f32_16x16x32_bf16 v[88:91], v[212:215], v[176:179], v[88:91]
	v_mfma_f32_16x16x32_bf16 v[80:83], v[200:203], v[184:187], v[80:83]
	v_mfma_f32_16x16x32_bf16 v[72:75], v[212:215], v[184:187], v[72:75]
	v_mfma_f32_16x16x32_bf16 v[68:71], v[200:203], v[192:195], v[68:71]
	v_mfma_f32_16x16x32_bf16 v[64:67], v[212:215], v[192:195], v[64:67]
	s_setprio 0
	s_mov_b32 m0, s0
	v_lshl_add_u64 v[140:141], v[216:217], 0, s[2:3]
	s_barrier
	ds_read_b128 v[164:167], v146 offset:49152
	ds_read_b128 v[168:171], v146 offset:50176
	ds_read_b128 v[172:175], v146 offset:51200
	ds_read_b128 v[176:179], v146 offset:52224
	ds_read_b128 v[180:183], v146 offset:53248
	ds_read_b128 v[184:187], v146 offset:54272
	ds_read_b128 v[188:191], v146 offset:55296
	ds_read_b128 v[192:195], v146 offset:56320
	global_load_lds_dwordx4 v[140:141], off
	v_lshl_add_u64 v[140:141], v[218:219], 0, s[2:3]
	s_mov_b32 m0, s68
	s_nop 0
	global_load_lds_dwordx4 v[140:141], off
	s_barrier
	s_waitcnt lgkmcnt(0)
	s_setprio 1
	v_mfma_f32_16x16x32_bf16 v[60:63], v[148:151], v[164:167], v[60:63]
	v_mfma_f32_16x16x32_bf16 v[56:59], v[156:159], v[164:167], v[56:59]
	v_mfma_f32_16x16x32_bf16 v[52:55], v[148:151], v[172:175], v[52:55]
	v_mfma_f32_16x16x32_bf16 v[44:47], v[156:159], v[172:175], v[44:47]
	v_mfma_f32_16x16x32_bf16 v[36:39], v[148:151], v[180:183], v[36:39]
	v_mfma_f32_16x16x32_bf16 v[28:31], v[156:159], v[180:183], v[28:31]
	v_mfma_f32_16x16x32_bf16 v[20:23], v[148:151], v[188:191], v[20:23]
	v_mfma_f32_16x16x32_bf16 v[12:15], v[156:159], v[188:191], v[12:15]
	v_mfma_f32_16x16x32_bf16 v[60:63], v[152:155], v[168:171], v[60:63]
	v_mfma_f32_16x16x32_bf16 v[56:59], v[160:163], v[168:171], v[56:59]
	v_mfma_f32_16x16x32_bf16 v[52:55], v[152:155], v[176:179], v[52:55]
	v_mfma_f32_16x16x32_bf16 v[44:47], v[160:163], v[176:179], v[44:47]
	v_mfma_f32_16x16x32_bf16 v[36:39], v[152:155], v[184:187], v[36:39]
	v_mfma_f32_16x16x32_bf16 v[28:31], v[160:163], v[184:187], v[28:31]
	v_mfma_f32_16x16x32_bf16 v[20:23], v[152:155], v[192:195], v[20:23]
	v_mfma_f32_16x16x32_bf16 v[12:15], v[160:163], v[192:195], v[12:15]
	s_setprio 0
	s_barrier
	s_add_u32 s40, s40, 0x40080
	s_addc_u32 s41, s41, 0
	s_add_i32 s42, s42, s64
	v_lshl_add_u64 v[140:141], s[40:41], 0, v[128:129]
	s_mov_b32 m0, s42
	s_nop 0
	global_load_lds_dwordx4 v[140:141], off
	v_lshl_add_u64 v[140:141], s[40:41], 0, v[134:135]
	s_add_i32 m0, s42, 0x2000
	s_nop 0
	global_load_lds_dwordx4 v[140:141], off
	s_waitcnt vmcnt(6)
	s_barrier
	s_setprio 1
	v_mfma_f32_16x16x32_bf16 v[48:51], v[196:199], v[164:167], v[48:51]
	v_mfma_f32_16x16x32_bf16 v[40:43], v[204:207], v[164:167], v[40:43]
	v_mfma_f32_16x16x32_bf16 v[32:35], v[196:199], v[172:175], v[32:35]
	v_mfma_f32_16x16x32_bf16 v[24:27], v[204:207], v[172:175], v[24:27]
	v_mfma_f32_16x16x32_bf16 v[16:19], v[196:199], v[180:183], v[16:19]
	v_mfma_f32_16x16x32_bf16 v[8:11], v[204:207], v[180:183], v[8:11]
	v_mfma_f32_16x16x32_bf16 v[4:7], v[196:199], v[188:191], v[4:7]
	v_mfma_f32_16x16x32_bf16 v[0:3], v[204:207], v[188:191], v[0:3]
	v_mfma_f32_16x16x32_bf16 v[48:51], v[200:203], v[168:171], v[48:51]
	v_mfma_f32_16x16x32_bf16 v[40:43], v[212:215], v[168:171], v[40:43]
	v_mfma_f32_16x16x32_bf16 v[32:35], v[200:203], v[176:179], v[32:35]
	v_mfma_f32_16x16x32_bf16 v[24:27], v[212:215], v[176:179], v[24:27]
	v_mfma_f32_16x16x32_bf16 v[16:19], v[200:203], v[184:187], v[16:19]
	v_mfma_f32_16x16x32_bf16 v[8:11], v[212:215], v[184:187], v[8:11]
	v_mfma_f32_16x16x32_bf16 v[4:7], v[200:203], v[192:195], v[4:7]
	v_mfma_f32_16x16x32_bf16 v[0:3], v[212:215], v[192:195], v[0:3]
	s_setprio 0
	s_add_i32 s75, s75, 2
	s_add_u32 s38, s38, 0x100
	s_addc_u32 s39, s39, 0
	s_add_u32 s73, s73, 0x100
	s_addc_u32 s74, s74, 0
	s_cmp_gt_u32 s75, 13
	s_barrier
	s_cbranch_scc0 .LBB0_220
	v_lshl_add_u32 v148, s30, 8, v143
	v_ashrrev_i32_e32 v149, 31, v148
	v_lshl_or_b32 v140, s70, 8, v145
	v_ashrrev_i32_e32 v141, 31, v140
	v_lshlrev_b64 v[150:151], 13, v[148:149]
	v_lshl_add_u64 v[150:151], s[8:9], 0, v[150:151]
	v_lshlrev_b64 v[152:153], 1, v[140:141]
	v_lshl_add_u64 v[140:141], v[150:151], 0, v[152:153]
	v_cvt_pk_bf16_f32 v124, v124, v125
	v_cvt_pk_bf16_f32 v125, v126, v127
	v_cvt_pk_bf16_f32 v126, v120, v121
	v_cvt_pk_bf16_f32 v127, v122, v123
	global_store_dwordx4 v[140:141], v[124:127], off nt
	v_cvt_pk_bf16_f32 v112, v112, v113
	v_cvt_pk_bf16_f32 v113, v114, v115
	v_cvt_pk_bf16_f32 v114, v104, v105
	v_or_b32_e32 v104, 16, v148
	v_ashrrev_i32_e32 v105, 31, v104
	v_lshlrev_b64 v[104:105], 13, v[104:105]
	v_lshl_add_u64 v[104:105], s[8:9], 0, v[104:105]
	v_cvt_pk_bf16_f32 v115, v106, v107
	global_store_dwordx4 v[140:141], v[112:115], off offset:256 nt
	s_mov_b32 s15, 0x100000
	s_mov_b64 s[38:39], 0x100000
	v_lshl_add_u64 v[112:113], v[104:105], 0, v[152:153]
	v_cvt_pk_bf16_f32 v104, v116, v117
	v_cvt_pk_bf16_f32 v105, v118, v119
	v_cvt_pk_bf16_f32 v106, v108, v109
	v_cvt_pk_bf16_f32 v107, v110, v111
	global_store_dwordx4 v[112:113], v[104:107], off nt
	v_cvt_pk_bf16_f32 v96, v96, v97
	v_cvt_pk_bf16_f32 v97, v98, v99
	v_cvt_pk_bf16_f32 v98, v88, v89
	v_or_b32_e32 v88, 32, v148
	v_ashrrev_i32_e32 v89, 31, v88
	v_lshlrev_b64 v[88:89], 13, v[88:89]
	v_lshl_add_u64 v[88:89], s[8:9], 0, v[88:89]
	v_cvt_pk_bf16_f32 v99, v90, v91
	global_store_dwordx4 v[112:113], v[96:99], off offset:256 nt
	s_mov_b32 s70, s14
	s_mov_b32 s30, s28
	v_lshl_add_u64 v[96:97], v[88:89], 0, v[152:153]
	v_cvt_pk_bf16_f32 v88, v100, v101
	v_cvt_pk_bf16_f32 v89, v102, v103
	v_cvt_pk_bf16_f32 v90, v92, v93
	v_cvt_pk_bf16_f32 v91, v94, v95
	global_store_dwordx4 v[96:97], v[88:91], off nt
	v_cvt_pk_bf16_f32 v80, v80, v81
	v_cvt_pk_bf16_f32 v81, v82, v83
	v_cvt_pk_bf16_f32 v82, v72, v73
	v_or_b32_e32 v72, 48, v148
	v_ashrrev_i32_e32 v73, 31, v72
	v_lshlrev_b64 v[72:73], 13, v[72:73]
	v_lshl_add_u64 v[72:73], s[8:9], 0, v[72:73]
	v_cvt_pk_bf16_f32 v83, v74, v75
	global_store_dwordx4 v[96:97], v[80:83], off offset:256 nt
	s_mov_b64 s[40:41], s[36:37]
	s_nop 0
	v_lshl_add_u64 v[80:81], v[72:73], 0, v[152:153]
	v_cvt_pk_bf16_f32 v72, v84, v85
	v_cvt_pk_bf16_f32 v73, v86, v87
	v_cvt_pk_bf16_f32 v74, v76, v77
	v_cvt_pk_bf16_f32 v75, v78, v79
	global_store_dwordx4 v[80:81], v[72:75], off nt
	v_cvt_pk_bf16_f32 v68, v68, v69
	v_cvt_pk_bf16_f32 v69, v70, v71
	v_cvt_pk_bf16_f32 v70, v64, v65
	v_cvt_pk_bf16_f32 v71, v66, v67
	global_store_dwordx4 v[80:81], v[68:71], off offset:256 nt
	v_cvt_pk_bf16_f32 v60, v60, v61
	v_cvt_pk_bf16_f32 v61, v62, v63
	v_cvt_pk_bf16_f32 v62, v56, v57
	v_add_co_u32_e32 v56, vcc, s15, v140
	v_lshl_add_u64 v[64:65], v[140:141], 0, s[38:39]
	s_nop 0
	v_addc_co_u32_e32 v57, vcc, 0, v141, vcc
	s_mov_b32 s15, 0x120000
	v_cvt_pk_bf16_f32 v63, v58, v59
	global_store_dwordx4 v[56:57], v[60:63], off nt
	v_cvt_pk_bf16_f32 v48, v48, v49
	v_cvt_pk_bf16_f32 v49, v50, v51
	v_cvt_pk_bf16_f32 v50, v40, v41
	v_cvt_pk_bf16_f32 v51, v42, v43
	global_store_dwordx4 v[64:65], v[48:51], off offset:256 nt
	s_mov_b64 s[38:39], 0x120000
	v_cvt_pk_bf16_f32 v40, v52, v53
	v_cvt_pk_bf16_f32 v41, v54, v55
	v_cvt_pk_bf16_f32 v42, v44, v45
	v_add_co_u32_e32 v44, vcc, s15, v140
	v_lshl_add_u64 v[48:49], v[140:141], 0, s[38:39]
	s_nop 0
	v_addc_co_u32_e32 v45, vcc, 0, v141, vcc
	s_mov_b32 s15, 0x140000
	v_cvt_pk_bf16_f32 v43, v46, v47
	global_store_dwordx4 v[44:45], v[40:43], off nt
	v_cvt_pk_bf16_f32 v32, v32, v33
	v_cvt_pk_bf16_f32 v33, v34, v35
	v_cvt_pk_bf16_f32 v34, v24, v25
	v_cvt_pk_bf16_f32 v35, v26, v27
	global_store_dwordx4 v[48:49], v[32:35], off offset:256 nt
	s_mov_b64 s[38:39], 0x140000
	v_cvt_pk_bf16_f32 v24, v36, v37
	v_cvt_pk_bf16_f32 v25, v38, v39
	v_cvt_pk_bf16_f32 v26, v28, v29
	v_add_co_u32_e32 v28, vcc, s15, v140
	v_lshl_add_u64 v[32:33], v[140:141], 0, s[38:39]
	s_nop 0
	v_addc_co_u32_e32 v29, vcc, 0, v141, vcc
	s_mov_b32 s15, 0x160000
	v_cvt_pk_bf16_f32 v27, v30, v31
	global_store_dwordx4 v[28:29], v[24:27], off nt
	v_cvt_pk_bf16_f32 v16, v16, v17
	v_cvt_pk_bf16_f32 v17, v18, v19
	v_cvt_pk_bf16_f32 v18, v8, v9
	v_cvt_pk_bf16_f32 v19, v10, v11
	global_store_dwordx4 v[32:33], v[16:19], off offset:256 nt
	v_cvt_pk_bf16_f32 v8, v20, v21
	v_cvt_pk_bf16_f32 v9, v22, v23
	v_cvt_pk_bf16_f32 v10, v12, v13
	v_add_co_u32_e32 v12, vcc, s15, v140
	s_mov_b64 s[38:39], 0x160000
	s_nop 0
	v_addc_co_u32_e32 v13, vcc, 0, v141, vcc
	v_lshl_add_u64 v[16:17], v[140:141], 0, s[38:39]
	s_and_b64 vcc, exec, s[12:13]
	s_mov_b64 s[38:39], s[34:35]
	v_cvt_pk_bf16_f32 v11, v14, v15
	global_store_dwordx4 v[12:13], v[8:11], off nt
	v_cvt_pk_bf16_f32 v4, v4, v5
	v_cvt_pk_bf16_f32 v5, v6, v7
	v_cvt_pk_bf16_f32 v6, v0, v1
	v_cvt_pk_bf16_f32 v7, v2, v3
	global_store_dwordx4 v[16:17], v[4:7], off offset:256 nt
	s_cbranch_vccz .LBB0_213
	s_waitcnt vmcnt(0)
	s_cmpk_gt_u32 s49, 0xff
	s_cbranch_scc1 .LBB0_183
	s_barrier
	s_branch .LBB0_183

.LBB0_262:
	ds_read_b128 v[128:131], v157
	ds_read_b128 v[132:135], v157 offset:1024
	ds_read_b128 v[160:163], v157 offset:2048
	ds_read_b128 v[164:167], v157 offset:3072
	s_add_u32 s34, s30, 0xfffc0080
	s_addc_u32 s35, s31, -1
	s_cmp_eq_u32 s59, 28
	s_cselect_b32 s37, s1, s35
	s_cselect_b32 s36, s2, s34
	s_cselect_b32 s35, s13, s58
	s_cselect_b32 s34, s15, s55
	v_lshl_add_u64 v[152:153], s[30:31], 0, v[148:149]
	s_add_i32 m0, s40, 0xc000
	ds_read_b128 v[168:171], v158
	ds_read_b128 v[172:175], v158 offset:1024
	ds_read_b128 v[176:179], v158 offset:2048
	ds_read_b128 v[180:183], v158 offset:3072
	ds_read_b128 v[184:187], v158 offset:4096
	ds_read_b128 v[188:191], v158 offset:5120
	ds_read_b128 v[192:195], v158 offset:6144
	ds_read_b128 v[196:199], v158 offset:7168
	global_load_lds_dwordx4 v[152:153], off
	v_lshl_add_u64 v[152:153], s[30:31], 0, v[150:151]
	s_add_i32 m0, s40, 0xe000
	s_nop 0
	global_load_lds_dwordx4 v[152:153], off
	s_waitcnt lgkmcnt(8)
	s_barrier
	s_waitcnt lgkmcnt(0)
	s_setprio 1
	v_mfma_f32_16x16x32_bf16 v[124:127], v[128:131], v[168:171], v[124:127]
	v_mfma_f32_16x16x32_bf16 v[100:103], v[160:163], v[168:171], v[100:103]
	v_mfma_f32_16x16x32_bf16 v[116:119], v[128:131], v[176:179], v[116:119]
	v_mfma_f32_16x16x32_bf16 v[96:99], v[160:163], v[176:179], v[96:99]
	v_mfma_f32_16x16x32_bf16 v[92:95], v[128:131], v[184:187], v[92:95]
	v_mfma_f32_16x16x32_bf16 v[72:75], v[160:163], v[184:187], v[72:75]
	v_mfma_f32_16x16x32_bf16 v[84:87], v[128:131], v[192:195], v[84:87]
	v_mfma_f32_16x16x32_bf16 v[60:63], v[160:163], v[192:195], v[60:63]
	v_mfma_f32_16x16x32_bf16 v[124:127], v[132:135], v[172:175], v[124:127]
	v_mfma_f32_16x16x32_bf16 v[100:103], v[164:167], v[172:175], v[100:103]
	v_mfma_f32_16x16x32_bf16 v[116:119], v[132:135], v[180:183], v[116:119]
	v_mfma_f32_16x16x32_bf16 v[96:99], v[164:167], v[180:183], v[96:99]
	v_mfma_f32_16x16x32_bf16 v[92:95], v[132:135], v[188:191], v[92:95]
	v_mfma_f32_16x16x32_bf16 v[72:75], v[164:167], v[188:191], v[72:75]
	v_mfma_f32_16x16x32_bf16 v[84:87], v[132:135], v[196:199], v[84:87]
	v_mfma_f32_16x16x32_bf16 v[60:63], v[164:167], v[196:199], v[60:63]
	s_setprio 0
	s_barrier
	s_add_i32 s60, s51, s39
	v_lshl_add_u64 v[152:153], s[34:35], 0, v[138:139]
	s_mov_b32 m0, s60
	ds_read_b128 v[200:203], v159
	ds_read_b128 v[204:207], v159 offset:1024
	ds_read_b128 v[212:215], v159 offset:2048
	ds_read_b128 v[216:219], v159 offset:3072
	global_load_lds_dwordx4 v[152:153], off
	v_lshl_add_u64 v[208:209], s[34:35], 0, v[142:143]
	s_add_i32 m0, s60, 0x2000
	s_nop 0
	global_load_lds_dwordx4 v[208:209], off
	s_barrier
	s_waitcnt lgkmcnt(0)
	s_setprio 1
	v_mfma_f32_16x16x32_bf16 v[120:123], v[200:203], v[168:171], v[120:123]
	v_mfma_f32_16x16x32_bf16 v[108:111], v[212:215], v[168:171], v[108:111]
	v_mfma_f32_16x16x32_bf16 v[112:115], v[200:203], v[176:179], v[112:115]
	v_mfma_f32_16x16x32_bf16 v[104:107], v[212:215], v[176:179], v[104:107]
	v_mfma_f32_16x16x32_bf16 v[88:91], v[200:203], v[184:187], v[88:91]
	v_mfma_f32_16x16x32_bf16 v[80:83], v[212:215], v[184:187], v[80:83]
	v_mfma_f32_16x16x32_bf16 v[76:79], v[200:203], v[192:195], v[76:79]
	v_mfma_f32_16x16x32_bf16 v[68:71], v[212:215], v[192:195], v[68:71]
	v_mfma_f32_16x16x32_bf16 v[120:123], v[204:207], v[172:175], v[120:123]
	v_mfma_f32_16x16x32_bf16 v[108:111], v[216:219], v[172:175], v[108:111]
	v_mfma_f32_16x16x32_bf16 v[112:115], v[204:207], v[180:183], v[112:115]
	v_mfma_f32_16x16x32_bf16 v[104:107], v[216:219], v[180:183], v[104:107]
	v_mfma_f32_16x16x32_bf16 v[88:91], v[204:207], v[188:191], v[88:91]
	v_mfma_f32_16x16x32_bf16 v[80:83], v[216:219], v[188:191], v[80:83]
	v_mfma_f32_16x16x32_bf16 v[76:79], v[204:207], v[196:199], v[76:79]
	v_mfma_f32_16x16x32_bf16 v[68:71], v[216:219], v[196:199], v[68:71]
	s_setprio 0
	s_mov_b32 m0, s40
	v_lshl_add_u64 v[220:221], s[36:37], 0, v[136:137]
	s_barrier
	ds_read_b128 v[168:171], v158 offset:16384
	ds_read_b128 v[172:175], v158 offset:17408
	ds_read_b128 v[176:179], v158 offset:18432
	ds_read_b128 v[180:183], v158 offset:19456
	ds_read_b128 v[184:187], v158 offset:20480
	ds_read_b128 v[188:191], v158 offset:21504
	ds_read_b128 v[192:195], v158 offset:22528
	ds_read_b128 v[196:199], v158 offset:23552
	global_load_lds_dwordx4 v[220:221], off
	v_lshl_add_u64 v[222:223], s[36:37], 0, v[140:141]
	s_mov_b32 m0, s41
	s_nop 0
	global_load_lds_dwordx4 v[222:223], off
	s_barrier
	s_waitcnt lgkmcnt(0)
	s_setprio 1
	v_mfma_f32_16x16x32_bf16 v[64:67], v[128:131], v[168:171], v[64:67]
	v_mfma_f32_16x16x32_bf16 v[48:51], v[160:163], v[168:171], v[48:51]
	v_mfma_f32_16x16x32_bf16 v[44:47], v[128:131], v[176:179], v[44:47]
	v_mfma_f32_16x16x32_bf16 v[32:35], v[160:163], v[176:179], v[32:35]
	v_mfma_f32_16x16x32_bf16 v[28:31], v[128:131], v[184:187], v[28:31]
	v_mfma_f32_16x16x32_bf16 v[16:19], v[160:163], v[184:187], v[16:19]
	v_mfma_f32_16x16x32_bf16 v[12:15], v[128:131], v[192:195], v[12:15]
	v_mfma_f32_16x16x32_bf16 v[0:3], v[160:163], v[192:195], v[0:3]
	v_mfma_f32_16x16x32_bf16 v[64:67], v[132:135], v[172:175], v[64:67]
	v_mfma_f32_16x16x32_bf16 v[48:51], v[164:167], v[172:175], v[48:51]
	v_mfma_f32_16x16x32_bf16 v[44:47], v[132:135], v[180:183], v[44:47]
	v_mfma_f32_16x16x32_bf16 v[32:35], v[164:167], v[180:183], v[32:35]
	v_mfma_f32_16x16x32_bf16 v[28:31], v[132:135], v[188:191], v[28:31]
	v_mfma_f32_16x16x32_bf16 v[16:19], v[164:167], v[188:191], v[16:19]
	v_mfma_f32_16x16x32_bf16 v[12:15], v[132:135], v[196:199], v[12:15]
	v_mfma_f32_16x16x32_bf16 v[0:3], v[164:167], v[196:199], v[0:3]
	s_setprio 0
	s_barrier
	s_add_u32 s60, s34, 0x80000
	s_addc_u32 s61, s35, 0
	s_add_i32 s62, s53, s39
	v_lshl_add_u64 v[128:129], s[60:61], 0, v[138:139]
	s_mov_b32 m0, s62
	s_nop 0
	global_load_lds_dwordx4 v[128:129], off
	v_lshl_add_u64 v[128:129], s[60:61], 0, v[142:143]
	s_add_i32 m0, s62, 0x2000
	s_nop 0
	global_load_lds_dwordx4 v[128:129], off
	s_waitcnt vmcnt(6)
	s_barrier
	s_setprio 1
	v_mfma_f32_16x16x32_bf16 v[56:59], v[200:203], v[168:171], v[56:59]
	v_mfma_f32_16x16x32_bf16 v[52:55], v[212:215], v[168:171], v[52:55]
	v_mfma_f32_16x16x32_bf16 v[40:43], v[200:203], v[176:179], v[40:43]
	v_mfma_f32_16x16x32_bf16 v[36:39], v[212:215], v[176:179], v[36:39]
	v_mfma_f32_16x16x32_bf16 v[24:27], v[200:203], v[184:187], v[24:27]
	v_mfma_f32_16x16x32_bf16 v[20:23], v[212:215], v[184:187], v[20:23]
	v_mfma_f32_16x16x32_bf16 v[8:11], v[200:203], v[192:195], v[8:11]
	v_mfma_f32_16x16x32_bf16 v[4:7], v[212:215], v[192:195], v[4:7]
	v_mfma_f32_16x16x32_bf16 v[56:59], v[204:207], v[172:175], v[56:59]
	v_mfma_f32_16x16x32_bf16 v[52:55], v[216:219], v[172:175], v[52:55]
	v_mfma_f32_16x16x32_bf16 v[40:43], v[204:207], v[180:183], v[40:43]
	v_mfma_f32_16x16x32_bf16 v[36:39], v[216:219], v[180:183], v[36:39]
	v_mfma_f32_16x16x32_bf16 v[24:27], v[204:207], v[188:191], v[24:27]
	v_mfma_f32_16x16x32_bf16 v[20:23], v[216:219], v[188:191], v[20:23]
	v_mfma_f32_16x16x32_bf16 v[8:11], v[204:207], v[196:199], v[8:11]
	v_mfma_f32_16x16x32_bf16 v[4:7], v[216:219], v[196:199], v[4:7]
	s_setprio 0
	s_add_i32 s60, 0, 0x18000
	v_add_u32_e32 v164, s60, v156
	s_barrier
	ds_read_b128 v[128:131], v164
	ds_read_b128 v[132:135], v164 offset:1024
	ds_read_b128 v[160:163], v164 offset:2048
	ds_read_b128 v[164:167], v164 offset:3072
	s_add_u32 s36, s36, 0x40000
	s_addc_u32 s37, s37, 0
	s_mov_b32 m0, s42
	v_lshl_add_u64 v[200:201], s[36:37], 0, v[136:137]
	ds_read_b128 v[168:171], v158 offset:32768
	ds_read_b128 v[172:175], v158 offset:33792
	ds_read_b128 v[176:179], v158 offset:34816
	ds_read_b128 v[180:183], v158 offset:35840
	ds_read_b128 v[184:187], v158 offset:36864
	ds_read_b128 v[188:191], v158 offset:37888
	ds_read_b128 v[192:195], v158 offset:38912
	ds_read_b128 v[196:199], v158 offset:39936
	global_load_lds_dwordx4 v[200:201], off
	v_lshl_add_u64 v[200:201], s[36:37], 0, v[140:141]
	s_mov_b32 m0, s43
	s_nop 0
	global_load_lds_dwordx4 v[200:201], off
	s_waitcnt lgkmcnt(8)
	s_barrier
	s_waitcnt lgkmcnt(0)
	s_setprio 1
	v_mfma_f32_16x16x32_bf16 v[124:127], v[128:131], v[168:171], v[124:127]
	v_mfma_f32_16x16x32_bf16 v[100:103], v[160:163], v[168:171], v[100:103]
	v_mfma_f32_16x16x32_bf16 v[116:119], v[128:131], v[176:179], v[116:119]
	v_mfma_f32_16x16x32_bf16 v[96:99], v[160:163], v[176:179], v[96:99]
	v_mfma_f32_16x16x32_bf16 v[92:95], v[128:131], v[184:187], v[92:95]
	v_mfma_f32_16x16x32_bf16 v[72:75], v[160:163], v[184:187], v[72:75]
	v_mfma_f32_16x16x32_bf16 v[84:87], v[128:131], v[192:195], v[84:87]
	v_mfma_f32_16x16x32_bf16 v[60:63], v[160:163], v[192:195], v[60:63]
	v_mfma_f32_16x16x32_bf16 v[124:127], v[132:135], v[172:175], v[124:127]
	v_mfma_f32_16x16x32_bf16 v[100:103], v[164:167], v[172:175], v[100:103]
	v_mfma_f32_16x16x32_bf16 v[116:119], v[132:135], v[180:183], v[116:119]
	v_mfma_f32_16x16x32_bf16 v[96:99], v[164:167], v[180:183], v[96:99]
	v_mfma_f32_16x16x32_bf16 v[92:95], v[132:135], v[188:191], v[92:95]
	v_mfma_f32_16x16x32_bf16 v[72:75], v[164:167], v[188:191], v[72:75]
	v_mfma_f32_16x16x32_bf16 v[84:87], v[132:135], v[196:199], v[84:87]
	v_mfma_f32_16x16x32_bf16 v[60:63], v[164:167], v[196:199], v[60:63]
	s_setprio 0
	s_barrier
	s_add_i32 s36, 0, 0x1c000
	s_add_i32 s37, s60, s39
	v_add_u32_e32 v211, s36, v156
	v_lshl_add_u64 v[152:153], v[152:153], 0, s[4:5]
	s_mov_b32 m0, s37
	ds_read_b128 v[200:203], v211
	ds_read_b128 v[204:207], v211 offset:1024
	ds_read_b128 v[212:215], v211 offset:2048
	ds_read_b128 v[216:219], v211 offset:3072
	global_load_lds_dwordx4 v[152:153], off
	v_lshl_add_u64 v[152:153], v[208:209], 0, s[4:5]
	s_add_i32 m0, s37, 0x2000
	s_nop 0
	global_load_lds_dwordx4 v[152:153], off
	s_barrier
	s_waitcnt lgkmcnt(0)
	s_setprio 1
	v_mfma_f32_16x16x32_bf16 v[120:123], v[200:203], v[168:171], v[120:123]
	v_mfma_f32_16x16x32_bf16 v[108:111], v[212:215], v[168:171], v[108:111]
	v_mfma_f32_16x16x32_bf16 v[112:115], v[200:203], v[176:179], v[112:115]
	v_mfma_f32_16x16x32_bf16 v[104:107], v[212:215], v[176:179], v[104:107]
	v_mfma_f32_16x16x32_bf16 v[88:91], v[200:203], v[184:187], v[88:91]
	v_mfma_f32_16x16x32_bf16 v[80:83], v[212:215], v[184:187], v[80:83]
	v_mfma_f32_16x16x32_bf16 v[76:79], v[200:203], v[192:195], v[76:79]
	v_mfma_f32_16x16x32_bf16 v[68:71], v[212:215], v[192:195], v[68:71]
	v_mfma_f32_16x16x32_bf16 v[120:123], v[204:207], v[172:175], v[120:123]
	v_mfma_f32_16x16x32_bf16 v[108:111], v[216:219], v[172:175], v[108:111]
	v_mfma_f32_16x16x32_bf16 v[112:115], v[204:207], v[180:183], v[112:115]
	v_mfma_f32_16x16x32_bf16 v[104:107], v[216:219], v[180:183], v[104:107]
	v_mfma_f32_16x16x32_bf16 v[88:91], v[204:207], v[188:191], v[88:91]
	v_mfma_f32_16x16x32_bf16 v[80:83], v[216:219], v[188:191], v[80:83]
	v_mfma_f32_16x16x32_bf16 v[76:79], v[204:207], v[196:199], v[76:79]
	v_mfma_f32_16x16x32_bf16 v[68:71], v[216:219], v[196:199], v[68:71]
	s_setprio 0
	s_mov_b32 m0, s48
	v_lshl_add_u64 v[152:153], v[220:221], 0, s[4:5]
	s_barrier
	ds_read_b128 v[168:171], v158 offset:49152
	ds_read_b128 v[172:175], v158 offset:50176
	ds_read_b128 v[176:179], v158 offset:51200
	ds_read_b128 v[180:183], v158 offset:52224
	ds_read_b128 v[184:187], v158 offset:53248
	ds_read_b128 v[188:191], v158 offset:54272
	ds_read_b128 v[192:195], v158 offset:55296
	ds_read_b128 v[196:199], v158 offset:56320
	global_load_lds_dwordx4 v[152:153], off
	v_lshl_add_u64 v[152:153], v[222:223], 0, s[4:5]
	s_mov_b32 m0, s49
	s_nop 0
	global_load_lds_dwordx4 v[152:153], off
	s_barrier
	s_waitcnt lgkmcnt(0)
	s_setprio 1
	v_mfma_f32_16x16x32_bf16 v[64:67], v[128:131], v[168:171], v[64:67]
	v_mfma_f32_16x16x32_bf16 v[48:51], v[160:163], v[168:171], v[48:51]
	v_mfma_f32_16x16x32_bf16 v[44:47], v[128:131], v[176:179], v[44:47]
	v_mfma_f32_16x16x32_bf16 v[32:35], v[160:163], v[176:179], v[32:35]
	v_mfma_f32_16x16x32_bf16 v[28:31], v[128:131], v[184:187], v[28:31]
	v_mfma_f32_16x16x32_bf16 v[16:19], v[160:163], v[184:187], v[16:19]
	v_mfma_f32_16x16x32_bf16 v[12:15], v[128:131], v[192:195], v[12:15]
	v_mfma_f32_16x16x32_bf16 v[0:3], v[160:163], v[192:195], v[0:3]
	v_mfma_f32_16x16x32_bf16 v[64:67], v[132:135], v[172:175], v[64:67]
	v_mfma_f32_16x16x32_bf16 v[48:51], v[164:167], v[172:175], v[48:51]
	v_mfma_f32_16x16x32_bf16 v[44:47], v[132:135], v[180:183], v[44:47]
	v_mfma_f32_16x16x32_bf16 v[32:35], v[164:167], v[180:183], v[32:35]
	v_mfma_f32_16x16x32_bf16 v[28:31], v[132:135], v[188:191], v[28:31]
	v_mfma_f32_16x16x32_bf16 v[16:19], v[164:167], v[188:191], v[16:19]
	v_mfma_f32_16x16x32_bf16 v[12:15], v[132:135], v[196:199], v[12:15]
	v_mfma_f32_16x16x32_bf16 v[0:3], v[164:167], v[196:199], v[0:3]
	s_setprio 0
	s_barrier
	s_add_u32 s34, s34, 0x80080
	s_addc_u32 s35, s35, 0
	s_add_i32 s36, s36, s39
	v_lshl_add_u64 v[128:129], s[34:35], 0, v[138:139]
	s_mov_b32 m0, s36
	s_nop 0
	global_load_lds_dwordx4 v[128:129], off
	v_lshl_add_u64 v[128:129], s[34:35], 0, v[142:143]
	s_add_i32 m0, s36, 0x2000
	s_nop 0
	global_load_lds_dwordx4 v[128:129], off
	s_waitcnt vmcnt(6)
	s_barrier
	s_setprio 1
	v_mfma_f32_16x16x32_bf16 v[56:59], v[200:203], v[168:171], v[56:59]
	v_mfma_f32_16x16x32_bf16 v[52:55], v[212:215], v[168:171], v[52:55]
	v_mfma_f32_16x16x32_bf16 v[40:43], v[200:203], v[176:179], v[40:43]
	v_mfma_f32_16x16x32_bf16 v[36:39], v[212:215], v[176:179], v[36:39]
	v_mfma_f32_16x16x32_bf16 v[24:27], v[200:203], v[184:187], v[24:27]
	v_mfma_f32_16x16x32_bf16 v[20:23], v[212:215], v[184:187], v[20:23]
	v_mfma_f32_16x16x32_bf16 v[8:11], v[200:203], v[192:195], v[8:11]
	v_mfma_f32_16x16x32_bf16 v[4:7], v[212:215], v[192:195], v[4:7]
	v_mfma_f32_16x16x32_bf16 v[56:59], v[204:207], v[172:175], v[56:59]
	v_mfma_f32_16x16x32_bf16 v[52:55], v[216:219], v[172:175], v[52:55]
	v_mfma_f32_16x16x32_bf16 v[40:43], v[204:207], v[180:183], v[40:43]
	v_mfma_f32_16x16x32_bf16 v[36:39], v[216:219], v[180:183], v[36:39]
	v_mfma_f32_16x16x32_bf16 v[24:27], v[204:207], v[188:191], v[24:27]
	v_mfma_f32_16x16x32_bf16 v[20:23], v[216:219], v[188:191], v[20:23]
	v_mfma_f32_16x16x32_bf16 v[8:11], v[204:207], v[196:199], v[8:11]
	v_mfma_f32_16x16x32_bf16 v[4:7], v[216:219], v[196:199], v[4:7]
	s_setprio 0
	s_add_i32 s59, s59, 2
	s_add_u32 s30, s30, 0x100
	s_addc_u32 s31, s31, 0
	s_add_u32 s55, s55, 0x100
	s_addc_u32 s58, s58, 0
	s_cmp_gt_u32 s59, 29
	s_barrier
	s_cbranch_scc0 .LBB0_262
	s_cmp_gt_i32 s0, 31
	s_cselect_b64 vcc, -1, 0
	s_and_b64 s[30:31], vcc, exec
	s_cselect_b32 s2, 0x200, 0
	v_lshl_add_u64 v[128:129], v[144:145], 0, s[2:3]
	global_load_dwordx4 v[132:135], v[128:129], off
	s_nop 0
	global_load_dwordx4 v[128:131], v[128:129], off offset:16
	v_cndmask_b32_e32 v121, v125, v121, vcc
	v_cndmask_b32_e32 v120, v124, v120, vcc
	v_cndmask_b32_e32 v101, v101, v109, vcc
	v_cndmask_b32_e32 v100, v100, v108, vcc
	v_cndmask_b32_e32 v123, v127, v123, vcc
	v_cndmask_b32_e32 v122, v126, v122, vcc
	v_cndmask_b32_e32 v103, v103, v111, vcc
	v_cndmask_b32_e32 v102, v102, v110, vcc
	v_cndmask_b32_e32 v111, v119, v115, vcc
	v_cndmask_b32_e32 v110, v118, v114, vcc
	v_cndmask_b32_e32 v99, v99, v107, vcc
	v_cndmask_b32_e32 v98, v98, v106, vcc
	v_cndmask_b32_e32 v109, v117, v113, vcc
	v_cndmask_b32_e32 v108, v116, v112, vcc
	v_cndmask_b32_e32 v89, v93, v89, vcc
	v_cndmask_b32_e32 v88, v92, v88, vcc
	v_cndmask_b32_e32 v73, v73, v81, vcc
	v_cndmask_b32_e32 v72, v72, v80, vcc
	v_cndmask_b32_e32 v105, v97, v105, vcc
	v_cndmask_b32_e32 v104, v96, v104, vcc
	v_cndmask_b32_e32 v74, v74, v82, vcc
	v_lshl_add_u32 v152, s0, 8, v155
	v_ashrrev_i32_e32 v153, 31, v152
	v_lshlrev_b64 v[162:163], 8, v[152:153]
	v_cndmask_b32_e32 v75, v75, v83, vcc
	v_lshl_add_u64 v[96:97], v[146:147], 0, v[162:163]
	v_cndmask_b32_e32 v91, v95, v91, vcc
	v_cndmask_b32_e32 v90, v94, v90, vcc
	v_or_b32_e32 v160, 16, v152
	v_ashrrev_i32_e32 v161, 31, v160
	v_lshlrev_b64 v[106:107], 8, v[160:161]
	v_cndmask_b32_e32 v61, v61, v69, vcc
	v_cndmask_b32_e32 v60, v60, v68, vcc
	v_cndmask_b32_e32 v57, v65, v57, vcc
	v_cndmask_b32_e32 v56, v64, v56, vcc
	v_cndmask_b32_e32 v49, v49, v53, vcc
	v_cndmask_b32_e32 v48, v48, v52, vcc
	v_cndmask_b32_e32 v62, v62, v70, vcc
	v_cndmask_b32_e32 v50, v50, v54, vcc
	v_cndmask_b32_e32 v41, v45, v41, vcc
	v_cndmask_b32_e32 v40, v44, v40, vcc
	v_cndmask_b32_e32 v33, v33, v37, vcc
	v_cndmask_b32_e32 v32, v32, v36, vcc
	v_cndmask_b32_e32 v25, v29, v25, vcc
	v_cndmask_b32_e32 v24, v28, v24, vcc
	v_cndmask_b32_e32 v17, v17, v21, vcc
	v_cndmask_b32_e32 v16, v16, v20, vcc
	v_cndmask_b32_e32 v34, v34, v38, vcc
	v_cndmask_b32_e32 v18, v18, v22, vcc
	v_cndmask_b32_e32 v9, v13, v9, vcc
	v_cndmask_b32_e32 v8, v12, v8, vcc
	v_cndmask_b32_e32 v1, v1, v5, vcc
	v_cndmask_b32_e32 v0, v0, v4, vcc
	v_cndmask_b32_e32 v63, v63, v71, vcc
	v_cndmask_b32_e32 v51, v51, v55, vcc
	v_cndmask_b32_e32 v2, v2, v6, vcc
	v_cndmask_b32_e32 v35, v35, v39, vcc
	v_cndmask_b32_e32 v59, v67, v59, vcc
	v_cndmask_b32_e32 v58, v66, v58, vcc
	v_cndmask_b32_e32 v19, v19, v23, vcc
	v_cndmask_b32_e32 v43, v47, v43, vcc
	v_cndmask_b32_e32 v42, v46, v42, vcc
	v_cndmask_b32_e32 v3, v3, v7, vcc
	v_cndmask_b32_e32 v27, v31, v27, vcc
	v_cndmask_b32_e32 v26, v30, v26, vcc
	v_cndmask_b32_e32 v11, v15, v11, vcc
	v_cndmask_b32_e32 v10, v14, v10, vcc
	s_mov_b32 s0, 0x9000
	s_mov_b64 s[34:35], s[28:29]
	s_mov_b64 s[30:31], s[26:27]
	s_waitcnt vmcnt(0)
	v_pk_add_f32 v[114:115], v[120:121], v[132:133]
	v_pk_add_f32 v[100:101], v[100:101], v[128:129]
	v_pk_add_f32 v[112:113], v[122:123], v[134:135]
	v_pk_add_f32 v[102:103], v[102:103], v[130:131]
	v_pk_add_f32 v[116:117], v[98:99], v[130:131]
	v_mul_f32_e32 v98, 0xbfb8aa3b, v114
	v_mul_f32_e32 v99, 0xbfb8aa3b, v100
	v_mul_f32_e32 v118, 0xbfb8aa3b, v115
	v_mul_f32_e32 v119, 0xbfb8aa3b, v101
	v_mul_f32_e32 v120, 0xbfb8aa3b, v112
	v_mul_f32_e32 v121, 0xbfb8aa3b, v102
	v_mul_f32_e32 v122, 0xbfb8aa3b, v113
	v_mul_f32_e32 v123, 0xbfb8aa3b, v103
	v_exp_f32_e32 v98, v98
	v_exp_f32_e32 v99, v99
	v_exp_f32_e32 v118, v118
	v_exp_f32_e32 v119, v119
	v_exp_f32_e32 v120, v120
	v_exp_f32_e32 v121, v121
	v_exp_f32_e32 v122, v122
	v_exp_f32_e32 v123, v123
	v_pk_add_f32 v[88:89], v[88:89], v[132:133]
	v_pk_add_f32 v[72:73], v[72:73], v[128:129]
	v_add_f32_e32 v98, 1.0, v98
	v_add_f32_e32 v99, 1.0, v99
	v_add_f32_e32 v118, 1.0, v118
	v_add_f32_e32 v119, 1.0, v119
	v_mul_f32_e32 v80, 0xbfb8aa3b, v88
	v_mul_f32_e32 v81, 0xbfb8aa3b, v72
	v_mul_f32_e32 v82, 0xbfb8aa3b, v89
	v_pk_add_f32 v[104:105], v[104:105], v[128:129]
	v_add_f32_e32 v120, 1.0, v120
	v_add_f32_e32 v121, 1.0, v121
	v_add_f32_e32 v122, 1.0, v122
	v_add_f32_e32 v123, 1.0, v123
	v_rcp_f32_e32 v98, v98
	v_rcp_f32_e32 v99, v99
	v_rcp_f32_e32 v118, v118
	v_rcp_f32_e32 v119, v119
	v_exp_f32_e32 v80, v80
	v_exp_f32_e32 v81, v81
	v_exp_f32_e32 v82, v82
	v_mul_f32_e32 v127, 0xbfb8aa3b, v105
	v_rcp_f32_e32 v120, v120
	v_rcp_f32_e32 v121, v121
	v_rcp_f32_e32 v122, v122
	v_rcp_f32_e32 v123, v123
	v_exp_f32_e32 v127, v127
	v_mul_f32_e32 v98, v114, v98
	v_mul_f32_e32 v100, v100, v99
	v_mul_f32_e32 v99, v115, v118
	v_mul_f32_e32 v101, v101, v119
	v_add_f32_e32 v80, 1.0, v80
	v_add_f32_e32 v81, 1.0, v81
	v_add_f32_e32 v82, 1.0, v82
	v_mul_f32_e32 v83, 0xbfb8aa3b, v73
	v_pk_add_f32 v[110:111], v[110:111], v[134:135]
	v_mul_f32_e32 v112, v112, v120
	v_mul_f32_e32 v102, v102, v121
	v_mul_f32_e32 v113, v113, v122
	v_mul_f32_e32 v103, v103, v123
	v_cvt_pk_bf16_f32 v98, v98, v99
	v_cvt_pk_bf16_f32 v99, v112, v113
	v_cvt_pk_bf16_f32 v100, v100, v101
	v_cvt_pk_bf16_f32 v101, v102, v103
	v_rcp_f32_e32 v80, v80
	v_rcp_f32_e32 v81, v81
	v_rcp_f32_e32 v82, v82
	v_exp_f32_e32 v83, v83
	global_store_dwordx4 v[96:97], v[98:101], off
	v_pk_add_f32 v[90:91], v[90:91], v[134:135]
	v_pk_add_f32 v[74:75], v[74:75], v[130:131]
	v_add_f32_e32 v99, 1.0, v127
	v_mul_f32_e32 v100, 0xbfb8aa3b, v110
	v_mul_f32_e32 v101, 0xbfb8aa3b, v116
	v_rcp_f32_e32 v99, v99
	v_exp_f32_e32 v100, v100
	v_exp_f32_e32 v101, v101
	v_pk_add_f32 v[108:109], v[108:109], v[132:133]
	v_mul_f32_e32 v88, v88, v80
	v_mul_f32_e32 v92, v72, v81
	v_mul_f32_e32 v72, v89, v82
	v_add_f32_e32 v80, 1.0, v83
	v_mul_f32_e32 v81, 0xbfb8aa3b, v90
	v_mul_f32_e32 v82, 0xbfb8aa3b, v74
	v_mul_f32_e32 v126, 0xbfb8aa3b, v109
	v_rcp_f32_e32 v80, v80
	v_exp_f32_e32 v81, v81
	v_exp_f32_e32 v82, v82
	v_mul_f32_e32 v124, 0xbfb8aa3b, v108
	v_exp_f32_e32 v126, v126
	v_mul_f32_e32 v105, v105, v99
	v_add_f32_e32 v99, 1.0, v100
	v_add_f32_e32 v100, 1.0, v101
	v_mul_f32_e32 v101, 0xbfb8aa3b, v111
	v_mul_f32_e32 v102, 0xbfb8aa3b, v117
	v_mul_f32_e32 v125, 0xbfb8aa3b, v104
	v_exp_f32_e32 v124, v124
	v_exp_f32_e32 v101, v101
	v_exp_f32_e32 v102, v102
	v_exp_f32_e32 v125, v125
	v_mul_f32_e32 v83, v73, v80
	v_add_f32_e32 v73, 1.0, v81
	v_add_f32_e32 v80, 1.0, v82
	v_mul_f32_e32 v81, 0xbfb8aa3b, v91
	v_mul_f32_e32 v82, 0xbfb8aa3b, v75
	v_add_f32_e32 v126, 1.0, v126
	v_exp_f32_e32 v81, v81
	v_exp_f32_e32 v82, v82
	v_add_f32_e32 v124, 1.0, v124
	v_rcp_f32_e32 v126, v126
	v_add_f32_e32 v101, 1.0, v101
	v_add_f32_e32 v102, 1.0, v102
	v_add_f32_e32 v125, 1.0, v125
	v_rcp_f32_e32 v124, v124
	v_rcp_f32_e32 v99, v99
	v_rcp_f32_e32 v100, v100
	v_rcp_f32_e32 v101, v101
	v_rcp_f32_e32 v102, v102
	v_rcp_f32_e32 v125, v125
	v_add_f32_e32 v81, 1.0, v81
	v_add_f32_e32 v82, 1.0, v82
	v_mul_f32_e32 v98, v109, v126
	v_rcp_f32_e32 v73, v73
	v_rcp_f32_e32 v80, v80
	v_rcp_f32_e32 v81, v81
	v_rcp_f32_e32 v82, v82
	v_mul_f32_e32 v108, v108, v124
	v_mul_f32_e32 v99, v110, v99
	v_mul_f32_e32 v109, v116, v100
	v_mul_f32_e32 v100, v111, v101
	v_mul_f32_e32 v101, v117, v102
	v_lshl_add_u64 v[102:103], v[146:147], 0, v[106:107]
	v_cvt_pk_bf16_f32 v98, v108, v98
	v_mul_f32_e32 v104, v104, v125
	v_cvt_pk_bf16_f32 v99, v99, v100
	v_cvt_pk_bf16_f32 v100, v104, v105
	v_cvt_pk_bf16_f32 v101, v109, v101
	global_store_dwordx4 v[102:103], v[98:101], off
	v_mul_f32_e32 v73, v90, v73
	v_mul_f32_e32 v89, v74, v80
	v_or_b32_e32 v98, 32, v152
	v_ashrrev_i32_e32 v99, 31, v98
	v_lshlrev_b64 v[98:99], 8, v[98:99]
	v_mul_f32_e32 v74, v91, v81
	v_mul_f32_e32 v75, v75, v82
	v_lshl_add_u64 v[80:81], v[146:147], 0, v[98:99]
	v_cvt_pk_bf16_f32 v72, v88, v72
	v_cvt_pk_bf16_f32 v73, v73, v74
	v_cvt_pk_bf16_f32 v74, v92, v83
	v_cvt_pk_bf16_f32 v75, v89, v75
	global_store_dwordx4 v[80:81], v[72:75], off
	v_pk_add_f32 v[60:61], v[60:61], v[128:129]
	v_pk_add_f32 v[56:57], v[56:57], v[132:133]
	v_cndmask_b32_e32 v75, v85, v77, vcc
	v_cndmask_b32_e32 v74, v84, v76, vcc
	v_pk_add_f32 v[74:75], v[74:75], v[132:133]
	v_mul_f32_e32 v69, 0xbfb8aa3b, v60
	v_mul_f32_e32 v68, 0xbfb8aa3b, v74
	v_mul_f32_e32 v70, 0xbfb8aa3b, v75
	v_pk_add_f32 v[48:49], v[48:49], v[128:129]
	v_exp_f32_e32 v68, v68
	v_exp_f32_e32 v69, v69
	v_exp_f32_e32 v70, v70
	v_mul_f32_e32 v52, 0xbfb8aa3b, v56
	v_mul_f32_e32 v53, 0xbfb8aa3b, v48
	v_mul_f32_e32 v54, 0xbfb8aa3b, v57
	v_exp_f32_e32 v52, v52
	v_exp_f32_e32 v53, v53
	v_exp_f32_e32 v54, v54
	v_pk_add_f32 v[40:41], v[40:41], v[132:133]
	v_pk_add_f32 v[32:33], v[32:33], v[128:129]
	v_mul_f32_e32 v36, 0xbfb8aa3b, v40
	v_mul_f32_e32 v37, 0xbfb8aa3b, v32
	v_mul_f32_e32 v38, 0xbfb8aa3b, v41
	v_pk_add_f32 v[24:25], v[24:25], v[132:133]
	v_pk_add_f32 v[16:17], v[16:17], v[128:129]
	v_exp_f32_e32 v36, v36
	v_exp_f32_e32 v37, v37
	v_exp_f32_e32 v38, v38
	v_mul_f32_e32 v20, 0xbfb8aa3b, v24
	v_mul_f32_e32 v21, 0xbfb8aa3b, v16
	v_mul_f32_e32 v22, 0xbfb8aa3b, v25
	v_add_f32_e32 v68, 1.0, v68
	v_add_f32_e32 v69, 1.0, v69
	v_add_f32_e32 v70, 1.0, v70
	v_mul_f32_e32 v71, 0xbfb8aa3b, v61
	v_exp_f32_e32 v20, v20
	v_exp_f32_e32 v21, v21
	v_exp_f32_e32 v22, v22
	v_pk_add_f32 v[8:9], v[8:9], v[132:133]
	v_pk_add_f32 v[0:1], v[0:1], v[128:129]
	v_rcp_f32_e32 v68, v68
	v_rcp_f32_e32 v69, v69
	v_rcp_f32_e32 v70, v70
	v_exp_f32_e32 v71, v71
	v_add_f32_e32 v52, 1.0, v52
	v_add_f32_e32 v53, 1.0, v53
	v_add_f32_e32 v54, 1.0, v54
	v_mul_f32_e32 v55, 0xbfb8aa3b, v49
	v_mul_f32_e32 v4, 0xbfb8aa3b, v8
	v_mul_f32_e32 v5, 0xbfb8aa3b, v0
	v_mul_f32_e32 v6, 0xbfb8aa3b, v9
	v_rcp_f32_e32 v52, v52
	v_rcp_f32_e32 v53, v53
	v_rcp_f32_e32 v54, v54
	v_exp_f32_e32 v55, v55
	v_exp_f32_e32 v4, v4
	v_exp_f32_e32 v5, v5
	v_exp_f32_e32 v6, v6
	v_cndmask_b32_e32 v77, v87, v79, vcc
	v_cndmask_b32_e32 v76, v86, v78, vcc
	v_add_f32_e32 v36, 1.0, v36
	v_add_f32_e32 v37, 1.0, v37
	v_add_f32_e32 v38, 1.0, v38
	v_mul_f32_e32 v39, 0xbfb8aa3b, v33
	v_pk_add_f32 v[76:77], v[76:77], v[134:135]
	v_pk_add_f32 v[62:63], v[62:63], v[130:131]
	v_rcp_f32_e32 v36, v36
	v_rcp_f32_e32 v37, v37
	v_rcp_f32_e32 v38, v38
	v_exp_f32_e32 v39, v39
	v_add_f32_e32 v20, 1.0, v20
	v_add_f32_e32 v21, 1.0, v21
	v_add_f32_e32 v22, 1.0, v22
	v_mul_f32_e32 v23, 0xbfb8aa3b, v17
	v_mul_f32_e32 v74, v74, v68
	v_mul_f32_e32 v78, v60, v69
	v_mul_f32_e32 v60, v75, v70
	v_add_f32_e32 v68, 1.0, v71
	v_mul_f32_e32 v69, 0xbfb8aa3b, v76
	v_mul_f32_e32 v70, 0xbfb8aa3b, v62
	v_pk_add_f32 v[58:59], v[58:59], v[134:135]
	v_pk_add_f32 v[50:51], v[50:51], v[130:131]
	v_rcp_f32_e32 v20, v20
	v_rcp_f32_e32 v21, v21
	v_rcp_f32_e32 v22, v22
	v_exp_f32_e32 v23, v23
	v_rcp_f32_e32 v68, v68
	v_exp_f32_e32 v69, v69
	v_exp_f32_e32 v70, v70
	v_mul_f32_e32 v52, v56, v52
	v_mul_f32_e32 v53, v48, v53
	v_mul_f32_e32 v48, v57, v54
	v_add_f32_e32 v54, 1.0, v55
	v_mul_f32_e32 v55, 0xbfb8aa3b, v58
	v_mul_f32_e32 v56, 0xbfb8aa3b, v50
	v_add_f32_e32 v4, 1.0, v4
	v_add_f32_e32 v5, 1.0, v5
	v_add_f32_e32 v6, 1.0, v6
	v_mul_f32_e32 v7, 0xbfb8aa3b, v1
	v_rcp_f32_e32 v54, v54
	v_exp_f32_e32 v55, v55
	v_exp_f32_e32 v56, v56
	v_pk_add_f32 v[42:43], v[42:43], v[134:135]
	v_pk_add_f32 v[34:35], v[34:35], v[130:131]
	v_rcp_f32_e32 v4, v4
	v_rcp_f32_e32 v5, v5
	v_rcp_f32_e32 v6, v6
	v_exp_f32_e32 v7, v7
	v_mul_f32_e32 v36, v40, v36
	v_mul_f32_e32 v37, v32, v37
	v_mul_f32_e32 v32, v41, v38
	v_add_f32_e32 v38, 1.0, v39
	v_mul_f32_e32 v39, 0xbfb8aa3b, v42
	v_mul_f32_e32 v40, 0xbfb8aa3b, v34
	v_pk_add_f32 v[26:27], v[26:27], v[134:135]
	v_pk_add_f32 v[18:19], v[18:19], v[130:131]
	v_rcp_f32_e32 v38, v38
	v_exp_f32_e32 v39, v39
	v_exp_f32_e32 v40, v40
	v_mul_f32_e32 v20, v24, v20
	v_mul_f32_e32 v21, v16, v21
	v_mul_f32_e32 v16, v25, v22
	v_add_f32_e32 v22, 1.0, v23
	v_mul_f32_e32 v23, 0xbfb8aa3b, v26
	v_mul_f32_e32 v24, 0xbfb8aa3b, v18
	v_mul_f32_e32 v71, v61, v68
	v_add_f32_e32 v61, 1.0, v69
	v_add_f32_e32 v68, 1.0, v70
	v_mul_f32_e32 v69, 0xbfb8aa3b, v77
	v_mul_f32_e32 v70, 0xbfb8aa3b, v63
	v_rcp_f32_e32 v22, v22
	v_exp_f32_e32 v23, v23
	v_exp_f32_e32 v24, v24
	v_pk_add_f32 v[10:11], v[10:11], v[134:135]
	v_pk_add_f32 v[2:3], v[2:3], v[130:131]
	v_exp_f32_e32 v69, v69
	v_exp_f32_e32 v70, v70
	v_mul_f32_e32 v54, v49, v54
	v_add_f32_e32 v49, 1.0, v55
	v_add_f32_e32 v55, 1.0, v56
	v_mul_f32_e32 v56, 0xbfb8aa3b, v59
	v_mul_f32_e32 v4, v8, v4
	v_mul_f32_e32 v5, v0, v5
	v_mul_f32_e32 v0, v9, v6
	v_add_f32_e32 v6, 1.0, v7
	v_mul_f32_e32 v7, 0xbfb8aa3b, v10
	v_mul_f32_e32 v8, 0xbfb8aa3b, v2
	v_exp_f32_e32 v56, v56
	v_rcp_f32_e32 v6, v6
	v_exp_f32_e32 v7, v7
	v_exp_f32_e32 v8, v8
	v_mul_f32_e32 v57, 0xbfb8aa3b, v51
	v_mul_f32_e32 v38, v33, v38
	v_add_f32_e32 v33, 1.0, v39
	v_add_f32_e32 v39, 1.0, v40
	v_mul_f32_e32 v40, 0xbfb8aa3b, v43
	v_mul_f32_e32 v41, 0xbfb8aa3b, v35
	v_exp_f32_e32 v57, v57
	v_exp_f32_e32 v40, v40
	v_exp_f32_e32 v41, v41
	v_mul_f32_e32 v22, v17, v22
	v_add_f32_e32 v17, 1.0, v23
	v_add_f32_e32 v23, 1.0, v24
	v_mul_f32_e32 v24, 0xbfb8aa3b, v27
	v_add_f32_e32 v69, 1.0, v69
	v_add_f32_e32 v70, 1.0, v70
	v_exp_f32_e32 v24, v24
	v_mul_f32_e32 v25, 0xbfb8aa3b, v19
	v_rcp_f32_e32 v61, v61
	v_rcp_f32_e32 v68, v68
	v_rcp_f32_e32 v69, v69
	v_rcp_f32_e32 v70, v70
	v_add_f32_e32 v56, 1.0, v56
	v_exp_f32_e32 v25, v25
	v_mul_f32_e32 v6, v1, v6
	v_add_f32_e32 v1, 1.0, v7
	v_add_f32_e32 v7, 1.0, v8
	v_mul_f32_e32 v8, 0xbfb8aa3b, v11
	v_or_b32_e32 v72, 48, v152
	v_rcp_f32_e32 v49, v49
	v_rcp_f32_e32 v55, v55
	v_rcp_f32_e32 v56, v56
	v_exp_f32_e32 v8, v8
	v_ashrrev_i32_e32 v73, 31, v72
	v_add_f32_e32 v57, 1.0, v57
	v_add_f32_e32 v40, 1.0, v40
	v_add_f32_e32 v41, 1.0, v41
	v_mul_f32_e32 v9, 0xbfb8aa3b, v3
	v_lshlrev_b64 v[72:73], 8, v[72:73]
	v_rcp_f32_e32 v57, v57
	v_rcp_f32_e32 v33, v33
	v_rcp_f32_e32 v39, v39
	v_rcp_f32_e32 v40, v40
	v_rcp_f32_e32 v41, v41
	v_add_f32_e32 v24, 1.0, v24
	v_exp_f32_e32 v9, v9
	v_mul_f32_e32 v61, v76, v61
	v_mul_f32_e32 v75, v62, v68
	v_mul_f32_e32 v62, v77, v69
	v_mul_f32_e32 v63, v63, v70
	v_lshl_add_u64 v[68:69], v[146:147], 0, v[72:73]
	v_rcp_f32_e32 v17, v17
	v_rcp_f32_e32 v23, v23
	v_rcp_f32_e32 v24, v24
	v_add_f32_e32 v25, 1.0, v25
	v_cvt_pk_bf16_f32 v60, v74, v60
	v_cvt_pk_bf16_f32 v61, v61, v62
	v_cvt_pk_bf16_f32 v62, v78, v71
	v_cvt_pk_bf16_f32 v63, v75, v63
	global_store_dwordx4 v[68:69], v[60:63], off
	v_mul_f32_e32 v49, v58, v49
	v_mul_f32_e32 v55, v50, v55
	v_mul_f32_e32 v50, v59, v56
	v_cvt_pk_bf16_f32 v48, v52, v48
	v_add_co_u32_e64 v52, s[0:1], s0, v96
	v_rcp_f32_e32 v25, v25
	v_add_f32_e32 v8, 1.0, v8
	v_cvt_pk_bf16_f32 v49, v49, v50
	v_cvt_pk_bf16_f32 v50, v53, v54
	v_addc_co_u32_e64 v53, s[0:1], 0, v97, s[0:1]
	v_rcp_f32_e32 v1, v1
	v_rcp_f32_e32 v7, v7
	v_rcp_f32_e32 v8, v8
	v_mul_f32_e32 v51, v51, v57
	v_mul_f32_e32 v33, v42, v33
	v_mul_f32_e32 v39, v34, v39
	v_mul_f32_e32 v34, v43, v40
	v_mul_f32_e32 v35, v35, v41
	s_mov_b32 s0, 0xa000
	v_add_f32_e32 v9, 1.0, v9
	v_cvt_pk_bf16_f32 v51, v55, v51
	global_store_dwordx4 v[52:53], v[48:51], off offset:-4096
	v_cvt_pk_bf16_f32 v32, v36, v32
	v_cvt_pk_bf16_f32 v33, v33, v34
	v_cvt_pk_bf16_f32 v34, v37, v38
	v_cvt_pk_bf16_f32 v35, v39, v35
	global_store_dwordx4 v[52:53], v[32:35], off
	v_mul_f32_e32 v17, v26, v17
	v_mul_f32_e32 v23, v18, v23
	v_mul_f32_e32 v18, v27, v24
	v_cvt_pk_bf16_f32 v16, v20, v16
	v_add_co_u32_e64 v20, s[0:1], s0, v96
	v_rcp_f32_e32 v9, v9
	v_mul_f32_e32 v19, v19, v25
	v_cvt_pk_bf16_f32 v17, v17, v18
	v_cvt_pk_bf16_f32 v18, v21, v22
	v_addc_co_u32_e64 v21, s[0:1], 0, v97, s[0:1]
	v_cvt_pk_bf16_f32 v19, v23, v19
	global_store_dwordx4 v[20:21], v[16:19], off
	v_mul_f32_e32 v1, v10, v1
	v_mul_f32_e32 v7, v2, v7
	v_mul_f32_e32 v2, v11, v8
	v_cvt_pk_bf16_f32 v0, v4, v0
	v_add_co_u32_e32 v4, vcc, 0xb000, v96
	v_cvt_pk_bf16_f32 v1, v1, v2
	v_cvt_pk_bf16_f32 v2, v5, v6
	v_mul_f32_e32 v3, v3, v9
	s_nop 0
	v_addc_co_u32_e32 v5, vcc, 0, v97, vcc
	s_and_b64 vcc, exec, s[8:9]
	s_mov_b32 s0, s14
	v_cvt_pk_bf16_f32 v3, v7, v3
	global_store_dwordx4 v[4:5], v[0:3], off
	s_cbranch_vccz .LBB0_255
	s_waitcnt vmcnt(0)
	s_cmpk_gt_u32 s33, 0xff
	s_cbranch_scc1 .LBB0_266
	s_barrier

.LBB0_654:
	ds_read_b128 v[144:147], v157
	ds_read_b128 v[148:151], v157 offset:1024
	ds_read_b128 v[160:163], v157 offset:2048
	ds_read_b128 v[164:167], v157 offset:3072
	s_add_u32 s24, s22, 0xfffc0080
	s_addc_u32 s25, s23, -1
	s_cmp_eq_u32 s49, 12
	s_cselect_b32 s27, s13, s25
	s_cselect_b32 s26, s19, s24
	s_cselect_b32 s25, s3, s48
	s_cselect_b32 s24, s42, s43
	v_lshl_add_u64 v[152:153], s[22:23], 0, v[136:137]
	s_add_i32 m0, s21, 0xc000
	ds_read_b128 v[168:171], v158
	ds_read_b128 v[176:179], v158 offset:1024
	ds_read_b128 v[180:183], v158 offset:2048
	ds_read_b128 v[184:187], v158 offset:3072
	ds_read_b128 v[188:191], v158 offset:4096
	ds_read_b128 v[192:195], v158 offset:5120
	ds_read_b128 v[196:199], v158 offset:6144
	ds_read_b128 v[200:203], v158 offset:7168
	global_load_lds_dwordx4 v[152:153], off
	v_lshl_add_u64 v[152:153], s[22:23], 0, v[138:139]
	s_add_i32 m0, s21, 0xe000
	s_nop 0
	global_load_lds_dwordx4 v[152:153], off
	s_waitcnt lgkmcnt(8)
	s_barrier
	s_waitcnt lgkmcnt(0)
	s_setprio 1
	v_mfma_f32_16x16x32_bf16 v[124:127], v[144:147], v[168:171], v[124:127]
	v_mfma_f32_16x16x32_bf16 v[120:123], v[160:163], v[168:171], v[120:123]
	v_mfma_f32_16x16x32_bf16 v[116:119], v[144:147], v[180:183], v[116:119]
	v_mfma_f32_16x16x32_bf16 v[112:115], v[160:163], v[180:183], v[112:115]
	v_mfma_f32_16x16x32_bf16 v[96:99], v[144:147], v[188:191], v[96:99]
	v_mfma_f32_16x16x32_bf16 v[88:91], v[160:163], v[188:191], v[88:91]
	v_mfma_f32_16x16x32_bf16 v[80:83], v[144:147], v[196:199], v[80:83]
	v_mfma_f32_16x16x32_bf16 v[72:75], v[160:163], v[196:199], v[72:75]
	v_mfma_f32_16x16x32_bf16 v[124:127], v[148:151], v[176:179], v[124:127]
	v_mfma_f32_16x16x32_bf16 v[120:123], v[164:167], v[176:179], v[120:123]
	v_mfma_f32_16x16x32_bf16 v[116:119], v[148:151], v[184:187], v[116:119]
	v_mfma_f32_16x16x32_bf16 v[112:115], v[164:167], v[184:187], v[112:115]
	v_mfma_f32_16x16x32_bf16 v[96:99], v[148:151], v[192:195], v[96:99]
	v_mfma_f32_16x16x32_bf16 v[88:91], v[164:167], v[192:195], v[88:91]
	v_mfma_f32_16x16x32_bf16 v[80:83], v[148:151], v[200:203], v[80:83]
	v_mfma_f32_16x16x32_bf16 v[72:75], v[164:167], v[200:203], v[72:75]
	s_setprio 0
	s_barrier
	s_add_i32 s50, s40, s29
	v_lshl_add_u64 v[152:153], s[24:25], 0, v[130:131]
	s_mov_b32 m0, s50
	ds_read_b128 v[204:207], v159
	ds_read_b128 v[212:215], v159 offset:1024
	ds_read_b128 v[216:219], v159 offset:2048
	ds_read_b128 v[220:223], v159 offset:3072
	global_load_lds_dwordx4 v[152:153], off
	v_lshl_add_u64 v[172:173], s[24:25], 0, v[134:135]
	s_add_i32 m0, s50, 0x2000
	s_nop 0
	global_load_lds_dwordx4 v[172:173], off
	s_barrier
	s_waitcnt lgkmcnt(0)
	s_setprio 1
	v_mfma_f32_16x16x32_bf16 v[108:111], v[204:207], v[168:171], v[108:111]
	v_mfma_f32_16x16x32_bf16 v[104:107], v[216:219], v[168:171], v[104:107]
	v_mfma_f32_16x16x32_bf16 v[100:103], v[204:207], v[180:183], v[100:103]
	v_mfma_f32_16x16x32_bf16 v[92:95], v[216:219], v[180:183], v[92:95]
	v_mfma_f32_16x16x32_bf16 v[84:87], v[204:207], v[188:191], v[84:87]
	v_mfma_f32_16x16x32_bf16 v[76:79], v[216:219], v[188:191], v[76:79]
	v_mfma_f32_16x16x32_bf16 v[68:71], v[204:207], v[196:199], v[68:71]
	v_mfma_f32_16x16x32_bf16 v[64:67], v[216:219], v[196:199], v[64:67]
	v_mfma_f32_16x16x32_bf16 v[108:111], v[212:215], v[176:179], v[108:111]
	v_mfma_f32_16x16x32_bf16 v[104:107], v[220:223], v[176:179], v[104:107]
	v_mfma_f32_16x16x32_bf16 v[100:103], v[212:215], v[184:187], v[100:103]
	v_mfma_f32_16x16x32_bf16 v[92:95], v[220:223], v[184:187], v[92:95]
	v_mfma_f32_16x16x32_bf16 v[84:87], v[212:215], v[192:195], v[84:87]
	v_mfma_f32_16x16x32_bf16 v[76:79], v[220:223], v[192:195], v[76:79]
	v_mfma_f32_16x16x32_bf16 v[68:71], v[212:215], v[200:203], v[68:71]
	v_mfma_f32_16x16x32_bf16 v[64:67], v[220:223], v[200:203], v[64:67]
	s_setprio 0
	s_mov_b32 m0, s21
	v_lshl_add_u64 v[208:209], s[26:27], 0, v[128:129]
	s_barrier
	ds_read_b128 v[168:171], v158 offset:16384
	ds_read_b128 v[176:179], v158 offset:17408
	ds_read_b128 v[180:183], v158 offset:18432
	ds_read_b128 v[184:187], v158 offset:19456
	ds_read_b128 v[188:191], v158 offset:20480
	ds_read_b128 v[192:195], v158 offset:21504
	ds_read_b128 v[196:199], v158 offset:22528
	ds_read_b128 v[200:203], v158 offset:23552
	global_load_lds_dwordx4 v[208:209], off
	v_lshl_add_u64 v[224:225], s[26:27], 0, v[132:133]
	s_mov_b32 m0, s30
	s_nop 0
	global_load_lds_dwordx4 v[224:225], off
	s_barrier
	s_waitcnt lgkmcnt(0)
	s_setprio 1
	v_mfma_f32_16x16x32_bf16 v[60:63], v[144:147], v[168:171], v[60:63]
	v_mfma_f32_16x16x32_bf16 v[56:59], v[160:163], v[168:171], v[56:59]
	v_mfma_f32_16x16x32_bf16 v[52:55], v[144:147], v[180:183], v[52:55]
	v_mfma_f32_16x16x32_bf16 v[48:51], v[160:163], v[180:183], v[48:51]
	v_mfma_f32_16x16x32_bf16 v[32:35], v[144:147], v[188:191], v[32:35]
	v_mfma_f32_16x16x32_bf16 v[24:27], v[160:163], v[188:191], v[24:27]
	v_mfma_f32_16x16x32_bf16 v[16:19], v[144:147], v[196:199], v[16:19]
	v_mfma_f32_16x16x32_bf16 v[8:11], v[160:163], v[196:199], v[8:11]
	v_mfma_f32_16x16x32_bf16 v[60:63], v[148:151], v[176:179], v[60:63]
	v_mfma_f32_16x16x32_bf16 v[56:59], v[164:167], v[176:179], v[56:59]
	v_mfma_f32_16x16x32_bf16 v[52:55], v[148:151], v[184:187], v[52:55]
	v_mfma_f32_16x16x32_bf16 v[48:51], v[164:167], v[184:187], v[48:51]
	v_mfma_f32_16x16x32_bf16 v[32:35], v[148:151], v[192:195], v[32:35]
	v_mfma_f32_16x16x32_bf16 v[24:27], v[164:167], v[192:195], v[24:27]
	v_mfma_f32_16x16x32_bf16 v[16:19], v[148:151], v[200:203], v[16:19]
	v_mfma_f32_16x16x32_bf16 v[8:11], v[164:167], v[200:203], v[8:11]
	s_setprio 0
	s_barrier
	s_add_u32 s50, s24, 0x40000
	s_addc_u32 s51, s25, 0
	s_add_i32 s52, s41, s29
	v_lshl_add_u64 v[144:145], s[50:51], 0, v[130:131]
	s_mov_b32 m0, s52
	s_nop 0
	global_load_lds_dwordx4 v[144:145], off
	v_lshl_add_u64 v[144:145], s[50:51], 0, v[134:135]
	s_add_i32 m0, s52, 0x2000
	s_nop 0
	global_load_lds_dwordx4 v[144:145], off
	s_waitcnt vmcnt(6)
	s_barrier
	s_setprio 1
	v_mfma_f32_16x16x32_bf16 v[44:47], v[204:207], v[168:171], v[44:47]
	v_mfma_f32_16x16x32_bf16 v[40:43], v[216:219], v[168:171], v[40:43]
	v_mfma_f32_16x16x32_bf16 v[36:39], v[204:207], v[180:183], v[36:39]
	v_mfma_f32_16x16x32_bf16 v[28:31], v[216:219], v[180:183], v[28:31]
	v_mfma_f32_16x16x32_bf16 v[20:23], v[204:207], v[188:191], v[20:23]
	v_mfma_f32_16x16x32_bf16 v[12:15], v[216:219], v[188:191], v[12:15]
	v_mfma_f32_16x16x32_bf16 v[4:7], v[204:207], v[196:199], v[4:7]
	v_mfma_f32_16x16x32_bf16 v[0:3], v[216:219], v[196:199], v[0:3]
	v_mfma_f32_16x16x32_bf16 v[44:47], v[212:215], v[176:179], v[44:47]
	v_mfma_f32_16x16x32_bf16 v[40:43], v[220:223], v[176:179], v[40:43]
	v_mfma_f32_16x16x32_bf16 v[36:39], v[212:215], v[184:187], v[36:39]
	v_mfma_f32_16x16x32_bf16 v[28:31], v[220:223], v[184:187], v[28:31]
	v_mfma_f32_16x16x32_bf16 v[20:23], v[212:215], v[192:195], v[20:23]
	v_mfma_f32_16x16x32_bf16 v[12:15], v[220:223], v[192:195], v[12:15]
	v_mfma_f32_16x16x32_bf16 v[4:7], v[212:215], v[200:203], v[4:7]
	v_mfma_f32_16x16x32_bf16 v[0:3], v[220:223], v[200:203], v[0:3]
	s_setprio 0
	s_add_i32 s50, 0, 0x18000
	v_add_u32_e32 v164, s50, v155
	s_barrier
	ds_read_b128 v[144:147], v164
	ds_read_b128 v[148:151], v164 offset:1024
	ds_read_b128 v[160:163], v164 offset:2048
	ds_read_b128 v[164:167], v164 offset:3072
	s_add_u32 s26, s26, 0x40000
	s_addc_u32 s27, s27, 0
	s_mov_b32 m0, s31
	v_lshl_add_u64 v[204:205], s[26:27], 0, v[128:129]
	ds_read_b128 v[168:171], v158 offset:32768
	ds_read_b128 v[176:179], v158 offset:33792
	ds_read_b128 v[180:183], v158 offset:34816
	ds_read_b128 v[184:187], v158 offset:35840
	ds_read_b128 v[188:191], v158 offset:36864
	ds_read_b128 v[192:195], v158 offset:37888
	ds_read_b128 v[196:199], v158 offset:38912
	ds_read_b128 v[200:203], v158 offset:39936
	global_load_lds_dwordx4 v[204:205], off
	v_lshl_add_u64 v[204:205], s[26:27], 0, v[132:133]
	s_mov_b32 m0, s33
	s_nop 0
	global_load_lds_dwordx4 v[204:205], off
	s_waitcnt lgkmcnt(8)
	s_barrier
	s_waitcnt lgkmcnt(0)
	s_setprio 1
	v_mfma_f32_16x16x32_bf16 v[124:127], v[144:147], v[168:171], v[124:127]
	v_mfma_f32_16x16x32_bf16 v[120:123], v[160:163], v[168:171], v[120:123]
	v_mfma_f32_16x16x32_bf16 v[116:119], v[144:147], v[180:183], v[116:119]
	v_mfma_f32_16x16x32_bf16 v[112:115], v[160:163], v[180:183], v[112:115]
	v_mfma_f32_16x16x32_bf16 v[96:99], v[144:147], v[188:191], v[96:99]
	v_mfma_f32_16x16x32_bf16 v[88:91], v[160:163], v[188:191], v[88:91]
	v_mfma_f32_16x16x32_bf16 v[80:83], v[144:147], v[196:199], v[80:83]
	v_mfma_f32_16x16x32_bf16 v[72:75], v[160:163], v[196:199], v[72:75]
	v_mfma_f32_16x16x32_bf16 v[124:127], v[148:151], v[176:179], v[124:127]
	v_mfma_f32_16x16x32_bf16 v[120:123], v[164:167], v[176:179], v[120:123]
	v_mfma_f32_16x16x32_bf16 v[116:119], v[148:151], v[184:187], v[116:119]
	v_mfma_f32_16x16x32_bf16 v[112:115], v[164:167], v[184:187], v[112:115]
	v_mfma_f32_16x16x32_bf16 v[96:99], v[148:151], v[192:195], v[96:99]
	v_mfma_f32_16x16x32_bf16 v[88:91], v[164:167], v[192:195], v[88:91]
	v_mfma_f32_16x16x32_bf16 v[80:83], v[148:151], v[200:203], v[80:83]
	v_mfma_f32_16x16x32_bf16 v[72:75], v[164:167], v[200:203], v[72:75]
	s_setprio 0
	s_barrier
	s_add_i32 s26, 0, 0x1c000
	s_add_i32 s27, s50, s29
	v_add_u32_e32 v175, s26, v155
	v_lshl_add_u64 v[152:153], v[152:153], 0, s[0:1]
	s_mov_b32 m0, s27
	ds_read_b128 v[204:207], v175
	ds_read_b128 v[212:215], v175 offset:1024
	ds_read_b128 v[216:219], v175 offset:2048
	ds_read_b128 v[220:223], v175 offset:3072
	global_load_lds_dwordx4 v[152:153], off
	v_lshl_add_u64 v[152:153], v[172:173], 0, s[0:1]
	s_add_i32 m0, s27, 0x2000
	s_nop 0
	global_load_lds_dwordx4 v[152:153], off
	s_barrier
	s_waitcnt lgkmcnt(0)
	s_setprio 1
	v_mfma_f32_16x16x32_bf16 v[108:111], v[204:207], v[168:171], v[108:111]
	v_mfma_f32_16x16x32_bf16 v[104:107], v[216:219], v[168:171], v[104:107]
	v_mfma_f32_16x16x32_bf16 v[100:103], v[204:207], v[180:183], v[100:103]
	v_mfma_f32_16x16x32_bf16 v[92:95], v[216:219], v[180:183], v[92:95]
	v_mfma_f32_16x16x32_bf16 v[84:87], v[204:207], v[188:191], v[84:87]
	v_mfma_f32_16x16x32_bf16 v[76:79], v[216:219], v[188:191], v[76:79]
	v_mfma_f32_16x16x32_bf16 v[68:71], v[204:207], v[196:199], v[68:71]
	v_mfma_f32_16x16x32_bf16 v[64:67], v[216:219], v[196:199], v[64:67]
	v_mfma_f32_16x16x32_bf16 v[108:111], v[212:215], v[176:179], v[108:111]
	v_mfma_f32_16x16x32_bf16 v[104:107], v[220:223], v[176:179], v[104:107]
	v_mfma_f32_16x16x32_bf16 v[100:103], v[212:215], v[184:187], v[100:103]
	v_mfma_f32_16x16x32_bf16 v[92:95], v[220:223], v[184:187], v[92:95]
	v_mfma_f32_16x16x32_bf16 v[84:87], v[212:215], v[192:195], v[84:87]
	v_mfma_f32_16x16x32_bf16 v[76:79], v[220:223], v[192:195], v[76:79]
	v_mfma_f32_16x16x32_bf16 v[68:71], v[212:215], v[200:203], v[68:71]
	v_mfma_f32_16x16x32_bf16 v[64:67], v[220:223], v[200:203], v[64:67]
	s_setprio 0
	s_mov_b32 m0, s35
	v_lshl_add_u64 v[152:153], v[208:209], 0, s[0:1]
	s_barrier
	ds_read_b128 v[168:171], v158 offset:49152
	ds_read_b128 v[176:179], v158 offset:50176
	ds_read_b128 v[180:183], v158 offset:51200
	ds_read_b128 v[184:187], v158 offset:52224
	ds_read_b128 v[188:191], v158 offset:53248
	ds_read_b128 v[192:195], v158 offset:54272
	ds_read_b128 v[196:199], v158 offset:55296
	ds_read_b128 v[200:203], v158 offset:56320
	global_load_lds_dwordx4 v[152:153], off
	v_lshl_add_u64 v[152:153], v[224:225], 0, s[0:1]
	s_mov_b32 m0, s36
	s_nop 0
	global_load_lds_dwordx4 v[152:153], off
	s_barrier
	s_waitcnt lgkmcnt(0)
	s_setprio 1
	v_mfma_f32_16x16x32_bf16 v[60:63], v[144:147], v[168:171], v[60:63]
	v_mfma_f32_16x16x32_bf16 v[56:59], v[160:163], v[168:171], v[56:59]
	v_mfma_f32_16x16x32_bf16 v[52:55], v[144:147], v[180:183], v[52:55]
	v_mfma_f32_16x16x32_bf16 v[48:51], v[160:163], v[180:183], v[48:51]
	v_mfma_f32_16x16x32_bf16 v[32:35], v[144:147], v[188:191], v[32:35]
	v_mfma_f32_16x16x32_bf16 v[24:27], v[160:163], v[188:191], v[24:27]
	v_mfma_f32_16x16x32_bf16 v[16:19], v[144:147], v[196:199], v[16:19]
	v_mfma_f32_16x16x32_bf16 v[8:11], v[160:163], v[196:199], v[8:11]
	v_mfma_f32_16x16x32_bf16 v[60:63], v[148:151], v[176:179], v[60:63]
	v_mfma_f32_16x16x32_bf16 v[56:59], v[164:167], v[176:179], v[56:59]
	v_mfma_f32_16x16x32_bf16 v[52:55], v[148:151], v[184:187], v[52:55]
	v_mfma_f32_16x16x32_bf16 v[48:51], v[164:167], v[184:187], v[48:51]
	v_mfma_f32_16x16x32_bf16 v[32:35], v[148:151], v[192:195], v[32:35]
	v_mfma_f32_16x16x32_bf16 v[24:27], v[164:167], v[192:195], v[24:27]
	v_mfma_f32_16x16x32_bf16 v[16:19], v[148:151], v[200:203], v[16:19]
	v_mfma_f32_16x16x32_bf16 v[8:11], v[164:167], v[200:203], v[8:11]
	s_setprio 0
	s_barrier
	s_add_u32 s24, s24, 0x40080
	s_addc_u32 s25, s25, 0
	s_add_i32 s26, s26, s29
	v_lshl_add_u64 v[144:145], s[24:25], 0, v[130:131]
	s_mov_b32 m0, s26
	s_nop 0
	global_load_lds_dwordx4 v[144:145], off
	v_lshl_add_u64 v[144:145], s[24:25], 0, v[134:135]
	s_add_i32 m0, s26, 0x2000
	s_nop 0
	global_load_lds_dwordx4 v[144:145], off
	s_waitcnt vmcnt(6)
	s_barrier
	s_setprio 1
	v_mfma_f32_16x16x32_bf16 v[44:47], v[204:207], v[168:171], v[44:47]
	v_mfma_f32_16x16x32_bf16 v[40:43], v[216:219], v[168:171], v[40:43]
	v_mfma_f32_16x16x32_bf16 v[36:39], v[204:207], v[180:183], v[36:39]
	v_mfma_f32_16x16x32_bf16 v[28:31], v[216:219], v[180:183], v[28:31]
	v_mfma_f32_16x16x32_bf16 v[20:23], v[204:207], v[188:191], v[20:23]
	v_mfma_f32_16x16x32_bf16 v[12:15], v[216:219], v[188:191], v[12:15]
	v_mfma_f32_16x16x32_bf16 v[4:7], v[204:207], v[196:199], v[4:7]
	v_mfma_f32_16x16x32_bf16 v[0:3], v[216:219], v[196:199], v[0:3]
	v_mfma_f32_16x16x32_bf16 v[44:47], v[212:215], v[176:179], v[44:47]
	v_mfma_f32_16x16x32_bf16 v[40:43], v[220:223], v[176:179], v[40:43]
	v_mfma_f32_16x16x32_bf16 v[36:39], v[212:215], v[184:187], v[36:39]
	v_mfma_f32_16x16x32_bf16 v[28:31], v[220:223], v[184:187], v[28:31]
	v_mfma_f32_16x16x32_bf16 v[20:23], v[212:215], v[192:195], v[20:23]
	v_mfma_f32_16x16x32_bf16 v[12:15], v[220:223], v[192:195], v[12:15]
	v_mfma_f32_16x16x32_bf16 v[4:7], v[212:215], v[200:203], v[4:7]
	v_mfma_f32_16x16x32_bf16 v[0:3], v[220:223], v[200:203], v[0:3]
	s_setprio 0
	s_add_i32 s49, s49, 2
	s_add_u32 s22, s22, 0x100
	s_addc_u32 s23, s23, 0
	s_add_u32 s43, s43, 0x100
	s_addc_u32 s48, s48, 0
	s_cmp_gt_u32 s49, 13
	s_barrier
	s_cbranch_scc0 .LBB0_654
	v_lshl_add_u32 v148, s18, 8, v154
	v_lshl_or_b32 v144, s20, 8, v156
	v_readlane_b32 s48, v253, 12
	v_ashrrev_i32_e32 v145, 31, v144
	v_ashrrev_i32_e32 v149, 31, v148
	v_readlane_b32 s49, v253, 13
	v_lshlrev_b64 v[150:151], 12, v[148:149]
	v_or_b32_e32 v172, 16, v148
	v_lshl_add_u64 v[146:147], v[144:145], 2, s[48:49]
	v_lshl_add_u64 v[150:151], v[146:147], 0, v[150:151]
	v_ashrrev_i32_e32 v173, 31, v172
	global_load_dwordx4 v[160:163], v[150:151], off
	global_load_dwordx4 v[164:167], v[150:151], off offset:16
	global_load_dwordx4 v[168:171], v[150:151], off offset:512
	global_load_dwordx4 v[176:179], v[150:151], off offset:528
	v_lshlrev_b64 v[150:151], 12, v[172:173]
	v_or_b32_e32 v152, 32, v148
	v_lshl_add_u64 v[150:151], v[146:147], 0, v[150:151]
	v_ashrrev_i32_e32 v153, 31, v152
	global_load_dwordx4 v[180:183], v[150:151], off
	global_load_dwordx4 v[184:187], v[150:151], off offset:16
	global_load_dwordx4 v[188:191], v[150:151], off offset:512
	global_load_dwordx4 v[192:195], v[150:151], off offset:528
	v_lshlrev_b64 v[150:151], 12, v[152:153]
	v_lshl_add_u64 v[208:209], v[146:147], 0, v[150:151]
	v_or_b32_e32 v150, 48, v148
	global_load_dwordx4 v[196:199], v[208:209], off
	global_load_dwordx4 v[200:203], v[208:209], off offset:16
	v_ashrrev_i32_e32 v151, 31, v150
	v_lshlrev_b64 v[204:205], 11, v[148:149]
	v_lshlrev_b64 v[216:217], 12, v[150:151]
	v_lshl_add_u64 v[218:219], s[10:11], 0, v[204:205]
	global_load_dwordx4 v[204:207], v[208:209], off offset:528
	global_load_dwordx4 v[212:215], v[208:209], off offset:512
	v_lshlrev_b64 v[144:145], 1, v[144:145]
	v_lshl_add_u64 v[208:209], v[146:147], 0, v[216:217]
	v_lshl_add_u64 v[232:233], v[218:219], 0, v[144:145]
	global_load_dwordx4 v[216:219], v[208:209], off offset:16
	global_load_dwordx4 v[220:223], v[208:209], off
	global_load_dwordx4 v[224:227], v[208:209], off offset:528
	global_load_dwordx4 v[228:231], v[208:209], off offset:512
	v_lshlrev_b64 v[172:173], 11, v[172:173]
	v_lshl_add_u64 v[172:173], s[10:11], 0, v[172:173]
	v_lshl_add_u64 v[172:173], v[172:173], 0, v[144:145]
	v_readlane_b32 s50, v253, 14
	v_readlane_b32 s51, v253, 15
	v_readlane_b32 s52, v253, 16
	v_readlane_b32 s53, v253, 17
	v_readlane_b32 s54, v253, 18
	v_readlane_b32 s55, v253, 19
	v_readlane_b32 s56, v253, 20
	v_readlane_b32 s57, v253, 21
	v_readlane_b32 s58, v253, 22
	v_readlane_b32 s59, v253, 23
	v_readlane_b32 s60, v253, 24
	v_readlane_b32 s61, v253, 25
	v_readlane_b32 s62, v253, 26
	v_readlane_b32 s63, v253, 27
	s_waitcnt vmcnt(0)
	v_pk_add_f32 v[126:127], v[126:127], v[162:163]
	v_pk_add_f32 v[124:125], v[124:125], v[160:161]
	v_pk_add_f32 v[160:161], v[122:123], v[166:167]
	v_pk_add_f32 v[162:163], v[120:121], v[164:165]
	v_pk_add_f32 v[164:165], v[110:111], v[170:171]
	v_pk_add_f32 v[166:167], v[108:109], v[168:169]
	v_pk_add_f32 v[168:169], v[106:107], v[178:179]
	v_cvt_pk_bf16_f32 v120, v124, v125
	v_cvt_pk_bf16_f32 v121, v126, v127
	v_cvt_pk_bf16_f32 v122, v162, v163
	v_cvt_pk_bf16_f32 v123, v160, v161
	v_pk_add_f32 v[106:107], v[112:113], v[184:185]
	global_store_dwordx4 v[232:233], v[120:123], off
	v_cvt_pk_bf16_f32 v112, v166, v167
	v_cvt_pk_bf16_f32 v113, v164, v165
	v_pk_add_f32 v[170:171], v[104:105], v[176:177]
	v_pk_add_f32 v[108:109], v[118:119], v[182:183]
	v_pk_add_f32 v[110:111], v[116:117], v[180:181]
	v_pk_add_f32 v[104:105], v[114:115], v[186:187]
	v_cvt_pk_bf16_f32 v114, v170, v171
	v_cvt_pk_bf16_f32 v115, v168, v169
	global_store_dwordx4 v[232:233], v[112:115], off offset:256
	v_mul_f32_e32 v175, v125, v125
	v_mul_f32_e32 v176, v127, v127
	v_cvt_pk_bf16_f32 v112, v110, v111
	v_cvt_pk_bf16_f32 v113, v108, v109
	v_mul_f32_e32 v125, v167, v167
	v_mul_f32_e32 v127, v165, v165
	v_cvt_pk_bf16_f32 v114, v106, v107
	v_cvt_pk_bf16_f32 v115, v104, v105
	global_store_dwordx4 v[172:173], v[112:115], off
	v_mul_f32_e32 v177, v163, v163
	v_mul_f32_e32 v178, v161, v161
	v_pk_add_f32 v[112:113], v[100:101], v[188:189]
	v_pk_add_f32 v[100:101], v[92:93], v[192:193]
	v_pk_add_f32 v[92:93], v[98:99], v[198:199]
	v_lshlrev_b64 v[98:99], 11, v[152:153]
	v_mul_f32_e32 v161, v171, v171
	v_fmac_f32_e32 v175, v124, v124
	v_fmac_f32_e32 v176, v126, v126
	v_fmac_f32_e32 v125, v166, v166
	v_fmac_f32_e32 v127, v164, v164
	v_lshl_add_u64 v[98:99], s[10:11], 0, v[98:99]
	v_mul_f32_e32 v163, v169, v169
	v_fmac_f32_e32 v177, v162, v162
	v_fmac_f32_e32 v161, v170, v170
	v_add_f32_e32 v116, v175, v176
	v_add_f32_e32 v117, v125, v127
	v_lshl_add_u64 v[118:119], v[98:99], 0, v[144:145]
	v_pk_add_f32 v[98:99], v[84:85], v[212:213]
	v_pk_add_f32 v[84:85], v[76:77], v[204:205]
	v_pk_add_f32 v[76:77], v[82:83], v[222:223]
	v_lshlrev_b64 v[82:83], 11, v[150:151]
	v_fmac_f32_e32 v178, v160, v160
	v_fmac_f32_e32 v163, v168, v168
	v_add_f32_e32 v116, v116, v177
	v_add_f32_e32 v117, v117, v161
	v_lshl_add_u64 v[82:83], s[10:11], 0, v[82:83]
	v_add_f32_e32 v116, v178, v116
	v_add_f32_e32 v117, v163, v117
	v_cvt_pk_bf16_f32 v114, v112, v113
	v_lshl_add_u64 v[122:123], v[82:83], 0, v[144:145]
	v_pk_add_f32 v[82:83], v[68:69], v[228:229]
	v_pk_add_f32 v[68:69], v[64:65], v[224:225]
	v_and_b32_e32 v65, 64, v174
	v_add_f32_e32 v120, v116, v117
	v_pk_add_f32 v[102:103], v[102:103], v[190:191]
	v_pk_add_f32 v[94:95], v[94:95], v[194:195]
	v_cvt_pk_bf16_f32 v115, v102, v103
	v_cvt_pk_bf16_f32 v116, v100, v101
	v_pk_add_f32 v[96:97], v[96:97], v[196:197]
	v_cvt_pk_bf16_f32 v117, v94, v95
	global_store_dwordx4 v[172:173], v[114:117], off offset:256
	v_xor_b32_e32 v64, 16, v174
	v_add_u32_e32 v65, 64, v65
	v_cvt_pk_bf16_f32 v114, v96, v97
	v_pk_add_f32 v[90:91], v[90:91], v[202:203]
	v_pk_add_f32 v[88:89], v[88:89], v[200:201]
	v_cvt_pk_bf16_f32 v115, v92, v93
	v_cmp_lt_i32_e32 vcc, v64, v65
	v_cvt_pk_bf16_f32 v116, v88, v89
	v_cvt_pk_bf16_f32 v117, v90, v91
	global_store_dwordx4 v[118:119], v[114:117], off
	v_pk_add_f32 v[86:87], v[86:87], v[214:215]
	v_pk_add_f32 v[78:79], v[78:79], v[206:207]
	v_cvt_pk_bf16_f32 v114, v98, v99
	v_cvt_pk_bf16_f32 v115, v86, v87
	v_cvt_pk_bf16_f32 v116, v84, v85
	v_pk_add_f32 v[80:81], v[80:81], v[220:221]
	v_cvt_pk_bf16_f32 v117, v78, v79
	global_store_dwordx4 v[118:119], v[114:117], off offset:256
	v_cndmask_b32_e32 v64, v174, v64, vcc
	v_pk_add_f32 v[74:75], v[74:75], v[218:219]
	v_cvt_pk_bf16_f32 v114, v80, v81
	v_pk_add_f32 v[72:73], v[72:73], v[216:217]
	v_cvt_pk_bf16_f32 v115, v76, v77
	v_pk_add_f32 v[70:71], v[70:71], v[230:231]
	v_cvt_pk_bf16_f32 v116, v72, v73
	v_cvt_pk_bf16_f32 v117, v74, v75
	global_store_dwordx4 v[122:123], v[114:117], off
	v_pk_add_f32 v[66:67], v[66:67], v[226:227]
	v_cvt_pk_bf16_f32 v118, v82, v83
	v_cvt_pk_bf16_f32 v119, v70, v71
	s_nop 0
	v_lshlrev_b32_e32 v114, 2, v64
	ds_bpermute_b32 v64, v114, v120
	v_xor_b32_e32 v115, 32, v174
	v_cmp_lt_i32_e32 vcc, v115, v65
	s_waitcnt lgkmcnt(0)
	v_add_f32_e32 v116, v120, v64
	v_cndmask_b32_e32 v65, v174, v115, vcc
	v_lshlrev_b32_e32 v115, 2, v65
	ds_bpermute_b32 v117, v115, v116
	v_lshl_add_u64 v[64:65], v[148:149], 2, s[66:67]
	v_cvt_pk_bf16_f32 v120, v68, v69
	v_cvt_pk_bf16_f32 v121, v66, v67
	global_store_dwordx4 v[122:123], v[118:121], off offset:256
	s_and_saveexec_b64 s[18:19], s[6:7]
	s_cbranch_execz .LBB0_657
	s_waitcnt lgkmcnt(0)
	v_add_f32_e32 v116, v116, v117
	global_atomic_add_f32 v[64:65], v116, off

.LBB0_712:
	ds_read_b128 v[144:147], v151
	ds_read_b128 v[156:159], v151 offset:1024
	ds_read_b128 v[160:163], v151 offset:2048
	ds_read_b128 v[164:167], v151 offset:3072
	s_add_u32 s26, s2, 0xfffc0080
	s_addc_u32 s27, s3, -1
	s_cmp_eq_u32 s56, 12
	s_cselect_b32 s29, s21, s27
	s_cselect_b32 s28, s52, s26
	s_cselect_b32 s27, s19, s55
	s_cselect_b32 s26, s53, s54
	v_lshl_add_u64 v[172:173], s[2:3], 0, v[136:137]
	s_add_i32 m0, s34, 0xc000
	ds_read_b128 v[168:171], v152
	ds_read_b128 v[176:179], v152 offset:1024
	ds_read_b128 v[180:183], v152 offset:2048
	ds_read_b128 v[184:187], v152 offset:3072
	ds_read_b128 v[188:191], v152 offset:4096
	ds_read_b128 v[192:195], v152 offset:5120
	ds_read_b128 v[196:199], v152 offset:6144
	ds_read_b128 v[200:203], v152 offset:7168
	global_load_lds_dwordx4 v[172:173], off
	v_lshl_add_u64 v[172:173], s[2:3], 0, v[138:139]
	s_add_i32 m0, s34, 0xe000
	s_nop 0
	global_load_lds_dwordx4 v[172:173], off
	s_waitcnt lgkmcnt(8)
	s_barrier
	s_waitcnt lgkmcnt(0)
	s_setprio 1
	v_mfma_f32_16x16x32_bf16 v[124:127], v[144:147], v[168:171], v[124:127]
	v_mfma_f32_16x16x32_bf16 v[120:123], v[160:163], v[168:171], v[120:123]
	v_mfma_f32_16x16x32_bf16 v[116:119], v[144:147], v[180:183], v[116:119]
	v_mfma_f32_16x16x32_bf16 v[112:115], v[160:163], v[180:183], v[112:115]
	v_mfma_f32_16x16x32_bf16 v[104:107], v[144:147], v[188:191], v[104:107]
	v_mfma_f32_16x16x32_bf16 v[96:99], v[160:163], v[188:191], v[96:99]
	v_mfma_f32_16x16x32_bf16 v[76:79], v[144:147], v[196:199], v[76:79]
	v_mfma_f32_16x16x32_bf16 v[72:75], v[160:163], v[196:199], v[72:75]
	v_mfma_f32_16x16x32_bf16 v[124:127], v[156:159], v[176:179], v[124:127]
	v_mfma_f32_16x16x32_bf16 v[120:123], v[164:167], v[176:179], v[120:123]
	v_mfma_f32_16x16x32_bf16 v[116:119], v[156:159], v[184:187], v[116:119]
	v_mfma_f32_16x16x32_bf16 v[112:115], v[164:167], v[184:187], v[112:115]
	v_mfma_f32_16x16x32_bf16 v[104:107], v[156:159], v[192:195], v[104:107]
	v_mfma_f32_16x16x32_bf16 v[96:99], v[164:167], v[192:195], v[96:99]
	v_mfma_f32_16x16x32_bf16 v[76:79], v[156:159], v[200:203], v[76:79]
	v_mfma_f32_16x16x32_bf16 v[72:75], v[164:167], v[200:203], v[72:75]
	s_setprio 0
	s_barrier
	s_add_i32 s57, s43, s33
	v_lshl_add_u64 v[172:173], s[26:27], 0, v[130:131]
	s_mov_b32 m0, s57
	ds_read_b128 v[204:207], v153
	ds_read_b128 v[212:215], v153 offset:1024
	ds_read_b128 v[216:219], v153 offset:2048
	ds_read_b128 v[220:223], v153 offset:3072
	global_load_lds_dwordx4 v[172:173], off
	v_lshl_add_u64 v[208:209], s[26:27], 0, v[134:135]
	s_add_i32 m0, s57, 0x2000
	s_nop 0
	global_load_lds_dwordx4 v[208:209], off
	s_barrier
	s_waitcnt lgkmcnt(0)
	s_setprio 1
	v_mfma_f32_16x16x32_bf16 v[108:111], v[204:207], v[168:171], v[108:111]
	v_mfma_f32_16x16x32_bf16 v[100:103], v[216:219], v[168:171], v[100:103]
	v_mfma_f32_16x16x32_bf16 v[92:95], v[204:207], v[180:183], v[92:95]
	v_mfma_f32_16x16x32_bf16 v[88:91], v[216:219], v[180:183], v[88:91]
	v_mfma_f32_16x16x32_bf16 v[84:87], v[204:207], v[188:191], v[84:87]
	v_mfma_f32_16x16x32_bf16 v[80:83], v[216:219], v[188:191], v[80:83]
	v_mfma_f32_16x16x32_bf16 v[68:71], v[204:207], v[196:199], v[68:71]
	v_mfma_f32_16x16x32_bf16 v[64:67], v[216:219], v[196:199], v[64:67]
	v_mfma_f32_16x16x32_bf16 v[108:111], v[212:215], v[176:179], v[108:111]
	v_mfma_f32_16x16x32_bf16 v[100:103], v[220:223], v[176:179], v[100:103]
	v_mfma_f32_16x16x32_bf16 v[92:95], v[212:215], v[184:187], v[92:95]
	v_mfma_f32_16x16x32_bf16 v[88:91], v[220:223], v[184:187], v[88:91]
	v_mfma_f32_16x16x32_bf16 v[84:87], v[212:215], v[192:195], v[84:87]
	v_mfma_f32_16x16x32_bf16 v[80:83], v[220:223], v[192:195], v[80:83]
	v_mfma_f32_16x16x32_bf16 v[68:71], v[212:215], v[200:203], v[68:71]
	v_mfma_f32_16x16x32_bf16 v[64:67], v[220:223], v[200:203], v[64:67]
	s_setprio 0
	s_mov_b32 m0, s34
	v_lshl_add_u64 v[224:225], s[28:29], 0, v[128:129]
	s_barrier
	ds_read_b128 v[168:171], v152 offset:16384
	ds_read_b128 v[176:179], v152 offset:17408
	ds_read_b128 v[180:183], v152 offset:18432
	ds_read_b128 v[184:187], v152 offset:19456
	ds_read_b128 v[188:191], v152 offset:20480
	ds_read_b128 v[192:195], v152 offset:21504
	ds_read_b128 v[196:199], v152 offset:22528
	ds_read_b128 v[200:203], v152 offset:23552
	global_load_lds_dwordx4 v[224:225], off
	v_lshl_add_u64 v[226:227], s[28:29], 0, v[132:133]
	s_mov_b32 m0, s35
	s_nop 0
	global_load_lds_dwordx4 v[226:227], off
	s_barrier
	s_waitcnt lgkmcnt(0)
	s_setprio 1
	v_mfma_f32_16x16x32_bf16 v[60:63], v[144:147], v[168:171], v[60:63]
	v_mfma_f32_16x16x32_bf16 v[56:59], v[160:163], v[168:171], v[56:59]
	v_mfma_f32_16x16x32_bf16 v[44:47], v[144:147], v[180:183], v[44:47]
	v_mfma_f32_16x16x32_bf16 v[40:43], v[160:163], v[180:183], v[40:43]
	v_mfma_f32_16x16x32_bf16 v[28:31], v[144:147], v[188:191], v[28:31]
	v_mfma_f32_16x16x32_bf16 v[24:27], v[160:163], v[188:191], v[24:27]
	v_mfma_f32_16x16x32_bf16 v[12:15], v[144:147], v[196:199], v[12:15]
	v_mfma_f32_16x16x32_bf16 v[8:11], v[160:163], v[196:199], v[8:11]
	v_mfma_f32_16x16x32_bf16 v[60:63], v[156:159], v[176:179], v[60:63]
	v_mfma_f32_16x16x32_bf16 v[56:59], v[164:167], v[176:179], v[56:59]
	v_mfma_f32_16x16x32_bf16 v[44:47], v[156:159], v[184:187], v[44:47]
	v_mfma_f32_16x16x32_bf16 v[40:43], v[164:167], v[184:187], v[40:43]
	v_mfma_f32_16x16x32_bf16 v[28:31], v[156:159], v[192:195], v[28:31]
	v_mfma_f32_16x16x32_bf16 v[24:27], v[164:167], v[192:195], v[24:27]
	v_mfma_f32_16x16x32_bf16 v[12:15], v[156:159], v[200:203], v[12:15]
	v_mfma_f32_16x16x32_bf16 v[8:11], v[164:167], v[200:203], v[8:11]
	s_setprio 0
	s_barrier
	s_add_u32 s58, s26, 0x40000
	s_addc_u32 s59, s27, 0
	s_add_i32 s57, s48, s33
	v_lshl_add_u64 v[144:145], s[58:59], 0, v[130:131]
	s_mov_b32 m0, s57
	s_nop 0
	global_load_lds_dwordx4 v[144:145], off
	v_lshl_add_u64 v[144:145], s[58:59], 0, v[134:135]
	s_add_i32 m0, s57, 0x2000
	s_nop 0
	global_load_lds_dwordx4 v[144:145], off
	s_waitcnt vmcnt(6)
	s_barrier
	s_setprio 1
	v_mfma_f32_16x16x32_bf16 v[52:55], v[204:207], v[168:171], v[52:55]
	v_mfma_f32_16x16x32_bf16 v[48:51], v[216:219], v[168:171], v[48:51]
	v_mfma_f32_16x16x32_bf16 v[36:39], v[204:207], v[180:183], v[36:39]
	v_mfma_f32_16x16x32_bf16 v[32:35], v[216:219], v[180:183], v[32:35]
	v_mfma_f32_16x16x32_bf16 v[20:23], v[204:207], v[188:191], v[20:23]
	v_mfma_f32_16x16x32_bf16 v[16:19], v[216:219], v[188:191], v[16:19]
	v_mfma_f32_16x16x32_bf16 v[4:7], v[204:207], v[196:199], v[4:7]
	v_mfma_f32_16x16x32_bf16 v[0:3], v[216:219], v[196:199], v[0:3]
	v_mfma_f32_16x16x32_bf16 v[52:55], v[212:215], v[176:179], v[52:55]
	v_mfma_f32_16x16x32_bf16 v[48:51], v[220:223], v[176:179], v[48:51]
	v_mfma_f32_16x16x32_bf16 v[36:39], v[212:215], v[184:187], v[36:39]
	v_mfma_f32_16x16x32_bf16 v[32:35], v[220:223], v[184:187], v[32:35]
	v_mfma_f32_16x16x32_bf16 v[20:23], v[212:215], v[192:195], v[20:23]
	v_mfma_f32_16x16x32_bf16 v[16:19], v[220:223], v[192:195], v[16:19]
	v_mfma_f32_16x16x32_bf16 v[4:7], v[212:215], v[200:203], v[4:7]
	v_mfma_f32_16x16x32_bf16 v[0:3], v[220:223], v[200:203], v[0:3]
	s_setprio 0
	s_add_i32 s57, 0, 0x18000
	v_add_u32_e32 v155, s57, v149
	s_barrier
	ds_read_b128 v[144:147], v155
	ds_read_b128 v[156:159], v155 offset:1024
	ds_read_b128 v[160:163], v155 offset:2048
	ds_read_b128 v[164:167], v155 offset:3072
	s_add_u32 s28, s28, 0x40000
	s_addc_u32 s29, s29, 0
	s_mov_b32 m0, s36
	v_lshl_add_u64 v[204:205], s[28:29], 0, v[128:129]
	ds_read_b128 v[168:171], v152 offset:32768
	ds_read_b128 v[176:179], v152 offset:33792
	ds_read_b128 v[180:183], v152 offset:34816
	ds_read_b128 v[184:187], v152 offset:35840
	ds_read_b128 v[188:191], v152 offset:36864
	ds_read_b128 v[192:195], v152 offset:37888
	ds_read_b128 v[196:199], v152 offset:38912
	ds_read_b128 v[200:203], v152 offset:39936
	global_load_lds_dwordx4 v[204:205], off
	v_lshl_add_u64 v[204:205], s[28:29], 0, v[132:133]
	s_mov_b32 m0, s37
	s_nop 0
	global_load_lds_dwordx4 v[204:205], off
	s_waitcnt lgkmcnt(8)
	s_barrier
	s_waitcnt lgkmcnt(0)
	s_setprio 1
	v_mfma_f32_16x16x32_bf16 v[124:127], v[144:147], v[168:171], v[124:127]
	v_mfma_f32_16x16x32_bf16 v[120:123], v[160:163], v[168:171], v[120:123]
	v_mfma_f32_16x16x32_bf16 v[116:119], v[144:147], v[180:183], v[116:119]
	v_mfma_f32_16x16x32_bf16 v[112:115], v[160:163], v[180:183], v[112:115]
	v_mfma_f32_16x16x32_bf16 v[104:107], v[144:147], v[188:191], v[104:107]
	v_mfma_f32_16x16x32_bf16 v[96:99], v[160:163], v[188:191], v[96:99]
	v_mfma_f32_16x16x32_bf16 v[76:79], v[144:147], v[196:199], v[76:79]
	v_mfma_f32_16x16x32_bf16 v[72:75], v[160:163], v[196:199], v[72:75]
	v_mfma_f32_16x16x32_bf16 v[124:127], v[156:159], v[176:179], v[124:127]
	v_mfma_f32_16x16x32_bf16 v[120:123], v[164:167], v[176:179], v[120:123]
	v_mfma_f32_16x16x32_bf16 v[116:119], v[156:159], v[184:187], v[116:119]
	v_mfma_f32_16x16x32_bf16 v[112:115], v[164:167], v[184:187], v[112:115]
	v_mfma_f32_16x16x32_bf16 v[104:107], v[156:159], v[192:195], v[104:107]
	v_mfma_f32_16x16x32_bf16 v[96:99], v[164:167], v[192:195], v[96:99]
	v_mfma_f32_16x16x32_bf16 v[76:79], v[156:159], v[200:203], v[76:79]
	v_mfma_f32_16x16x32_bf16 v[72:75], v[164:167], v[200:203], v[72:75]
	s_setprio 0
	s_barrier
	s_add_i32 s28, 0, 0x1c000
	s_add_i32 s29, s57, s33
	v_add_u32_e32 v155, s28, v149
	v_lshl_add_u64 v[172:173], v[172:173], 0, s[8:9]
	s_mov_b32 m0, s29
	ds_read_b128 v[204:207], v155
	ds_read_b128 v[212:215], v155 offset:1024
	ds_read_b128 v[216:219], v155 offset:2048
	ds_read_b128 v[220:223], v155 offset:3072
	global_load_lds_dwordx4 v[172:173], off
	v_lshl_add_u64 v[172:173], v[208:209], 0, s[8:9]
	s_add_i32 m0, s29, 0x2000
	s_nop 0
	global_load_lds_dwordx4 v[172:173], off
	s_barrier
	s_waitcnt lgkmcnt(0)
	s_setprio 1
	v_mfma_f32_16x16x32_bf16 v[108:111], v[204:207], v[168:171], v[108:111]
	v_mfma_f32_16x16x32_bf16 v[100:103], v[216:219], v[168:171], v[100:103]
	v_mfma_f32_16x16x32_bf16 v[92:95], v[204:207], v[180:183], v[92:95]
	v_mfma_f32_16x16x32_bf16 v[88:91], v[216:219], v[180:183], v[88:91]
	v_mfma_f32_16x16x32_bf16 v[84:87], v[204:207], v[188:191], v[84:87]
	v_mfma_f32_16x16x32_bf16 v[80:83], v[216:219], v[188:191], v[80:83]
	v_mfma_f32_16x16x32_bf16 v[68:71], v[204:207], v[196:199], v[68:71]
	v_mfma_f32_16x16x32_bf16 v[64:67], v[216:219], v[196:199], v[64:67]
	v_mfma_f32_16x16x32_bf16 v[108:111], v[212:215], v[176:179], v[108:111]
	v_mfma_f32_16x16x32_bf16 v[100:103], v[220:223], v[176:179], v[100:103]
	v_mfma_f32_16x16x32_bf16 v[92:95], v[212:215], v[184:187], v[92:95]
	v_mfma_f32_16x16x32_bf16 v[88:91], v[220:223], v[184:187], v[88:91]
	v_mfma_f32_16x16x32_bf16 v[84:87], v[212:215], v[192:195], v[84:87]
	v_mfma_f32_16x16x32_bf16 v[80:83], v[220:223], v[192:195], v[80:83]
	v_mfma_f32_16x16x32_bf16 v[68:71], v[212:215], v[200:203], v[68:71]
	v_mfma_f32_16x16x32_bf16 v[64:67], v[220:223], v[200:203], v[64:67]
	s_setprio 0
	s_mov_b32 m0, s39
	v_lshl_add_u64 v[172:173], v[224:225], 0, s[8:9]
	s_barrier
	ds_read_b128 v[168:171], v152 offset:49152
	ds_read_b128 v[176:179], v152 offset:50176
	ds_read_b128 v[180:183], v152 offset:51200
	ds_read_b128 v[184:187], v152 offset:52224
	ds_read_b128 v[188:191], v152 offset:53248
	ds_read_b128 v[192:195], v152 offset:54272
	ds_read_b128 v[196:199], v152 offset:55296
	ds_read_b128 v[200:203], v152 offset:56320
	global_load_lds_dwordx4 v[172:173], off
	v_lshl_add_u64 v[172:173], v[226:227], 0, s[8:9]
	s_mov_b32 m0, s40
	s_nop 0
	global_load_lds_dwordx4 v[172:173], off
	s_barrier
	s_waitcnt lgkmcnt(0)
	s_setprio 1
	v_mfma_f32_16x16x32_bf16 v[60:63], v[144:147], v[168:171], v[60:63]
	v_mfma_f32_16x16x32_bf16 v[56:59], v[160:163], v[168:171], v[56:59]
	v_mfma_f32_16x16x32_bf16 v[44:47], v[144:147], v[180:183], v[44:47]
	v_mfma_f32_16x16x32_bf16 v[40:43], v[160:163], v[180:183], v[40:43]
	v_mfma_f32_16x16x32_bf16 v[28:31], v[144:147], v[188:191], v[28:31]
	v_mfma_f32_16x16x32_bf16 v[24:27], v[160:163], v[188:191], v[24:27]
	v_mfma_f32_16x16x32_bf16 v[12:15], v[144:147], v[196:199], v[12:15]
	v_mfma_f32_16x16x32_bf16 v[8:11], v[160:163], v[196:199], v[8:11]
	v_mfma_f32_16x16x32_bf16 v[60:63], v[156:159], v[176:179], v[60:63]
	v_mfma_f32_16x16x32_bf16 v[56:59], v[164:167], v[176:179], v[56:59]
	v_mfma_f32_16x16x32_bf16 v[44:47], v[156:159], v[184:187], v[44:47]
	v_mfma_f32_16x16x32_bf16 v[40:43], v[164:167], v[184:187], v[40:43]
	v_mfma_f32_16x16x32_bf16 v[28:31], v[156:159], v[192:195], v[28:31]
	v_mfma_f32_16x16x32_bf16 v[24:27], v[164:167], v[192:195], v[24:27]
	v_mfma_f32_16x16x32_bf16 v[12:15], v[156:159], v[200:203], v[12:15]
	v_mfma_f32_16x16x32_bf16 v[8:11], v[164:167], v[200:203], v[8:11]
	s_setprio 0
	s_barrier
	s_add_u32 s26, s26, 0x40080
	s_addc_u32 s27, s27, 0
	s_add_i32 s28, s28, s33
	v_lshl_add_u64 v[144:145], s[26:27], 0, v[130:131]
	s_mov_b32 m0, s28
	s_nop 0
	global_load_lds_dwordx4 v[144:145], off
	v_lshl_add_u64 v[144:145], s[26:27], 0, v[134:135]
	s_add_i32 m0, s28, 0x2000
	s_nop 0
	global_load_lds_dwordx4 v[144:145], off
	s_waitcnt vmcnt(6)
	s_barrier
	s_setprio 1
	v_mfma_f32_16x16x32_bf16 v[52:55], v[204:207], v[168:171], v[52:55]
	v_mfma_f32_16x16x32_bf16 v[48:51], v[216:219], v[168:171], v[48:51]
	v_mfma_f32_16x16x32_bf16 v[36:39], v[204:207], v[180:183], v[36:39]
	v_mfma_f32_16x16x32_bf16 v[32:35], v[216:219], v[180:183], v[32:35]
	v_mfma_f32_16x16x32_bf16 v[20:23], v[204:207], v[188:191], v[20:23]
	v_mfma_f32_16x16x32_bf16 v[16:19], v[216:219], v[188:191], v[16:19]
	v_mfma_f32_16x16x32_bf16 v[4:7], v[204:207], v[196:199], v[4:7]
	v_mfma_f32_16x16x32_bf16 v[0:3], v[216:219], v[196:199], v[0:3]
	v_mfma_f32_16x16x32_bf16 v[52:55], v[212:215], v[176:179], v[52:55]
	v_mfma_f32_16x16x32_bf16 v[48:51], v[220:223], v[176:179], v[48:51]
	v_mfma_f32_16x16x32_bf16 v[36:39], v[212:215], v[184:187], v[36:39]
	v_mfma_f32_16x16x32_bf16 v[32:35], v[220:223], v[184:187], v[32:35]
	v_mfma_f32_16x16x32_bf16 v[20:23], v[212:215], v[192:195], v[20:23]
	v_mfma_f32_16x16x32_bf16 v[16:19], v[220:223], v[192:195], v[16:19]
	v_mfma_f32_16x16x32_bf16 v[4:7], v[212:215], v[200:203], v[4:7]
	v_mfma_f32_16x16x32_bf16 v[0:3], v[220:223], v[200:203], v[0:3]
	s_setprio 0
	s_add_i32 s56, s56, 2
	s_add_u32 s2, s2, 0x100
	s_addc_u32 s3, s3, 0
	s_add_u32 s54, s54, 0x100
	s_addc_u32 s55, s55, 0
	s_cmp_gt_u32 s56, 13
	s_barrier
	s_cbranch_scc0 .LBB0_712
	v_lshl_add_u32 v146, s0, 8, v148
	v_ashrrev_i32_e32 v147, 31, v146
	v_lshl_add_u64 v[144:145], v[146:147], 2, s[66:67]
	global_load_dword v155, v[144:145], off
	global_load_dword v164, v[144:145], off offset:64
	global_load_dword v165, v[144:145], off offset:128
	global_load_dword v166, v[144:145], off offset:192
	global_load_dword v167, v[144:145], off offset:512
	global_load_dword v168, v[144:145], off offset:576
	global_load_dword v169, v[144:145], off offset:640
	global_load_dword v170, v[144:145], off offset:704
	v_lshl_or_b32 v144, s1, 8, v150
	v_ashrrev_i32_e32 v145, 31, v144
	v_lshlrev_b64 v[160:161], 10, v[146:147]
	v_lshlrev_b64 v[162:163], 1, v[144:145]
	v_lshl_add_u64 v[144:145], s[92:93], 0, v[160:161]
	v_or_b32_e32 v156, 16, v146
	v_ashrrev_i32_e32 v157, 31, v156
	v_or_b32_e32 v158, 32, v146
	v_lshlrev_b64 v[156:157], 10, v[156:157]
	v_lshl_add_u64 v[144:145], v[144:145], 0, v[162:163]
	v_ashrrev_i32_e32 v159, 31, v158
	v_lshl_add_u64 v[156:157], s[92:93], 0, v[156:157]
	v_lshlrev_b64 v[158:159], 10, v[158:159]
	v_lshl_add_u64 v[156:157], v[156:157], 0, v[162:163]
	v_lshl_add_u64 v[158:159], s[92:93], 0, v[158:159]
	v_lshl_add_u64 v[158:159], v[158:159], 0, v[162:163]
	s_mov_b64 s[26:27], s[24:25]
	s_waitcnt vmcnt(0)
	v_fmamk_f32 v147, v155, 0x3a800000, v154
	v_fmamk_f32 v155, v164, 0x3a800000, v154
	v_fmamk_f32 v160, v165, 0x3a800000, v154
	v_mul_f32_e32 v161, 0x4b800000, v147
	v_mul_f32_e32 v164, 0x4b800000, v155
	v_cmp_gt_f32_e32 vcc, s49, v147
	v_cmp_gt_f32_e64 s[0:1], s49, v155
	v_mul_f32_e32 v165, 0x4b800000, v160
	v_cndmask_b32_e32 v147, v147, v161, vcc
	v_cndmask_b32_e64 v155, v155, v164, s[0:1]
	v_cmp_gt_f32_e64 s[2:3], s49, v160
	v_rsq_f32_e32 v147, v147
	v_rsq_f32_e32 v155, v155
	v_cndmask_b32_e64 v160, v160, v165, s[2:3]
	v_rsq_f32_e32 v160, v160
	v_mul_f32_e32 v161, 0x45800000, v147
	v_mul_f32_e32 v164, 0x45800000, v155
	v_cndmask_b32_e32 v147, v147, v161, vcc
	v_mul_f32_e32 v165, 0x45800000, v160
	v_cndmask_b32_e64 v155, v155, v164, s[0:1]
	v_cndmask_b32_e64 v161, v160, v165, s[2:3]
	v_mul_f32_e32 v160, 0x3e0293ee, v147
	v_mul_f32_e32 v164, 0x3e0293ee, v155
	v_fmamk_f32 v171, v166, 0x3a800000, v154
	v_mul_f32_e32 v166, 0x3e0293ee, v161
	v_pk_mul_f32 v[126:127], v[126:127], v[160:161] op_sel_hi:[1,0]
	v_pk_mul_f32 v[124:125], v[124:125], v[160:161] op_sel_hi:[1,0]
	v_pk_mul_f32 v[122:123], v[122:123], v[160:161] op_sel_hi:[1,0]
	v_pk_mul_f32 v[120:121], v[120:121], v[160:161] op_sel_hi:[1,0]
	v_pk_mul_f32 v[110:111], v[110:111], v[160:161] op_sel_hi:[1,0]
	v_pk_mul_f32 v[108:109], v[108:109], v[160:161] op_sel_hi:[1,0]
	v_pk_mul_f32 v[102:103], v[102:103], v[160:161] op_sel_hi:[1,0]
	v_pk_mul_f32 v[100:101], v[100:101], v[160:161] op_sel_hi:[1,0]
	v_pk_mul_f32 v[118:119], v[118:119], v[164:165] op_sel_hi:[1,0]
	v_pk_mul_f32 v[116:117], v[116:117], v[164:165] op_sel_hi:[1,0]
	v_pk_mul_f32 v[114:115], v[114:115], v[164:165] op_sel_hi:[1,0]
	v_pk_mul_f32 v[112:113], v[112:113], v[164:165] op_sel_hi:[1,0]
	v_pk_mul_f32 v[94:95], v[94:95], v[164:165] op_sel_hi:[1,0]
	v_pk_mul_f32 v[92:93], v[92:93], v[164:165] op_sel_hi:[1,0]
	v_pk_mul_f32 v[160:161], v[90:91], v[164:165] op_sel_hi:[1,0]
	v_pk_mul_f32 v[164:165], v[88:89], v[164:165] op_sel_hi:[1,0]
	v_cvt_pk_bf16_f32 v88, v124, v125
	v_cvt_pk_bf16_f32 v89, v126, v127
	v_cvt_pk_bf16_f32 v90, v120, v121
	v_cvt_pk_bf16_f32 v91, v122, v123
	global_store_dwordx4 v[144:145], v[88:91], off
	v_fmamk_f32 v167, v167, 0x3a800000, v154
	v_pk_mul_f32 v[106:107], v[106:107], v[166:167] op_sel_hi:[1,0]
	v_cvt_pk_bf16_f32 v88, v108, v109
	v_cvt_pk_bf16_f32 v89, v110, v111
	v_cvt_pk_bf16_f32 v90, v100, v101
	v_cvt_pk_bf16_f32 v91, v102, v103
	global_store_dwordx4 v[144:145], v[88:91], off offset:256
	v_pk_mul_f32 v[104:105], v[104:105], v[166:167] op_sel_hi:[1,0]
	v_pk_mul_f32 v[98:99], v[98:99], v[166:167] op_sel_hi:[1,0]
	v_cvt_pk_bf16_f32 v88, v116, v117
	v_cvt_pk_bf16_f32 v89, v118, v119
	v_cvt_pk_bf16_f32 v90, v112, v113
	v_cvt_pk_bf16_f32 v91, v114, v115
	global_store_dwordx4 v[156:157], v[88:91], off
	v_pk_mul_f32 v[96:97], v[96:97], v[166:167] op_sel_hi:[1,0]
	v_pk_mul_f32 v[86:87], v[86:87], v[166:167] op_sel_hi:[1,0]
	v_cvt_pk_bf16_f32 v88, v92, v93
	v_cvt_pk_bf16_f32 v89, v94, v95
	v_cvt_pk_bf16_f32 v90, v164, v165
	v_cvt_pk_bf16_f32 v91, v160, v161
	global_store_dwordx4 v[156:157], v[88:91], off offset:256
	v_pk_mul_f32 v[84:85], v[84:85], v[166:167] op_sel_hi:[1,0]
	v_cmp_gt_f32_e32 vcc, s49, v171
	v_cvt_pk_bf16_f32 v88, v104, v105
	v_cvt_pk_bf16_f32 v89, v106, v107
	v_cvt_pk_bf16_f32 v90, v96, v97
	v_cvt_pk_bf16_f32 v91, v98, v99
	global_store_dwordx4 v[158:159], v[88:91], off
	s_mov_b64 s[0:1], 0x20000
	v_fmamk_f32 v168, v168, 0x3a800000, v154
	v_pk_mul_f32 v[88:89], v[82:83], v[166:167] op_sel_hi:[1,0]
	v_pk_mul_f32 v[82:83], v[80:81], v[166:167] op_sel_hi:[1,0]
	v_cvt_pk_bf16_f32 v80, v84, v85
	v_cvt_pk_bf16_f32 v81, v86, v87
	v_fmamk_f32 v169, v169, 0x3a800000, v154
	v_cvt_pk_bf16_f32 v82, v82, v83
	v_cvt_pk_bf16_f32 v83, v88, v89
	global_store_dwordx4 v[158:159], v[80:83], off offset:256
	v_fmamk_f32 v170, v170, 0x3a800000, v154
	s_mov_b64 s[2:3], s[22:23]
	v_mul_f32_e32 v82, 0x4b800000, v171
	v_cndmask_b32_e32 v82, v171, v82, vcc
	v_rsq_f32_e32 v82, v82
	v_or_b32_e32 v80, 48, v146
	v_ashrrev_i32_e32 v81, 31, v80
	v_lshlrev_b64 v[80:81], 10, v[80:81]
	v_mul_f32_e32 v83, 0x45800000, v82
	v_cndmask_b32_e32 v82, v82, v83, vcc
	v_lshl_add_u64 v[80:81], s[92:93], 0, v[80:81]
	v_mul_f32_e32 v82, 0x3e0293ee, v82
	v_lshl_add_u64 v[80:81], v[80:81], 0, v[162:163]
	v_pk_mul_f32 v[78:79], v[78:79], v[82:83] op_sel_hi:[1,0]
	v_pk_mul_f32 v[76:77], v[76:77], v[82:83] op_sel_hi:[1,0]
	v_pk_mul_f32 v[84:85], v[74:75], v[82:83] op_sel_hi:[1,0]
	v_pk_mul_f32 v[74:75], v[72:73], v[82:83] op_sel_hi:[1,0]
	v_cvt_pk_bf16_f32 v72, v76, v77
	v_cvt_pk_bf16_f32 v73, v78, v79
	v_pk_mul_f32 v[70:71], v[70:71], v[82:83] op_sel_hi:[1,0]
	v_cvt_pk_bf16_f32 v74, v74, v75
	v_cvt_pk_bf16_f32 v75, v84, v85
	global_store_dwordx4 v[80:81], v[72:75], off
	v_pk_mul_f32 v[68:69], v[68:69], v[82:83] op_sel_hi:[1,0]
	v_cmp_gt_f32_e32 vcc, s49, v167
	v_pk_mul_f32 v[72:73], v[66:67], v[82:83] op_sel_hi:[1,0]
	v_pk_mul_f32 v[66:67], v[64:65], v[82:83] op_sel_hi:[1,0]
	v_cvt_pk_bf16_f32 v64, v68, v69
	v_cvt_pk_bf16_f32 v65, v70, v71
	s_nop 0
	v_cvt_pk_bf16_f32 v66, v66, v67
	v_mul_f32_e32 v67, 0x4b800000, v167
	v_cndmask_b32_e32 v67, v167, v67, vcc
	v_rsq_f32_e32 v68, v67
	v_cvt_pk_bf16_f32 v67, v72, v73
	global_store_dwordx4 v[80:81], v[64:67], off offset:256
	s_nop 1
	v_mul_f32_e32 v66, 0x45800000, v68
	v_cndmask_b32_e32 v66, v68, v66, vcc
	v_mul_f32_e32 v66, 0x3e0293ee, v66
	v_lshl_add_u64 v[64:65], v[144:145], 0, s[0:1]
	v_pk_mul_f32 v[60:61], v[60:61], v[66:67] op_sel_hi:[1,0]
	s_mov_b32 s0, 0x20000
	v_pk_mul_f32 v[68:69], v[58:59], v[66:67] op_sel_hi:[1,0]
	v_pk_mul_f32 v[58:59], v[56:57], v[66:67] op_sel_hi:[1,0]
	v_cvt_pk_bf16_f32 v56, v60, v61
	v_add_co_u32_e32 v60, vcc, s0, v144
	v_pk_mul_f32 v[62:63], v[62:63], v[66:67] op_sel_hi:[1,0]
	s_nop 0
	v_addc_co_u32_e32 v61, vcc, 0, v145, vcc
	v_cvt_pk_bf16_f32 v57, v62, v63
	v_cvt_pk_bf16_f32 v58, v58, v59
	v_cvt_pk_bf16_f32 v59, v68, v69
	global_store_dwordx4 v[60:61], v[56:59], off
	v_pk_mul_f32 v[54:55], v[54:55], v[66:67] op_sel_hi:[1,0]
	v_pk_mul_f32 v[52:53], v[52:53], v[66:67] op_sel_hi:[1,0]
	v_pk_mul_f32 v[56:57], v[50:51], v[66:67] op_sel_hi:[1,0]
	v_pk_mul_f32 v[50:51], v[48:49], v[66:67] op_sel_hi:[1,0]
	v_cvt_pk_bf16_f32 v48, v52, v53
	v_cvt_pk_bf16_f32 v49, v54, v55
	v_cmp_gt_f32_e32 vcc, s49, v168
	v_cvt_pk_bf16_f32 v50, v50, v51
	v_mul_f32_e32 v51, 0x4b800000, v168
	s_mov_b64 s[0:1], 0x24000
	v_cndmask_b32_e32 v51, v168, v51, vcc
	v_rsq_f32_e32 v52, v51
	v_cvt_pk_bf16_f32 v51, v56, v57
	global_store_dwordx4 v[64:65], v[48:51], off offset:256
	s_nop 1
	v_mul_f32_e32 v50, 0x45800000, v52
	v_cndmask_b32_e32 v50, v52, v50, vcc
	v_mul_f32_e32 v50, 0x3e0293ee, v50
	v_lshl_add_u64 v[48:49], v[144:145], 0, s[0:1]
	v_pk_mul_f32 v[44:45], v[44:45], v[50:51] op_sel_hi:[1,0]
	s_mov_b32 s0, 0x24000
	v_pk_mul_f32 v[52:53], v[42:43], v[50:51] op_sel_hi:[1,0]
	v_pk_mul_f32 v[42:43], v[40:41], v[50:51] op_sel_hi:[1,0]
	v_cvt_pk_bf16_f32 v40, v44, v45
	v_add_co_u32_e32 v44, vcc, s0, v144
	v_pk_mul_f32 v[46:47], v[46:47], v[50:51] op_sel_hi:[1,0]
	s_nop 0
	v_addc_co_u32_e32 v45, vcc, 0, v145, vcc
	v_cvt_pk_bf16_f32 v41, v46, v47
	v_cvt_pk_bf16_f32 v42, v42, v43
	v_cvt_pk_bf16_f32 v43, v52, v53
	global_store_dwordx4 v[44:45], v[40:43], off
	v_pk_mul_f32 v[38:39], v[38:39], v[50:51] op_sel_hi:[1,0]
	v_pk_mul_f32 v[36:37], v[36:37], v[50:51] op_sel_hi:[1,0]
	v_pk_mul_f32 v[40:41], v[34:35], v[50:51] op_sel_hi:[1,0]
	v_pk_mul_f32 v[34:35], v[32:33], v[50:51] op_sel_hi:[1,0]
	v_cvt_pk_bf16_f32 v32, v36, v37
	v_cvt_pk_bf16_f32 v33, v38, v39
	v_cmp_gt_f32_e32 vcc, s49, v169
	v_cvt_pk_bf16_f32 v34, v34, v35
	v_mul_f32_e32 v35, 0x4b800000, v169
	s_mov_b32 s1, s18
	v_cndmask_b32_e32 v35, v169, v35, vcc
	v_rsq_f32_e32 v36, v35
	v_cvt_pk_bf16_f32 v35, v40, v41
	global_store_dwordx4 v[48:49], v[32:35], off offset:256
	s_mov_b32 s0, s20
	s_nop 0
	v_mul_f32_e32 v34, 0x45800000, v36
	v_cndmask_b32_e32 v34, v36, v34, vcc
	v_mul_f32_e32 v34, 0x3e0293ee, v34
	v_pk_mul_f32 v[28:29], v[28:29], v[34:35] op_sel_hi:[1,0]
	v_pk_mul_f32 v[36:37], v[26:27], v[34:35] op_sel_hi:[1,0]
	v_pk_mul_f32 v[26:27], v[24:25], v[34:35] op_sel_hi:[1,0]
	v_cvt_pk_bf16_f32 v24, v28, v29
	v_add_co_u32_e32 v28, vcc, s50, v144
	v_pk_mul_f32 v[30:31], v[30:31], v[34:35] op_sel_hi:[1,0]
	s_nop 0
	v_addc_co_u32_e32 v29, vcc, 0, v145, vcc
	v_cvt_pk_bf16_f32 v25, v30, v31
	v_cvt_pk_bf16_f32 v26, v26, v27
	v_cvt_pk_bf16_f32 v27, v36, v37
	global_store_dwordx4 v[28:29], v[24:27], off
	v_pk_mul_f32 v[22:23], v[22:23], v[34:35] op_sel_hi:[1,0]
	v_pk_mul_f32 v[20:21], v[20:21], v[34:35] op_sel_hi:[1,0]
	v_pk_mul_f32 v[24:25], v[18:19], v[34:35] op_sel_hi:[1,0]
	v_pk_mul_f32 v[18:19], v[16:17], v[34:35] op_sel_hi:[1,0]
	v_cvt_pk_bf16_f32 v16, v20, v21
	v_cvt_pk_bf16_f32 v17, v22, v23
	v_cmp_gt_f32_e32 vcc, s49, v170
	v_cvt_pk_bf16_f32 v18, v18, v19
	v_mul_f32_e32 v19, 0x4b800000, v170
	v_lshl_add_u64 v[32:33], v[144:145], 0, s[12:13]
	v_cndmask_b32_e32 v19, v170, v19, vcc
	v_rsq_f32_e32 v20, v19
	v_cvt_pk_bf16_f32 v19, v24, v25
	global_store_dwordx4 v[32:33], v[16:19], off offset:256
	s_nop 1
	v_mul_f32_e32 v18, 0x45800000, v20
	v_cndmask_b32_e32 v18, v20, v18, vcc
	v_mul_f32_e32 v18, 0x3e0293ee, v18
	v_pk_mul_f32 v[12:13], v[12:13], v[18:19] op_sel_hi:[1,0]
	v_pk_mul_f32 v[20:21], v[10:11], v[18:19] op_sel_hi:[1,0]
	v_pk_mul_f32 v[10:11], v[8:9], v[18:19] op_sel_hi:[1,0]
	v_cvt_pk_bf16_f32 v8, v12, v13
	v_add_co_u32_e32 v12, vcc, s51, v144
	v_pk_mul_f32 v[14:15], v[14:15], v[18:19] op_sel_hi:[1,0]
	s_nop 0
	v_addc_co_u32_e32 v13, vcc, 0, v145, vcc
	v_cvt_pk_bf16_f32 v9, v14, v15
	v_lshl_add_u64 v[16:17], v[144:145], 0, s[16:17]
	v_cvt_pk_bf16_f32 v10, v10, v11
	v_cvt_pk_bf16_f32 v11, v20, v21
	global_store_dwordx4 v[12:13], v[8:11], off
	s_and_b64 vcc, exec, s[6:7]
	v_pk_mul_f32 v[6:7], v[6:7], v[18:19] op_sel_hi:[1,0]
	v_pk_mul_f32 v[8:9], v[2:3], v[18:19] op_sel_hi:[1,0]
	v_pk_mul_f32 v[2:3], v[0:1], v[18:19] op_sel_hi:[1,0]
	v_pk_mul_f32 v[4:5], v[4:5], v[18:19] op_sel_hi:[1,0]
	s_nop 0
	v_cvt_pk_bf16_f32 v0, v4, v5
	v_cvt_pk_bf16_f32 v1, v6, v7
	v_cvt_pk_bf16_f32 v2, v2, v3
	v_cvt_pk_bf16_f32 v3, v8, v9
	global_store_dwordx4 v[16:17], v[0:3], off offset:256
	s_cbranch_vccz .LBB0_705
	s_waitcnt vmcnt(0)
	s_cmpk_gt_u32 s30, 0xff
	s_cbranch_scc1 .LBB0_716
	s_barrier

.LBB0_792:
	ds_read_b128 v[144:147], v178
	ds_read_b128 v[148:151], v178 offset:1024
	ds_read_b128 v[152:155], v178 offset:2048
	ds_read_b128 v[156:159], v178 offset:3072
	s_add_u32 s40, s38, 0xfffe0080
	s_addc_u32 s41, s39, -1
	s_cmp_eq_u32 s63, 4
	s_cselect_b32 s43, s27, s41
	s_cselect_b32 s42, s35, s40
	s_cselect_b32 s41, s25, s62
	s_cselect_b32 s40, s60, s61
	v_lshl_add_u64 v[172:173], s[38:39], 0, v[136:137]
	s_add_i32 m0, s37, 0xc000
	ds_read_b128 v[160:163], v179
	ds_read_b128 v[164:167], v179 offset:1024
	ds_read_b128 v[168:171], v179 offset:2048
	ds_read_b128 v[182:185], v179 offset:3072
	ds_read_b128 v[186:189], v179 offset:4096
	ds_read_b128 v[190:193], v179 offset:5120
	ds_read_b128 v[194:197], v179 offset:6144
	ds_read_b128 v[198:201], v179 offset:7168
	global_load_lds_dwordx4 v[172:173], off
	v_lshl_add_u64 v[172:173], s[38:39], 0, v[138:139]
	s_add_i32 m0, s37, 0xe000
	s_nop 0
	global_load_lds_dwordx4 v[172:173], off
	s_waitcnt lgkmcnt(8)
	s_barrier
	s_waitcnt lgkmcnt(0)
	s_setprio 1
	v_mfma_f32_16x16x32_bf16 v[124:127], v[144:147], v[160:163], v[124:127]
	v_mfma_f32_16x16x32_bf16 v[120:123], v[152:155], v[160:163], v[120:123]
	v_mfma_f32_16x16x32_bf16 v[108:111], v[144:147], v[168:171], v[108:111]
	v_mfma_f32_16x16x32_bf16 v[104:107], v[152:155], v[168:171], v[104:107]
	v_mfma_f32_16x16x32_bf16 v[96:99], v[144:147], v[186:189], v[96:99]
	v_mfma_f32_16x16x32_bf16 v[88:91], v[152:155], v[186:189], v[88:91]
	v_mfma_f32_16x16x32_bf16 v[80:83], v[144:147], v[194:197], v[80:83]
	v_mfma_f32_16x16x32_bf16 v[72:75], v[152:155], v[194:197], v[72:75]
	v_mfma_f32_16x16x32_bf16 v[124:127], v[148:151], v[164:167], v[124:127]
	v_mfma_f32_16x16x32_bf16 v[120:123], v[156:159], v[164:167], v[120:123]
	v_mfma_f32_16x16x32_bf16 v[108:111], v[148:151], v[182:185], v[108:111]
	v_mfma_f32_16x16x32_bf16 v[104:107], v[156:159], v[182:185], v[104:107]
	v_mfma_f32_16x16x32_bf16 v[96:99], v[148:151], v[190:193], v[96:99]
	v_mfma_f32_16x16x32_bf16 v[88:91], v[156:159], v[190:193], v[88:91]
	v_mfma_f32_16x16x32_bf16 v[80:83], v[148:151], v[198:201], v[80:83]
	v_mfma_f32_16x16x32_bf16 v[72:75], v[156:159], v[198:201], v[72:75]
	s_setprio 0
	s_barrier
	s_add_i32 s64, s58, s48
	v_lshl_add_u64 v[172:173], s[40:41], 0, v[130:131]
	s_mov_b32 m0, s64
	ds_read_b128 v[202:205], v180
	ds_read_b128 v[206:209], v180 offset:1024
	ds_read_b128 v[212:215], v180 offset:2048
	ds_read_b128 v[216:219], v180 offset:3072
	global_load_lds_dwordx4 v[172:173], off
	v_lshl_add_u64 v[220:221], s[40:41], 0, v[134:135]
	s_add_i32 m0, s64, 0x2000
	s_nop 0
	global_load_lds_dwordx4 v[220:221], off
	s_barrier
	s_waitcnt lgkmcnt(0)
	s_setprio 1
	v_mfma_f32_16x16x32_bf16 v[116:119], v[202:205], v[160:163], v[116:119]
	v_mfma_f32_16x16x32_bf16 v[112:115], v[212:215], v[160:163], v[112:115]
	v_mfma_f32_16x16x32_bf16 v[100:103], v[202:205], v[168:171], v[100:103]
	v_mfma_f32_16x16x32_bf16 v[92:95], v[212:215], v[168:171], v[92:95]
	v_mfma_f32_16x16x32_bf16 v[84:87], v[202:205], v[186:189], v[84:87]
	v_mfma_f32_16x16x32_bf16 v[76:79], v[212:215], v[186:189], v[76:79]
	v_mfma_f32_16x16x32_bf16 v[68:71], v[202:205], v[194:197], v[68:71]
	v_mfma_f32_16x16x32_bf16 v[64:67], v[212:215], v[194:197], v[64:67]
	v_mfma_f32_16x16x32_bf16 v[116:119], v[206:209], v[164:167], v[116:119]
	v_mfma_f32_16x16x32_bf16 v[112:115], v[216:219], v[164:167], v[112:115]
	v_mfma_f32_16x16x32_bf16 v[100:103], v[206:209], v[182:185], v[100:103]
	v_mfma_f32_16x16x32_bf16 v[92:95], v[216:219], v[182:185], v[92:95]
	v_mfma_f32_16x16x32_bf16 v[84:87], v[206:209], v[190:193], v[84:87]
	v_mfma_f32_16x16x32_bf16 v[76:79], v[216:219], v[190:193], v[76:79]
	v_mfma_f32_16x16x32_bf16 v[68:71], v[206:209], v[198:201], v[68:71]
	v_mfma_f32_16x16x32_bf16 v[64:67], v[216:219], v[198:201], v[64:67]
	s_setprio 0
	s_mov_b32 m0, s37
	v_lshl_add_u64 v[222:223], s[42:43], 0, v[128:129]
	s_barrier
	ds_read_b128 v[160:163], v179 offset:16384
	ds_read_b128 v[164:167], v179 offset:17408
	ds_read_b128 v[168:171], v179 offset:18432
	ds_read_b128 v[182:185], v179 offset:19456
	ds_read_b128 v[186:189], v179 offset:20480
	ds_read_b128 v[190:193], v179 offset:21504
	ds_read_b128 v[194:197], v179 offset:22528
	ds_read_b128 v[198:201], v179 offset:23552
	global_load_lds_dwordx4 v[222:223], off
	v_lshl_add_u64 v[224:225], s[42:43], 0, v[132:133]
	s_mov_b32 m0, s49
	s_nop 0
	global_load_lds_dwordx4 v[224:225], off
	s_barrier
	s_waitcnt lgkmcnt(0)
	s_setprio 1
	v_mfma_f32_16x16x32_bf16 v[60:63], v[144:147], v[160:163], v[60:63]
	v_mfma_f32_16x16x32_bf16 v[56:59], v[152:155], v[160:163], v[56:59]
	v_mfma_f32_16x16x32_bf16 v[44:47], v[144:147], v[168:171], v[44:47]
	v_mfma_f32_16x16x32_bf16 v[40:43], v[152:155], v[168:171], v[40:43]
	v_mfma_f32_16x16x32_bf16 v[32:35], v[144:147], v[186:189], v[32:35]
	v_mfma_f32_16x16x32_bf16 v[24:27], v[152:155], v[186:189], v[24:27]
	v_mfma_f32_16x16x32_bf16 v[16:19], v[144:147], v[194:197], v[16:19]
	v_mfma_f32_16x16x32_bf16 v[8:11], v[152:155], v[194:197], v[8:11]
	v_mfma_f32_16x16x32_bf16 v[60:63], v[148:151], v[164:167], v[60:63]
	v_mfma_f32_16x16x32_bf16 v[56:59], v[156:159], v[164:167], v[56:59]
	v_mfma_f32_16x16x32_bf16 v[44:47], v[148:151], v[182:185], v[44:47]
	v_mfma_f32_16x16x32_bf16 v[40:43], v[156:159], v[182:185], v[40:43]
	v_mfma_f32_16x16x32_bf16 v[32:35], v[148:151], v[190:193], v[32:35]
	v_mfma_f32_16x16x32_bf16 v[24:27], v[156:159], v[190:193], v[24:27]
	v_mfma_f32_16x16x32_bf16 v[16:19], v[148:151], v[198:201], v[16:19]
	v_mfma_f32_16x16x32_bf16 v[8:11], v[156:159], v[198:201], v[8:11]
	s_setprio 0
	s_barrier
	s_add_u32 s64, s40, 0x20000
	s_addc_u32 s65, s41, 0
	s_add_i32 s66, s59, s48
	v_lshl_add_u64 v[144:145], s[64:65], 0, v[130:131]
	s_mov_b32 m0, s66
	s_nop 0
	global_load_lds_dwordx4 v[144:145], off
	v_lshl_add_u64 v[144:145], s[64:65], 0, v[134:135]
	s_add_i32 m0, s66, 0x2000
	s_nop 0
	global_load_lds_dwordx4 v[144:145], off
	s_waitcnt vmcnt(6)
	s_barrier
	s_setprio 1
	v_mfma_f32_16x16x32_bf16 v[52:55], v[202:205], v[160:163], v[52:55]
	v_mfma_f32_16x16x32_bf16 v[48:51], v[212:215], v[160:163], v[48:51]
	v_mfma_f32_16x16x32_bf16 v[36:39], v[202:205], v[168:171], v[36:39]
	v_mfma_f32_16x16x32_bf16 v[28:31], v[212:215], v[168:171], v[28:31]
	v_mfma_f32_16x16x32_bf16 v[20:23], v[202:205], v[186:189], v[20:23]
	v_mfma_f32_16x16x32_bf16 v[12:15], v[212:215], v[186:189], v[12:15]
	v_mfma_f32_16x16x32_bf16 v[4:7], v[202:205], v[194:197], v[4:7]
	v_mfma_f32_16x16x32_bf16 v[0:3], v[212:215], v[194:197], v[0:3]
	v_mfma_f32_16x16x32_bf16 v[52:55], v[206:209], v[164:167], v[52:55]
	v_mfma_f32_16x16x32_bf16 v[48:51], v[216:219], v[164:167], v[48:51]
	v_mfma_f32_16x16x32_bf16 v[36:39], v[206:209], v[182:185], v[36:39]
	v_mfma_f32_16x16x32_bf16 v[28:31], v[216:219], v[182:185], v[28:31]
	v_mfma_f32_16x16x32_bf16 v[20:23], v[206:209], v[190:193], v[20:23]
	v_mfma_f32_16x16x32_bf16 v[12:15], v[216:219], v[190:193], v[12:15]
	v_mfma_f32_16x16x32_bf16 v[4:7], v[206:209], v[198:201], v[4:7]
	v_mfma_f32_16x16x32_bf16 v[0:3], v[216:219], v[198:201], v[0:3]
	s_setprio 0
	s_add_i32 s64, 0, 0x18000
	v_add_u32_e32 v156, s64, v176
	s_barrier
	ds_read_b128 v[144:147], v156
	ds_read_b128 v[148:151], v156 offset:1024
	ds_read_b128 v[152:155], v156 offset:2048
	ds_read_b128 v[156:159], v156 offset:3072
	s_add_u32 s42, s42, 0x20000
	s_addc_u32 s43, s43, 0
	s_mov_b32 m0, s50
	v_lshl_add_u64 v[202:203], s[42:43], 0, v[128:129]
	ds_read_b128 v[160:163], v179 offset:32768
	ds_read_b128 v[164:167], v179 offset:33792
	ds_read_b128 v[168:171], v179 offset:34816
	ds_read_b128 v[182:185], v179 offset:35840
	ds_read_b128 v[186:189], v179 offset:36864
	ds_read_b128 v[190:193], v179 offset:37888
	ds_read_b128 v[194:197], v179 offset:38912
	ds_read_b128 v[198:201], v179 offset:39936
	global_load_lds_dwordx4 v[202:203], off
	v_lshl_add_u64 v[202:203], s[42:43], 0, v[132:133]
	s_mov_b32 m0, s51
	s_nop 0
	global_load_lds_dwordx4 v[202:203], off
	s_waitcnt lgkmcnt(8)
	s_barrier
	s_waitcnt lgkmcnt(0)
	s_setprio 1
	v_mfma_f32_16x16x32_bf16 v[124:127], v[144:147], v[160:163], v[124:127]
	v_mfma_f32_16x16x32_bf16 v[120:123], v[152:155], v[160:163], v[120:123]
	v_mfma_f32_16x16x32_bf16 v[108:111], v[144:147], v[168:171], v[108:111]
	v_mfma_f32_16x16x32_bf16 v[104:107], v[152:155], v[168:171], v[104:107]
	v_mfma_f32_16x16x32_bf16 v[96:99], v[144:147], v[186:189], v[96:99]
	v_mfma_f32_16x16x32_bf16 v[88:91], v[152:155], v[186:189], v[88:91]
	v_mfma_f32_16x16x32_bf16 v[80:83], v[144:147], v[194:197], v[80:83]
	v_mfma_f32_16x16x32_bf16 v[72:75], v[152:155], v[194:197], v[72:75]
	v_mfma_f32_16x16x32_bf16 v[124:127], v[148:151], v[164:167], v[124:127]
	v_mfma_f32_16x16x32_bf16 v[120:123], v[156:159], v[164:167], v[120:123]
	v_mfma_f32_16x16x32_bf16 v[108:111], v[148:151], v[182:185], v[108:111]
	v_mfma_f32_16x16x32_bf16 v[104:107], v[156:159], v[182:185], v[104:107]
	v_mfma_f32_16x16x32_bf16 v[96:99], v[148:151], v[190:193], v[96:99]
	v_mfma_f32_16x16x32_bf16 v[88:91], v[156:159], v[190:193], v[88:91]
	v_mfma_f32_16x16x32_bf16 v[80:83], v[148:151], v[198:201], v[80:83]
	v_mfma_f32_16x16x32_bf16 v[72:75], v[156:159], v[198:201], v[72:75]
	s_setprio 0
	s_barrier
	s_add_i32 s42, 0, 0x1c000
	s_add_i32 s43, s64, s48
	v_add_u32_e32 v181, s42, v176
	v_lshl_add_u64 v[172:173], v[172:173], 0, s[0:1]
	s_mov_b32 m0, s43
	ds_read_b128 v[202:205], v181
	ds_read_b128 v[206:209], v181 offset:1024
	ds_read_b128 v[212:215], v181 offset:2048
	ds_read_b128 v[216:219], v181 offset:3072
	global_load_lds_dwordx4 v[172:173], off
	v_lshl_add_u64 v[172:173], v[220:221], 0, s[0:1]
	s_add_i32 m0, s43, 0x2000
	s_nop 0
	global_load_lds_dwordx4 v[172:173], off
	s_barrier
	s_waitcnt lgkmcnt(0)
	s_setprio 1
	v_mfma_f32_16x16x32_bf16 v[116:119], v[202:205], v[160:163], v[116:119]
	v_mfma_f32_16x16x32_bf16 v[112:115], v[212:215], v[160:163], v[112:115]
	v_mfma_f32_16x16x32_bf16 v[100:103], v[202:205], v[168:171], v[100:103]
	v_mfma_f32_16x16x32_bf16 v[92:95], v[212:215], v[168:171], v[92:95]
	v_mfma_f32_16x16x32_bf16 v[84:87], v[202:205], v[186:189], v[84:87]
	v_mfma_f32_16x16x32_bf16 v[76:79], v[212:215], v[186:189], v[76:79]
	v_mfma_f32_16x16x32_bf16 v[68:71], v[202:205], v[194:197], v[68:71]
	v_mfma_f32_16x16x32_bf16 v[64:67], v[212:215], v[194:197], v[64:67]
	v_mfma_f32_16x16x32_bf16 v[116:119], v[206:209], v[164:167], v[116:119]
	v_mfma_f32_16x16x32_bf16 v[112:115], v[216:219], v[164:167], v[112:115]
	v_mfma_f32_16x16x32_bf16 v[100:103], v[206:209], v[182:185], v[100:103]
	v_mfma_f32_16x16x32_bf16 v[92:95], v[216:219], v[182:185], v[92:95]
	v_mfma_f32_16x16x32_bf16 v[84:87], v[206:209], v[190:193], v[84:87]
	v_mfma_f32_16x16x32_bf16 v[76:79], v[216:219], v[190:193], v[76:79]
	v_mfma_f32_16x16x32_bf16 v[68:71], v[206:209], v[198:201], v[68:71]
	v_mfma_f32_16x16x32_bf16 v[64:67], v[216:219], v[198:201], v[64:67]
	s_setprio 0
	s_mov_b32 m0, s53
	v_lshl_add_u64 v[172:173], v[222:223], 0, s[0:1]
	s_barrier
	ds_read_b128 v[160:163], v179 offset:49152
	ds_read_b128 v[164:167], v179 offset:50176
	ds_read_b128 v[168:171], v179 offset:51200
	ds_read_b128 v[182:185], v179 offset:52224
	ds_read_b128 v[186:189], v179 offset:53248
	ds_read_b128 v[190:193], v179 offset:54272
	ds_read_b128 v[194:197], v179 offset:55296
	ds_read_b128 v[198:201], v179 offset:56320
	global_load_lds_dwordx4 v[172:173], off
	v_lshl_add_u64 v[172:173], v[224:225], 0, s[0:1]
	s_mov_b32 m0, s54
	s_nop 0
	global_load_lds_dwordx4 v[172:173], off
	s_barrier
	s_waitcnt lgkmcnt(0)
	s_setprio 1
	v_mfma_f32_16x16x32_bf16 v[60:63], v[144:147], v[160:163], v[60:63]
	v_mfma_f32_16x16x32_bf16 v[56:59], v[152:155], v[160:163], v[56:59]
	v_mfma_f32_16x16x32_bf16 v[44:47], v[144:147], v[168:171], v[44:47]
	v_mfma_f32_16x16x32_bf16 v[40:43], v[152:155], v[168:171], v[40:43]
	v_mfma_f32_16x16x32_bf16 v[32:35], v[144:147], v[186:189], v[32:35]
	v_mfma_f32_16x16x32_bf16 v[24:27], v[152:155], v[186:189], v[24:27]
	v_mfma_f32_16x16x32_bf16 v[16:19], v[144:147], v[194:197], v[16:19]
	v_mfma_f32_16x16x32_bf16 v[8:11], v[152:155], v[194:197], v[8:11]
	v_mfma_f32_16x16x32_bf16 v[60:63], v[148:151], v[164:167], v[60:63]
	v_mfma_f32_16x16x32_bf16 v[56:59], v[156:159], v[164:167], v[56:59]
	v_mfma_f32_16x16x32_bf16 v[44:47], v[148:151], v[182:185], v[44:47]
	v_mfma_f32_16x16x32_bf16 v[40:43], v[156:159], v[182:185], v[40:43]
	v_mfma_f32_16x16x32_bf16 v[32:35], v[148:151], v[190:193], v[32:35]
	v_mfma_f32_16x16x32_bf16 v[24:27], v[156:159], v[190:193], v[24:27]
	v_mfma_f32_16x16x32_bf16 v[16:19], v[148:151], v[198:201], v[16:19]
	v_mfma_f32_16x16x32_bf16 v[8:11], v[156:159], v[198:201], v[8:11]
	s_setprio 0
	s_barrier
	s_add_u32 s40, s40, 0x20080
	s_addc_u32 s41, s41, 0
	s_add_i32 s42, s42, s48
	v_lshl_add_u64 v[144:145], s[40:41], 0, v[130:131]
	s_mov_b32 m0, s42
	s_nop 0
	global_load_lds_dwordx4 v[144:145], off
	v_lshl_add_u64 v[144:145], s[40:41], 0, v[134:135]
	s_add_i32 m0, s42, 0x2000
	s_nop 0
	global_load_lds_dwordx4 v[144:145], off
	s_waitcnt vmcnt(6)
	s_barrier
	s_setprio 1
	v_mfma_f32_16x16x32_bf16 v[52:55], v[202:205], v[160:163], v[52:55]
	v_mfma_f32_16x16x32_bf16 v[48:51], v[212:215], v[160:163], v[48:51]
	v_mfma_f32_16x16x32_bf16 v[36:39], v[202:205], v[168:171], v[36:39]
	v_mfma_f32_16x16x32_bf16 v[28:31], v[212:215], v[168:171], v[28:31]
	v_mfma_f32_16x16x32_bf16 v[20:23], v[202:205], v[186:189], v[20:23]
	v_mfma_f32_16x16x32_bf16 v[12:15], v[212:215], v[186:189], v[12:15]
	v_mfma_f32_16x16x32_bf16 v[4:7], v[202:205], v[194:197], v[4:7]
	v_mfma_f32_16x16x32_bf16 v[0:3], v[212:215], v[194:197], v[0:3]
	v_mfma_f32_16x16x32_bf16 v[52:55], v[206:209], v[164:167], v[52:55]
	v_mfma_f32_16x16x32_bf16 v[48:51], v[216:219], v[164:167], v[48:51]
	v_mfma_f32_16x16x32_bf16 v[36:39], v[206:209], v[182:185], v[36:39]
	v_mfma_f32_16x16x32_bf16 v[28:31], v[216:219], v[182:185], v[28:31]
	v_mfma_f32_16x16x32_bf16 v[20:23], v[206:209], v[190:193], v[20:23]
	v_mfma_f32_16x16x32_bf16 v[12:15], v[216:219], v[190:193], v[12:15]
	v_mfma_f32_16x16x32_bf16 v[4:7], v[206:209], v[198:201], v[4:7]
	v_mfma_f32_16x16x32_bf16 v[0:3], v[216:219], v[198:201], v[0:3]
	s_setprio 0
	s_add_i32 s63, s63, 2
	s_add_u32 s38, s38, 0x100
	s_addc_u32 s39, s39, 0
	s_add_u32 s61, s61, 0x100
	s_addc_u32 s62, s62, 0
	s_cmp_gt_u32 s63, 5
	s_barrier
	s_cbranch_scc0 .LBB0_792
	v_lshl_or_b32 v144, s36, 8, v177
	v_lshl_add_u32 v150, s34, 8, v175
	v_ashrrev_i32_e32 v145, 31, v144
	v_ashrrev_i32_e32 v151, 31, v150
	v_lshlrev_b64 v[144:145], 1, v[144:145]
	v_lshl_add_u64 v[146:147], s[10:11], 0, v[144:145]
	v_lshlrev_b64 v[148:149], 11, v[150:151]
	v_lshl_add_u64 v[152:153], v[146:147], 0, v[148:149]
	global_load_dwordx4 v[156:159], v[152:153], off
	global_load_dwordx4 v[160:163], v[152:153], off offset:256
	v_or_b32_e32 v152, 16, v150
	v_ashrrev_i32_e32 v153, 31, v152
	v_lshlrev_b64 v[170:171], 11, v[152:153]
	v_lshl_add_u64 v[152:153], v[146:147], 0, v[170:171]
	global_load_dwordx4 v[164:167], v[152:153], off
	global_load_dwordx4 v[182:185], v[152:153], off offset:256
	v_or_b32_e32 v152, 32, v150
	v_ashrrev_i32_e32 v153, 31, v152
	v_lshlrev_b64 v[154:155], 11, v[152:153]
	v_lshl_add_u64 v[152:153], v[146:147], 0, v[154:155]
	global_load_dwordx4 v[186:189], v[152:153], off
	global_load_dwordx4 v[190:193], v[152:153], off offset:256
	v_or_b32_e32 v152, 48, v150
	v_ashrrev_i32_e32 v153, 31, v152
	v_lshlrev_b64 v[152:153], 11, v[152:153]
	v_lshl_add_u64 v[168:169], v[146:147], 0, v[152:153]
	global_load_dwordx4 v[194:197], v[168:169], off
	global_load_dwordx4 v[198:201], v[168:169], off offset:256
	s_waitcnt vmcnt(0)
	v_lshlrev_b32_e32 v202, 16, v156
	v_and_b32_e32 v203, 0xffff0000, v156
	v_lshlrev_b32_e32 v204, 16, v157
	v_and_b32_e32 v205, 0xffff0000, v157
	v_lshlrev_b32_e32 v206, 16, v158
	v_and_b32_e32 v207, 0xffff0000, v158
	v_lshlrev_b32_e32 v208, 16, v159
	v_and_b32_e32 v209, 0xffff0000, v159
	v_pk_add_f32 v[126:127], v[126:127], v[204:205]
	v_pk_add_f32 v[124:125], v[124:125], v[202:203]
	v_lshlrev_b32_e32 v224, 16, v166
	v_and_b32_e32 v225, 0xffff0000, v166
	v_lshlrev_b32_e32 v226, 16, v167
	v_and_b32_e32 v227, 0xffff0000, v167
	v_lshlrev_b32_e32 v212, 16, v160
	v_lshlrev_b32_e32 v166, 16, v194
	v_and_b32_e32 v167, 0xffff0000, v194
	v_lshlrev_b32_e32 v172, 16, v195
	v_and_b32_e32 v173, 0xffff0000, v195
	v_pk_add_f32 v[194:195], v[122:123], v[208:209]
	v_pk_add_f32 v[122:123], v[120:121], v[206:207]
	v_mul_f32_e32 v120, v125, v125
	v_mul_f32_e32 v121, v127, v127
	v_fmac_f32_e32 v120, v124, v124
	v_fmac_f32_e32 v121, v126, v126
	v_add_f32_e32 v120, v120, v121
	v_mul_f32_e32 v121, v123, v123
	v_fmac_f32_e32 v121, v122, v122
	v_add_f32_e32 v120, v121, v120
	v_mul_f32_e32 v121, v195, v195
	v_fmac_f32_e32 v121, v194, v194
	v_and_b32_e32 v213, 0xffff0000, v160
	v_lshlrev_b32_e32 v214, 16, v161
	v_and_b32_e32 v215, 0xffff0000, v161
	v_add_f32_e32 v181, v121, v120
	v_cvt_pk_bf16_f32 v120, v124, v125
	v_lshl_add_u64 v[124:125], s[90:91], 0, v[148:149]
	v_lshlrev_b32_e32 v216, 16, v162
	v_and_b32_e32 v217, 0xffff0000, v162
	v_lshlrev_b32_e32 v218, 16, v163
	v_and_b32_e32 v219, 0xffff0000, v163
	v_cvt_pk_bf16_f32 v121, v126, v127
	v_lshl_add_u64 v[124:125], v[124:125], 0, v[144:145]
	v_pk_add_f32 v[118:119], v[118:119], v[214:215]
	v_pk_add_f32 v[116:117], v[116:117], v[212:213]
	v_cvt_pk_bf16_f32 v122, v122, v123
	v_cvt_pk_bf16_f32 v123, v194, v195
	global_store_dwordx4 v[124:125], v[120:123], off
	v_lshlrev_b32_e32 v220, 16, v164
	v_and_b32_e32 v221, 0xffff0000, v164
	v_pk_add_f32 v[120:121], v[114:115], v[218:219]
	v_pk_add_f32 v[114:115], v[112:113], v[216:217]
	v_mul_f32_e32 v112, v117, v117
	v_mul_f32_e32 v113, v119, v119
	v_fmac_f32_e32 v112, v116, v116
	v_fmac_f32_e32 v113, v118, v118
	v_add_f32_e32 v112, v112, v113
	v_mul_f32_e32 v113, v115, v115
	v_fmac_f32_e32 v113, v114, v114
	v_add_f32_e32 v112, v113, v112
	v_mul_f32_e32 v113, v121, v121
	v_fmac_f32_e32 v113, v120, v120
	v_add_f32_e32 v112, v113, v112
	v_lshlrev_b32_e32 v222, 16, v165
	v_and_b32_e32 v223, 0xffff0000, v165
	v_add_f32_e32 v126, v181, v112
	v_cvt_pk_bf16_f32 v112, v116, v117
	v_cvt_pk_bf16_f32 v113, v118, v119
	v_lshl_add_u64 v[116:117], s[90:91], 0, v[170:171]
	v_lshlrev_b32_e32 v230, 16, v184
	v_and_b32_e32 v231, 0xffff0000, v184
	v_lshlrev_b32_e32 v232, 16, v186
	v_and_b32_e32 v233, 0xffff0000, v186
	v_lshlrev_b32_e32 v186, 16, v187
	v_and_b32_e32 v187, 0xffff0000, v187
	v_cvt_pk_bf16_f32 v114, v114, v115
	v_cvt_pk_bf16_f32 v115, v120, v121
	global_store_dwordx4 v[124:125], v[112:115], off offset:256
	v_pk_add_f32 v[110:111], v[110:111], v[222:223]
	v_pk_add_f32 v[108:109], v[108:109], v[220:221]
	v_lshl_add_u64 v[118:119], v[116:117], 0, v[144:145]
	v_cvt_pk_bf16_f32 v112, v108, v109
	v_cvt_pk_bf16_f32 v113, v110, v111
	v_lshlrev_b32_e32 v228, 16, v182
	v_and_b32_e32 v229, 0xffff0000, v182
	v_lshlrev_b32_e32 v182, 16, v183
	v_and_b32_e32 v183, 0xffff0000, v183
	v_lshlrev_b32_e32 v184, 16, v185
	v_and_b32_e32 v185, 0xffff0000, v185
	v_lshlrev_b32_e32 v238, 16, v192
	v_and_b32_e32 v239, 0xffff0000, v192
	v_pk_add_f32 v[106:107], v[106:107], v[226:227]
	v_pk_add_f32 v[104:105], v[104:105], v[224:225]
	v_lshlrev_b32_e32 v156, 16, v200
	v_cvt_pk_bf16_f32 v114, v104, v105
	v_cvt_pk_bf16_f32 v115, v106, v107
	global_store_dwordx4 v[118:119], v[112:115], off
	v_and_b32_e32 v157, 0xffff0000, v200
	v_pk_add_f32 v[102:103], v[102:103], v[182:183]
	v_pk_add_f32 v[112:113], v[92:93], v[230:231]
	v_pk_add_f32 v[92:93], v[98:99], v[186:187]
	v_lshl_add_u64 v[98:99], s[90:91], 0, v[154:155]
	v_pk_add_f32 v[100:101], v[100:101], v[228:229]
	v_pk_add_f32 v[94:95], v[94:95], v[184:185]
	v_cvt_pk_bf16_f32 v114, v100, v101
	v_cvt_pk_bf16_f32 v115, v102, v103
	v_cvt_pk_bf16_f32 v116, v112, v113
	v_lshlrev_b32_e32 v234, 16, v188
	v_cvt_pk_bf16_f32 v117, v94, v95
	global_store_dwordx4 v[118:119], v[114:117], off offset:256
	v_lshl_add_u64 v[118:119], v[98:99], 0, v[144:145]
	v_pk_add_f32 v[98:99], v[76:77], v[238:239]
	v_pk_add_f32 v[76:77], v[82:83], v[172:173]
	v_lshl_add_u64 v[82:83], s[90:91], 0, v[152:153]
	v_lshl_add_u64 v[122:123], v[82:83], 0, v[144:145]
	v_pk_add_f32 v[82:83], v[64:65], v[156:157]
	v_and_b32_e32 v65, 64, v174
	v_and_b32_e32 v235, 0xffff0000, v188
	v_lshlrev_b32_e32 v188, 16, v189
	v_and_b32_e32 v189, 0xffff0000, v189
	v_lshlrev_b32_e32 v236, 16, v190
	v_and_b32_e32 v237, 0xffff0000, v190
	v_pk_add_f32 v[96:97], v[96:97], v[232:233]
	v_xor_b32_e32 v64, 16, v174
	v_cvt_pk_bf16_f32 v114, v96, v97
	v_add_u32_e32 v65, 64, v65
	v_lshlrev_b32_e32 v190, 16, v191
	v_and_b32_e32 v191, 0xffff0000, v191
	v_lshlrev_b32_e32 v192, 16, v193
	v_and_b32_e32 v193, 0xffff0000, v193
	v_pk_add_f32 v[90:91], v[90:91], v[188:189]
	v_pk_add_f32 v[88:89], v[88:89], v[234:235]
	v_cvt_pk_bf16_f32 v115, v92, v93
	v_pk_add_f32 v[84:85], v[84:85], v[236:237]
	v_cvt_pk_bf16_f32 v116, v88, v89
	v_cvt_pk_bf16_f32 v117, v90, v91
	global_store_dwordx4 v[118:119], v[114:117], off
	v_cmp_lt_i32_e32 vcc, v64, v65
	v_lshlrev_b32_e32 v164, 16, v196
	v_cvt_pk_bf16_f32 v114, v84, v85
	v_and_b32_e32 v165, 0xffff0000, v196
	v_lshlrev_b32_e32 v168, 16, v197
	v_and_b32_e32 v169, 0xffff0000, v197
	v_pk_add_f32 v[86:87], v[86:87], v[190:191]
	v_pk_add_f32 v[78:79], v[78:79], v[192:193]
	v_cvt_pk_bf16_f32 v115, v86, v87
	v_cvt_pk_bf16_f32 v116, v98, v99
	v_pk_add_f32 v[80:81], v[80:81], v[166:167]
	v_cvt_pk_bf16_f32 v117, v78, v79
	global_store_dwordx4 v[118:119], v[114:117], off offset:256
	v_cndmask_b32_e32 v64, v174, v64, vcc
	v_pk_add_f32 v[74:75], v[74:75], v[168:169]
	v_cvt_pk_bf16_f32 v114, v80, v81
	v_pk_add_f32 v[72:73], v[72:73], v[164:165]
	v_cvt_pk_bf16_f32 v115, v76, v77
	v_lshlrev_b32_e32 v158, 16, v198
	v_cvt_pk_bf16_f32 v116, v72, v73
	v_cvt_pk_bf16_f32 v117, v74, v75
	global_store_dwordx4 v[122:123], v[114:117], off
	v_and_b32_e32 v159, 0xffff0000, v198
	v_lshlrev_b32_e32 v162, 16, v199
	v_lshlrev_b32_e32 v114, 2, v64
	ds_bpermute_b32 v64, v114, v126
	v_xor_b32_e32 v115, 32, v174
	v_cmp_lt_i32_e32 vcc, v115, v65
	v_and_b32_e32 v163, 0xffff0000, v199
	v_lshlrev_b32_e32 v160, 16, v201
	v_cndmask_b32_e32 v65, v174, v115, vcc
	v_lshlrev_b32_e32 v115, 2, v65
	s_waitcnt lgkmcnt(0)
	v_add_f32_e32 v116, v126, v64
	ds_bpermute_b32 v117, v115, v116
	v_and_b32_e32 v161, 0xffff0000, v201
	v_pk_add_f32 v[70:71], v[70:71], v[162:163]
	v_pk_add_f32 v[68:69], v[68:69], v[158:159]
	v_pk_add_f32 v[66:67], v[66:67], v[160:161]
	v_lshl_add_u64 v[64:65], v[150:151], 2, s[2:3]
	v_cvt_pk_bf16_f32 v118, v68, v69
	v_cvt_pk_bf16_f32 v119, v70, v71
	v_cvt_pk_bf16_f32 v120, v82, v83
	v_cvt_pk_bf16_f32 v121, v66, v67
	global_store_dwordx4 v[122:123], v[118:121], off offset:256
	s_and_saveexec_b64 s[34:35], s[6:7]
	s_cbranch_execz .LBB0_795
	s_waitcnt lgkmcnt(0)
	v_add_f32_e32 v116, v116, v117
	global_atomic_add_f32 v[64:65], v116, off

.LBB0_850:
	ds_read_b128 v[144:147], v151
	ds_read_b128 v[156:159], v151 offset:1024
	ds_read_b128 v[160:163], v151 offset:2048
	ds_read_b128 v[164:167], v151 offset:3072
	s_add_u32 s36, s34, 0xfffc0080
	s_addc_u32 s37, s35, -1
	s_cmp_eq_u32 s66, 12
	s_cselect_b32 s39, s27, s37
	s_cselect_b32 s38, s62, s36
	s_cselect_b32 s37, s25, s65
	s_cselect_b32 s36, s63, s64
	v_lshl_add_u64 v[172:173], s[34:35], 0, v[136:137]
	s_add_i32 m0, s42, 0xc000
	ds_read_b128 v[168:171], v152
	ds_read_b128 v[176:179], v152 offset:1024
	ds_read_b128 v[180:183], v152 offset:2048
	ds_read_b128 v[184:187], v152 offset:3072
	ds_read_b128 v[188:191], v152 offset:4096
	ds_read_b128 v[192:195], v152 offset:5120
	ds_read_b128 v[196:199], v152 offset:6144
	ds_read_b128 v[200:203], v152 offset:7168
	global_load_lds_dwordx4 v[172:173], off
	v_lshl_add_u64 v[172:173], s[34:35], 0, v[138:139]
	s_add_i32 m0, s42, 0xe000
	s_nop 0
	global_load_lds_dwordx4 v[172:173], off
	s_waitcnt lgkmcnt(8)
	s_barrier
	s_waitcnt lgkmcnt(0)
	s_setprio 1
	v_mfma_f32_16x16x32_bf16 v[124:127], v[144:147], v[168:171], v[124:127]
	v_mfma_f32_16x16x32_bf16 v[120:123], v[160:163], v[168:171], v[120:123]
	v_mfma_f32_16x16x32_bf16 v[116:119], v[144:147], v[180:183], v[116:119]
	v_mfma_f32_16x16x32_bf16 v[112:115], v[160:163], v[180:183], v[112:115]
	v_mfma_f32_16x16x32_bf16 v[92:95], v[144:147], v[188:191], v[92:95]
	v_mfma_f32_16x16x32_bf16 v[88:91], v[160:163], v[188:191], v[88:91]
	v_mfma_f32_16x16x32_bf16 v[76:79], v[144:147], v[196:199], v[76:79]
	v_mfma_f32_16x16x32_bf16 v[72:75], v[160:163], v[196:199], v[72:75]
	v_mfma_f32_16x16x32_bf16 v[124:127], v[156:159], v[176:179], v[124:127]
	v_mfma_f32_16x16x32_bf16 v[120:123], v[164:167], v[176:179], v[120:123]
	v_mfma_f32_16x16x32_bf16 v[116:119], v[156:159], v[184:187], v[116:119]
	v_mfma_f32_16x16x32_bf16 v[112:115], v[164:167], v[184:187], v[112:115]
	v_mfma_f32_16x16x32_bf16 v[92:95], v[156:159], v[192:195], v[92:95]
	v_mfma_f32_16x16x32_bf16 v[88:91], v[164:167], v[192:195], v[88:91]
	v_mfma_f32_16x16x32_bf16 v[76:79], v[156:159], v[200:203], v[76:79]
	v_mfma_f32_16x16x32_bf16 v[72:75], v[164:167], v[200:203], v[72:75]
	s_setprio 0
	s_barrier
	s_add_i32 s67, s55, s41
	v_lshl_add_u64 v[172:173], s[36:37], 0, v[130:131]
	s_mov_b32 m0, s67
	ds_read_b128 v[204:207], v153
	ds_read_b128 v[212:215], v153 offset:1024
	ds_read_b128 v[216:219], v153 offset:2048
	ds_read_b128 v[220:223], v153 offset:3072
	global_load_lds_dwordx4 v[172:173], off
	v_lshl_add_u64 v[208:209], s[36:37], 0, v[134:135]
	s_add_i32 m0, s67, 0x2000
	s_nop 0
	global_load_lds_dwordx4 v[208:209], off
	s_barrier
	s_waitcnt lgkmcnt(0)
	s_setprio 1
	v_mfma_f32_16x16x32_bf16 v[108:111], v[204:207], v[168:171], v[108:111]
	v_mfma_f32_16x16x32_bf16 v[104:107], v[216:219], v[168:171], v[104:107]
	v_mfma_f32_16x16x32_bf16 v[100:103], v[204:207], v[180:183], v[100:103]
	v_mfma_f32_16x16x32_bf16 v[96:99], v[216:219], v[180:183], v[96:99]
	v_mfma_f32_16x16x32_bf16 v[84:87], v[204:207], v[188:191], v[84:87]
	v_mfma_f32_16x16x32_bf16 v[80:83], v[216:219], v[188:191], v[80:83]
	v_mfma_f32_16x16x32_bf16 v[68:71], v[204:207], v[196:199], v[68:71]
	v_mfma_f32_16x16x32_bf16 v[64:67], v[216:219], v[196:199], v[64:67]
	v_mfma_f32_16x16x32_bf16 v[108:111], v[212:215], v[176:179], v[108:111]
	v_mfma_f32_16x16x32_bf16 v[104:107], v[220:223], v[176:179], v[104:107]
	v_mfma_f32_16x16x32_bf16 v[100:103], v[212:215], v[184:187], v[100:103]
	v_mfma_f32_16x16x32_bf16 v[96:99], v[220:223], v[184:187], v[96:99]
	v_mfma_f32_16x16x32_bf16 v[84:87], v[212:215], v[192:195], v[84:87]
	v_mfma_f32_16x16x32_bf16 v[80:83], v[220:223], v[192:195], v[80:83]
	v_mfma_f32_16x16x32_bf16 v[68:71], v[212:215], v[200:203], v[68:71]
	v_mfma_f32_16x16x32_bf16 v[64:67], v[220:223], v[200:203], v[64:67]
	s_setprio 0
	s_mov_b32 m0, s42
	v_lshl_add_u64 v[224:225], s[38:39], 0, v[128:129]
	s_barrier
	ds_read_b128 v[168:171], v152 offset:16384
	ds_read_b128 v[176:179], v152 offset:17408
	ds_read_b128 v[180:183], v152 offset:18432
	ds_read_b128 v[184:187], v152 offset:19456
	ds_read_b128 v[188:191], v152 offset:20480
	ds_read_b128 v[192:195], v152 offset:21504
	ds_read_b128 v[196:199], v152 offset:22528
	ds_read_b128 v[200:203], v152 offset:23552
	global_load_lds_dwordx4 v[224:225], off
	v_lshl_add_u64 v[226:227], s[38:39], 0, v[132:133]
	s_mov_b32 m0, s43
	s_nop 0
	global_load_lds_dwordx4 v[226:227], off
	s_barrier
	s_waitcnt lgkmcnt(0)
	s_setprio 1
	v_mfma_f32_16x16x32_bf16 v[60:63], v[144:147], v[168:171], v[60:63]
	v_mfma_f32_16x16x32_bf16 v[56:59], v[160:163], v[168:171], v[56:59]
	v_mfma_f32_16x16x32_bf16 v[44:47], v[144:147], v[180:183], v[44:47]
	v_mfma_f32_16x16x32_bf16 v[40:43], v[160:163], v[180:183], v[40:43]
	v_mfma_f32_16x16x32_bf16 v[28:31], v[144:147], v[188:191], v[28:31]
	v_mfma_f32_16x16x32_bf16 v[24:27], v[160:163], v[188:191], v[24:27]
	v_mfma_f32_16x16x32_bf16 v[12:15], v[144:147], v[196:199], v[12:15]
	v_mfma_f32_16x16x32_bf16 v[8:11], v[160:163], v[196:199], v[8:11]
	v_mfma_f32_16x16x32_bf16 v[60:63], v[156:159], v[176:179], v[60:63]
	v_mfma_f32_16x16x32_bf16 v[56:59], v[164:167], v[176:179], v[56:59]
	v_mfma_f32_16x16x32_bf16 v[44:47], v[156:159], v[184:187], v[44:47]
	v_mfma_f32_16x16x32_bf16 v[40:43], v[164:167], v[184:187], v[40:43]
	v_mfma_f32_16x16x32_bf16 v[28:31], v[156:159], v[192:195], v[28:31]
	v_mfma_f32_16x16x32_bf16 v[24:27], v[164:167], v[192:195], v[24:27]
	v_mfma_f32_16x16x32_bf16 v[12:15], v[156:159], v[200:203], v[12:15]
	v_mfma_f32_16x16x32_bf16 v[8:11], v[164:167], v[200:203], v[8:11]
	s_setprio 0
	s_barrier
	s_add_u32 s68, s36, 0x40000
	s_addc_u32 s69, s37, 0
	s_add_i32 s67, s56, s41
	v_lshl_add_u64 v[144:145], s[68:69], 0, v[130:131]
	s_mov_b32 m0, s67
	s_nop 0
	global_load_lds_dwordx4 v[144:145], off
	v_lshl_add_u64 v[144:145], s[68:69], 0, v[134:135]
	s_add_i32 m0, s67, 0x2000
	s_nop 0
	global_load_lds_dwordx4 v[144:145], off
	s_waitcnt vmcnt(6)
	s_barrier
	s_setprio 1
	v_mfma_f32_16x16x32_bf16 v[52:55], v[204:207], v[168:171], v[52:55]
	v_mfma_f32_16x16x32_bf16 v[48:51], v[216:219], v[168:171], v[48:51]
	v_mfma_f32_16x16x32_bf16 v[36:39], v[204:207], v[180:183], v[36:39]
	v_mfma_f32_16x16x32_bf16 v[32:35], v[216:219], v[180:183], v[32:35]
	v_mfma_f32_16x16x32_bf16 v[20:23], v[204:207], v[188:191], v[20:23]
	v_mfma_f32_16x16x32_bf16 v[16:19], v[216:219], v[188:191], v[16:19]
	v_mfma_f32_16x16x32_bf16 v[4:7], v[204:207], v[196:199], v[4:7]
	v_mfma_f32_16x16x32_bf16 v[0:3], v[216:219], v[196:199], v[0:3]
	v_mfma_f32_16x16x32_bf16 v[52:55], v[212:215], v[176:179], v[52:55]
	v_mfma_f32_16x16x32_bf16 v[48:51], v[220:223], v[176:179], v[48:51]
	v_mfma_f32_16x16x32_bf16 v[36:39], v[212:215], v[184:187], v[36:39]
	v_mfma_f32_16x16x32_bf16 v[32:35], v[220:223], v[184:187], v[32:35]
	v_mfma_f32_16x16x32_bf16 v[20:23], v[212:215], v[192:195], v[20:23]
	v_mfma_f32_16x16x32_bf16 v[16:19], v[220:223], v[192:195], v[16:19]
	v_mfma_f32_16x16x32_bf16 v[4:7], v[212:215], v[200:203], v[4:7]
	v_mfma_f32_16x16x32_bf16 v[0:3], v[220:223], v[200:203], v[0:3]
	s_setprio 0
	s_add_i32 s67, 0, 0x18000
	v_add_u32_e32 v155, s67, v149
	s_barrier
	ds_read_b128 v[144:147], v155
	ds_read_b128 v[156:159], v155 offset:1024
	ds_read_b128 v[160:163], v155 offset:2048
	ds_read_b128 v[164:167], v155 offset:3072
	s_add_u32 s38, s38, 0x40000
	s_addc_u32 s39, s39, 0
	s_mov_b32 m0, s48
	v_lshl_add_u64 v[204:205], s[38:39], 0, v[128:129]
	ds_read_b128 v[168:171], v152 offset:32768
	ds_read_b128 v[176:179], v152 offset:33792
	ds_read_b128 v[180:183], v152 offset:34816
	ds_read_b128 v[184:187], v152 offset:35840
	ds_read_b128 v[188:191], v152 offset:36864
	ds_read_b128 v[192:195], v152 offset:37888
	ds_read_b128 v[196:199], v152 offset:38912
	ds_read_b128 v[200:203], v152 offset:39936
	global_load_lds_dwordx4 v[204:205], off
	v_lshl_add_u64 v[204:205], s[38:39], 0, v[132:133]
	s_mov_b32 m0, s49
	s_nop 0
	global_load_lds_dwordx4 v[204:205], off
	s_waitcnt lgkmcnt(8)
	s_barrier
	s_waitcnt lgkmcnt(0)
	s_setprio 1
	v_mfma_f32_16x16x32_bf16 v[124:127], v[144:147], v[168:171], v[124:127]
	v_mfma_f32_16x16x32_bf16 v[120:123], v[160:163], v[168:171], v[120:123]
	v_mfma_f32_16x16x32_bf16 v[116:119], v[144:147], v[180:183], v[116:119]
	v_mfma_f32_16x16x32_bf16 v[112:115], v[160:163], v[180:183], v[112:115]
	v_mfma_f32_16x16x32_bf16 v[92:95], v[144:147], v[188:191], v[92:95]
	v_mfma_f32_16x16x32_bf16 v[88:91], v[160:163], v[188:191], v[88:91]
	v_mfma_f32_16x16x32_bf16 v[76:79], v[144:147], v[196:199], v[76:79]
	v_mfma_f32_16x16x32_bf16 v[72:75], v[160:163], v[196:199], v[72:75]
	v_mfma_f32_16x16x32_bf16 v[124:127], v[156:159], v[176:179], v[124:127]
	v_mfma_f32_16x16x32_bf16 v[120:123], v[164:167], v[176:179], v[120:123]
	v_mfma_f32_16x16x32_bf16 v[116:119], v[156:159], v[184:187], v[116:119]
	v_mfma_f32_16x16x32_bf16 v[112:115], v[164:167], v[184:187], v[112:115]
	v_mfma_f32_16x16x32_bf16 v[92:95], v[156:159], v[192:195], v[92:95]
	v_mfma_f32_16x16x32_bf16 v[88:91], v[164:167], v[192:195], v[88:91]
	v_mfma_f32_16x16x32_bf16 v[76:79], v[156:159], v[200:203], v[76:79]
	v_mfma_f32_16x16x32_bf16 v[72:75], v[164:167], v[200:203], v[72:75]
	s_setprio 0
	s_barrier
	s_add_i32 s38, 0, 0x1c000
	s_add_i32 s39, s67, s41
	v_add_u32_e32 v155, s38, v149
	v_lshl_add_u64 v[172:173], v[172:173], 0, s[8:9]
	s_mov_b32 m0, s39
	ds_read_b128 v[204:207], v155
	ds_read_b128 v[212:215], v155 offset:1024
	ds_read_b128 v[216:219], v155 offset:2048
	ds_read_b128 v[220:223], v155 offset:3072
	global_load_lds_dwordx4 v[172:173], off
	v_lshl_add_u64 v[172:173], v[208:209], 0, s[8:9]
	s_add_i32 m0, s39, 0x2000
	s_nop 0
	global_load_lds_dwordx4 v[172:173], off
	s_barrier
	s_waitcnt lgkmcnt(0)
	s_setprio 1
	v_mfma_f32_16x16x32_bf16 v[108:111], v[204:207], v[168:171], v[108:111]
	v_mfma_f32_16x16x32_bf16 v[104:107], v[216:219], v[168:171], v[104:107]
	v_mfma_f32_16x16x32_bf16 v[100:103], v[204:207], v[180:183], v[100:103]
	v_mfma_f32_16x16x32_bf16 v[96:99], v[216:219], v[180:183], v[96:99]
	v_mfma_f32_16x16x32_bf16 v[84:87], v[204:207], v[188:191], v[84:87]
	v_mfma_f32_16x16x32_bf16 v[80:83], v[216:219], v[188:191], v[80:83]
	v_mfma_f32_16x16x32_bf16 v[68:71], v[204:207], v[196:199], v[68:71]
	v_mfma_f32_16x16x32_bf16 v[64:67], v[216:219], v[196:199], v[64:67]
	v_mfma_f32_16x16x32_bf16 v[108:111], v[212:215], v[176:179], v[108:111]
	v_mfma_f32_16x16x32_bf16 v[104:107], v[220:223], v[176:179], v[104:107]
	v_mfma_f32_16x16x32_bf16 v[100:103], v[212:215], v[184:187], v[100:103]
	v_mfma_f32_16x16x32_bf16 v[96:99], v[220:223], v[184:187], v[96:99]
	v_mfma_f32_16x16x32_bf16 v[84:87], v[212:215], v[192:195], v[84:87]
	v_mfma_f32_16x16x32_bf16 v[80:83], v[220:223], v[192:195], v[80:83]
	v_mfma_f32_16x16x32_bf16 v[68:71], v[212:215], v[200:203], v[68:71]
	v_mfma_f32_16x16x32_bf16 v[64:67], v[220:223], v[200:203], v[64:67]
	s_setprio 0
	s_mov_b32 m0, s51
	v_lshl_add_u64 v[172:173], v[224:225], 0, s[8:9]
	s_barrier
	ds_read_b128 v[168:171], v152 offset:49152
	ds_read_b128 v[176:179], v152 offset:50176
	ds_read_b128 v[180:183], v152 offset:51200
	ds_read_b128 v[184:187], v152 offset:52224
	ds_read_b128 v[188:191], v152 offset:53248
	ds_read_b128 v[192:195], v152 offset:54272
	ds_read_b128 v[196:199], v152 offset:55296
	ds_read_b128 v[200:203], v152 offset:56320
	global_load_lds_dwordx4 v[172:173], off
	v_lshl_add_u64 v[172:173], v[226:227], 0, s[8:9]
	s_mov_b32 m0, s52
	s_nop 0
	global_load_lds_dwordx4 v[172:173], off
	s_barrier
	s_waitcnt lgkmcnt(0)
	s_setprio 1
	v_mfma_f32_16x16x32_bf16 v[60:63], v[144:147], v[168:171], v[60:63]
	v_mfma_f32_16x16x32_bf16 v[56:59], v[160:163], v[168:171], v[56:59]
	v_mfma_f32_16x16x32_bf16 v[44:47], v[144:147], v[180:183], v[44:47]
	v_mfma_f32_16x16x32_bf16 v[40:43], v[160:163], v[180:183], v[40:43]
	v_mfma_f32_16x16x32_bf16 v[28:31], v[144:147], v[188:191], v[28:31]
	v_mfma_f32_16x16x32_bf16 v[24:27], v[160:163], v[188:191], v[24:27]
	v_mfma_f32_16x16x32_bf16 v[12:15], v[144:147], v[196:199], v[12:15]
	v_mfma_f32_16x16x32_bf16 v[8:11], v[160:163], v[196:199], v[8:11]
	v_mfma_f32_16x16x32_bf16 v[60:63], v[156:159], v[176:179], v[60:63]
	v_mfma_f32_16x16x32_bf16 v[56:59], v[164:167], v[176:179], v[56:59]
	v_mfma_f32_16x16x32_bf16 v[44:47], v[156:159], v[184:187], v[44:47]
	v_mfma_f32_16x16x32_bf16 v[40:43], v[164:167], v[184:187], v[40:43]
	v_mfma_f32_16x16x32_bf16 v[28:31], v[156:159], v[192:195], v[28:31]
	v_mfma_f32_16x16x32_bf16 v[24:27], v[164:167], v[192:195], v[24:27]
	v_mfma_f32_16x16x32_bf16 v[12:15], v[156:159], v[200:203], v[12:15]
	v_mfma_f32_16x16x32_bf16 v[8:11], v[164:167], v[200:203], v[8:11]
	s_setprio 0
	s_barrier
	s_add_u32 s36, s36, 0x40080
	s_addc_u32 s37, s37, 0
	s_add_i32 s38, s38, s41
	v_lshl_add_u64 v[144:145], s[36:37], 0, v[130:131]
	s_mov_b32 m0, s38
	s_nop 0
	global_load_lds_dwordx4 v[144:145], off
	v_lshl_add_u64 v[144:145], s[36:37], 0, v[134:135]
	s_add_i32 m0, s38, 0x2000
	s_nop 0
	global_load_lds_dwordx4 v[144:145], off
	s_waitcnt vmcnt(6)
	s_barrier
	s_setprio 1
	v_mfma_f32_16x16x32_bf16 v[52:55], v[204:207], v[168:171], v[52:55]
	v_mfma_f32_16x16x32_bf16 v[48:51], v[216:219], v[168:171], v[48:51]
	v_mfma_f32_16x16x32_bf16 v[36:39], v[204:207], v[180:183], v[36:39]
	v_mfma_f32_16x16x32_bf16 v[32:35], v[216:219], v[180:183], v[32:35]
	v_mfma_f32_16x16x32_bf16 v[20:23], v[204:207], v[188:191], v[20:23]
	v_mfma_f32_16x16x32_bf16 v[16:19], v[216:219], v[188:191], v[16:19]
	v_mfma_f32_16x16x32_bf16 v[4:7], v[204:207], v[196:199], v[4:7]
	v_mfma_f32_16x16x32_bf16 v[0:3], v[216:219], v[196:199], v[0:3]
	v_mfma_f32_16x16x32_bf16 v[52:55], v[212:215], v[176:179], v[52:55]
	v_mfma_f32_16x16x32_bf16 v[48:51], v[220:223], v[176:179], v[48:51]
	v_mfma_f32_16x16x32_bf16 v[36:39], v[212:215], v[184:187], v[36:39]
	v_mfma_f32_16x16x32_bf16 v[32:35], v[220:223], v[184:187], v[32:35]
	v_mfma_f32_16x16x32_bf16 v[20:23], v[212:215], v[192:195], v[20:23]
	v_mfma_f32_16x16x32_bf16 v[16:19], v[220:223], v[192:195], v[16:19]
	v_mfma_f32_16x16x32_bf16 v[4:7], v[212:215], v[200:203], v[4:7]
	v_mfma_f32_16x16x32_bf16 v[0:3], v[220:223], v[200:203], v[0:3]
	s_setprio 0
	s_add_i32 s66, s66, 2
	s_add_u32 s34, s34, 0x100
	s_addc_u32 s35, s35, 0
	s_add_u32 s64, s64, 0x100
	s_addc_u32 s65, s65, 0
	s_cmp_gt_u32 s66, 13
	s_barrier
	s_cbranch_scc0 .LBB0_850
	v_lshl_add_u32 v146, s0, 8, v148
	v_ashrrev_i32_e32 v147, 31, v146
	v_lshl_add_u64 v[144:145], v[146:147], 2, s[2:3]
	global_load_dword v155, v[144:145], off
	global_load_dword v162, v[144:145], off offset:64
	global_load_dword v163, v[144:145], off offset:128
	global_load_dword v164, v[144:145], off offset:192
	global_load_dword v165, v[144:145], off offset:512
	global_load_dword v166, v[144:145], off offset:576
	global_load_dword v167, v[144:145], off offset:640
	global_load_dword v168, v[144:145], off offset:704
	v_lshl_or_b32 v144, s1, 8, v150
	v_ashrrev_i32_e32 v145, 31, v144
	v_lshlrev_b64 v[158:159], 13, v[146:147]
	v_lshlrev_b64 v[160:161], 1, v[144:145]
	v_lshl_add_u64 v[144:145], s[92:93], 0, v[158:159]
	v_lshl_add_u64 v[144:145], v[144:145], 0, v[160:161]
	v_or_b32_e32 v156, 16, v146
	v_ashrrev_i32_e32 v157, 31, v156
	v_lshlrev_b64 v[156:157], 13, v[156:157]
	v_lshl_add_u64 v[156:157], s[92:93], 0, v[156:157]
	v_lshl_add_u64 v[156:157], v[156:157], 0, v[160:161]
	s_mov_b64 s[36:37], s[30:31]
	s_mov_b64 s[34:35], s[28:29]
	s_waitcnt vmcnt(0)
	v_fmamk_f32 v147, v155, 0x3a800000, v154
	v_mul_f32_e32 v158, 0x4b800000, v147
	v_cmp_gt_f32_e32 vcc, s57, v147
	v_fmamk_f32 v155, v162, 0x3a800000, v154
	v_mul_f32_e32 v162, 0x4b800000, v155
	v_cndmask_b32_e32 v147, v147, v158, vcc
	v_rsq_f32_e32 v158, v147
	v_cmp_gt_f32_e64 s[0:1], s57, v155
	v_fmamk_f32 v159, v163, 0x3a800000, v154
	v_fmamk_f32 v163, v164, 0x3a800000, v154
	v_cndmask_b32_e64 v155, v155, v162, s[0:1]
	v_rsq_f32_e32 v155, v155
	v_mul_f32_e32 v162, 0x45800000, v158
	v_cndmask_b32_e32 v158, v158, v162, vcc
	v_pk_mul_f32 v[124:125], v[124:125], v[158:159] op_sel_hi:[1,0]
	v_pk_mul_f32 v[104:105], v[104:105], v[158:159] op_sel_hi:[1,0]
	v_fmamk_f32 v164, v165, 0x3a800000, v154
	v_fmamk_f32 v165, v166, 0x3a800000, v154
	v_fmamk_f32 v166, v167, 0x3a800000, v154
	v_mul_f32_e32 v167, 0x45800000, v155
	v_pk_mul_f32 v[126:127], v[126:127], v[158:159] op_sel_hi:[1,0]
	v_pk_mul_f32 v[122:123], v[122:123], v[158:159] op_sel_hi:[1,0]
	v_pk_mul_f32 v[120:121], v[120:121], v[158:159] op_sel_hi:[1,0]
	v_pk_mul_f32 v[108:109], v[108:109], v[158:159] op_sel_hi:[1,0]
	v_pk_mul_f32 v[106:107], v[106:107], v[158:159] op_sel_hi:[1,0]
	v_max_f32_e32 v124, 0, v124
	v_max_f32_e32 v125, 0, v125
	v_max_f32_e32 v104, 0, v104
	v_cndmask_b32_e64 v162, v155, v167, s[0:1]
	v_pk_mul_f32 v[110:111], v[110:111], v[158:159] op_sel_hi:[1,0]
	v_max_f32_e32 v120, 0, v120
	v_max_f32_e32 v121, 0, v121
	v_max_f32_e32 v126, 0, v126
	v_max_f32_e32 v122, 0, v122
	v_max_f32_e32 v127, 0, v127
	v_max_f32_e32 v123, 0, v123
	v_max_f32_e32 v108, 0, v108
	v_max_f32_e32 v109, 0, v109
	v_max_f32_e32 v105, 0, v105
	v_max_f32_e32 v106, 0, v106
	v_max_f32_e32 v107, 0, v107
	v_mul_f32_e32 v124, v124, v124
	v_mul_f32_e32 v125, v125, v125
	v_mul_f32_e32 v155, v104, v104
	v_cvt_pk_bf16_f32 v104, v124, v125
	v_fmamk_f32 v147, v168, 0x3a800000, v154
	v_pk_mul_f32 v[112:113], v[112:113], v[162:163] op_sel_hi:[1,0]
	v_max_f32_e32 v110, 0, v110
	v_max_f32_e32 v111, 0, v111
	v_mul_f32_e32 v120, v120, v120
	v_mul_f32_e32 v121, v121, v121
	v_mul_f32_e32 v126, v126, v126
	v_mul_f32_e32 v122, v122, v122
	v_mul_f32_e32 v127, v127, v127
	v_mul_f32_e32 v123, v123, v123
	v_mul_f32_e32 v108, v108, v108
	v_mul_f32_e32 v109, v109, v109
	v_mul_f32_e32 v158, v105, v105
	v_mul_f32_e32 v167, v106, v106
	v_mul_f32_e32 v168, v107, v107
	v_cvt_pk_bf16_f32 v105, v126, v127
	v_cvt_pk_bf16_f32 v106, v120, v121
	v_cvt_pk_bf16_f32 v107, v122, v123
	global_store_dwordx4 v[144:145], v[104:107], off nt
	v_pk_mul_f32 v[116:117], v[116:117], v[162:163] op_sel_hi:[1,0]
	v_mul_f32_e32 v110, v110, v110
	v_cvt_pk_bf16_f32 v104, v108, v109
	v_mul_f32_e32 v111, v111, v111
	v_cvt_pk_bf16_f32 v105, v110, v111
	v_cvt_pk_bf16_f32 v106, v155, v158
	v_cvt_pk_bf16_f32 v107, v167, v168
	global_store_dwordx4 v[144:145], v[104:107], off offset:256 nt
	v_pk_mul_f32 v[118:119], v[118:119], v[162:163] op_sel_hi:[1,0]
	v_pk_mul_f32 v[114:115], v[114:115], v[162:163] op_sel_hi:[1,0]
	v_max_f32_e32 v104, 0, v112
	v_mul_f32_e32 v106, v104, v104
	v_max_f32_e32 v104, 0, v117
	v_max_f32_e32 v116, 0, v116
	v_max_f32_e32 v107, 0, v113
	v_mul_f32_e32 v104, v104, v104
	v_pk_mul_f32 v[98:99], v[98:99], v[162:163] op_sel_hi:[1,0]
	v_pk_mul_f32 v[96:97], v[96:97], v[162:163] op_sel_hi:[1,0]
	v_mul_f32_e32 v105, v116, v116
	v_mul_f32_e32 v107, v107, v107
	v_max_f32_e32 v108, 0, v118
	v_max_f32_e32 v109, 0, v114
	v_max_f32_e32 v110, 0, v119
	v_max_f32_e32 v111, 0, v115
	v_cvt_pk_bf16_f32 v104, v105, v104
	v_pk_mul_f32 v[102:103], v[102:103], v[162:163] op_sel_hi:[1,0]
	v_pk_mul_f32 v[100:101], v[100:101], v[162:163] op_sel_hi:[1,0]
	v_max_f32_e32 v96, 0, v96
	v_max_f32_e32 v97, 0, v97
	v_max_f32_e32 v98, 0, v98
	v_mul_f32_e32 v108, v108, v108
	v_mul_f32_e32 v109, v109, v109
	v_mul_f32_e32 v110, v110, v110
	v_mul_f32_e32 v111, v111, v111
	v_cvt_pk_bf16_f32 v105, v108, v110
	v_cvt_pk_bf16_f32 v106, v106, v107
	v_cvt_pk_bf16_f32 v107, v109, v111
	global_store_dwordx4 v[156:157], v[104:107], off nt
	v_max_f32_e32 v100, 0, v100
	v_max_f32_e32 v99, 0, v99
	v_mul_f32_e32 v104, v96, v96
	v_max_f32_e32 v96, 0, v101
	v_mul_f32_e32 v101, v97, v97
	v_max_f32_e32 v97, 0, v102
	v_mul_f32_e32 v102, v98, v98
	v_max_f32_e32 v98, 0, v103
	v_mul_f32_e32 v96, v96, v96
	v_mul_f32_e32 v97, v97, v97
	v_mul_f32_e32 v98, v98, v98
	v_mul_f32_e32 v100, v100, v100
	v_mul_f32_e32 v99, v99, v99
	v_cvt_pk_bf16_f32 v96, v100, v96
	v_cvt_pk_bf16_f32 v97, v97, v98
	v_cvt_pk_bf16_f32 v98, v104, v101
	v_cvt_pk_bf16_f32 v99, v102, v99
	global_store_dwordx4 v[156:157], v[96:99], off offset:256 nt
	v_cmp_gt_f32_e32 vcc, s57, v159
	s_mov_b64 s[0:1], 0x100000
	v_mul_f32_e32 v98, 0x4b800000, v159
	v_cndmask_b32_e32 v98, v159, v98, vcc
	v_rsq_f32_e32 v98, v98
	v_or_b32_e32 v96, 32, v146
	v_ashrrev_i32_e32 v97, 31, v96
	v_lshlrev_b64 v[96:97], 13, v[96:97]
	v_mul_f32_e32 v99, 0x45800000, v98
	v_cndmask_b32_e32 v98, v98, v99, vcc
	v_pk_mul_f32 v[88:89], v[88:89], v[98:99] op_sel_hi:[1,0]
	v_pk_mul_f32 v[92:93], v[92:93], v[98:99] op_sel_hi:[1,0]
	v_pk_mul_f32 v[90:91], v[90:91], v[98:99] op_sel_hi:[1,0]
	v_max_f32_e32 v88, 0, v88
	v_pk_mul_f32 v[94:95], v[94:95], v[98:99] op_sel_hi:[1,0]
	v_mul_f32_e32 v99, v88, v88
	v_max_f32_e32 v88, 0, v93
	v_max_f32_e32 v89, 0, v89
	v_max_f32_e32 v90, 0, v90
	v_lshl_add_u64 v[96:97], s[92:93], 0, v[96:97]
	v_max_f32_e32 v92, 0, v92
	v_mul_f32_e32 v88, v88, v88
	v_mul_f32_e32 v93, v89, v89
	v_max_f32_e32 v89, 0, v94
	v_mul_f32_e32 v94, v90, v90
	v_max_f32_e32 v90, 0, v95
	v_max_f32_e32 v91, 0, v91
	v_pk_mul_f32 v[82:83], v[82:83], v[98:99] op_sel_hi:[1,0]
	v_pk_mul_f32 v[80:81], v[80:81], v[98:99] op_sel_hi:[1,0]
	v_lshl_add_u64 v[96:97], v[96:97], 0, v[160:161]
	v_mul_f32_e32 v92, v92, v92
	v_mul_f32_e32 v89, v89, v89
	v_mul_f32_e32 v90, v90, v90
	v_mul_f32_e32 v91, v91, v91
	v_cvt_pk_bf16_f32 v88, v92, v88
	v_pk_mul_f32 v[86:87], v[86:87], v[98:99] op_sel_hi:[1,0]
	v_pk_mul_f32 v[84:85], v[84:85], v[98:99] op_sel_hi:[1,0]
	v_max_f32_e32 v80, 0, v80
	v_max_f32_e32 v81, 0, v81
	v_max_f32_e32 v82, 0, v82
	v_cvt_pk_bf16_f32 v89, v89, v90
	v_cvt_pk_bf16_f32 v90, v99, v93
	v_cvt_pk_bf16_f32 v91, v94, v91
	global_store_dwordx4 v[96:97], v[88:91], off nt
	v_max_f32_e32 v84, 0, v84
	v_max_f32_e32 v83, 0, v83
	v_mul_f32_e32 v88, v80, v80
	v_max_f32_e32 v80, 0, v85
	v_mul_f32_e32 v85, v81, v81
	v_max_f32_e32 v81, 0, v86
	v_mul_f32_e32 v86, v82, v82
	v_max_f32_e32 v82, 0, v87
	v_mul_f32_e32 v80, v80, v80
	v_mul_f32_e32 v81, v81, v81
	v_mul_f32_e32 v82, v82, v82
	v_mul_f32_e32 v84, v84, v84
	v_mul_f32_e32 v83, v83, v83
	v_cvt_pk_bf16_f32 v80, v84, v80
	v_cvt_pk_bf16_f32 v81, v81, v82
	v_cvt_pk_bf16_f32 v82, v88, v85
	v_cvt_pk_bf16_f32 v83, v86, v83
	global_store_dwordx4 v[96:97], v[80:83], off offset:256 nt
	v_cmp_gt_f32_e32 vcc, s57, v163
	s_nop 0
	v_mul_f32_e32 v82, 0x4b800000, v163
	v_cndmask_b32_e32 v82, v163, v82, vcc
	v_rsq_f32_e32 v82, v82
	v_or_b32_e32 v80, 48, v146
	v_ashrrev_i32_e32 v81, 31, v80
	v_lshlrev_b64 v[80:81], 13, v[80:81]
	v_mul_f32_e32 v83, 0x45800000, v82
	v_cndmask_b32_e32 v82, v82, v83, vcc
	v_pk_mul_f32 v[72:73], v[72:73], v[82:83] op_sel_hi:[1,0]
	v_pk_mul_f32 v[76:77], v[76:77], v[82:83] op_sel_hi:[1,0]
	v_pk_mul_f32 v[74:75], v[74:75], v[82:83] op_sel_hi:[1,0]
	v_max_f32_e32 v72, 0, v72
	v_pk_mul_f32 v[78:79], v[78:79], v[82:83] op_sel_hi:[1,0]
	v_mul_f32_e32 v83, v72, v72
	v_max_f32_e32 v72, 0, v77
	v_max_f32_e32 v73, 0, v73
	v_max_f32_e32 v74, 0, v74
	v_lshl_add_u64 v[80:81], s[92:93], 0, v[80:81]
	v_max_f32_e32 v76, 0, v76
	v_mul_f32_e32 v72, v72, v72
	v_mul_f32_e32 v77, v73, v73
	v_max_f32_e32 v73, 0, v78
	v_mul_f32_e32 v78, v74, v74
	v_max_f32_e32 v74, 0, v79
	v_max_f32_e32 v75, 0, v75
	v_pk_mul_f32 v[64:65], v[64:65], v[82:83] op_sel_hi:[1,0]
	v_lshl_add_u64 v[80:81], v[80:81], 0, v[160:161]
	v_mul_f32_e32 v76, v76, v76
	v_mul_f32_e32 v73, v73, v73
	v_mul_f32_e32 v74, v74, v74
	v_mul_f32_e32 v75, v75, v75
	v_cvt_pk_bf16_f32 v72, v76, v72
	v_pk_mul_f32 v[68:69], v[68:69], v[82:83] op_sel_hi:[1,0]
	v_max_f32_e32 v64, 0, v64
	v_cvt_pk_bf16_f32 v73, v73, v74
	v_cvt_pk_bf16_f32 v74, v83, v77
	v_cvt_pk_bf16_f32 v75, v78, v75
	global_store_dwordx4 v[80:81], v[72:75], off nt
	v_max_f32_e32 v68, 0, v68
	v_mul_f32_e32 v68, v68, v68
	v_mul_f32_e32 v72, v64, v64
	v_max_f32_e32 v64, 0, v69
	v_mul_f32_e32 v64, v64, v64
	v_cvt_pk_bf16_f32 v64, v68, v64
	v_mul_f32_e32 v68, 0x4b800000, v164
	v_cmp_gt_f32_e32 vcc, s57, v164
	v_pk_mul_f32 v[66:67], v[66:67], v[82:83] op_sel_hi:[1,0]
	v_pk_mul_f32 v[70:71], v[70:71], v[82:83] op_sel_hi:[1,0]
	v_cndmask_b32_e32 v68, v164, v68, vcc
	v_max_f32_e32 v65, 0, v65
	v_max_f32_e32 v66, 0, v66
	v_rsq_f32_e32 v68, v68
	v_mul_f32_e32 v69, v65, v65
	v_max_f32_e32 v65, 0, v70
	v_mul_f32_e32 v70, v66, v66
	v_max_f32_e32 v66, 0, v71
	v_mul_f32_e32 v65, v65, v65
	v_max_f32_e32 v67, 0, v67
	v_mul_f32_e32 v66, v66, v66
	v_mul_f32_e32 v67, v67, v67
	v_cvt_pk_bf16_f32 v65, v65, v66
	v_cvt_pk_bf16_f32 v66, v72, v69
	v_cvt_pk_bf16_f32 v67, v70, v67
	global_store_dwordx4 v[80:81], v[64:67], off offset:256 nt
	s_nop 1
	v_mul_f32_e32 v66, 0x45800000, v68
	v_cndmask_b32_e32 v66, v68, v66, vcc
	v_pk_mul_f32 v[56:57], v[56:57], v[66:67] op_sel_hi:[1,0]
	v_pk_mul_f32 v[60:61], v[60:61], v[66:67] op_sel_hi:[1,0]
	v_pk_mul_f32 v[58:59], v[58:59], v[66:67] op_sel_hi:[1,0]
	v_max_f32_e32 v56, 0, v56
	v_pk_mul_f32 v[62:63], v[62:63], v[66:67] op_sel_hi:[1,0]
	v_max_f32_e32 v60, 0, v60
	v_mul_f32_e32 v67, v56, v56
	v_max_f32_e32 v56, 0, v61
	v_max_f32_e32 v57, 0, v57
	v_max_f32_e32 v58, 0, v58
	v_mul_f32_e32 v60, v60, v60
	v_mul_f32_e32 v56, v56, v56
	v_mul_f32_e32 v61, v57, v57
	v_max_f32_e32 v57, 0, v62
	v_mul_f32_e32 v62, v58, v58
	v_max_f32_e32 v58, 0, v63
	v_mul_f32_e32 v57, v57, v57
	v_max_f32_e32 v59, 0, v59
	v_mul_f32_e32 v58, v58, v58
	v_cvt_pk_bf16_f32 v56, v60, v56
	v_add_co_u32_e32 v60, vcc, s58, v144
	v_pk_mul_f32 v[48:49], v[48:49], v[66:67] op_sel_hi:[1,0]
	v_mul_f32_e32 v59, v59, v59
	v_cvt_pk_bf16_f32 v57, v57, v58
	v_cvt_pk_bf16_f32 v58, v67, v61
	v_addc_co_u32_e32 v61, vcc, 0, v145, vcc
	v_pk_mul_f32 v[52:53], v[52:53], v[66:67] op_sel_hi:[1,0]
	v_max_f32_e32 v48, 0, v48
	v_cvt_pk_bf16_f32 v59, v62, v59
	global_store_dwordx4 v[60:61], v[56:59], off nt
	v_max_f32_e32 v52, 0, v52
	v_mul_f32_e32 v52, v52, v52
	v_mul_f32_e32 v56, v48, v48
	v_max_f32_e32 v48, 0, v53
	v_mul_f32_e32 v48, v48, v48
	v_cvt_pk_bf16_f32 v48, v52, v48
	v_mul_f32_e32 v52, 0x4b800000, v165
	v_cmp_gt_f32_e32 vcc, s57, v165
	v_pk_mul_f32 v[50:51], v[50:51], v[66:67] op_sel_hi:[1,0]
	v_pk_mul_f32 v[54:55], v[54:55], v[66:67] op_sel_hi:[1,0]
	v_cndmask_b32_e32 v52, v165, v52, vcc
	v_max_f32_e32 v49, 0, v49
	v_max_f32_e32 v50, 0, v50
	v_rsq_f32_e32 v52, v52
	v_mul_f32_e32 v53, v49, v49
	v_max_f32_e32 v49, 0, v54
	v_mul_f32_e32 v54, v50, v50
	v_max_f32_e32 v50, 0, v55
	v_mul_f32_e32 v49, v49, v49
	v_max_f32_e32 v51, 0, v51
	v_mul_f32_e32 v50, v50, v50
	v_lshl_add_u64 v[64:65], v[144:145], 0, s[0:1]
	v_mul_f32_e32 v51, v51, v51
	v_cvt_pk_bf16_f32 v49, v49, v50
	v_cvt_pk_bf16_f32 v50, v56, v53
	v_cvt_pk_bf16_f32 v51, v54, v51
	global_store_dwordx4 v[64:65], v[48:51], off offset:256 nt
	s_mov_b32 s1, s24
	s_mov_b32 s0, s26
	v_mul_f32_e32 v50, 0x45800000, v52
	v_cndmask_b32_e32 v50, v52, v50, vcc
	v_pk_mul_f32 v[40:41], v[40:41], v[50:51] op_sel_hi:[1,0]
	v_pk_mul_f32 v[44:45], v[44:45], v[50:51] op_sel_hi:[1,0]
	v_pk_mul_f32 v[42:43], v[42:43], v[50:51] op_sel_hi:[1,0]
	v_max_f32_e32 v40, 0, v40
	v_pk_mul_f32 v[46:47], v[46:47], v[50:51] op_sel_hi:[1,0]
	v_max_f32_e32 v44, 0, v44
	v_mul_f32_e32 v51, v40, v40
	v_max_f32_e32 v40, 0, v45
	v_max_f32_e32 v41, 0, v41
	v_max_f32_e32 v42, 0, v42
	v_mul_f32_e32 v44, v44, v44
	v_mul_f32_e32 v40, v40, v40
	v_mul_f32_e32 v45, v41, v41
	v_max_f32_e32 v41, 0, v46
	v_mul_f32_e32 v46, v42, v42
	v_max_f32_e32 v42, 0, v47
	v_mul_f32_e32 v41, v41, v41
	v_max_f32_e32 v43, 0, v43
	v_mul_f32_e32 v42, v42, v42
	v_cvt_pk_bf16_f32 v40, v44, v40
	v_add_co_u32_e32 v44, vcc, s59, v144
	v_pk_mul_f32 v[32:33], v[32:33], v[50:51] op_sel_hi:[1,0]
	v_mul_f32_e32 v43, v43, v43
	v_cvt_pk_bf16_f32 v41, v41, v42
	v_cvt_pk_bf16_f32 v42, v51, v45
	v_addc_co_u32_e32 v45, vcc, 0, v145, vcc
	v_pk_mul_f32 v[36:37], v[36:37], v[50:51] op_sel_hi:[1,0]
	v_max_f32_e32 v32, 0, v32
	v_cvt_pk_bf16_f32 v43, v46, v43
	global_store_dwordx4 v[44:45], v[40:43], off nt
	v_max_f32_e32 v36, 0, v36
	v_mul_f32_e32 v36, v36, v36
	v_mul_f32_e32 v40, v32, v32
	v_max_f32_e32 v32, 0, v37
	v_mul_f32_e32 v32, v32, v32
	v_cvt_pk_bf16_f32 v32, v36, v32
	v_mul_f32_e32 v36, 0x4b800000, v166
	v_cmp_gt_f32_e32 vcc, s57, v166
	v_pk_mul_f32 v[34:35], v[34:35], v[50:51] op_sel_hi:[1,0]
	v_pk_mul_f32 v[38:39], v[38:39], v[50:51] op_sel_hi:[1,0]
	v_cndmask_b32_e32 v36, v166, v36, vcc
	v_max_f32_e32 v33, 0, v33
	v_max_f32_e32 v34, 0, v34
	v_rsq_f32_e32 v36, v36
	v_mul_f32_e32 v37, v33, v33
	v_max_f32_e32 v33, 0, v38
	v_mul_f32_e32 v38, v34, v34
	v_max_f32_e32 v34, 0, v39
	v_mul_f32_e32 v33, v33, v33
	v_max_f32_e32 v35, 0, v35
	v_mul_f32_e32 v34, v34, v34
	v_lshl_add_u64 v[48:49], v[144:145], 0, s[18:19]
	v_mul_f32_e32 v35, v35, v35
	v_cvt_pk_bf16_f32 v33, v33, v34
	v_cvt_pk_bf16_f32 v34, v40, v37
	v_cvt_pk_bf16_f32 v35, v38, v35
	global_store_dwordx4 v[48:49], v[32:35], off offset:256 nt
	s_nop 1
	v_mul_f32_e32 v34, 0x45800000, v36
	v_cndmask_b32_e32 v34, v36, v34, vcc
	v_pk_mul_f32 v[24:25], v[24:25], v[34:35] op_sel_hi:[1,0]
	v_pk_mul_f32 v[28:29], v[28:29], v[34:35] op_sel_hi:[1,0]
	v_pk_mul_f32 v[26:27], v[26:27], v[34:35] op_sel_hi:[1,0]
	v_max_f32_e32 v24, 0, v24
	v_pk_mul_f32 v[30:31], v[30:31], v[34:35] op_sel_hi:[1,0]
	v_max_f32_e32 v28, 0, v28
	v_mul_f32_e32 v35, v24, v24
	v_max_f32_e32 v24, 0, v29
	v_max_f32_e32 v25, 0, v25
	v_max_f32_e32 v26, 0, v26
	v_mul_f32_e32 v28, v28, v28
	v_mul_f32_e32 v24, v24, v24
	v_mul_f32_e32 v29, v25, v25
	v_max_f32_e32 v25, 0, v30
	v_mul_f32_e32 v30, v26, v26
	v_max_f32_e32 v26, 0, v31
	v_mul_f32_e32 v25, v25, v25
	v_max_f32_e32 v27, 0, v27
	v_mul_f32_e32 v26, v26, v26
	v_cvt_pk_bf16_f32 v24, v28, v24
	v_add_co_u32_e32 v28, vcc, s60, v144
	v_pk_mul_f32 v[16:17], v[16:17], v[34:35] op_sel_hi:[1,0]
	v_mul_f32_e32 v27, v27, v27
	v_cvt_pk_bf16_f32 v25, v25, v26
	v_cvt_pk_bf16_f32 v26, v35, v29
	v_addc_co_u32_e32 v29, vcc, 0, v145, vcc
	v_pk_mul_f32 v[20:21], v[20:21], v[34:35] op_sel_hi:[1,0]
	v_max_f32_e32 v16, 0, v16
	v_cvt_pk_bf16_f32 v27, v30, v27
	global_store_dwordx4 v[28:29], v[24:27], off nt
	v_max_f32_e32 v20, 0, v20
	v_mul_f32_e32 v20, v20, v20
	v_mul_f32_e32 v24, v16, v16
	v_max_f32_e32 v16, 0, v21
	v_mul_f32_e32 v16, v16, v16
	v_cvt_pk_bf16_f32 v16, v20, v16
	v_mul_f32_e32 v20, 0x4b800000, v147
	v_cmp_gt_f32_e32 vcc, s57, v147
	v_pk_mul_f32 v[18:19], v[18:19], v[34:35] op_sel_hi:[1,0]
	v_pk_mul_f32 v[22:23], v[22:23], v[34:35] op_sel_hi:[1,0]
	v_cndmask_b32_e32 v20, v147, v20, vcc
	v_max_f32_e32 v17, 0, v17
	v_max_f32_e32 v18, 0, v18
	v_rsq_f32_e32 v20, v20
	v_mul_f32_e32 v21, v17, v17
	v_max_f32_e32 v17, 0, v22
	v_mul_f32_e32 v22, v18, v18
	v_max_f32_e32 v18, 0, v23
	v_mul_f32_e32 v17, v17, v17
	v_max_f32_e32 v19, 0, v19
	v_mul_f32_e32 v18, v18, v18
	v_lshl_add_u64 v[32:33], v[144:145], 0, s[20:21]
	v_mul_f32_e32 v19, v19, v19
	v_cvt_pk_bf16_f32 v17, v17, v18
	v_cvt_pk_bf16_f32 v18, v24, v21
	v_cvt_pk_bf16_f32 v19, v22, v19
	global_store_dwordx4 v[32:33], v[16:19], off offset:256 nt
	s_nop 1
	v_mul_f32_e32 v18, 0x45800000, v20
	v_cndmask_b32_e32 v18, v20, v18, vcc
	v_pk_mul_f32 v[8:9], v[8:9], v[18:19] op_sel_hi:[1,0]
	v_pk_mul_f32 v[12:13], v[12:13], v[18:19] op_sel_hi:[1,0]
	v_pk_mul_f32 v[10:11], v[10:11], v[18:19] op_sel_hi:[1,0]
	v_max_f32_e32 v8, 0, v8
	v_pk_mul_f32 v[14:15], v[14:15], v[18:19] op_sel_hi:[1,0]
	v_max_f32_e32 v12, 0, v12
	v_mul_f32_e32 v19, v8, v8
	v_max_f32_e32 v8, 0, v13
	v_max_f32_e32 v9, 0, v9
	v_max_f32_e32 v10, 0, v10
	v_mul_f32_e32 v12, v12, v12
	v_mul_f32_e32 v8, v8, v8
	v_mul_f32_e32 v13, v9, v9
	v_max_f32_e32 v9, 0, v14
	v_mul_f32_e32 v14, v10, v10
	v_max_f32_e32 v10, 0, v15
	v_mul_f32_e32 v9, v9, v9
	v_max_f32_e32 v11, 0, v11
	v_mul_f32_e32 v10, v10, v10
	v_cvt_pk_bf16_f32 v8, v12, v8
	v_add_co_u32_e32 v12, vcc, s61, v144
	v_pk_mul_f32 v[2:3], v[2:3], v[18:19] op_sel_hi:[1,0]
	v_pk_mul_f32 v[0:1], v[0:1], v[18:19] op_sel_hi:[1,0]
	v_mul_f32_e32 v11, v11, v11
	v_cvt_pk_bf16_f32 v9, v9, v10
	v_cvt_pk_bf16_f32 v10, v19, v13
	v_addc_co_u32_e32 v13, vcc, 0, v145, vcc
	v_pk_mul_f32 v[6:7], v[6:7], v[18:19] op_sel_hi:[1,0]
	v_pk_mul_f32 v[4:5], v[4:5], v[18:19] op_sel_hi:[1,0]
	v_max_f32_e32 v0, 0, v0
	v_max_f32_e32 v1, 0, v1
	v_max_f32_e32 v2, 0, v2
	v_cvt_pk_bf16_f32 v11, v14, v11
	global_store_dwordx4 v[12:13], v[8:11], off nt
	v_max_f32_e32 v3, 0, v3
	v_lshl_add_u64 v[16:17], v[144:145], 0, s[22:23]
	v_mul_f32_e32 v8, v0, v0
	v_max_f32_e32 v0, 0, v5
	v_mul_f32_e32 v5, v1, v1
	v_max_f32_e32 v1, 0, v6
	v_mul_f32_e32 v6, v2, v2
	v_max_f32_e32 v2, 0, v7
	v_max_f32_e32 v4, 0, v4
	v_mul_f32_e32 v0, v0, v0
	v_mul_f32_e32 v1, v1, v1
	v_mul_f32_e32 v2, v2, v2
	v_mul_f32_e32 v3, v3, v3
	s_and_b64 vcc, exec, s[6:7]
	v_mul_f32_e32 v4, v4, v4
	v_cvt_pk_bf16_f32 v0, v4, v0
	v_cvt_pk_bf16_f32 v1, v1, v2
	v_cvt_pk_bf16_f32 v2, v8, v5
	v_cvt_pk_bf16_f32 v3, v6, v3
	global_store_dwordx4 v[16:17], v[0:3], off offset:256 nt
	s_cbranch_vccz .LBB0_843
	s_waitcnt vmcnt(0)
	s_cmpk_gt_u32 s33, 0xff
	s_cbranch_scc1 .LBB0_854
	s_barrier

.LBB0_896:
	ds_read_b128 v[144:147], v178
	ds_read_b128 v[148:151], v178 offset:1024
	ds_read_b128 v[152:155], v178 offset:2048
	ds_read_b128 v[156:159], v178 offset:3072
	s_add_u32 s42, s40, 0xfff00080
	s_addc_u32 s43, s41, -1
	s_cmp_eq_u32 s65, 60
	s_cselect_b32 s49, s29, s43
	s_cselect_b32 s48, s37, s42
	s_cselect_b32 s43, s27, s64
	s_cselect_b32 s42, s62, s63
	v_lshl_add_u64 v[172:173], s[40:41], 0, v[136:137]
	s_add_i32 m0, s39, 0xc000
	ds_read_b128 v[160:163], v179
	ds_read_b128 v[164:167], v179 offset:1024
	ds_read_b128 v[168:171], v179 offset:2048
	ds_read_b128 v[182:185], v179 offset:3072
	ds_read_b128 v[186:189], v179 offset:4096
	ds_read_b128 v[190:193], v179 offset:5120
	ds_read_b128 v[194:197], v179 offset:6144
	ds_read_b128 v[198:201], v179 offset:7168
	global_load_lds_dwordx4 v[172:173], off
	v_lshl_add_u64 v[172:173], s[40:41], 0, v[138:139]
	s_add_i32 m0, s39, 0xe000
	s_nop 0
	global_load_lds_dwordx4 v[172:173], off
	s_waitcnt lgkmcnt(8)
	s_barrier
	s_waitcnt lgkmcnt(0)
	s_setprio 1
	v_mfma_f32_16x16x32_bf16 v[124:127], v[144:147], v[160:163], v[124:127]
	v_mfma_f32_16x16x32_bf16 v[120:123], v[152:155], v[160:163], v[120:123]
	v_mfma_f32_16x16x32_bf16 v[108:111], v[144:147], v[168:171], v[108:111]
	v_mfma_f32_16x16x32_bf16 v[104:107], v[152:155], v[168:171], v[104:107]
	v_mfma_f32_16x16x32_bf16 v[96:99], v[144:147], v[186:189], v[96:99]
	v_mfma_f32_16x16x32_bf16 v[88:91], v[152:155], v[186:189], v[88:91]
	v_mfma_f32_16x16x32_bf16 v[80:83], v[144:147], v[194:197], v[80:83]
	v_mfma_f32_16x16x32_bf16 v[72:75], v[152:155], v[194:197], v[72:75]
	v_mfma_f32_16x16x32_bf16 v[124:127], v[148:151], v[164:167], v[124:127]
	v_mfma_f32_16x16x32_bf16 v[120:123], v[156:159], v[164:167], v[120:123]
	v_mfma_f32_16x16x32_bf16 v[108:111], v[148:151], v[182:185], v[108:111]
	v_mfma_f32_16x16x32_bf16 v[104:107], v[156:159], v[182:185], v[104:107]
	v_mfma_f32_16x16x32_bf16 v[96:99], v[148:151], v[190:193], v[96:99]
	v_mfma_f32_16x16x32_bf16 v[88:91], v[156:159], v[190:193], v[88:91]
	v_mfma_f32_16x16x32_bf16 v[80:83], v[148:151], v[198:201], v[80:83]
	v_mfma_f32_16x16x32_bf16 v[72:75], v[156:159], v[198:201], v[72:75]
	s_setprio 0
	s_barrier
	s_add_i32 s66, s60, s50
	v_lshl_add_u64 v[172:173], s[42:43], 0, v[130:131]
	s_mov_b32 m0, s66
	ds_read_b128 v[202:205], v180
	ds_read_b128 v[206:209], v180 offset:1024
	ds_read_b128 v[212:215], v180 offset:2048
	ds_read_b128 v[216:219], v180 offset:3072
	global_load_lds_dwordx4 v[172:173], off
	v_lshl_add_u64 v[220:221], s[42:43], 0, v[134:135]
	s_add_i32 m0, s66, 0x2000
	s_nop 0
	global_load_lds_dwordx4 v[220:221], off
	s_barrier
	s_waitcnt lgkmcnt(0)
	s_setprio 1
	v_mfma_f32_16x16x32_bf16 v[116:119], v[202:205], v[160:163], v[116:119]
	v_mfma_f32_16x16x32_bf16 v[112:115], v[212:215], v[160:163], v[112:115]
	v_mfma_f32_16x16x32_bf16 v[100:103], v[202:205], v[168:171], v[100:103]
	v_mfma_f32_16x16x32_bf16 v[92:95], v[212:215], v[168:171], v[92:95]
	v_mfma_f32_16x16x32_bf16 v[84:87], v[202:205], v[186:189], v[84:87]
	v_mfma_f32_16x16x32_bf16 v[76:79], v[212:215], v[186:189], v[76:79]
	v_mfma_f32_16x16x32_bf16 v[68:71], v[202:205], v[194:197], v[68:71]
	v_mfma_f32_16x16x32_bf16 v[64:67], v[212:215], v[194:197], v[64:67]
	v_mfma_f32_16x16x32_bf16 v[116:119], v[206:209], v[164:167], v[116:119]
	v_mfma_f32_16x16x32_bf16 v[112:115], v[216:219], v[164:167], v[112:115]
	v_mfma_f32_16x16x32_bf16 v[100:103], v[206:209], v[182:185], v[100:103]
	v_mfma_f32_16x16x32_bf16 v[92:95], v[216:219], v[182:185], v[92:95]
	v_mfma_f32_16x16x32_bf16 v[84:87], v[206:209], v[190:193], v[84:87]
	v_mfma_f32_16x16x32_bf16 v[76:79], v[216:219], v[190:193], v[76:79]
	v_mfma_f32_16x16x32_bf16 v[68:71], v[206:209], v[198:201], v[68:71]
	v_mfma_f32_16x16x32_bf16 v[64:67], v[216:219], v[198:201], v[64:67]
	s_setprio 0
	s_mov_b32 m0, s39
	v_lshl_add_u64 v[222:223], s[48:49], 0, v[128:129]
	s_barrier
	ds_read_b128 v[160:163], v179 offset:16384
	ds_read_b128 v[164:167], v179 offset:17408
	ds_read_b128 v[168:171], v179 offset:18432
	ds_read_b128 v[182:185], v179 offset:19456
	ds_read_b128 v[186:189], v179 offset:20480
	ds_read_b128 v[190:193], v179 offset:21504
	ds_read_b128 v[194:197], v179 offset:22528
	ds_read_b128 v[198:201], v179 offset:23552
	global_load_lds_dwordx4 v[222:223], off
	v_lshl_add_u64 v[224:225], s[48:49], 0, v[132:133]
	s_mov_b32 m0, s51
	s_nop 0
	global_load_lds_dwordx4 v[224:225], off
	s_barrier
	s_waitcnt lgkmcnt(0)
	s_setprio 1
	v_mfma_f32_16x16x32_bf16 v[60:63], v[144:147], v[160:163], v[60:63]
	v_mfma_f32_16x16x32_bf16 v[56:59], v[152:155], v[160:163], v[56:59]
	v_mfma_f32_16x16x32_bf16 v[44:47], v[144:147], v[168:171], v[44:47]
	v_mfma_f32_16x16x32_bf16 v[40:43], v[152:155], v[168:171], v[40:43]
	v_mfma_f32_16x16x32_bf16 v[32:35], v[144:147], v[186:189], v[32:35]
	v_mfma_f32_16x16x32_bf16 v[24:27], v[152:155], v[186:189], v[24:27]
	v_mfma_f32_16x16x32_bf16 v[16:19], v[144:147], v[194:197], v[16:19]
	v_mfma_f32_16x16x32_bf16 v[8:11], v[152:155], v[194:197], v[8:11]
	v_mfma_f32_16x16x32_bf16 v[60:63], v[148:151], v[164:167], v[60:63]
	v_mfma_f32_16x16x32_bf16 v[56:59], v[156:159], v[164:167], v[56:59]
	v_mfma_f32_16x16x32_bf16 v[44:47], v[148:151], v[182:185], v[44:47]
	v_mfma_f32_16x16x32_bf16 v[40:43], v[156:159], v[182:185], v[40:43]
	v_mfma_f32_16x16x32_bf16 v[32:35], v[148:151], v[190:193], v[32:35]
	v_mfma_f32_16x16x32_bf16 v[24:27], v[156:159], v[190:193], v[24:27]
	v_mfma_f32_16x16x32_bf16 v[16:19], v[148:151], v[198:201], v[16:19]
	v_mfma_f32_16x16x32_bf16 v[8:11], v[156:159], v[198:201], v[8:11]
	s_setprio 0
	s_barrier
	s_add_u32 s66, s42, 0x100000
	s_addc_u32 s67, s43, 0
	s_add_i32 s68, s61, s50
	v_lshl_add_u64 v[144:145], s[66:67], 0, v[130:131]
	s_mov_b32 m0, s68
	s_nop 0
	global_load_lds_dwordx4 v[144:145], off
	v_lshl_add_u64 v[144:145], s[66:67], 0, v[134:135]
	s_add_i32 m0, s68, 0x2000
	s_nop 0
	global_load_lds_dwordx4 v[144:145], off
	s_waitcnt vmcnt(6)
	s_barrier
	s_setprio 1
	v_mfma_f32_16x16x32_bf16 v[52:55], v[202:205], v[160:163], v[52:55]
	v_mfma_f32_16x16x32_bf16 v[48:51], v[212:215], v[160:163], v[48:51]
	v_mfma_f32_16x16x32_bf16 v[36:39], v[202:205], v[168:171], v[36:39]
	v_mfma_f32_16x16x32_bf16 v[28:31], v[212:215], v[168:171], v[28:31]
	v_mfma_f32_16x16x32_bf16 v[20:23], v[202:205], v[186:189], v[20:23]
	v_mfma_f32_16x16x32_bf16 v[12:15], v[212:215], v[186:189], v[12:15]
	v_mfma_f32_16x16x32_bf16 v[4:7], v[202:205], v[194:197], v[4:7]
	v_mfma_f32_16x16x32_bf16 v[0:3], v[212:215], v[194:197], v[0:3]
	v_mfma_f32_16x16x32_bf16 v[52:55], v[206:209], v[164:167], v[52:55]
	v_mfma_f32_16x16x32_bf16 v[48:51], v[216:219], v[164:167], v[48:51]
	v_mfma_f32_16x16x32_bf16 v[36:39], v[206:209], v[182:185], v[36:39]
	v_mfma_f32_16x16x32_bf16 v[28:31], v[216:219], v[182:185], v[28:31]
	v_mfma_f32_16x16x32_bf16 v[20:23], v[206:209], v[190:193], v[20:23]
	v_mfma_f32_16x16x32_bf16 v[12:15], v[216:219], v[190:193], v[12:15]
	v_mfma_f32_16x16x32_bf16 v[4:7], v[206:209], v[198:201], v[4:7]
	v_mfma_f32_16x16x32_bf16 v[0:3], v[216:219], v[198:201], v[0:3]
	s_setprio 0
	s_add_i32 s66, 0, 0x18000
	v_add_u32_e32 v156, s66, v176
	s_barrier
	ds_read_b128 v[144:147], v156
	ds_read_b128 v[148:151], v156 offset:1024
	ds_read_b128 v[152:155], v156 offset:2048
	ds_read_b128 v[156:159], v156 offset:3072
	s_add_u32 s48, s48, 0x100000
	s_addc_u32 s49, s49, 0
	s_mov_b32 m0, s52
	v_lshl_add_u64 v[202:203], s[48:49], 0, v[128:129]
	ds_read_b128 v[160:163], v179 offset:32768
	ds_read_b128 v[164:167], v179 offset:33792
	ds_read_b128 v[168:171], v179 offset:34816
	ds_read_b128 v[182:185], v179 offset:35840
	ds_read_b128 v[186:189], v179 offset:36864
	ds_read_b128 v[190:193], v179 offset:37888
	ds_read_b128 v[194:197], v179 offset:38912
	ds_read_b128 v[198:201], v179 offset:39936
	global_load_lds_dwordx4 v[202:203], off
	v_lshl_add_u64 v[202:203], s[48:49], 0, v[132:133]
	s_mov_b32 m0, s53
	s_nop 0
	global_load_lds_dwordx4 v[202:203], off
	s_waitcnt lgkmcnt(8)
	s_barrier
	s_waitcnt lgkmcnt(0)
	s_setprio 1
	v_mfma_f32_16x16x32_bf16 v[124:127], v[144:147], v[160:163], v[124:127]
	v_mfma_f32_16x16x32_bf16 v[120:123], v[152:155], v[160:163], v[120:123]
	v_mfma_f32_16x16x32_bf16 v[108:111], v[144:147], v[168:171], v[108:111]
	v_mfma_f32_16x16x32_bf16 v[104:107], v[152:155], v[168:171], v[104:107]
	v_mfma_f32_16x16x32_bf16 v[96:99], v[144:147], v[186:189], v[96:99]
	v_mfma_f32_16x16x32_bf16 v[88:91], v[152:155], v[186:189], v[88:91]
	v_mfma_f32_16x16x32_bf16 v[80:83], v[144:147], v[194:197], v[80:83]
	v_mfma_f32_16x16x32_bf16 v[72:75], v[152:155], v[194:197], v[72:75]
	v_mfma_f32_16x16x32_bf16 v[124:127], v[148:151], v[164:167], v[124:127]
	v_mfma_f32_16x16x32_bf16 v[120:123], v[156:159], v[164:167], v[120:123]
	v_mfma_f32_16x16x32_bf16 v[108:111], v[148:151], v[182:185], v[108:111]
	v_mfma_f32_16x16x32_bf16 v[104:107], v[156:159], v[182:185], v[104:107]
	v_mfma_f32_16x16x32_bf16 v[96:99], v[148:151], v[190:193], v[96:99]
	v_mfma_f32_16x16x32_bf16 v[88:91], v[156:159], v[190:193], v[88:91]
	v_mfma_f32_16x16x32_bf16 v[80:83], v[148:151], v[198:201], v[80:83]
	v_mfma_f32_16x16x32_bf16 v[72:75], v[156:159], v[198:201], v[72:75]
	s_setprio 0
	s_barrier
	s_add_i32 s48, 0, 0x1c000
	s_add_i32 s49, s66, s50
	v_add_u32_e32 v181, s48, v176
	v_lshl_add_u64 v[172:173], v[172:173], 0, s[0:1]
	s_mov_b32 m0, s49
	ds_read_b128 v[202:205], v181
	ds_read_b128 v[206:209], v181 offset:1024
	ds_read_b128 v[212:215], v181 offset:2048
	ds_read_b128 v[216:219], v181 offset:3072
	global_load_lds_dwordx4 v[172:173], off
	v_lshl_add_u64 v[172:173], v[220:221], 0, s[0:1]
	s_add_i32 m0, s49, 0x2000
	s_nop 0
	global_load_lds_dwordx4 v[172:173], off
	s_barrier
	s_waitcnt lgkmcnt(0)
	s_setprio 1
	v_mfma_f32_16x16x32_bf16 v[116:119], v[202:205], v[160:163], v[116:119]
	v_mfma_f32_16x16x32_bf16 v[112:115], v[212:215], v[160:163], v[112:115]
	v_mfma_f32_16x16x32_bf16 v[100:103], v[202:205], v[168:171], v[100:103]
	v_mfma_f32_16x16x32_bf16 v[92:95], v[212:215], v[168:171], v[92:95]
	v_mfma_f32_16x16x32_bf16 v[84:87], v[202:205], v[186:189], v[84:87]
	v_mfma_f32_16x16x32_bf16 v[76:79], v[212:215], v[186:189], v[76:79]
	v_mfma_f32_16x16x32_bf16 v[68:71], v[202:205], v[194:197], v[68:71]
	v_mfma_f32_16x16x32_bf16 v[64:67], v[212:215], v[194:197], v[64:67]
	v_mfma_f32_16x16x32_bf16 v[116:119], v[206:209], v[164:167], v[116:119]
	v_mfma_f32_16x16x32_bf16 v[112:115], v[216:219], v[164:167], v[112:115]
	v_mfma_f32_16x16x32_bf16 v[100:103], v[206:209], v[182:185], v[100:103]
	v_mfma_f32_16x16x32_bf16 v[92:95], v[216:219], v[182:185], v[92:95]
	v_mfma_f32_16x16x32_bf16 v[84:87], v[206:209], v[190:193], v[84:87]
	v_mfma_f32_16x16x32_bf16 v[76:79], v[216:219], v[190:193], v[76:79]
	v_mfma_f32_16x16x32_bf16 v[68:71], v[206:209], v[198:201], v[68:71]
	v_mfma_f32_16x16x32_bf16 v[64:67], v[216:219], v[198:201], v[64:67]
	s_setprio 0
	s_mov_b32 m0, s55
	v_lshl_add_u64 v[172:173], v[222:223], 0, s[0:1]
	s_barrier
	ds_read_b128 v[160:163], v179 offset:49152
	ds_read_b128 v[164:167], v179 offset:50176
	ds_read_b128 v[168:171], v179 offset:51200
	ds_read_b128 v[182:185], v179 offset:52224
	ds_read_b128 v[186:189], v179 offset:53248
	ds_read_b128 v[190:193], v179 offset:54272
	ds_read_b128 v[194:197], v179 offset:55296
	ds_read_b128 v[198:201], v179 offset:56320
	global_load_lds_dwordx4 v[172:173], off
	v_lshl_add_u64 v[172:173], v[224:225], 0, s[0:1]
	s_mov_b32 m0, s56
	s_nop 0
	global_load_lds_dwordx4 v[172:173], off
	s_barrier
	s_waitcnt lgkmcnt(0)
	s_setprio 1
	v_mfma_f32_16x16x32_bf16 v[60:63], v[144:147], v[160:163], v[60:63]
	v_mfma_f32_16x16x32_bf16 v[56:59], v[152:155], v[160:163], v[56:59]
	v_mfma_f32_16x16x32_bf16 v[44:47], v[144:147], v[168:171], v[44:47]
	v_mfma_f32_16x16x32_bf16 v[40:43], v[152:155], v[168:171], v[40:43]
	v_mfma_f32_16x16x32_bf16 v[32:35], v[144:147], v[186:189], v[32:35]
	v_mfma_f32_16x16x32_bf16 v[24:27], v[152:155], v[186:189], v[24:27]
	v_mfma_f32_16x16x32_bf16 v[16:19], v[144:147], v[194:197], v[16:19]
	v_mfma_f32_16x16x32_bf16 v[8:11], v[152:155], v[194:197], v[8:11]
	v_mfma_f32_16x16x32_bf16 v[60:63], v[148:151], v[164:167], v[60:63]
	v_mfma_f32_16x16x32_bf16 v[56:59], v[156:159], v[164:167], v[56:59]
	v_mfma_f32_16x16x32_bf16 v[44:47], v[148:151], v[182:185], v[44:47]
	v_mfma_f32_16x16x32_bf16 v[40:43], v[156:159], v[182:185], v[40:43]
	v_mfma_f32_16x16x32_bf16 v[32:35], v[148:151], v[190:193], v[32:35]
	v_mfma_f32_16x16x32_bf16 v[24:27], v[156:159], v[190:193], v[24:27]
	v_mfma_f32_16x16x32_bf16 v[16:19], v[148:151], v[198:201], v[16:19]
	v_mfma_f32_16x16x32_bf16 v[8:11], v[156:159], v[198:201], v[8:11]
	s_setprio 0
	s_barrier
	s_add_u32 s42, s42, 0x100080
	s_addc_u32 s43, s43, 0
	s_add_i32 s48, s48, s50
	v_lshl_add_u64 v[144:145], s[42:43], 0, v[130:131]
	s_mov_b32 m0, s48
	s_nop 0
	global_load_lds_dwordx4 v[144:145], off
	v_lshl_add_u64 v[144:145], s[42:43], 0, v[134:135]
	s_add_i32 m0, s48, 0x2000
	s_nop 0
	global_load_lds_dwordx4 v[144:145], off
	s_waitcnt vmcnt(6)
	s_barrier
	s_setprio 1
	v_mfma_f32_16x16x32_bf16 v[52:55], v[202:205], v[160:163], v[52:55]
	v_mfma_f32_16x16x32_bf16 v[48:51], v[212:215], v[160:163], v[48:51]
	v_mfma_f32_16x16x32_bf16 v[36:39], v[202:205], v[168:171], v[36:39]
	v_mfma_f32_16x16x32_bf16 v[28:31], v[212:215], v[168:171], v[28:31]
	v_mfma_f32_16x16x32_bf16 v[20:23], v[202:205], v[186:189], v[20:23]
	v_mfma_f32_16x16x32_bf16 v[12:15], v[212:215], v[186:189], v[12:15]
	v_mfma_f32_16x16x32_bf16 v[4:7], v[202:205], v[194:197], v[4:7]
	v_mfma_f32_16x16x32_bf16 v[0:3], v[212:215], v[194:197], v[0:3]
	v_mfma_f32_16x16x32_bf16 v[52:55], v[206:209], v[164:167], v[52:55]
	v_mfma_f32_16x16x32_bf16 v[48:51], v[216:219], v[164:167], v[48:51]
	v_mfma_f32_16x16x32_bf16 v[36:39], v[206:209], v[182:185], v[36:39]
	v_mfma_f32_16x16x32_bf16 v[28:31], v[216:219], v[182:185], v[28:31]
	v_mfma_f32_16x16x32_bf16 v[20:23], v[206:209], v[190:193], v[20:23]
	v_mfma_f32_16x16x32_bf16 v[12:15], v[216:219], v[190:193], v[12:15]
	v_mfma_f32_16x16x32_bf16 v[4:7], v[206:209], v[198:201], v[4:7]
	v_mfma_f32_16x16x32_bf16 v[0:3], v[216:219], v[198:201], v[0:3]
	s_setprio 0
	s_add_i32 s65, s65, 2
	s_add_u32 s40, s40, 0x100
	s_addc_u32 s41, s41, 0
	s_add_u32 s63, s63, 0x100
	s_addc_u32 s64, s64, 0
	s_cmp_gt_u32 s65, 61
	s_barrier
	s_cbranch_scc0 .LBB0_896
	v_lshl_or_b32 v144, s38, 8, v177
	v_lshl_add_u32 v150, s36, 8, v175
	v_ashrrev_i32_e32 v145, 31, v144
	v_ashrrev_i32_e32 v151, 31, v150
	v_lshlrev_b64 v[144:145], 1, v[144:145]
	v_lshl_add_u64 v[146:147], s[90:91], 0, v[144:145]
	v_lshlrev_b64 v[148:149], 11, v[150:151]
	v_lshl_add_u64 v[152:153], v[146:147], 0, v[148:149]
	global_load_dwordx4 v[156:159], v[152:153], off
	global_load_dwordx4 v[160:163], v[152:153], off offset:256
	v_or_b32_e32 v152, 16, v150
	v_ashrrev_i32_e32 v153, 31, v152
	v_lshlrev_b64 v[170:171], 11, v[152:153]
	v_lshl_add_u64 v[152:153], v[146:147], 0, v[170:171]
	global_load_dwordx4 v[164:167], v[152:153], off
	global_load_dwordx4 v[182:185], v[152:153], off offset:256
	v_or_b32_e32 v152, 32, v150
	v_ashrrev_i32_e32 v153, 31, v152
	v_lshlrev_b64 v[154:155], 11, v[152:153]
	v_lshl_add_u64 v[152:153], v[146:147], 0, v[154:155]
	global_load_dwordx4 v[186:189], v[152:153], off
	global_load_dwordx4 v[190:193], v[152:153], off offset:256
	v_or_b32_e32 v152, 48, v150
	v_ashrrev_i32_e32 v153, 31, v152
	v_lshlrev_b64 v[152:153], 11, v[152:153]
	v_lshl_add_u64 v[168:169], v[146:147], 0, v[152:153]
	global_load_dwordx4 v[194:197], v[168:169], off
	global_load_dwordx4 v[198:201], v[168:169], off offset:256
	s_waitcnt vmcnt(0)
	v_lshlrev_b32_e32 v202, 16, v156
	v_and_b32_e32 v203, 0xffff0000, v156
	v_lshlrev_b32_e32 v204, 16, v157
	v_and_b32_e32 v205, 0xffff0000, v157
	v_lshlrev_b32_e32 v206, 16, v158
	v_and_b32_e32 v207, 0xffff0000, v158
	v_lshlrev_b32_e32 v208, 16, v159
	v_and_b32_e32 v209, 0xffff0000, v159
	v_pk_add_f32 v[126:127], v[126:127], v[204:205]
	v_pk_add_f32 v[124:125], v[124:125], v[202:203]
	v_lshlrev_b32_e32 v224, 16, v166
	v_and_b32_e32 v225, 0xffff0000, v166
	v_lshlrev_b32_e32 v226, 16, v167
	v_and_b32_e32 v227, 0xffff0000, v167
	v_lshlrev_b32_e32 v212, 16, v160
	v_lshlrev_b32_e32 v166, 16, v194
	v_and_b32_e32 v167, 0xffff0000, v194
	v_lshlrev_b32_e32 v172, 16, v195
	v_and_b32_e32 v173, 0xffff0000, v195
	v_pk_add_f32 v[194:195], v[122:123], v[208:209]
	v_pk_add_f32 v[122:123], v[120:121], v[206:207]
	v_mul_f32_e32 v120, v125, v125
	v_mul_f32_e32 v121, v127, v127
	v_fmac_f32_e32 v120, v124, v124
	v_fmac_f32_e32 v121, v126, v126
	v_add_f32_e32 v120, v120, v121
	v_mul_f32_e32 v121, v123, v123
	v_fmac_f32_e32 v121, v122, v122
	v_add_f32_e32 v120, v121, v120
	v_mul_f32_e32 v121, v195, v195
	v_fmac_f32_e32 v121, v194, v194
	v_and_b32_e32 v213, 0xffff0000, v160
	v_lshlrev_b32_e32 v214, 16, v161
	v_and_b32_e32 v215, 0xffff0000, v161
	v_add_f32_e32 v181, v121, v120
	v_cvt_pk_bf16_f32 v120, v124, v125
	v_lshl_add_u64 v[124:125], s[10:11], 0, v[148:149]
	v_lshlrev_b32_e32 v216, 16, v162
	v_and_b32_e32 v217, 0xffff0000, v162
	v_lshlrev_b32_e32 v218, 16, v163
	v_and_b32_e32 v219, 0xffff0000, v163
	v_cvt_pk_bf16_f32 v121, v126, v127
	v_lshl_add_u64 v[124:125], v[124:125], 0, v[144:145]
	v_pk_add_f32 v[118:119], v[118:119], v[214:215]
	v_pk_add_f32 v[116:117], v[116:117], v[212:213]
	v_cvt_pk_bf16_f32 v122, v122, v123
	v_cvt_pk_bf16_f32 v123, v194, v195
	global_store_dwordx4 v[124:125], v[120:123], off
	v_lshlrev_b32_e32 v220, 16, v164
	v_and_b32_e32 v221, 0xffff0000, v164
	v_pk_add_f32 v[120:121], v[114:115], v[218:219]
	v_pk_add_f32 v[114:115], v[112:113], v[216:217]
	v_mul_f32_e32 v112, v117, v117
	v_mul_f32_e32 v113, v119, v119
	v_fmac_f32_e32 v112, v116, v116
	v_fmac_f32_e32 v113, v118, v118
	v_add_f32_e32 v112, v112, v113
	v_mul_f32_e32 v113, v115, v115
	v_fmac_f32_e32 v113, v114, v114
	v_add_f32_e32 v112, v113, v112
	v_mul_f32_e32 v113, v121, v121
	v_fmac_f32_e32 v113, v120, v120
	v_add_f32_e32 v112, v113, v112
	v_lshlrev_b32_e32 v222, 16, v165
	v_and_b32_e32 v223, 0xffff0000, v165
	v_add_f32_e32 v126, v181, v112
	v_cvt_pk_bf16_f32 v112, v116, v117
	v_cvt_pk_bf16_f32 v113, v118, v119
	v_lshl_add_u64 v[116:117], s[10:11], 0, v[170:171]
	v_lshlrev_b32_e32 v230, 16, v184
	v_and_b32_e32 v231, 0xffff0000, v184
	v_lshlrev_b32_e32 v232, 16, v186
	v_and_b32_e32 v233, 0xffff0000, v186
	v_lshlrev_b32_e32 v186, 16, v187
	v_and_b32_e32 v187, 0xffff0000, v187
	v_cvt_pk_bf16_f32 v114, v114, v115
	v_cvt_pk_bf16_f32 v115, v120, v121
	global_store_dwordx4 v[124:125], v[112:115], off offset:256
	v_pk_add_f32 v[110:111], v[110:111], v[222:223]
	v_pk_add_f32 v[108:109], v[108:109], v[220:221]
	v_lshl_add_u64 v[118:119], v[116:117], 0, v[144:145]
	v_cvt_pk_bf16_f32 v112, v108, v109
	v_cvt_pk_bf16_f32 v113, v110, v111
	v_lshlrev_b32_e32 v228, 16, v182
	v_and_b32_e32 v229, 0xffff0000, v182
	v_lshlrev_b32_e32 v182, 16, v183
	v_and_b32_e32 v183, 0xffff0000, v183
	v_lshlrev_b32_e32 v184, 16, v185
	v_and_b32_e32 v185, 0xffff0000, v185
	v_lshlrev_b32_e32 v238, 16, v192
	v_and_b32_e32 v239, 0xffff0000, v192
	v_pk_add_f32 v[106:107], v[106:107], v[226:227]
	v_pk_add_f32 v[104:105], v[104:105], v[224:225]
	v_lshlrev_b32_e32 v156, 16, v200
	v_cvt_pk_bf16_f32 v114, v104, v105
	v_cvt_pk_bf16_f32 v115, v106, v107
	global_store_dwordx4 v[118:119], v[112:115], off
	v_and_b32_e32 v157, 0xffff0000, v200
	v_pk_add_f32 v[102:103], v[102:103], v[182:183]
	v_pk_add_f32 v[112:113], v[92:93], v[230:231]
	v_pk_add_f32 v[92:93], v[98:99], v[186:187]
	v_lshl_add_u64 v[98:99], s[10:11], 0, v[154:155]
	v_pk_add_f32 v[100:101], v[100:101], v[228:229]
	v_pk_add_f32 v[94:95], v[94:95], v[184:185]
	v_cvt_pk_bf16_f32 v114, v100, v101
	v_cvt_pk_bf16_f32 v115, v102, v103
	v_cvt_pk_bf16_f32 v116, v112, v113
	v_lshlrev_b32_e32 v234, 16, v188
	v_cvt_pk_bf16_f32 v117, v94, v95
	global_store_dwordx4 v[118:119], v[114:117], off offset:256
	v_lshl_add_u64 v[118:119], v[98:99], 0, v[144:145]
	v_pk_add_f32 v[98:99], v[76:77], v[238:239]
	v_pk_add_f32 v[76:77], v[82:83], v[172:173]
	v_lshl_add_u64 v[82:83], s[10:11], 0, v[152:153]
	v_lshl_add_u64 v[122:123], v[82:83], 0, v[144:145]
	v_pk_add_f32 v[82:83], v[64:65], v[156:157]
	v_and_b32_e32 v65, 64, v174
	v_and_b32_e32 v235, 0xffff0000, v188
	v_lshlrev_b32_e32 v188, 16, v189
	v_and_b32_e32 v189, 0xffff0000, v189
	v_lshlrev_b32_e32 v236, 16, v190
	v_and_b32_e32 v237, 0xffff0000, v190
	v_pk_add_f32 v[96:97], v[96:97], v[232:233]
	v_xor_b32_e32 v64, 16, v174
	v_cvt_pk_bf16_f32 v114, v96, v97
	v_add_u32_e32 v65, 64, v65
	v_lshlrev_b32_e32 v190, 16, v191
	v_and_b32_e32 v191, 0xffff0000, v191
	v_lshlrev_b32_e32 v192, 16, v193
	v_and_b32_e32 v193, 0xffff0000, v193
	v_pk_add_f32 v[90:91], v[90:91], v[188:189]
	v_pk_add_f32 v[88:89], v[88:89], v[234:235]
	v_cvt_pk_bf16_f32 v115, v92, v93
	v_pk_add_f32 v[84:85], v[84:85], v[236:237]
	v_cvt_pk_bf16_f32 v116, v88, v89
	v_cvt_pk_bf16_f32 v117, v90, v91
	global_store_dwordx4 v[118:119], v[114:117], off
	v_cmp_lt_i32_e32 vcc, v64, v65
	v_lshlrev_b32_e32 v164, 16, v196
	v_cvt_pk_bf16_f32 v114, v84, v85
	v_and_b32_e32 v165, 0xffff0000, v196
	v_lshlrev_b32_e32 v168, 16, v197
	v_and_b32_e32 v169, 0xffff0000, v197
	v_pk_add_f32 v[86:87], v[86:87], v[190:191]
	v_pk_add_f32 v[78:79], v[78:79], v[192:193]
	v_cvt_pk_bf16_f32 v115, v86, v87
	v_cvt_pk_bf16_f32 v116, v98, v99
	v_pk_add_f32 v[80:81], v[80:81], v[166:167]
	v_cvt_pk_bf16_f32 v117, v78, v79
	global_store_dwordx4 v[118:119], v[114:117], off offset:256
	v_cndmask_b32_e32 v64, v174, v64, vcc
	v_pk_add_f32 v[74:75], v[74:75], v[168:169]
	v_cvt_pk_bf16_f32 v114, v80, v81
	v_pk_add_f32 v[72:73], v[72:73], v[164:165]
	v_cvt_pk_bf16_f32 v115, v76, v77
	v_lshlrev_b32_e32 v158, 16, v198
	v_cvt_pk_bf16_f32 v116, v72, v73
	v_cvt_pk_bf16_f32 v117, v74, v75
	global_store_dwordx4 v[122:123], v[114:117], off
	v_and_b32_e32 v159, 0xffff0000, v198
	v_lshlrev_b32_e32 v162, 16, v199
	v_lshlrev_b32_e32 v114, 2, v64
	ds_bpermute_b32 v64, v114, v126
	v_xor_b32_e32 v115, 32, v174
	v_cmp_lt_i32_e32 vcc, v115, v65
	v_and_b32_e32 v163, 0xffff0000, v199
	v_lshlrev_b32_e32 v160, 16, v201
	v_cndmask_b32_e32 v65, v174, v115, vcc
	v_lshlrev_b32_e32 v115, 2, v65
	s_waitcnt lgkmcnt(0)
	v_add_f32_e32 v116, v126, v64
	ds_bpermute_b32 v117, v115, v116
	v_and_b32_e32 v161, 0xffff0000, v201
	v_pk_add_f32 v[70:71], v[70:71], v[162:163]
	v_pk_add_f32 v[68:69], v[68:69], v[158:159]
	v_pk_add_f32 v[66:67], v[66:67], v[160:161]
	v_lshl_add_u64 v[64:65], v[150:151], 2, s[18:19]
	v_cvt_pk_bf16_f32 v118, v68, v69
	v_cvt_pk_bf16_f32 v119, v70, v71
	v_cvt_pk_bf16_f32 v120, v82, v83
	v_cvt_pk_bf16_f32 v121, v66, v67
	global_store_dwordx4 v[122:123], v[118:121], off offset:256
	s_and_saveexec_b64 s[36:37], s[6:7]
	s_cbranch_execz .LBB0_899
	s_waitcnt lgkmcnt(0)
	v_add_f32_e32 v116, v116, v117
	global_atomic_add_f32 v[64:65], v116, off

.LBB0_946:
	ds_read_b128 v[144:147], v153
	ds_read_b128 v[158:161], v153 offset:1024
	ds_read_b128 v[162:165], v153 offset:2048
	ds_read_b128 v[166:169], v153 offset:3072
	s_add_u32 s28, s2, 0xfffc0080
	s_addc_u32 s29, s3, -1
	s_cmp_eq_u32 s58, 12
	s_cselect_b32 s31, s23, s29
	s_cselect_b32 s30, s54, s28
	s_cselect_b32 s29, s21, s57
	s_cselect_b32 s28, s55, s56
	v_lshl_add_u64 v[148:149], s[2:3], 0, v[136:137]
	s_add_i32 m0, s37, 0xc000
	ds_read_b128 v[170:173], v154
	ds_read_b128 v[176:179], v154 offset:1024
	ds_read_b128 v[180:183], v154 offset:2048
	ds_read_b128 v[184:187], v154 offset:3072
	ds_read_b128 v[188:191], v154 offset:4096
	ds_read_b128 v[192:195], v154 offset:5120
	ds_read_b128 v[196:199], v154 offset:6144
	ds_read_b128 v[200:203], v154 offset:7168
	global_load_lds_dwordx4 v[148:149], off
	v_lshl_add_u64 v[148:149], s[2:3], 0, v[138:139]
	s_add_i32 m0, s37, 0xe000
	s_nop 0
	global_load_lds_dwordx4 v[148:149], off
	s_waitcnt lgkmcnt(8)
	s_barrier
	s_waitcnt lgkmcnt(0)
	s_setprio 1
	v_mfma_f32_16x16x32_bf16 v[124:127], v[144:147], v[170:173], v[124:127]
	v_mfma_f32_16x16x32_bf16 v[120:123], v[162:165], v[170:173], v[120:123]
	v_mfma_f32_16x16x32_bf16 v[116:119], v[144:147], v[180:183], v[116:119]
	v_mfma_f32_16x16x32_bf16 v[112:115], v[162:165], v[180:183], v[112:115]
	v_mfma_f32_16x16x32_bf16 v[104:107], v[144:147], v[188:191], v[104:107]
	v_mfma_f32_16x16x32_bf16 v[96:99], v[162:165], v[188:191], v[96:99]
	v_mfma_f32_16x16x32_bf16 v[76:79], v[144:147], v[196:199], v[76:79]
	v_mfma_f32_16x16x32_bf16 v[72:75], v[162:165], v[196:199], v[72:75]
	v_mfma_f32_16x16x32_bf16 v[124:127], v[158:161], v[176:179], v[124:127]
	v_mfma_f32_16x16x32_bf16 v[120:123], v[166:169], v[176:179], v[120:123]
	v_mfma_f32_16x16x32_bf16 v[116:119], v[158:161], v[184:187], v[116:119]
	v_mfma_f32_16x16x32_bf16 v[112:115], v[166:169], v[184:187], v[112:115]
	v_mfma_f32_16x16x32_bf16 v[104:107], v[158:161], v[192:195], v[104:107]
	v_mfma_f32_16x16x32_bf16 v[96:99], v[166:169], v[192:195], v[96:99]
	v_mfma_f32_16x16x32_bf16 v[76:79], v[158:161], v[200:203], v[76:79]
	v_mfma_f32_16x16x32_bf16 v[72:75], v[166:169], v[200:203], v[72:75]
	s_setprio 0
	s_barrier
	s_add_i32 s59, s50, s34
	v_lshl_add_u64 v[148:149], s[28:29], 0, v[132:133]
	s_mov_b32 m0, s59
	ds_read_b128 v[204:207], v155
	ds_read_b128 v[212:215], v155 offset:1024
	ds_read_b128 v[216:219], v155 offset:2048
	ds_read_b128 v[220:223], v155 offset:3072
	global_load_lds_dwordx4 v[148:149], off
	v_lshl_add_u64 v[208:209], s[28:29], 0, v[128:129]
	s_add_i32 m0, s59, 0x2000
	s_nop 0
	global_load_lds_dwordx4 v[208:209], off
	s_barrier
	s_waitcnt lgkmcnt(0)
	s_setprio 1
	v_mfma_f32_16x16x32_bf16 v[108:111], v[204:207], v[170:173], v[108:111]
	v_mfma_f32_16x16x32_bf16 v[100:103], v[216:219], v[170:173], v[100:103]
	v_mfma_f32_16x16x32_bf16 v[92:95], v[204:207], v[180:183], v[92:95]
	v_mfma_f32_16x16x32_bf16 v[88:91], v[216:219], v[180:183], v[88:91]
	v_mfma_f32_16x16x32_bf16 v[84:87], v[204:207], v[188:191], v[84:87]
	v_mfma_f32_16x16x32_bf16 v[80:83], v[216:219], v[188:191], v[80:83]
	v_mfma_f32_16x16x32_bf16 v[68:71], v[204:207], v[196:199], v[68:71]
	v_mfma_f32_16x16x32_bf16 v[64:67], v[216:219], v[196:199], v[64:67]
	v_mfma_f32_16x16x32_bf16 v[108:111], v[212:215], v[176:179], v[108:111]
	v_mfma_f32_16x16x32_bf16 v[100:103], v[220:223], v[176:179], v[100:103]
	v_mfma_f32_16x16x32_bf16 v[92:95], v[212:215], v[184:187], v[92:95]
	v_mfma_f32_16x16x32_bf16 v[88:91], v[220:223], v[184:187], v[88:91]
	v_mfma_f32_16x16x32_bf16 v[84:87], v[212:215], v[192:195], v[84:87]
	v_mfma_f32_16x16x32_bf16 v[80:83], v[220:223], v[192:195], v[80:83]
	v_mfma_f32_16x16x32_bf16 v[68:71], v[212:215], v[200:203], v[68:71]
	v_mfma_f32_16x16x32_bf16 v[64:67], v[220:223], v[200:203], v[64:67]
	s_setprio 0
	s_mov_b32 m0, s37
	v_lshl_add_u64 v[224:225], s[30:31], 0, v[134:135]
	s_barrier
	ds_read_b128 v[170:173], v154 offset:16384
	ds_read_b128 v[176:179], v154 offset:17408
	ds_read_b128 v[180:183], v154 offset:18432
	ds_read_b128 v[184:187], v154 offset:19456
	ds_read_b128 v[188:191], v154 offset:20480
	ds_read_b128 v[192:195], v154 offset:21504
	ds_read_b128 v[196:199], v154 offset:22528
	ds_read_b128 v[200:203], v154 offset:23552
	global_load_lds_dwordx4 v[224:225], off
	v_lshl_add_u64 v[226:227], s[30:31], 0, v[130:131]
	s_mov_b32 m0, s38
	s_nop 0
	global_load_lds_dwordx4 v[226:227], off
	s_barrier
	s_waitcnt lgkmcnt(0)
	s_setprio 1
	v_mfma_f32_16x16x32_bf16 v[60:63], v[144:147], v[170:173], v[60:63]
	v_mfma_f32_16x16x32_bf16 v[56:59], v[162:165], v[170:173], v[56:59]
	v_mfma_f32_16x16x32_bf16 v[44:47], v[144:147], v[180:183], v[44:47]
	v_mfma_f32_16x16x32_bf16 v[40:43], v[162:165], v[180:183], v[40:43]
	v_mfma_f32_16x16x32_bf16 v[28:31], v[144:147], v[188:191], v[28:31]
	v_mfma_f32_16x16x32_bf16 v[24:27], v[162:165], v[188:191], v[24:27]
	v_mfma_f32_16x16x32_bf16 v[12:15], v[144:147], v[196:199], v[12:15]
	v_mfma_f32_16x16x32_bf16 v[8:11], v[162:165], v[196:199], v[8:11]
	v_mfma_f32_16x16x32_bf16 v[60:63], v[158:161], v[176:179], v[60:63]
	v_mfma_f32_16x16x32_bf16 v[56:59], v[166:169], v[176:179], v[56:59]
	v_mfma_f32_16x16x32_bf16 v[44:47], v[158:161], v[184:187], v[44:47]
	v_mfma_f32_16x16x32_bf16 v[40:43], v[166:169], v[184:187], v[40:43]
	v_mfma_f32_16x16x32_bf16 v[28:31], v[158:161], v[192:195], v[28:31]
	v_mfma_f32_16x16x32_bf16 v[24:27], v[166:169], v[192:195], v[24:27]
	v_mfma_f32_16x16x32_bf16 v[12:15], v[158:161], v[200:203], v[12:15]
	v_mfma_f32_16x16x32_bf16 v[8:11], v[166:169], v[200:203], v[8:11]
	s_setprio 0
	s_barrier
	s_add_u32 s60, s28, 0x40000
	s_addc_u32 s61, s29, 0
	s_add_i32 s59, s51, s34
	v_lshl_add_u64 v[144:145], s[60:61], 0, v[132:133]
	s_mov_b32 m0, s59
	s_nop 0
	global_load_lds_dwordx4 v[144:145], off
	v_lshl_add_u64 v[144:145], s[60:61], 0, v[128:129]
	s_add_i32 m0, s59, 0x2000
	s_nop 0
	global_load_lds_dwordx4 v[144:145], off
	s_waitcnt vmcnt(6)
	s_barrier
	s_setprio 1
	v_mfma_f32_16x16x32_bf16 v[52:55], v[204:207], v[170:173], v[52:55]
	v_mfma_f32_16x16x32_bf16 v[48:51], v[216:219], v[170:173], v[48:51]
	v_mfma_f32_16x16x32_bf16 v[36:39], v[204:207], v[180:183], v[36:39]
	v_mfma_f32_16x16x32_bf16 v[32:35], v[216:219], v[180:183], v[32:35]
	v_mfma_f32_16x16x32_bf16 v[20:23], v[204:207], v[188:191], v[20:23]
	v_mfma_f32_16x16x32_bf16 v[16:19], v[216:219], v[188:191], v[16:19]
	v_mfma_f32_16x16x32_bf16 v[4:7], v[204:207], v[196:199], v[4:7]
	v_mfma_f32_16x16x32_bf16 v[0:3], v[216:219], v[196:199], v[0:3]
	v_mfma_f32_16x16x32_bf16 v[52:55], v[212:215], v[176:179], v[52:55]
	v_mfma_f32_16x16x32_bf16 v[48:51], v[220:223], v[176:179], v[48:51]
	v_mfma_f32_16x16x32_bf16 v[36:39], v[212:215], v[184:187], v[36:39]
	v_mfma_f32_16x16x32_bf16 v[32:35], v[220:223], v[184:187], v[32:35]
	v_mfma_f32_16x16x32_bf16 v[20:23], v[212:215], v[192:195], v[20:23]
	v_mfma_f32_16x16x32_bf16 v[16:19], v[220:223], v[192:195], v[16:19]
	v_mfma_f32_16x16x32_bf16 v[4:7], v[212:215], v[200:203], v[4:7]
	v_mfma_f32_16x16x32_bf16 v[0:3], v[220:223], v[200:203], v[0:3]
	s_setprio 0
	s_add_i32 s59, 0, 0x18000
	v_add_u32_e32 v157, s59, v151
	s_barrier
	ds_read_b128 v[144:147], v157
	ds_read_b128 v[158:161], v157 offset:1024
	ds_read_b128 v[162:165], v157 offset:2048
	ds_read_b128 v[166:169], v157 offset:3072
	s_add_u32 s30, s30, 0x40000
	s_addc_u32 s31, s31, 0
	s_mov_b32 m0, s39
	v_lshl_add_u64 v[204:205], s[30:31], 0, v[134:135]
	ds_read_b128 v[170:173], v154 offset:32768
	ds_read_b128 v[176:179], v154 offset:33792
	ds_read_b128 v[180:183], v154 offset:34816
	ds_read_b128 v[184:187], v154 offset:35840
	ds_read_b128 v[188:191], v154 offset:36864
	ds_read_b128 v[192:195], v154 offset:37888
	ds_read_b128 v[196:199], v154 offset:38912
	ds_read_b128 v[200:203], v154 offset:39936
	global_load_lds_dwordx4 v[204:205], off
	v_lshl_add_u64 v[204:205], s[30:31], 0, v[130:131]
	s_mov_b32 m0, s40
	s_nop 0
	global_load_lds_dwordx4 v[204:205], off
	s_waitcnt lgkmcnt(8)
	s_barrier
	s_waitcnt lgkmcnt(0)
	s_setprio 1
	v_mfma_f32_16x16x32_bf16 v[124:127], v[144:147], v[170:173], v[124:127]
	v_mfma_f32_16x16x32_bf16 v[120:123], v[162:165], v[170:173], v[120:123]
	v_mfma_f32_16x16x32_bf16 v[116:119], v[144:147], v[180:183], v[116:119]
	v_mfma_f32_16x16x32_bf16 v[112:115], v[162:165], v[180:183], v[112:115]
	v_mfma_f32_16x16x32_bf16 v[104:107], v[144:147], v[188:191], v[104:107]
	v_mfma_f32_16x16x32_bf16 v[96:99], v[162:165], v[188:191], v[96:99]
	v_mfma_f32_16x16x32_bf16 v[76:79], v[144:147], v[196:199], v[76:79]
	v_mfma_f32_16x16x32_bf16 v[72:75], v[162:165], v[196:199], v[72:75]
	v_mfma_f32_16x16x32_bf16 v[124:127], v[158:161], v[176:179], v[124:127]
	v_mfma_f32_16x16x32_bf16 v[120:123], v[166:169], v[176:179], v[120:123]
	v_mfma_f32_16x16x32_bf16 v[116:119], v[158:161], v[184:187], v[116:119]
	v_mfma_f32_16x16x32_bf16 v[112:115], v[166:169], v[184:187], v[112:115]
	v_mfma_f32_16x16x32_bf16 v[104:107], v[158:161], v[192:195], v[104:107]
	v_mfma_f32_16x16x32_bf16 v[96:99], v[166:169], v[192:195], v[96:99]
	v_mfma_f32_16x16x32_bf16 v[76:79], v[158:161], v[200:203], v[76:79]
	v_mfma_f32_16x16x32_bf16 v[72:75], v[166:169], v[200:203], v[72:75]
	s_setprio 0
	s_barrier
	s_add_i32 s30, 0, 0x1c000
	s_add_i32 s31, s59, s34
	v_add_u32_e32 v157, s30, v151
	v_lshl_add_u64 v[148:149], v[148:149], 0, s[8:9]
	s_mov_b32 m0, s31
	ds_read_b128 v[204:207], v157
	ds_read_b128 v[212:215], v157 offset:1024
	ds_read_b128 v[216:219], v157 offset:2048
	ds_read_b128 v[220:223], v157 offset:3072
	global_load_lds_dwordx4 v[148:149], off
	v_lshl_add_u64 v[148:149], v[208:209], 0, s[8:9]
	s_add_i32 m0, s31, 0x2000
	s_nop 0
	global_load_lds_dwordx4 v[148:149], off
	s_barrier
	s_waitcnt lgkmcnt(0)
	s_setprio 1
	v_mfma_f32_16x16x32_bf16 v[108:111], v[204:207], v[170:173], v[108:111]
	v_mfma_f32_16x16x32_bf16 v[100:103], v[216:219], v[170:173], v[100:103]
	v_mfma_f32_16x16x32_bf16 v[92:95], v[204:207], v[180:183], v[92:95]
	v_mfma_f32_16x16x32_bf16 v[88:91], v[216:219], v[180:183], v[88:91]
	v_mfma_f32_16x16x32_bf16 v[84:87], v[204:207], v[188:191], v[84:87]
	v_mfma_f32_16x16x32_bf16 v[80:83], v[216:219], v[188:191], v[80:83]
	v_mfma_f32_16x16x32_bf16 v[68:71], v[204:207], v[196:199], v[68:71]
	v_mfma_f32_16x16x32_bf16 v[64:67], v[216:219], v[196:199], v[64:67]
	v_mfma_f32_16x16x32_bf16 v[108:111], v[212:215], v[176:179], v[108:111]
	v_mfma_f32_16x16x32_bf16 v[100:103], v[220:223], v[176:179], v[100:103]
	v_mfma_f32_16x16x32_bf16 v[92:95], v[212:215], v[184:187], v[92:95]
	v_mfma_f32_16x16x32_bf16 v[88:91], v[220:223], v[184:187], v[88:91]
	v_mfma_f32_16x16x32_bf16 v[84:87], v[212:215], v[192:195], v[84:87]
	v_mfma_f32_16x16x32_bf16 v[80:83], v[220:223], v[192:195], v[80:83]
	v_mfma_f32_16x16x32_bf16 v[68:71], v[212:215], v[200:203], v[68:71]
	v_mfma_f32_16x16x32_bf16 v[64:67], v[220:223], v[200:203], v[64:67]
	s_setprio 0
	s_mov_b32 m0, s42
	v_lshl_add_u64 v[148:149], v[224:225], 0, s[8:9]
	s_barrier
	ds_read_b128 v[170:173], v154 offset:49152
	ds_read_b128 v[176:179], v154 offset:50176
	ds_read_b128 v[180:183], v154 offset:51200
	ds_read_b128 v[184:187], v154 offset:52224
	ds_read_b128 v[188:191], v154 offset:53248
	ds_read_b128 v[192:195], v154 offset:54272
	ds_read_b128 v[196:199], v154 offset:55296
	ds_read_b128 v[200:203], v154 offset:56320
	global_load_lds_dwordx4 v[148:149], off
	v_lshl_add_u64 v[148:149], v[226:227], 0, s[8:9]
	s_mov_b32 m0, s43
	s_nop 0
	global_load_lds_dwordx4 v[148:149], off
	s_barrier
	s_waitcnt lgkmcnt(0)
	s_setprio 1
	v_mfma_f32_16x16x32_bf16 v[60:63], v[144:147], v[170:173], v[60:63]
	v_mfma_f32_16x16x32_bf16 v[56:59], v[162:165], v[170:173], v[56:59]
	v_mfma_f32_16x16x32_bf16 v[44:47], v[144:147], v[180:183], v[44:47]
	v_mfma_f32_16x16x32_bf16 v[40:43], v[162:165], v[180:183], v[40:43]
	v_mfma_f32_16x16x32_bf16 v[28:31], v[144:147], v[188:191], v[28:31]
	v_mfma_f32_16x16x32_bf16 v[24:27], v[162:165], v[188:191], v[24:27]
	v_mfma_f32_16x16x32_bf16 v[12:15], v[144:147], v[196:199], v[12:15]
	v_mfma_f32_16x16x32_bf16 v[8:11], v[162:165], v[196:199], v[8:11]
	v_mfma_f32_16x16x32_bf16 v[60:63], v[158:161], v[176:179], v[60:63]
	v_mfma_f32_16x16x32_bf16 v[56:59], v[166:169], v[176:179], v[56:59]
	v_mfma_f32_16x16x32_bf16 v[44:47], v[158:161], v[184:187], v[44:47]
	v_mfma_f32_16x16x32_bf16 v[40:43], v[166:169], v[184:187], v[40:43]
	v_mfma_f32_16x16x32_bf16 v[28:31], v[158:161], v[192:195], v[28:31]
	v_mfma_f32_16x16x32_bf16 v[24:27], v[166:169], v[192:195], v[24:27]
	v_mfma_f32_16x16x32_bf16 v[12:15], v[158:161], v[200:203], v[12:15]
	v_mfma_f32_16x16x32_bf16 v[8:11], v[166:169], v[200:203], v[8:11]
	s_setprio 0
	s_barrier
	s_add_u32 s28, s28, 0x40080
	s_addc_u32 s29, s29, 0
	s_add_i32 s30, s30, s34
	v_lshl_add_u64 v[144:145], s[28:29], 0, v[132:133]
	s_mov_b32 m0, s30
	s_nop 0
	global_load_lds_dwordx4 v[144:145], off
	v_lshl_add_u64 v[144:145], s[28:29], 0, v[128:129]
	s_add_i32 m0, s30, 0x2000
	s_nop 0
	global_load_lds_dwordx4 v[144:145], off
	s_waitcnt vmcnt(6)
	s_barrier
	s_setprio 1
	v_mfma_f32_16x16x32_bf16 v[52:55], v[204:207], v[170:173], v[52:55]
	v_mfma_f32_16x16x32_bf16 v[48:51], v[216:219], v[170:173], v[48:51]
	v_mfma_f32_16x16x32_bf16 v[36:39], v[204:207], v[180:183], v[36:39]
	v_mfma_f32_16x16x32_bf16 v[32:35], v[216:219], v[180:183], v[32:35]
	v_mfma_f32_16x16x32_bf16 v[20:23], v[204:207], v[188:191], v[20:23]
	v_mfma_f32_16x16x32_bf16 v[16:19], v[216:219], v[188:191], v[16:19]
	v_mfma_f32_16x16x32_bf16 v[4:7], v[204:207], v[196:199], v[4:7]
	v_mfma_f32_16x16x32_bf16 v[0:3], v[216:219], v[196:199], v[0:3]
	v_mfma_f32_16x16x32_bf16 v[52:55], v[212:215], v[176:179], v[52:55]
	v_mfma_f32_16x16x32_bf16 v[48:51], v[220:223], v[176:179], v[48:51]
	v_mfma_f32_16x16x32_bf16 v[36:39], v[212:215], v[184:187], v[36:39]
	v_mfma_f32_16x16x32_bf16 v[32:35], v[220:223], v[184:187], v[32:35]
	v_mfma_f32_16x16x32_bf16 v[20:23], v[212:215], v[192:195], v[20:23]
	v_mfma_f32_16x16x32_bf16 v[16:19], v[220:223], v[192:195], v[16:19]
	v_mfma_f32_16x16x32_bf16 v[4:7], v[212:215], v[200:203], v[4:7]
	v_mfma_f32_16x16x32_bf16 v[0:3], v[220:223], v[200:203], v[0:3]
	s_setprio 0
	s_add_i32 s58, s58, 2
	s_add_u32 s2, s2, 0x100
	s_addc_u32 s3, s3, 0
	s_add_u32 s56, s56, 0x100
	s_addc_u32 s57, s57, 0
	s_cmp_gt_u32 s58, 13
	s_barrier
	s_cbranch_scc0 .LBB0_946
	v_lshl_add_u32 v144, s0, 8, v150
	v_ashrrev_i32_e32 v145, 31, v144
	v_lshl_add_u64 v[146:147], v[144:145], 2, s[18:19]
	global_load_dword v145, v[146:147], off
	global_load_dword v157, v[146:147], off offset:64
	global_load_dword v164, v[146:147], off offset:128
	global_load_dword v165, v[146:147], off offset:192
	global_load_dword v166, v[146:147], off offset:512
	global_load_dword v167, v[146:147], off offset:576
	global_load_dword v168, v[146:147], off offset:640
	global_load_dword v169, v[146:147], off offset:704
	v_mov_b64_e32 v[146:147], s[92:93]
	v_or_b32_e32 v160, 16, v144
	v_or_b32_e32 v162, 32, v144
	v_lshl_or_b32 v148, s1, 8, v152
	v_mad_i64_i32 v[158:159], s[0:1], v144, s52, v[146:147]
	v_mad_i64_i32 v[160:161], s[0:1], v160, s52, v[146:147]
	v_mad_i64_i32 v[162:163], s[0:1], v162, s52, v[146:147]
	v_ashrrev_i32_e32 v149, 31, v148
	v_lshlrev_b64 v[148:149], 1, v[148:149]
	v_lshl_add_u64 v[158:159], v[158:159], 0, v[148:149]
	v_lshl_add_u64 v[160:161], v[160:161], 0, v[148:149]
	v_lshl_add_u64 v[162:163], v[162:163], 0, v[148:149]
	v_add_u32_e32 v170, 0x80, v144
	s_mov_b64 s[28:29], s[26:27]
	s_waitcnt vmcnt(0)
	v_fmamk_f32 v145, v145, 0x3a800000, v156
	v_fmamk_f32 v157, v157, 0x3a800000, v156
	v_fmamk_f32 v164, v164, 0x3a800000, v156
	v_fmamk_f32 v171, v165, 0x3a800000, v156
	v_fmamk_f32 v172, v166, 0x3a800000, v156
	v_mul_f32_e32 v165, 0x4b800000, v145
	v_mul_f32_e32 v166, 0x4b800000, v157
	v_cmp_gt_f32_e32 vcc, s53, v145
	v_cmp_gt_f32_e64 s[0:1], s53, v157
	v_fmamk_f32 v173, v167, 0x3a800000, v156
	v_mul_f32_e32 v167, 0x4b800000, v164
	v_cndmask_b32_e32 v145, v145, v165, vcc
	v_cndmask_b32_e64 v157, v157, v166, s[0:1]
	v_cmp_gt_f32_e64 s[2:3], s53, v164
	v_rsq_f32_e32 v145, v145
	v_rsq_f32_e32 v157, v157
	v_cndmask_b32_e64 v164, v164, v167, s[2:3]
	v_rsq_f32_e32 v165, v164
	v_mul_f32_e32 v164, 0x45800000, v145
	v_mul_f32_e32 v166, 0x45800000, v157
	v_cndmask_b32_e32 v164, v145, v164, vcc
	v_mul_f32_e32 v167, 0x45800000, v165
	v_cndmask_b32_e64 v166, v157, v166, s[0:1]
	v_fmamk_f32 v175, v168, 0x3a800000, v156
	v_cndmask_b32_e64 v168, v165, v167, s[2:3]
	v_pk_mul_f32 v[126:127], v[126:127], v[164:165] op_sel_hi:[1,0]
	v_pk_mul_f32 v[124:125], v[124:125], v[164:165] op_sel_hi:[1,0]
	v_pk_mul_f32 v[122:123], v[122:123], v[164:165] op_sel_hi:[1,0]
	v_pk_mul_f32 v[120:121], v[120:121], v[164:165] op_sel_hi:[1,0]
	v_pk_mul_f32 v[110:111], v[110:111], v[164:165] op_sel_hi:[1,0]
	v_pk_mul_f32 v[108:109], v[108:109], v[164:165] op_sel_hi:[1,0]
	v_pk_mul_f32 v[102:103], v[102:103], v[164:165] op_sel_hi:[1,0]
	v_pk_mul_f32 v[100:101], v[100:101], v[164:165] op_sel_hi:[1,0]
	v_pk_mul_f32 v[118:119], v[118:119], v[166:167] op_sel_hi:[1,0]
	v_pk_mul_f32 v[116:117], v[116:117], v[166:167] op_sel_hi:[1,0]
	v_pk_mul_f32 v[114:115], v[114:115], v[166:167] op_sel_hi:[1,0]
	v_pk_mul_f32 v[112:113], v[112:113], v[166:167] op_sel_hi:[1,0]
	v_pk_mul_f32 v[94:95], v[94:95], v[166:167] op_sel_hi:[1,0]
	v_pk_mul_f32 v[92:93], v[92:93], v[166:167] op_sel_hi:[1,0]
	v_pk_mul_f32 v[164:165], v[90:91], v[166:167] op_sel_hi:[1,0]
	v_pk_mul_f32 v[166:167], v[88:89], v[166:167] op_sel_hi:[1,0]
	v_cvt_pk_bf16_f32 v88, v124, v125
	v_cvt_pk_bf16_f32 v89, v126, v127
	v_cvt_pk_bf16_f32 v90, v120, v121
	v_cvt_pk_bf16_f32 v91, v122, v123
	global_store_dwordx4 v[158:159], v[88:91], off nt
	v_fmamk_f32 v169, v169, 0x3a800000, v156
	v_pk_mul_f32 v[106:107], v[106:107], v[168:169] op_sel_hi:[1,0]
	v_cvt_pk_bf16_f32 v88, v108, v109
	v_cvt_pk_bf16_f32 v89, v110, v111
	v_cvt_pk_bf16_f32 v90, v100, v101
	v_cvt_pk_bf16_f32 v91, v102, v103
	global_store_dwordx4 v[158:159], v[88:91], off offset:256 nt
	v_pk_mul_f32 v[104:105], v[104:105], v[168:169] op_sel_hi:[1,0]
	v_pk_mul_f32 v[98:99], v[98:99], v[168:169] op_sel_hi:[1,0]
	v_cvt_pk_bf16_f32 v88, v116, v117
	v_cvt_pk_bf16_f32 v89, v118, v119
	v_cvt_pk_bf16_f32 v90, v112, v113
	v_cvt_pk_bf16_f32 v91, v114, v115
	global_store_dwordx4 v[160:161], v[88:91], off nt
	v_pk_mul_f32 v[96:97], v[96:97], v[168:169] op_sel_hi:[1,0]
	v_pk_mul_f32 v[86:87], v[86:87], v[168:169] op_sel_hi:[1,0]
	v_cvt_pk_bf16_f32 v88, v92, v93
	v_cvt_pk_bf16_f32 v89, v94, v95
	v_cvt_pk_bf16_f32 v90, v166, v167
	v_cvt_pk_bf16_f32 v91, v164, v165
	global_store_dwordx4 v[160:161], v[88:91], off offset:256 nt
	v_pk_mul_f32 v[84:85], v[84:85], v[168:169] op_sel_hi:[1,0]
	v_cmp_gt_f32_e32 vcc, s53, v171
	v_cvt_pk_bf16_f32 v88, v104, v105
	v_cvt_pk_bf16_f32 v89, v106, v107
	v_cvt_pk_bf16_f32 v90, v96, v97
	v_cvt_pk_bf16_f32 v91, v98, v99
	global_store_dwordx4 v[162:163], v[88:91], off nt
	s_mov_b64 s[2:3], s[24:25]
	s_nop 0
	v_pk_mul_f32 v[88:89], v[82:83], v[168:169] op_sel_hi:[1,0]
	v_pk_mul_f32 v[82:83], v[80:81], v[168:169] op_sel_hi:[1,0]
	v_cvt_pk_bf16_f32 v80, v84, v85
	v_cvt_pk_bf16_f32 v81, v86, v87
	s_nop 0
	v_cvt_pk_bf16_f32 v82, v82, v83
	v_cvt_pk_bf16_f32 v83, v88, v89
	global_store_dwordx4 v[162:163], v[80:83], off offset:256 nt
	s_nop 1
	v_mul_f32_e32 v81, 0x4b800000, v171
	v_cndmask_b32_e32 v81, v171, v81, vcc
	v_rsq_f32_e32 v82, v81
	v_or_b32_e32 v80, 48, v144
	v_mad_i64_i32 v[80:81], s[0:1], v80, s52, v[146:147]
	v_mul_f32_e32 v83, 0x45800000, v82
	v_cndmask_b32_e32 v82, v82, v83, vcc
	v_lshl_add_u64 v[80:81], v[80:81], 0, v[148:149]
	v_pk_mul_f32 v[78:79], v[78:79], v[82:83] op_sel_hi:[1,0]
	v_pk_mul_f32 v[76:77], v[76:77], v[82:83] op_sel_hi:[1,0]
	v_pk_mul_f32 v[84:85], v[74:75], v[82:83] op_sel_hi:[1,0]
	v_pk_mul_f32 v[74:75], v[72:73], v[82:83] op_sel_hi:[1,0]
	v_cvt_pk_bf16_f32 v72, v76, v77
	v_cvt_pk_bf16_f32 v73, v78, v79
	v_pk_mul_f32 v[68:69], v[68:69], v[82:83] op_sel_hi:[1,0]
	v_cvt_pk_bf16_f32 v74, v74, v75
	v_cvt_pk_bf16_f32 v75, v84, v85
	global_store_dwordx4 v[80:81], v[72:75], off nt
	v_pk_mul_f32 v[70:71], v[70:71], v[82:83] op_sel_hi:[1,0]
	v_cmp_gt_f32_e32 vcc, s53, v172
	v_pk_mul_f32 v[72:73], v[66:67], v[82:83] op_sel_hi:[1,0]
	v_pk_mul_f32 v[66:67], v[64:65], v[82:83] op_sel_hi:[1,0]
	v_cvt_pk_bf16_f32 v64, v68, v69
	v_cvt_pk_bf16_f32 v65, v70, v71
	s_nop 0
	v_cvt_pk_bf16_f32 v66, v66, v67
	v_cvt_pk_bf16_f32 v67, v72, v73
	global_store_dwordx4 v[80:81], v[64:67], off offset:256 nt
	s_nop 1
	v_mul_f32_e32 v64, 0x4b800000, v172
	v_cndmask_b32_e32 v64, v172, v64, vcc
	v_rsq_f32_e32 v66, v64
	v_mad_i64_i32 v[64:65], s[0:1], v170, s52, v[146:147]
	v_lshl_add_u64 v[64:65], v[64:65], 0, v[148:149]
	v_mul_f32_e32 v67, 0x45800000, v66
	v_cndmask_b32_e32 v66, v66, v67, vcc
	v_pk_mul_f32 v[62:63], v[62:63], v[66:67] op_sel_hi:[1,0]
	v_pk_mul_f32 v[60:61], v[60:61], v[66:67] op_sel_hi:[1,0]
	v_pk_mul_f32 v[68:69], v[58:59], v[66:67] op_sel_hi:[1,0]
	v_pk_mul_f32 v[58:59], v[56:57], v[66:67] op_sel_hi:[1,0]
	v_cvt_pk_bf16_f32 v56, v60, v61
	v_cvt_pk_bf16_f32 v57, v62, v63
	v_pk_mul_f32 v[54:55], v[54:55], v[66:67] op_sel_hi:[1,0]
	v_cvt_pk_bf16_f32 v58, v58, v59
	v_cvt_pk_bf16_f32 v59, v68, v69
	global_store_dwordx4 v[64:65], v[56:59], off nt
	v_pk_mul_f32 v[52:53], v[52:53], v[66:67] op_sel_hi:[1,0]
	v_cmp_gt_f32_e32 vcc, s53, v173
	v_pk_mul_f32 v[56:57], v[50:51], v[66:67] op_sel_hi:[1,0]
	v_pk_mul_f32 v[50:51], v[48:49], v[66:67] op_sel_hi:[1,0]
	v_cvt_pk_bf16_f32 v48, v52, v53
	v_cvt_pk_bf16_f32 v49, v54, v55
	s_nop 0
	v_cvt_pk_bf16_f32 v50, v50, v51
	v_cvt_pk_bf16_f32 v51, v56, v57
	global_store_dwordx4 v[64:65], v[48:51], off offset:256 nt
	s_nop 1
	v_mul_f32_e32 v49, 0x4b800000, v173
	v_cndmask_b32_e32 v49, v173, v49, vcc
	v_rsq_f32_e32 v50, v49
	v_add_u32_e32 v48, 0x90, v144
	v_mad_i64_i32 v[48:49], s[0:1], v48, s52, v[146:147]
	v_mul_f32_e32 v51, 0x45800000, v50
	v_cndmask_b32_e32 v50, v50, v51, vcc
	v_lshl_add_u64 v[48:49], v[48:49], 0, v[148:149]
	v_pk_mul_f32 v[46:47], v[46:47], v[50:51] op_sel_hi:[1,0]
	v_pk_mul_f32 v[44:45], v[44:45], v[50:51] op_sel_hi:[1,0]
	v_pk_mul_f32 v[52:53], v[42:43], v[50:51] op_sel_hi:[1,0]
	v_pk_mul_f32 v[42:43], v[40:41], v[50:51] op_sel_hi:[1,0]
	v_cvt_pk_bf16_f32 v40, v44, v45
	v_cvt_pk_bf16_f32 v41, v46, v47
	v_pk_mul_f32 v[38:39], v[38:39], v[50:51] op_sel_hi:[1,0]
	v_cvt_pk_bf16_f32 v42, v42, v43
	v_cvt_pk_bf16_f32 v43, v52, v53
	global_store_dwordx4 v[48:49], v[40:43], off nt
	v_pk_mul_f32 v[36:37], v[36:37], v[50:51] op_sel_hi:[1,0]
	v_cmp_gt_f32_e32 vcc, s53, v175
	v_pk_mul_f32 v[40:41], v[34:35], v[50:51] op_sel_hi:[1,0]
	v_pk_mul_f32 v[34:35], v[32:33], v[50:51] op_sel_hi:[1,0]
	v_cvt_pk_bf16_f32 v32, v36, v37
	v_cvt_pk_bf16_f32 v33, v38, v39
	s_nop 0
	v_cvt_pk_bf16_f32 v34, v34, v35
	v_cvt_pk_bf16_f32 v35, v40, v41
	global_store_dwordx4 v[48:49], v[32:35], off offset:256 nt
	s_nop 1
	v_mul_f32_e32 v33, 0x4b800000, v175
	v_cndmask_b32_e32 v33, v175, v33, vcc
	v_rsq_f32_e32 v34, v33
	v_add_u32_e32 v32, 0xa0, v144
	v_mad_i64_i32 v[32:33], s[0:1], v32, s52, v[146:147]
	v_mul_f32_e32 v35, 0x45800000, v34
	v_cndmask_b32_e32 v34, v34, v35, vcc
	v_lshl_add_u64 v[32:33], v[32:33], 0, v[148:149]
	v_pk_mul_f32 v[30:31], v[30:31], v[34:35] op_sel_hi:[1,0]
	v_pk_mul_f32 v[28:29], v[28:29], v[34:35] op_sel_hi:[1,0]
	v_pk_mul_f32 v[36:37], v[26:27], v[34:35] op_sel_hi:[1,0]
	v_pk_mul_f32 v[26:27], v[24:25], v[34:35] op_sel_hi:[1,0]
	v_cvt_pk_bf16_f32 v24, v28, v29
	v_cvt_pk_bf16_f32 v25, v30, v31
	v_pk_mul_f32 v[22:23], v[22:23], v[34:35] op_sel_hi:[1,0]
	v_cvt_pk_bf16_f32 v26, v26, v27
	v_cvt_pk_bf16_f32 v27, v36, v37
	global_store_dwordx4 v[32:33], v[24:27], off nt
	v_pk_mul_f32 v[20:21], v[20:21], v[34:35] op_sel_hi:[1,0]
	v_cmp_gt_f32_e32 vcc, s53, v169
	v_pk_mul_f32 v[24:25], v[18:19], v[34:35] op_sel_hi:[1,0]
	v_pk_mul_f32 v[18:19], v[16:17], v[34:35] op_sel_hi:[1,0]
	v_cvt_pk_bf16_f32 v16, v20, v21
	v_cvt_pk_bf16_f32 v17, v22, v23
	s_nop 0
	v_cvt_pk_bf16_f32 v18, v18, v19
	v_cvt_pk_bf16_f32 v19, v24, v25
	global_store_dwordx4 v[32:33], v[16:19], off offset:256 nt
	s_nop 1
	v_mul_f32_e32 v17, 0x4b800000, v169
	v_cndmask_b32_e32 v17, v169, v17, vcc
	v_rsq_f32_e32 v18, v17
	v_add_u32_e32 v16, 0xb0, v144
	v_mad_i64_i32 v[16:17], s[0:1], v16, s52, v[146:147]
	v_mul_f32_e32 v19, 0x45800000, v18
	v_cndmask_b32_e32 v18, v18, v19, vcc
	v_lshl_add_u64 v[16:17], v[16:17], 0, v[148:149]
	v_pk_mul_f32 v[14:15], v[14:15], v[18:19] op_sel_hi:[1,0]
	v_pk_mul_f32 v[12:13], v[12:13], v[18:19] op_sel_hi:[1,0]
	v_pk_mul_f32 v[20:21], v[10:11], v[18:19] op_sel_hi:[1,0]
	v_pk_mul_f32 v[10:11], v[8:9], v[18:19] op_sel_hi:[1,0]
	v_cvt_pk_bf16_f32 v8, v12, v13
	v_cvt_pk_bf16_f32 v9, v14, v15
	s_and_b64 vcc, exec, s[6:7]
	v_cvt_pk_bf16_f32 v10, v10, v11
	v_cvt_pk_bf16_f32 v11, v20, v21
	global_store_dwordx4 v[16:17], v[8:11], off nt
	s_mov_b32 s1, s20
	s_mov_b32 s0, s22
	v_pk_mul_f32 v[8:9], v[2:3], v[18:19] op_sel_hi:[1,0]
	v_pk_mul_f32 v[2:3], v[0:1], v[18:19] op_sel_hi:[1,0]
	v_pk_mul_f32 v[6:7], v[6:7], v[18:19] op_sel_hi:[1,0]
	v_pk_mul_f32 v[4:5], v[4:5], v[18:19] op_sel_hi:[1,0]
	s_nop 0
	v_cvt_pk_bf16_f32 v0, v4, v5
	v_cvt_pk_bf16_f32 v1, v6, v7
	v_cvt_pk_bf16_f32 v2, v2, v3
	v_cvt_pk_bf16_f32 v3, v8, v9
	global_store_dwordx4 v[16:17], v[0:3], off offset:256 nt
	s_cbranch_vccz .LBB0_943
	s_waitcnt vmcnt(0)
	s_cmpk_gt_u32 s33, 0xff
	s_cbranch_scc1 .LBB0_950
	s_barrier

.LBB0_1022:
	ds_read_b128 v[144:147], v178
	ds_read_b128 v[148:151], v178 offset:1024
	ds_read_b128 v[152:155], v178 offset:2048
	ds_read_b128 v[156:159], v178 offset:3072
	s_add_u32 s42, s40, 0xfffc0080
	s_addc_u32 s43, s41, -1
	s_cmp_eq_u32 s64, 12
	s_cselect_b32 s49, s29, s43
	s_cselect_b32 s48, s37, s42
	s_cselect_b32 s43, s27, s63
	s_cselect_b32 s42, s61, s62
	v_lshl_add_u64 v[172:173], s[40:41], 0, v[136:137]
	s_add_i32 m0, s39, 0xc000
	ds_read_b128 v[160:163], v179
	ds_read_b128 v[164:167], v179 offset:1024
	ds_read_b128 v[168:171], v179 offset:2048
	ds_read_b128 v[182:185], v179 offset:3072
	ds_read_b128 v[186:189], v179 offset:4096
	ds_read_b128 v[190:193], v179 offset:5120
	ds_read_b128 v[194:197], v179 offset:6144
	ds_read_b128 v[198:201], v179 offset:7168
	global_load_lds_dwordx4 v[172:173], off
	v_lshl_add_u64 v[172:173], s[40:41], 0, v[138:139]
	s_add_i32 m0, s39, 0xe000
	s_nop 0
	global_load_lds_dwordx4 v[172:173], off
	s_waitcnt lgkmcnt(8)
	s_barrier
	s_waitcnt lgkmcnt(0)
	s_setprio 1
	v_mfma_f32_16x16x32_bf16 v[124:127], v[144:147], v[160:163], v[124:127]
	v_mfma_f32_16x16x32_bf16 v[120:123], v[152:155], v[160:163], v[120:123]
	v_mfma_f32_16x16x32_bf16 v[108:111], v[144:147], v[168:171], v[108:111]
	v_mfma_f32_16x16x32_bf16 v[104:107], v[152:155], v[168:171], v[104:107]
	v_mfma_f32_16x16x32_bf16 v[96:99], v[144:147], v[186:189], v[96:99]
	v_mfma_f32_16x16x32_bf16 v[88:91], v[152:155], v[186:189], v[88:91]
	v_mfma_f32_16x16x32_bf16 v[80:83], v[144:147], v[194:197], v[80:83]
	v_mfma_f32_16x16x32_bf16 v[72:75], v[152:155], v[194:197], v[72:75]
	v_mfma_f32_16x16x32_bf16 v[124:127], v[148:151], v[164:167], v[124:127]
	v_mfma_f32_16x16x32_bf16 v[120:123], v[156:159], v[164:167], v[120:123]
	v_mfma_f32_16x16x32_bf16 v[108:111], v[148:151], v[182:185], v[108:111]
	v_mfma_f32_16x16x32_bf16 v[104:107], v[156:159], v[182:185], v[104:107]
	v_mfma_f32_16x16x32_bf16 v[96:99], v[148:151], v[190:193], v[96:99]
	v_mfma_f32_16x16x32_bf16 v[88:91], v[156:159], v[190:193], v[88:91]
	v_mfma_f32_16x16x32_bf16 v[80:83], v[148:151], v[198:201], v[80:83]
	v_mfma_f32_16x16x32_bf16 v[72:75], v[156:159], v[198:201], v[72:75]
	s_setprio 0
	s_barrier
	s_add_i32 s65, s59, s50
	v_lshl_add_u64 v[172:173], s[42:43], 0, v[130:131]
	s_mov_b32 m0, s65
	ds_read_b128 v[202:205], v180
	ds_read_b128 v[206:209], v180 offset:1024
	ds_read_b128 v[212:215], v180 offset:2048
	ds_read_b128 v[216:219], v180 offset:3072
	global_load_lds_dwordx4 v[172:173], off
	v_lshl_add_u64 v[220:221], s[42:43], 0, v[134:135]
	s_add_i32 m0, s65, 0x2000
	s_nop 0
	global_load_lds_dwordx4 v[220:221], off
	s_barrier
	s_waitcnt lgkmcnt(0)
	s_setprio 1
	v_mfma_f32_16x16x32_bf16 v[116:119], v[202:205], v[160:163], v[116:119]
	v_mfma_f32_16x16x32_bf16 v[112:115], v[212:215], v[160:163], v[112:115]
	v_mfma_f32_16x16x32_bf16 v[100:103], v[202:205], v[168:171], v[100:103]
	v_mfma_f32_16x16x32_bf16 v[92:95], v[212:215], v[168:171], v[92:95]
	v_mfma_f32_16x16x32_bf16 v[84:87], v[202:205], v[186:189], v[84:87]
	v_mfma_f32_16x16x32_bf16 v[76:79], v[212:215], v[186:189], v[76:79]
	v_mfma_f32_16x16x32_bf16 v[68:71], v[202:205], v[194:197], v[68:71]
	v_mfma_f32_16x16x32_bf16 v[64:67], v[212:215], v[194:197], v[64:67]
	v_mfma_f32_16x16x32_bf16 v[116:119], v[206:209], v[164:167], v[116:119]
	v_mfma_f32_16x16x32_bf16 v[112:115], v[216:219], v[164:167], v[112:115]
	v_mfma_f32_16x16x32_bf16 v[100:103], v[206:209], v[182:185], v[100:103]
	v_mfma_f32_16x16x32_bf16 v[92:95], v[216:219], v[182:185], v[92:95]
	v_mfma_f32_16x16x32_bf16 v[84:87], v[206:209], v[190:193], v[84:87]
	v_mfma_f32_16x16x32_bf16 v[76:79], v[216:219], v[190:193], v[76:79]
	v_mfma_f32_16x16x32_bf16 v[68:71], v[206:209], v[198:201], v[68:71]
	v_mfma_f32_16x16x32_bf16 v[64:67], v[216:219], v[198:201], v[64:67]
	s_setprio 0
	s_mov_b32 m0, s39
	v_lshl_add_u64 v[222:223], s[48:49], 0, v[128:129]
	s_barrier
	ds_read_b128 v[160:163], v179 offset:16384
	ds_read_b128 v[164:167], v179 offset:17408
	ds_read_b128 v[168:171], v179 offset:18432
	ds_read_b128 v[182:185], v179 offset:19456
	ds_read_b128 v[186:189], v179 offset:20480
	ds_read_b128 v[190:193], v179 offset:21504
	ds_read_b128 v[194:197], v179 offset:22528
	ds_read_b128 v[198:201], v179 offset:23552
	global_load_lds_dwordx4 v[222:223], off
	v_lshl_add_u64 v[224:225], s[48:49], 0, v[132:133]
	s_mov_b32 m0, s51
	s_nop 0
	global_load_lds_dwordx4 v[224:225], off
	s_barrier
	s_waitcnt lgkmcnt(0)
	s_setprio 1
	v_mfma_f32_16x16x32_bf16 v[60:63], v[144:147], v[160:163], v[60:63]
	v_mfma_f32_16x16x32_bf16 v[56:59], v[152:155], v[160:163], v[56:59]
	v_mfma_f32_16x16x32_bf16 v[44:47], v[144:147], v[168:171], v[44:47]
	v_mfma_f32_16x16x32_bf16 v[40:43], v[152:155], v[168:171], v[40:43]
	v_mfma_f32_16x16x32_bf16 v[32:35], v[144:147], v[186:189], v[32:35]
	v_mfma_f32_16x16x32_bf16 v[24:27], v[152:155], v[186:189], v[24:27]
	v_mfma_f32_16x16x32_bf16 v[16:19], v[144:147], v[194:197], v[16:19]
	v_mfma_f32_16x16x32_bf16 v[8:11], v[152:155], v[194:197], v[8:11]
	v_mfma_f32_16x16x32_bf16 v[60:63], v[148:151], v[164:167], v[60:63]
	v_mfma_f32_16x16x32_bf16 v[56:59], v[156:159], v[164:167], v[56:59]
	v_mfma_f32_16x16x32_bf16 v[44:47], v[148:151], v[182:185], v[44:47]
	v_mfma_f32_16x16x32_bf16 v[40:43], v[156:159], v[182:185], v[40:43]
	v_mfma_f32_16x16x32_bf16 v[32:35], v[148:151], v[190:193], v[32:35]
	v_mfma_f32_16x16x32_bf16 v[24:27], v[156:159], v[190:193], v[24:27]
	v_mfma_f32_16x16x32_bf16 v[16:19], v[148:151], v[198:201], v[16:19]
	v_mfma_f32_16x16x32_bf16 v[8:11], v[156:159], v[198:201], v[8:11]
	s_setprio 0
	s_barrier
	s_add_u32 s66, s42, 0x40000
	s_addc_u32 s67, s43, 0
	s_add_i32 s65, s60, s50
	v_lshl_add_u64 v[144:145], s[66:67], 0, v[130:131]
	s_mov_b32 m0, s65
	s_nop 0
	global_load_lds_dwordx4 v[144:145], off
	v_lshl_add_u64 v[144:145], s[66:67], 0, v[134:135]
	s_add_i32 m0, s65, 0x2000
	s_nop 0
	global_load_lds_dwordx4 v[144:145], off
	s_waitcnt vmcnt(6)
	s_barrier
	s_setprio 1
	v_mfma_f32_16x16x32_bf16 v[52:55], v[202:205], v[160:163], v[52:55]
	v_mfma_f32_16x16x32_bf16 v[48:51], v[212:215], v[160:163], v[48:51]
	v_mfma_f32_16x16x32_bf16 v[36:39], v[202:205], v[168:171], v[36:39]
	v_mfma_f32_16x16x32_bf16 v[28:31], v[212:215], v[168:171], v[28:31]
	v_mfma_f32_16x16x32_bf16 v[20:23], v[202:205], v[186:189], v[20:23]
	v_mfma_f32_16x16x32_bf16 v[12:15], v[212:215], v[186:189], v[12:15]
	v_mfma_f32_16x16x32_bf16 v[4:7], v[202:205], v[194:197], v[4:7]
	v_mfma_f32_16x16x32_bf16 v[0:3], v[212:215], v[194:197], v[0:3]
	v_mfma_f32_16x16x32_bf16 v[52:55], v[206:209], v[164:167], v[52:55]
	v_mfma_f32_16x16x32_bf16 v[48:51], v[216:219], v[164:167], v[48:51]
	v_mfma_f32_16x16x32_bf16 v[36:39], v[206:209], v[182:185], v[36:39]
	v_mfma_f32_16x16x32_bf16 v[28:31], v[216:219], v[182:185], v[28:31]
	v_mfma_f32_16x16x32_bf16 v[20:23], v[206:209], v[190:193], v[20:23]
	v_mfma_f32_16x16x32_bf16 v[12:15], v[216:219], v[190:193], v[12:15]
	v_mfma_f32_16x16x32_bf16 v[4:7], v[206:209], v[198:201], v[4:7]
	v_mfma_f32_16x16x32_bf16 v[0:3], v[216:219], v[198:201], v[0:3]
	s_setprio 0
	s_add_i32 s65, 0, 0x18000
	v_add_u32_e32 v156, s65, v176
	s_barrier
	ds_read_b128 v[144:147], v156
	ds_read_b128 v[148:151], v156 offset:1024
	ds_read_b128 v[152:155], v156 offset:2048
	ds_read_b128 v[156:159], v156 offset:3072
	s_add_u32 s48, s48, 0x40000
	s_addc_u32 s49, s49, 0
	s_mov_b32 m0, s52
	v_lshl_add_u64 v[202:203], s[48:49], 0, v[128:129]
	ds_read_b128 v[160:163], v179 offset:32768
	ds_read_b128 v[164:167], v179 offset:33792
	ds_read_b128 v[168:171], v179 offset:34816
	ds_read_b128 v[182:185], v179 offset:35840
	ds_read_b128 v[186:189], v179 offset:36864
	ds_read_b128 v[190:193], v179 offset:37888
	ds_read_b128 v[194:197], v179 offset:38912
	ds_read_b128 v[198:201], v179 offset:39936
	global_load_lds_dwordx4 v[202:203], off
	v_lshl_add_u64 v[202:203], s[48:49], 0, v[132:133]
	s_mov_b32 m0, s53
	s_nop 0
	global_load_lds_dwordx4 v[202:203], off
	s_waitcnt lgkmcnt(8)
	s_barrier
	s_waitcnt lgkmcnt(0)
	s_setprio 1
	v_mfma_f32_16x16x32_bf16 v[124:127], v[144:147], v[160:163], v[124:127]
	v_mfma_f32_16x16x32_bf16 v[120:123], v[152:155], v[160:163], v[120:123]
	v_mfma_f32_16x16x32_bf16 v[108:111], v[144:147], v[168:171], v[108:111]
	v_mfma_f32_16x16x32_bf16 v[104:107], v[152:155], v[168:171], v[104:107]
	v_mfma_f32_16x16x32_bf16 v[96:99], v[144:147], v[186:189], v[96:99]
	v_mfma_f32_16x16x32_bf16 v[88:91], v[152:155], v[186:189], v[88:91]
	v_mfma_f32_16x16x32_bf16 v[80:83], v[144:147], v[194:197], v[80:83]
	v_mfma_f32_16x16x32_bf16 v[72:75], v[152:155], v[194:197], v[72:75]
	v_mfma_f32_16x16x32_bf16 v[124:127], v[148:151], v[164:167], v[124:127]
	v_mfma_f32_16x16x32_bf16 v[120:123], v[156:159], v[164:167], v[120:123]
	v_mfma_f32_16x16x32_bf16 v[108:111], v[148:151], v[182:185], v[108:111]
	v_mfma_f32_16x16x32_bf16 v[104:107], v[156:159], v[182:185], v[104:107]
	v_mfma_f32_16x16x32_bf16 v[96:99], v[148:151], v[190:193], v[96:99]
	v_mfma_f32_16x16x32_bf16 v[88:91], v[156:159], v[190:193], v[88:91]
	v_mfma_f32_16x16x32_bf16 v[80:83], v[148:151], v[198:201], v[80:83]
	v_mfma_f32_16x16x32_bf16 v[72:75], v[156:159], v[198:201], v[72:75]
	s_setprio 0
	s_barrier
	s_add_i32 s48, 0, 0x1c000
	s_add_i32 s49, s65, s50
	v_add_u32_e32 v181, s48, v176
	v_lshl_add_u64 v[172:173], v[172:173], 0, s[2:3]
	s_mov_b32 m0, s49
	ds_read_b128 v[202:205], v181
	ds_read_b128 v[206:209], v181 offset:1024
	ds_read_b128 v[212:215], v181 offset:2048
	ds_read_b128 v[216:219], v181 offset:3072
	global_load_lds_dwordx4 v[172:173], off
	v_lshl_add_u64 v[172:173], v[220:221], 0, s[2:3]
	s_add_i32 m0, s49, 0x2000
	s_nop 0
	global_load_lds_dwordx4 v[172:173], off
	s_barrier
	s_waitcnt lgkmcnt(0)
	s_setprio 1
	v_mfma_f32_16x16x32_bf16 v[116:119], v[202:205], v[160:163], v[116:119]
	v_mfma_f32_16x16x32_bf16 v[112:115], v[212:215], v[160:163], v[112:115]
	v_mfma_f32_16x16x32_bf16 v[100:103], v[202:205], v[168:171], v[100:103]
	v_mfma_f32_16x16x32_bf16 v[92:95], v[212:215], v[168:171], v[92:95]
	v_mfma_f32_16x16x32_bf16 v[84:87], v[202:205], v[186:189], v[84:87]
	v_mfma_f32_16x16x32_bf16 v[76:79], v[212:215], v[186:189], v[76:79]
	v_mfma_f32_16x16x32_bf16 v[68:71], v[202:205], v[194:197], v[68:71]
	v_mfma_f32_16x16x32_bf16 v[64:67], v[212:215], v[194:197], v[64:67]
	v_mfma_f32_16x16x32_bf16 v[116:119], v[206:209], v[164:167], v[116:119]
	v_mfma_f32_16x16x32_bf16 v[112:115], v[216:219], v[164:167], v[112:115]
	v_mfma_f32_16x16x32_bf16 v[100:103], v[206:209], v[182:185], v[100:103]
	v_mfma_f32_16x16x32_bf16 v[92:95], v[216:219], v[182:185], v[92:95]
	v_mfma_f32_16x16x32_bf16 v[84:87], v[206:209], v[190:193], v[84:87]
	v_mfma_f32_16x16x32_bf16 v[76:79], v[216:219], v[190:193], v[76:79]
	v_mfma_f32_16x16x32_bf16 v[68:71], v[206:209], v[198:201], v[68:71]
	v_mfma_f32_16x16x32_bf16 v[64:67], v[216:219], v[198:201], v[64:67]
	s_setprio 0
	s_mov_b32 m0, s55
	v_lshl_add_u64 v[172:173], v[222:223], 0, s[2:3]
	s_barrier
	ds_read_b128 v[160:163], v179 offset:49152
	ds_read_b128 v[164:167], v179 offset:50176
	ds_read_b128 v[168:171], v179 offset:51200
	ds_read_b128 v[182:185], v179 offset:52224
	ds_read_b128 v[186:189], v179 offset:53248
	ds_read_b128 v[190:193], v179 offset:54272
	ds_read_b128 v[194:197], v179 offset:55296
	ds_read_b128 v[198:201], v179 offset:56320
	global_load_lds_dwordx4 v[172:173], off
	v_lshl_add_u64 v[172:173], v[224:225], 0, s[2:3]
	s_mov_b32 m0, s56
	s_nop 0
	global_load_lds_dwordx4 v[172:173], off
	s_barrier
	s_waitcnt lgkmcnt(0)
	s_setprio 1
	v_mfma_f32_16x16x32_bf16 v[60:63], v[144:147], v[160:163], v[60:63]
	v_mfma_f32_16x16x32_bf16 v[56:59], v[152:155], v[160:163], v[56:59]
	v_mfma_f32_16x16x32_bf16 v[44:47], v[144:147], v[168:171], v[44:47]
	v_mfma_f32_16x16x32_bf16 v[40:43], v[152:155], v[168:171], v[40:43]
	v_mfma_f32_16x16x32_bf16 v[32:35], v[144:147], v[186:189], v[32:35]
	v_mfma_f32_16x16x32_bf16 v[24:27], v[152:155], v[186:189], v[24:27]
	v_mfma_f32_16x16x32_bf16 v[16:19], v[144:147], v[194:197], v[16:19]
	v_mfma_f32_16x16x32_bf16 v[8:11], v[152:155], v[194:197], v[8:11]
	v_mfma_f32_16x16x32_bf16 v[60:63], v[148:151], v[164:167], v[60:63]
	v_mfma_f32_16x16x32_bf16 v[56:59], v[156:159], v[164:167], v[56:59]
	v_mfma_f32_16x16x32_bf16 v[44:47], v[148:151], v[182:185], v[44:47]
	v_mfma_f32_16x16x32_bf16 v[40:43], v[156:159], v[182:185], v[40:43]
	v_mfma_f32_16x16x32_bf16 v[32:35], v[148:151], v[190:193], v[32:35]
	v_mfma_f32_16x16x32_bf16 v[24:27], v[156:159], v[190:193], v[24:27]
	v_mfma_f32_16x16x32_bf16 v[16:19], v[148:151], v[198:201], v[16:19]
	v_mfma_f32_16x16x32_bf16 v[8:11], v[156:159], v[198:201], v[8:11]
	s_setprio 0
	s_barrier
	s_add_u32 s42, s42, 0x40080
	s_addc_u32 s43, s43, 0
	s_add_i32 s48, s48, s50
	v_lshl_add_u64 v[144:145], s[42:43], 0, v[130:131]
	s_mov_b32 m0, s48
	s_nop 0
	global_load_lds_dwordx4 v[144:145], off
	v_lshl_add_u64 v[144:145], s[42:43], 0, v[134:135]
	s_add_i32 m0, s48, 0x2000
	s_nop 0
	global_load_lds_dwordx4 v[144:145], off
	s_waitcnt vmcnt(6)
	s_barrier
	s_setprio 1
	v_mfma_f32_16x16x32_bf16 v[52:55], v[202:205], v[160:163], v[52:55]
	v_mfma_f32_16x16x32_bf16 v[48:51], v[212:215], v[160:163], v[48:51]
	v_mfma_f32_16x16x32_bf16 v[36:39], v[202:205], v[168:171], v[36:39]
	v_mfma_f32_16x16x32_bf16 v[28:31], v[212:215], v[168:171], v[28:31]
	v_mfma_f32_16x16x32_bf16 v[20:23], v[202:205], v[186:189], v[20:23]
	v_mfma_f32_16x16x32_bf16 v[12:15], v[212:215], v[186:189], v[12:15]
	v_mfma_f32_16x16x32_bf16 v[4:7], v[202:205], v[194:197], v[4:7]
	v_mfma_f32_16x16x32_bf16 v[0:3], v[212:215], v[194:197], v[0:3]
	v_mfma_f32_16x16x32_bf16 v[52:55], v[206:209], v[164:167], v[52:55]
	v_mfma_f32_16x16x32_bf16 v[48:51], v[216:219], v[164:167], v[48:51]
	v_mfma_f32_16x16x32_bf16 v[36:39], v[206:209], v[182:185], v[36:39]
	v_mfma_f32_16x16x32_bf16 v[28:31], v[216:219], v[182:185], v[28:31]
	v_mfma_f32_16x16x32_bf16 v[20:23], v[206:209], v[190:193], v[20:23]
	v_mfma_f32_16x16x32_bf16 v[12:15], v[216:219], v[190:193], v[12:15]
	v_mfma_f32_16x16x32_bf16 v[4:7], v[206:209], v[198:201], v[4:7]
	v_mfma_f32_16x16x32_bf16 v[0:3], v[216:219], v[198:201], v[0:3]
	s_setprio 0
	s_add_i32 s64, s64, 2
	s_add_u32 s40, s40, 0x100
	s_addc_u32 s41, s41, 0
	s_add_u32 s62, s62, 0x100
	s_addc_u32 s63, s63, 0
	s_cmp_gt_u32 s64, 13
	s_barrier
	s_cbranch_scc0 .LBB0_1022
	v_lshl_or_b32 v144, s38, 8, v177
	v_lshl_add_u32 v150, s36, 8, v175
	v_ashrrev_i32_e32 v145, 31, v144
	v_ashrrev_i32_e32 v151, 31, v150
	v_lshlrev_b64 v[144:145], 1, v[144:145]
	v_lshl_add_u64 v[146:147], s[10:11], 0, v[144:145]
	v_lshlrev_b64 v[148:149], 11, v[150:151]
	v_lshl_add_u64 v[152:153], v[146:147], 0, v[148:149]
	global_load_dwordx4 v[156:159], v[152:153], off
	global_load_dwordx4 v[160:163], v[152:153], off offset:256
	v_or_b32_e32 v152, 16, v150
	v_ashrrev_i32_e32 v153, 31, v152
	v_lshlrev_b64 v[170:171], 11, v[152:153]
	v_lshl_add_u64 v[152:153], v[146:147], 0, v[170:171]
	global_load_dwordx4 v[164:167], v[152:153], off
	global_load_dwordx4 v[182:185], v[152:153], off offset:256
	v_or_b32_e32 v152, 32, v150
	v_ashrrev_i32_e32 v153, 31, v152
	v_lshlrev_b64 v[154:155], 11, v[152:153]
	v_lshl_add_u64 v[152:153], v[146:147], 0, v[154:155]
	global_load_dwordx4 v[186:189], v[152:153], off
	global_load_dwordx4 v[190:193], v[152:153], off offset:256
	v_or_b32_e32 v152, 48, v150
	v_ashrrev_i32_e32 v153, 31, v152
	v_lshlrev_b64 v[152:153], 11, v[152:153]
	v_lshl_add_u64 v[168:169], v[146:147], 0, v[152:153]
	global_load_dwordx4 v[194:197], v[168:169], off
	global_load_dwordx4 v[198:201], v[168:169], off offset:256
	s_waitcnt vmcnt(0)
	v_lshlrev_b32_e32 v202, 16, v156
	v_and_b32_e32 v203, 0xffff0000, v156
	v_lshlrev_b32_e32 v204, 16, v157
	v_and_b32_e32 v205, 0xffff0000, v157
	v_lshlrev_b32_e32 v206, 16, v158
	v_and_b32_e32 v207, 0xffff0000, v158
	v_lshlrev_b32_e32 v208, 16, v159
	v_and_b32_e32 v209, 0xffff0000, v159
	v_pk_add_f32 v[126:127], v[126:127], v[204:205]
	v_pk_add_f32 v[124:125], v[124:125], v[202:203]
	v_lshlrev_b32_e32 v224, 16, v166
	v_and_b32_e32 v225, 0xffff0000, v166
	v_lshlrev_b32_e32 v226, 16, v167
	v_and_b32_e32 v227, 0xffff0000, v167
	v_lshlrev_b32_e32 v212, 16, v160
	v_lshlrev_b32_e32 v166, 16, v194
	v_and_b32_e32 v167, 0xffff0000, v194
	v_lshlrev_b32_e32 v172, 16, v195
	v_and_b32_e32 v173, 0xffff0000, v195
	v_pk_add_f32 v[194:195], v[122:123], v[208:209]
	v_pk_add_f32 v[122:123], v[120:121], v[206:207]
	v_mul_f32_e32 v120, v125, v125
	v_mul_f32_e32 v121, v127, v127
	v_fmac_f32_e32 v120, v124, v124
	v_fmac_f32_e32 v121, v126, v126
	v_add_f32_e32 v120, v120, v121
	v_mul_f32_e32 v121, v123, v123
	v_fmac_f32_e32 v121, v122, v122
	v_add_f32_e32 v120, v121, v120
	v_mul_f32_e32 v121, v195, v195
	v_fmac_f32_e32 v121, v194, v194
	v_and_b32_e32 v213, 0xffff0000, v160
	v_lshlrev_b32_e32 v214, 16, v161
	v_and_b32_e32 v215, 0xffff0000, v161
	v_add_f32_e32 v181, v121, v120
	v_cvt_pk_bf16_f32 v120, v124, v125
	v_lshl_add_u64 v[124:125], s[10:11], 0, v[148:149]
	v_lshlrev_b32_e32 v216, 16, v162
	v_and_b32_e32 v217, 0xffff0000, v162
	v_lshlrev_b32_e32 v218, 16, v163
	v_and_b32_e32 v219, 0xffff0000, v163
	v_cvt_pk_bf16_f32 v121, v126, v127
	v_lshl_add_u64 v[124:125], v[124:125], 0, v[144:145]
	v_pk_add_f32 v[118:119], v[118:119], v[214:215]
	v_pk_add_f32 v[116:117], v[116:117], v[212:213]
	v_cvt_pk_bf16_f32 v122, v122, v123
	v_cvt_pk_bf16_f32 v123, v194, v195
	global_store_dwordx4 v[124:125], v[120:123], off
	v_lshlrev_b32_e32 v220, 16, v164
	v_and_b32_e32 v221, 0xffff0000, v164
	v_pk_add_f32 v[120:121], v[114:115], v[218:219]
	v_pk_add_f32 v[114:115], v[112:113], v[216:217]
	v_mul_f32_e32 v112, v117, v117
	v_mul_f32_e32 v113, v119, v119
	v_fmac_f32_e32 v112, v116, v116
	v_fmac_f32_e32 v113, v118, v118
	v_add_f32_e32 v112, v112, v113
	v_mul_f32_e32 v113, v115, v115
	v_fmac_f32_e32 v113, v114, v114
	v_add_f32_e32 v112, v113, v112
	v_mul_f32_e32 v113, v121, v121
	v_fmac_f32_e32 v113, v120, v120
	v_add_f32_e32 v112, v113, v112
	v_lshlrev_b32_e32 v222, 16, v165
	v_and_b32_e32 v223, 0xffff0000, v165
	v_add_f32_e32 v126, v181, v112
	v_cvt_pk_bf16_f32 v112, v116, v117
	v_cvt_pk_bf16_f32 v113, v118, v119
	v_lshl_add_u64 v[116:117], s[10:11], 0, v[170:171]
	v_lshlrev_b32_e32 v230, 16, v184
	v_and_b32_e32 v231, 0xffff0000, v184
	v_lshlrev_b32_e32 v232, 16, v186
	v_and_b32_e32 v233, 0xffff0000, v186
	v_lshlrev_b32_e32 v186, 16, v187
	v_and_b32_e32 v187, 0xffff0000, v187
	v_cvt_pk_bf16_f32 v114, v114, v115
	v_cvt_pk_bf16_f32 v115, v120, v121
	global_store_dwordx4 v[124:125], v[112:115], off offset:256
	v_pk_add_f32 v[110:111], v[110:111], v[222:223]
	v_pk_add_f32 v[108:109], v[108:109], v[220:221]
	v_lshl_add_u64 v[118:119], v[116:117], 0, v[144:145]
	v_cvt_pk_bf16_f32 v112, v108, v109
	v_cvt_pk_bf16_f32 v113, v110, v111
	v_lshlrev_b32_e32 v228, 16, v182
	v_and_b32_e32 v229, 0xffff0000, v182
	v_lshlrev_b32_e32 v182, 16, v183
	v_and_b32_e32 v183, 0xffff0000, v183
	v_lshlrev_b32_e32 v184, 16, v185
	v_and_b32_e32 v185, 0xffff0000, v185
	v_lshlrev_b32_e32 v238, 16, v192
	v_and_b32_e32 v239, 0xffff0000, v192
	v_pk_add_f32 v[106:107], v[106:107], v[226:227]
	v_pk_add_f32 v[104:105], v[104:105], v[224:225]
	v_lshlrev_b32_e32 v156, 16, v200
	v_cvt_pk_bf16_f32 v114, v104, v105
	v_cvt_pk_bf16_f32 v115, v106, v107
	global_store_dwordx4 v[118:119], v[112:115], off
	v_and_b32_e32 v157, 0xffff0000, v200
	v_pk_add_f32 v[102:103], v[102:103], v[182:183]
	v_pk_add_f32 v[112:113], v[92:93], v[230:231]
	v_pk_add_f32 v[92:93], v[98:99], v[186:187]
	v_lshl_add_u64 v[98:99], s[10:11], 0, v[154:155]
	v_pk_add_f32 v[100:101], v[100:101], v[228:229]
	v_pk_add_f32 v[94:95], v[94:95], v[184:185]
	v_cvt_pk_bf16_f32 v114, v100, v101
	v_cvt_pk_bf16_f32 v115, v102, v103
	v_cvt_pk_bf16_f32 v116, v112, v113
	v_lshlrev_b32_e32 v234, 16, v188
	v_cvt_pk_bf16_f32 v117, v94, v95
	global_store_dwordx4 v[118:119], v[114:117], off offset:256
	v_lshl_add_u64 v[118:119], v[98:99], 0, v[144:145]
	v_pk_add_f32 v[98:99], v[76:77], v[238:239]
	v_pk_add_f32 v[76:77], v[82:83], v[172:173]
	v_lshl_add_u64 v[82:83], s[10:11], 0, v[152:153]
	v_lshl_add_u64 v[122:123], v[82:83], 0, v[144:145]
	v_pk_add_f32 v[82:83], v[64:65], v[156:157]
	v_and_b32_e32 v65, 64, v174
	v_and_b32_e32 v235, 0xffff0000, v188
	v_lshlrev_b32_e32 v188, 16, v189
	v_and_b32_e32 v189, 0xffff0000, v189
	v_lshlrev_b32_e32 v236, 16, v190
	v_and_b32_e32 v237, 0xffff0000, v190
	v_pk_add_f32 v[96:97], v[96:97], v[232:233]
	v_xor_b32_e32 v64, 16, v174
	v_cvt_pk_bf16_f32 v114, v96, v97
	v_add_u32_e32 v65, 64, v65
	v_lshlrev_b32_e32 v190, 16, v191
	v_and_b32_e32 v191, 0xffff0000, v191
	v_lshlrev_b32_e32 v192, 16, v193
	v_and_b32_e32 v193, 0xffff0000, v193
	v_pk_add_f32 v[90:91], v[90:91], v[188:189]
	v_pk_add_f32 v[88:89], v[88:89], v[234:235]
	v_cvt_pk_bf16_f32 v115, v92, v93
	v_pk_add_f32 v[84:85], v[84:85], v[236:237]
	v_cvt_pk_bf16_f32 v116, v88, v89
	v_cvt_pk_bf16_f32 v117, v90, v91
	global_store_dwordx4 v[118:119], v[114:117], off
	v_cmp_lt_i32_e32 vcc, v64, v65
	v_lshlrev_b32_e32 v164, 16, v196
	v_cvt_pk_bf16_f32 v114, v84, v85
	v_and_b32_e32 v165, 0xffff0000, v196
	v_lshlrev_b32_e32 v168, 16, v197
	v_and_b32_e32 v169, 0xffff0000, v197
	v_pk_add_f32 v[86:87], v[86:87], v[190:191]
	v_pk_add_f32 v[78:79], v[78:79], v[192:193]
	v_cvt_pk_bf16_f32 v115, v86, v87
	v_cvt_pk_bf16_f32 v116, v98, v99
	v_pk_add_f32 v[80:81], v[80:81], v[166:167]
	v_cvt_pk_bf16_f32 v117, v78, v79
	global_store_dwordx4 v[118:119], v[114:117], off offset:256
	v_cndmask_b32_e32 v64, v174, v64, vcc
	v_pk_add_f32 v[74:75], v[74:75], v[168:169]
	v_cvt_pk_bf16_f32 v114, v80, v81
	v_pk_add_f32 v[72:73], v[72:73], v[164:165]
	v_cvt_pk_bf16_f32 v115, v76, v77
	v_lshlrev_b32_e32 v158, 16, v198
	v_cvt_pk_bf16_f32 v116, v72, v73
	v_cvt_pk_bf16_f32 v117, v74, v75
	global_store_dwordx4 v[122:123], v[114:117], off
	v_and_b32_e32 v159, 0xffff0000, v198
	v_lshlrev_b32_e32 v162, 16, v199
	v_lshlrev_b32_e32 v114, 2, v64
	ds_bpermute_b32 v64, v114, v126
	v_xor_b32_e32 v115, 32, v174
	v_cmp_lt_i32_e32 vcc, v115, v65
	v_and_b32_e32 v163, 0xffff0000, v199
	v_lshlrev_b32_e32 v160, 16, v201
	v_cndmask_b32_e32 v65, v174, v115, vcc
	v_lshlrev_b32_e32 v115, 2, v65
	s_waitcnt lgkmcnt(0)
	v_add_f32_e32 v116, v126, v64
	ds_bpermute_b32 v117, v115, v116
	v_and_b32_e32 v161, 0xffff0000, v201
	v_pk_add_f32 v[70:71], v[70:71], v[162:163]
	v_pk_add_f32 v[68:69], v[68:69], v[158:159]
	v_pk_add_f32 v[66:67], v[66:67], v[160:161]
	v_lshl_add_u64 v[64:65], v[150:151], 2, s[18:19]
	v_cvt_pk_bf16_f32 v118, v68, v69
	v_cvt_pk_bf16_f32 v119, v70, v71
	v_cvt_pk_bf16_f32 v120, v82, v83
	v_cvt_pk_bf16_f32 v121, v66, v67
	global_store_dwordx4 v[122:123], v[118:121], off offset:256
	s_and_saveexec_b64 s[36:37], s[6:7]
	s_cbranch_execz .LBB0_1025
	s_waitcnt lgkmcnt(0)
	v_add_f32_e32 v116, v116, v117
	global_atomic_add_f32 v[64:65], v116, off

.LBB0_1080:
	ds_read_b128 v[144:147], v151
	ds_read_b128 v[156:159], v151 offset:1024
	ds_read_b128 v[160:163], v151 offset:2048
	ds_read_b128 v[164:167], v151 offset:3072
	s_add_u32 s36, s2, 0xfffc0080
	s_addc_u32 s37, s3, -1
	s_cmp_eq_u32 s67, 12
	s_cselect_b32 s39, s29, s37
	s_cselect_b32 s38, s63, s36
	s_cselect_b32 s37, s27, s66
	s_cselect_b32 s36, s64, s65
	v_lshl_add_u64 v[172:173], s[2:3], 0, v[136:137]
	s_add_i32 m0, s48, 0xc000
	ds_read_b128 v[168:171], v152
	ds_read_b128 v[176:179], v152 offset:1024
	ds_read_b128 v[180:183], v152 offset:2048
	ds_read_b128 v[184:187], v152 offset:3072
	ds_read_b128 v[188:191], v152 offset:4096
	ds_read_b128 v[192:195], v152 offset:5120
	ds_read_b128 v[196:199], v152 offset:6144
	ds_read_b128 v[200:203], v152 offset:7168
	global_load_lds_dwordx4 v[172:173], off
	v_lshl_add_u64 v[172:173], s[2:3], 0, v[138:139]
	s_add_i32 m0, s48, 0xe000
	s_nop 0
	global_load_lds_dwordx4 v[172:173], off
	s_waitcnt lgkmcnt(8)
	s_barrier
	s_waitcnt lgkmcnt(0)
	s_setprio 1
	v_mfma_f32_16x16x32_bf16 v[124:127], v[144:147], v[168:171], v[124:127]
	v_mfma_f32_16x16x32_bf16 v[120:123], v[160:163], v[168:171], v[120:123]
	v_mfma_f32_16x16x32_bf16 v[116:119], v[144:147], v[180:183], v[116:119]
	v_mfma_f32_16x16x32_bf16 v[112:115], v[160:163], v[180:183], v[112:115]
	v_mfma_f32_16x16x32_bf16 v[104:107], v[144:147], v[188:191], v[104:107]
	v_mfma_f32_16x16x32_bf16 v[96:99], v[160:163], v[188:191], v[96:99]
	v_mfma_f32_16x16x32_bf16 v[76:79], v[144:147], v[196:199], v[76:79]
	v_mfma_f32_16x16x32_bf16 v[72:75], v[160:163], v[196:199], v[72:75]
	v_mfma_f32_16x16x32_bf16 v[124:127], v[156:159], v[176:179], v[124:127]
	v_mfma_f32_16x16x32_bf16 v[120:123], v[164:167], v[176:179], v[120:123]
	v_mfma_f32_16x16x32_bf16 v[116:119], v[156:159], v[184:187], v[116:119]
	v_mfma_f32_16x16x32_bf16 v[112:115], v[164:167], v[184:187], v[112:115]
	v_mfma_f32_16x16x32_bf16 v[104:107], v[156:159], v[192:195], v[104:107]
	v_mfma_f32_16x16x32_bf16 v[96:99], v[164:167], v[192:195], v[96:99]
	v_mfma_f32_16x16x32_bf16 v[76:79], v[156:159], v[200:203], v[76:79]
	v_mfma_f32_16x16x32_bf16 v[72:75], v[164:167], v[200:203], v[72:75]
	s_setprio 0
	s_barrier
	s_add_i32 s68, s56, s43
	v_lshl_add_u64 v[172:173], s[36:37], 0, v[130:131]
	s_mov_b32 m0, s68
	ds_read_b128 v[204:207], v153
	ds_read_b128 v[212:215], v153 offset:1024
	ds_read_b128 v[216:219], v153 offset:2048
	ds_read_b128 v[220:223], v153 offset:3072
	global_load_lds_dwordx4 v[172:173], off
	v_lshl_add_u64 v[208:209], s[36:37], 0, v[134:135]
	s_add_i32 m0, s68, 0x2000
	s_nop 0
	global_load_lds_dwordx4 v[208:209], off
	s_barrier
	s_waitcnt lgkmcnt(0)
	s_setprio 1
	v_mfma_f32_16x16x32_bf16 v[108:111], v[204:207], v[168:171], v[108:111]
	v_mfma_f32_16x16x32_bf16 v[100:103], v[216:219], v[168:171], v[100:103]
	v_mfma_f32_16x16x32_bf16 v[92:95], v[204:207], v[180:183], v[92:95]
	v_mfma_f32_16x16x32_bf16 v[88:91], v[216:219], v[180:183], v[88:91]
	v_mfma_f32_16x16x32_bf16 v[84:87], v[204:207], v[188:191], v[84:87]
	v_mfma_f32_16x16x32_bf16 v[80:83], v[216:219], v[188:191], v[80:83]
	v_mfma_f32_16x16x32_bf16 v[68:71], v[204:207], v[196:199], v[68:71]
	v_mfma_f32_16x16x32_bf16 v[64:67], v[216:219], v[196:199], v[64:67]
	v_mfma_f32_16x16x32_bf16 v[108:111], v[212:215], v[176:179], v[108:111]
	v_mfma_f32_16x16x32_bf16 v[100:103], v[220:223], v[176:179], v[100:103]
	v_mfma_f32_16x16x32_bf16 v[92:95], v[212:215], v[184:187], v[92:95]
	v_mfma_f32_16x16x32_bf16 v[88:91], v[220:223], v[184:187], v[88:91]
	v_mfma_f32_16x16x32_bf16 v[84:87], v[212:215], v[192:195], v[84:87]
	v_mfma_f32_16x16x32_bf16 v[80:83], v[220:223], v[192:195], v[80:83]
	v_mfma_f32_16x16x32_bf16 v[68:71], v[212:215], v[200:203], v[68:71]
	v_mfma_f32_16x16x32_bf16 v[64:67], v[220:223], v[200:203], v[64:67]
	s_setprio 0
	s_mov_b32 m0, s48
	v_lshl_add_u64 v[224:225], s[38:39], 0, v[128:129]
	s_barrier
	ds_read_b128 v[168:171], v152 offset:16384
	ds_read_b128 v[176:179], v152 offset:17408
	ds_read_b128 v[180:183], v152 offset:18432
	ds_read_b128 v[184:187], v152 offset:19456
	ds_read_b128 v[188:191], v152 offset:20480
	ds_read_b128 v[192:195], v152 offset:21504
	ds_read_b128 v[196:199], v152 offset:22528
	ds_read_b128 v[200:203], v152 offset:23552
	global_load_lds_dwordx4 v[224:225], off
	v_lshl_add_u64 v[226:227], s[38:39], 0, v[132:133]
	s_mov_b32 m0, s49
	s_nop 0
	global_load_lds_dwordx4 v[226:227], off
	s_barrier
	s_waitcnt lgkmcnt(0)
	s_setprio 1
	v_mfma_f32_16x16x32_bf16 v[60:63], v[144:147], v[168:171], v[60:63]
	v_mfma_f32_16x16x32_bf16 v[56:59], v[160:163], v[168:171], v[56:59]
	v_mfma_f32_16x16x32_bf16 v[44:47], v[144:147], v[180:183], v[44:47]
	v_mfma_f32_16x16x32_bf16 v[40:43], v[160:163], v[180:183], v[40:43]
	v_mfma_f32_16x16x32_bf16 v[28:31], v[144:147], v[188:191], v[28:31]
	v_mfma_f32_16x16x32_bf16 v[24:27], v[160:163], v[188:191], v[24:27]
	v_mfma_f32_16x16x32_bf16 v[12:15], v[144:147], v[196:199], v[12:15]
	v_mfma_f32_16x16x32_bf16 v[8:11], v[160:163], v[196:199], v[8:11]
	v_mfma_f32_16x16x32_bf16 v[60:63], v[156:159], v[176:179], v[60:63]
	v_mfma_f32_16x16x32_bf16 v[56:59], v[164:167], v[176:179], v[56:59]
	v_mfma_f32_16x16x32_bf16 v[44:47], v[156:159], v[184:187], v[44:47]
	v_mfma_f32_16x16x32_bf16 v[40:43], v[164:167], v[184:187], v[40:43]
	v_mfma_f32_16x16x32_bf16 v[28:31], v[156:159], v[192:195], v[28:31]
	v_mfma_f32_16x16x32_bf16 v[24:27], v[164:167], v[192:195], v[24:27]
	v_mfma_f32_16x16x32_bf16 v[12:15], v[156:159], v[200:203], v[12:15]
	v_mfma_f32_16x16x32_bf16 v[8:11], v[164:167], v[200:203], v[8:11]
	s_setprio 0
	s_barrier
	s_add_u32 s68, s36, 0x40000
	s_addc_u32 s69, s37, 0
	s_add_i32 s70, s57, s43
	v_lshl_add_u64 v[144:145], s[68:69], 0, v[130:131]
	s_mov_b32 m0, s70
	s_nop 0
	global_load_lds_dwordx4 v[144:145], off
	v_lshl_add_u64 v[144:145], s[68:69], 0, v[134:135]
	s_add_i32 m0, s70, 0x2000
	s_nop 0
	global_load_lds_dwordx4 v[144:145], off
	s_waitcnt vmcnt(6)
	s_barrier
	s_setprio 1
	v_mfma_f32_16x16x32_bf16 v[52:55], v[204:207], v[168:171], v[52:55]
	v_mfma_f32_16x16x32_bf16 v[48:51], v[216:219], v[168:171], v[48:51]
	v_mfma_f32_16x16x32_bf16 v[36:39], v[204:207], v[180:183], v[36:39]
	v_mfma_f32_16x16x32_bf16 v[32:35], v[216:219], v[180:183], v[32:35]
	v_mfma_f32_16x16x32_bf16 v[20:23], v[204:207], v[188:191], v[20:23]
	v_mfma_f32_16x16x32_bf16 v[16:19], v[216:219], v[188:191], v[16:19]
	v_mfma_f32_16x16x32_bf16 v[4:7], v[204:207], v[196:199], v[4:7]
	v_mfma_f32_16x16x32_bf16 v[0:3], v[216:219], v[196:199], v[0:3]
	v_mfma_f32_16x16x32_bf16 v[52:55], v[212:215], v[176:179], v[52:55]
	v_mfma_f32_16x16x32_bf16 v[48:51], v[220:223], v[176:179], v[48:51]
	v_mfma_f32_16x16x32_bf16 v[36:39], v[212:215], v[184:187], v[36:39]
	v_mfma_f32_16x16x32_bf16 v[32:35], v[220:223], v[184:187], v[32:35]
	v_mfma_f32_16x16x32_bf16 v[20:23], v[212:215], v[192:195], v[20:23]
	v_mfma_f32_16x16x32_bf16 v[16:19], v[220:223], v[192:195], v[16:19]
	v_mfma_f32_16x16x32_bf16 v[4:7], v[212:215], v[200:203], v[4:7]
	v_mfma_f32_16x16x32_bf16 v[0:3], v[220:223], v[200:203], v[0:3]
	s_setprio 0
	s_add_i32 s68, 0, 0x18000
	v_add_u32_e32 v155, s68, v149
	s_barrier
	ds_read_b128 v[144:147], v155
	ds_read_b128 v[156:159], v155 offset:1024
	ds_read_b128 v[160:163], v155 offset:2048
	ds_read_b128 v[164:167], v155 offset:3072
	s_add_u32 s38, s38, 0x40000
	s_addc_u32 s39, s39, 0
	s_mov_b32 m0, s50
	v_lshl_add_u64 v[204:205], s[38:39], 0, v[128:129]
	ds_read_b128 v[168:171], v152 offset:32768
	ds_read_b128 v[176:179], v152 offset:33792
	ds_read_b128 v[180:183], v152 offset:34816
	ds_read_b128 v[184:187], v152 offset:35840
	ds_read_b128 v[188:191], v152 offset:36864
	ds_read_b128 v[192:195], v152 offset:37888
	ds_read_b128 v[196:199], v152 offset:38912
	ds_read_b128 v[200:203], v152 offset:39936
	global_load_lds_dwordx4 v[204:205], off
	v_lshl_add_u64 v[204:205], s[38:39], 0, v[132:133]
	s_mov_b32 m0, s51
	s_nop 0
	global_load_lds_dwordx4 v[204:205], off
	s_waitcnt lgkmcnt(8)
	s_barrier
	s_waitcnt lgkmcnt(0)
	s_setprio 1
	v_mfma_f32_16x16x32_bf16 v[124:127], v[144:147], v[168:171], v[124:127]
	v_mfma_f32_16x16x32_bf16 v[120:123], v[160:163], v[168:171], v[120:123]
	v_mfma_f32_16x16x32_bf16 v[116:119], v[144:147], v[180:183], v[116:119]
	v_mfma_f32_16x16x32_bf16 v[112:115], v[160:163], v[180:183], v[112:115]
	v_mfma_f32_16x16x32_bf16 v[104:107], v[144:147], v[188:191], v[104:107]
	v_mfma_f32_16x16x32_bf16 v[96:99], v[160:163], v[188:191], v[96:99]
	v_mfma_f32_16x16x32_bf16 v[76:79], v[144:147], v[196:199], v[76:79]
	v_mfma_f32_16x16x32_bf16 v[72:75], v[160:163], v[196:199], v[72:75]
	v_mfma_f32_16x16x32_bf16 v[124:127], v[156:159], v[176:179], v[124:127]
	v_mfma_f32_16x16x32_bf16 v[120:123], v[164:167], v[176:179], v[120:123]
	v_mfma_f32_16x16x32_bf16 v[116:119], v[156:159], v[184:187], v[116:119]
	v_mfma_f32_16x16x32_bf16 v[112:115], v[164:167], v[184:187], v[112:115]
	v_mfma_f32_16x16x32_bf16 v[104:107], v[156:159], v[192:195], v[104:107]
	v_mfma_f32_16x16x32_bf16 v[96:99], v[164:167], v[192:195], v[96:99]
	v_mfma_f32_16x16x32_bf16 v[76:79], v[156:159], v[200:203], v[76:79]
	v_mfma_f32_16x16x32_bf16 v[72:75], v[164:167], v[200:203], v[72:75]
	s_setprio 0
	s_barrier
	s_add_i32 s38, 0, 0x1c000
	s_add_i32 s39, s68, s43
	v_add_u32_e32 v155, s38, v149
	v_lshl_add_u64 v[172:173], v[172:173], 0, s[8:9]
	s_mov_b32 m0, s39
	ds_read_b128 v[204:207], v155
	ds_read_b128 v[212:215], v155 offset:1024
	ds_read_b128 v[216:219], v155 offset:2048
	ds_read_b128 v[220:223], v155 offset:3072
	global_load_lds_dwordx4 v[172:173], off
	v_lshl_add_u64 v[172:173], v[208:209], 0, s[8:9]
	s_add_i32 m0, s39, 0x2000
	s_nop 0
	global_load_lds_dwordx4 v[172:173], off
	s_barrier
	s_waitcnt lgkmcnt(0)
	s_setprio 1
	v_mfma_f32_16x16x32_bf16 v[108:111], v[204:207], v[168:171], v[108:111]
	v_mfma_f32_16x16x32_bf16 v[100:103], v[216:219], v[168:171], v[100:103]
	v_mfma_f32_16x16x32_bf16 v[92:95], v[204:207], v[180:183], v[92:95]
	v_mfma_f32_16x16x32_bf16 v[88:91], v[216:219], v[180:183], v[88:91]
	v_mfma_f32_16x16x32_bf16 v[84:87], v[204:207], v[188:191], v[84:87]
	v_mfma_f32_16x16x32_bf16 v[80:83], v[216:219], v[188:191], v[80:83]
	v_mfma_f32_16x16x32_bf16 v[68:71], v[204:207], v[196:199], v[68:71]
	v_mfma_f32_16x16x32_bf16 v[64:67], v[216:219], v[196:199], v[64:67]
	v_mfma_f32_16x16x32_bf16 v[108:111], v[212:215], v[176:179], v[108:111]
	v_mfma_f32_16x16x32_bf16 v[100:103], v[220:223], v[176:179], v[100:103]
	v_mfma_f32_16x16x32_bf16 v[92:95], v[212:215], v[184:187], v[92:95]
	v_mfma_f32_16x16x32_bf16 v[88:91], v[220:223], v[184:187], v[88:91]
	v_mfma_f32_16x16x32_bf16 v[84:87], v[212:215], v[192:195], v[84:87]
	v_mfma_f32_16x16x32_bf16 v[80:83], v[220:223], v[192:195], v[80:83]
	v_mfma_f32_16x16x32_bf16 v[68:71], v[212:215], v[200:203], v[68:71]
	v_mfma_f32_16x16x32_bf16 v[64:67], v[220:223], v[200:203], v[64:67]
	s_setprio 0
	s_mov_b32 m0, s53
	v_lshl_add_u64 v[172:173], v[224:225], 0, s[8:9]
	s_barrier
	ds_read_b128 v[168:171], v152 offset:49152
	ds_read_b128 v[176:179], v152 offset:50176
	ds_read_b128 v[180:183], v152 offset:51200
	ds_read_b128 v[184:187], v152 offset:52224
	ds_read_b128 v[188:191], v152 offset:53248
	ds_read_b128 v[192:195], v152 offset:54272
	ds_read_b128 v[196:199], v152 offset:55296
	ds_read_b128 v[200:203], v152 offset:56320
	global_load_lds_dwordx4 v[172:173], off
	v_lshl_add_u64 v[172:173], v[226:227], 0, s[8:9]
	s_mov_b32 m0, s54
	s_nop 0
	global_load_lds_dwordx4 v[172:173], off
	s_barrier
	s_waitcnt lgkmcnt(0)
	s_setprio 1
	v_mfma_f32_16x16x32_bf16 v[60:63], v[144:147], v[168:171], v[60:63]
	v_mfma_f32_16x16x32_bf16 v[56:59], v[160:163], v[168:171], v[56:59]
	v_mfma_f32_16x16x32_bf16 v[44:47], v[144:147], v[180:183], v[44:47]
	v_mfma_f32_16x16x32_bf16 v[40:43], v[160:163], v[180:183], v[40:43]
	v_mfma_f32_16x16x32_bf16 v[28:31], v[144:147], v[188:191], v[28:31]
	v_mfma_f32_16x16x32_bf16 v[24:27], v[160:163], v[188:191], v[24:27]
	v_mfma_f32_16x16x32_bf16 v[12:15], v[144:147], v[196:199], v[12:15]
	v_mfma_f32_16x16x32_bf16 v[8:11], v[160:163], v[196:199], v[8:11]
	v_mfma_f32_16x16x32_bf16 v[60:63], v[156:159], v[176:179], v[60:63]
	v_mfma_f32_16x16x32_bf16 v[56:59], v[164:167], v[176:179], v[56:59]
	v_mfma_f32_16x16x32_bf16 v[44:47], v[156:159], v[184:187], v[44:47]
	v_mfma_f32_16x16x32_bf16 v[40:43], v[164:167], v[184:187], v[40:43]
	v_mfma_f32_16x16x32_bf16 v[28:31], v[156:159], v[192:195], v[28:31]
	v_mfma_f32_16x16x32_bf16 v[24:27], v[164:167], v[192:195], v[24:27]
	v_mfma_f32_16x16x32_bf16 v[12:15], v[156:159], v[200:203], v[12:15]
	v_mfma_f32_16x16x32_bf16 v[8:11], v[164:167], v[200:203], v[8:11]
	s_setprio 0
	s_barrier
	s_add_u32 s36, s36, 0x40080
	s_addc_u32 s37, s37, 0
	s_add_i32 s38, s38, s43
	v_lshl_add_u64 v[144:145], s[36:37], 0, v[130:131]
	s_mov_b32 m0, s38
	s_nop 0
	global_load_lds_dwordx4 v[144:145], off
	v_lshl_add_u64 v[144:145], s[36:37], 0, v[134:135]
	s_add_i32 m0, s38, 0x2000
	s_nop 0
	global_load_lds_dwordx4 v[144:145], off
	s_waitcnt vmcnt(6)
	s_barrier
	s_setprio 1
	v_mfma_f32_16x16x32_bf16 v[52:55], v[204:207], v[168:171], v[52:55]
	v_mfma_f32_16x16x32_bf16 v[48:51], v[216:219], v[168:171], v[48:51]
	v_mfma_f32_16x16x32_bf16 v[36:39], v[204:207], v[180:183], v[36:39]
	v_mfma_f32_16x16x32_bf16 v[32:35], v[216:219], v[180:183], v[32:35]
	v_mfma_f32_16x16x32_bf16 v[20:23], v[204:207], v[188:191], v[20:23]
	v_mfma_f32_16x16x32_bf16 v[16:19], v[216:219], v[188:191], v[16:19]
	v_mfma_f32_16x16x32_bf16 v[4:7], v[204:207], v[196:199], v[4:7]
	v_mfma_f32_16x16x32_bf16 v[0:3], v[216:219], v[196:199], v[0:3]
	v_mfma_f32_16x16x32_bf16 v[52:55], v[212:215], v[176:179], v[52:55]
	v_mfma_f32_16x16x32_bf16 v[48:51], v[220:223], v[176:179], v[48:51]
	v_mfma_f32_16x16x32_bf16 v[36:39], v[212:215], v[184:187], v[36:39]
	v_mfma_f32_16x16x32_bf16 v[32:35], v[220:223], v[184:187], v[32:35]
	v_mfma_f32_16x16x32_bf16 v[20:23], v[212:215], v[192:195], v[20:23]
	v_mfma_f32_16x16x32_bf16 v[16:19], v[220:223], v[192:195], v[16:19]
	v_mfma_f32_16x16x32_bf16 v[4:7], v[212:215], v[200:203], v[4:7]
	v_mfma_f32_16x16x32_bf16 v[0:3], v[220:223], v[200:203], v[0:3]
	s_setprio 0
	s_add_i32 s67, s67, 2
	s_add_u32 s2, s2, 0x100
	s_addc_u32 s3, s3, 0
	s_add_u32 s65, s65, 0x100
	s_addc_u32 s66, s66, 0
	s_cmp_gt_u32 s67, 13
	s_barrier
	s_cbranch_scc0 .LBB0_1080
	v_lshl_add_u32 v146, s0, 8, v148
	v_ashrrev_i32_e32 v147, 31, v146
	v_lshl_add_u64 v[144:145], v[146:147], 2, s[18:19]
	global_load_dword v155, v[144:145], off
	global_load_dword v164, v[144:145], off offset:64
	global_load_dword v165, v[144:145], off offset:128
	global_load_dword v166, v[144:145], off offset:192
	global_load_dword v167, v[144:145], off offset:512
	global_load_dword v168, v[144:145], off offset:576
	global_load_dword v169, v[144:145], off offset:640
	global_load_dword v170, v[144:145], off offset:704
	v_lshl_or_b32 v144, s1, 8, v150
	v_ashrrev_i32_e32 v145, 31, v144
	v_lshlrev_b64 v[160:161], 10, v[146:147]
	v_lshlrev_b64 v[162:163], 1, v[144:145]
	v_lshl_add_u64 v[144:145], s[92:93], 0, v[160:161]
	v_or_b32_e32 v156, 16, v146
	v_ashrrev_i32_e32 v157, 31, v156
	v_or_b32_e32 v158, 32, v146
	v_lshlrev_b64 v[156:157], 10, v[156:157]
	v_lshl_add_u64 v[144:145], v[144:145], 0, v[162:163]
	v_ashrrev_i32_e32 v159, 31, v158
	v_lshl_add_u64 v[156:157], s[92:93], 0, v[156:157]
	v_lshlrev_b64 v[158:159], 10, v[158:159]
	v_lshl_add_u64 v[156:157], v[156:157], 0, v[162:163]
	v_lshl_add_u64 v[158:159], s[92:93], 0, v[158:159]
	v_lshl_add_u64 v[158:159], v[158:159], 0, v[162:163]
	s_mov_b64 s[36:37], s[34:35]
	s_waitcnt vmcnt(0)
	v_fmamk_f32 v147, v155, 0x3a800000, v154
	v_fmamk_f32 v155, v164, 0x3a800000, v154
	v_fmamk_f32 v160, v165, 0x3a800000, v154
	v_mul_f32_e32 v161, 0x4b800000, v147
	v_mul_f32_e32 v164, 0x4b800000, v155
	v_cmp_gt_f32_e32 vcc, s58, v147
	v_cmp_gt_f32_e64 s[0:1], s58, v155
	v_mul_f32_e32 v165, 0x4b800000, v160
	v_cndmask_b32_e32 v147, v147, v161, vcc
	v_cndmask_b32_e64 v155, v155, v164, s[0:1]
	v_cmp_gt_f32_e64 s[2:3], s58, v160
	v_rsq_f32_e32 v147, v147
	v_rsq_f32_e32 v155, v155
	v_cndmask_b32_e64 v160, v160, v165, s[2:3]
	v_rsq_f32_e32 v160, v160
	v_mul_f32_e32 v161, 0x45800000, v147
	v_mul_f32_e32 v164, 0x45800000, v155
	v_cndmask_b32_e32 v147, v147, v161, vcc
	v_mul_f32_e32 v165, 0x45800000, v160
	v_cndmask_b32_e64 v155, v155, v164, s[0:1]
	v_cndmask_b32_e64 v161, v160, v165, s[2:3]
	v_mul_f32_e32 v160, 0x3e0293ee, v147
	v_mul_f32_e32 v164, 0x3e0293ee, v155
	v_fmamk_f32 v171, v166, 0x3a800000, v154
	v_mul_f32_e32 v166, 0x3e0293ee, v161
	v_pk_mul_f32 v[126:127], v[126:127], v[160:161] op_sel_hi:[1,0]
	v_pk_mul_f32 v[124:125], v[124:125], v[160:161] op_sel_hi:[1,0]
	v_pk_mul_f32 v[122:123], v[122:123], v[160:161] op_sel_hi:[1,0]
	v_pk_mul_f32 v[120:121], v[120:121], v[160:161] op_sel_hi:[1,0]
	v_pk_mul_f32 v[110:111], v[110:111], v[160:161] op_sel_hi:[1,0]
	v_pk_mul_f32 v[108:109], v[108:109], v[160:161] op_sel_hi:[1,0]
	v_pk_mul_f32 v[102:103], v[102:103], v[160:161] op_sel_hi:[1,0]
	v_pk_mul_f32 v[100:101], v[100:101], v[160:161] op_sel_hi:[1,0]
	v_pk_mul_f32 v[118:119], v[118:119], v[164:165] op_sel_hi:[1,0]
	v_pk_mul_f32 v[116:117], v[116:117], v[164:165] op_sel_hi:[1,0]
	v_pk_mul_f32 v[114:115], v[114:115], v[164:165] op_sel_hi:[1,0]
	v_pk_mul_f32 v[112:113], v[112:113], v[164:165] op_sel_hi:[1,0]
	v_pk_mul_f32 v[94:95], v[94:95], v[164:165] op_sel_hi:[1,0]
	v_pk_mul_f32 v[92:93], v[92:93], v[164:165] op_sel_hi:[1,0]
	v_pk_mul_f32 v[160:161], v[90:91], v[164:165] op_sel_hi:[1,0]
	v_pk_mul_f32 v[164:165], v[88:89], v[164:165] op_sel_hi:[1,0]
	v_cvt_pk_bf16_f32 v88, v124, v125
	v_cvt_pk_bf16_f32 v89, v126, v127
	v_cvt_pk_bf16_f32 v90, v120, v121
	v_cvt_pk_bf16_f32 v91, v122, v123
	global_store_dwordx4 v[144:145], v[88:91], off
	v_fmamk_f32 v167, v167, 0x3a800000, v154
	v_pk_mul_f32 v[106:107], v[106:107], v[166:167] op_sel_hi:[1,0]
	v_cvt_pk_bf16_f32 v88, v108, v109
	v_cvt_pk_bf16_f32 v89, v110, v111
	v_cvt_pk_bf16_f32 v90, v100, v101
	v_cvt_pk_bf16_f32 v91, v102, v103
	global_store_dwordx4 v[144:145], v[88:91], off offset:256
	v_pk_mul_f32 v[104:105], v[104:105], v[166:167] op_sel_hi:[1,0]
	v_pk_mul_f32 v[98:99], v[98:99], v[166:167] op_sel_hi:[1,0]
	v_cvt_pk_bf16_f32 v88, v116, v117
	v_cvt_pk_bf16_f32 v89, v118, v119
	v_cvt_pk_bf16_f32 v90, v112, v113
	v_cvt_pk_bf16_f32 v91, v114, v115
	global_store_dwordx4 v[156:157], v[88:91], off
	v_pk_mul_f32 v[96:97], v[96:97], v[166:167] op_sel_hi:[1,0]
	v_pk_mul_f32 v[86:87], v[86:87], v[166:167] op_sel_hi:[1,0]
	v_cvt_pk_bf16_f32 v88, v92, v93
	v_cvt_pk_bf16_f32 v89, v94, v95
	v_cvt_pk_bf16_f32 v90, v164, v165
	v_cvt_pk_bf16_f32 v91, v160, v161
	global_store_dwordx4 v[156:157], v[88:91], off offset:256
	v_pk_mul_f32 v[84:85], v[84:85], v[166:167] op_sel_hi:[1,0]
	v_cmp_gt_f32_e32 vcc, s58, v171
	v_cvt_pk_bf16_f32 v88, v104, v105
	v_cvt_pk_bf16_f32 v89, v106, v107
	v_cvt_pk_bf16_f32 v90, v96, v97
	v_cvt_pk_bf16_f32 v91, v98, v99
	global_store_dwordx4 v[158:159], v[88:91], off
	v_fmamk_f32 v168, v168, 0x3a800000, v154
	v_fmamk_f32 v169, v169, 0x3a800000, v154
	v_pk_mul_f32 v[88:89], v[82:83], v[166:167] op_sel_hi:[1,0]
	v_pk_mul_f32 v[82:83], v[80:81], v[166:167] op_sel_hi:[1,0]
	v_cvt_pk_bf16_f32 v80, v84, v85
	v_cvt_pk_bf16_f32 v81, v86, v87
	v_fmamk_f32 v170, v170, 0x3a800000, v154
	v_cvt_pk_bf16_f32 v82, v82, v83
	v_cvt_pk_bf16_f32 v83, v88, v89
	global_store_dwordx4 v[158:159], v[80:83], off offset:256
	s_mov_b32 s1, s26
	s_mov_b32 s0, s28
	v_mul_f32_e32 v82, 0x4b800000, v171
	v_cndmask_b32_e32 v82, v171, v82, vcc
	v_rsq_f32_e32 v82, v82
	v_or_b32_e32 v80, 48, v146
	v_ashrrev_i32_e32 v81, 31, v80
	v_lshlrev_b64 v[80:81], 10, v[80:81]
	v_mul_f32_e32 v83, 0x45800000, v82
	v_cndmask_b32_e32 v82, v82, v83, vcc
	v_lshl_add_u64 v[80:81], s[92:93], 0, v[80:81]
	v_mul_f32_e32 v82, 0x3e0293ee, v82
	v_lshl_add_u64 v[80:81], v[80:81], 0, v[162:163]
	v_pk_mul_f32 v[78:79], v[78:79], v[82:83] op_sel_hi:[1,0]
	v_pk_mul_f32 v[76:77], v[76:77], v[82:83] op_sel_hi:[1,0]
	v_pk_mul_f32 v[84:85], v[74:75], v[82:83] op_sel_hi:[1,0]
	v_pk_mul_f32 v[74:75], v[72:73], v[82:83] op_sel_hi:[1,0]
	v_cvt_pk_bf16_f32 v72, v76, v77
	v_cvt_pk_bf16_f32 v73, v78, v79
	v_pk_mul_f32 v[70:71], v[70:71], v[82:83] op_sel_hi:[1,0]
	v_cvt_pk_bf16_f32 v74, v74, v75
	v_cvt_pk_bf16_f32 v75, v84, v85
	global_store_dwordx4 v[80:81], v[72:75], off
	v_pk_mul_f32 v[68:69], v[68:69], v[82:83] op_sel_hi:[1,0]
	v_cmp_gt_f32_e32 vcc, s58, v167
	v_pk_mul_f32 v[72:73], v[66:67], v[82:83] op_sel_hi:[1,0]
	v_pk_mul_f32 v[66:67], v[64:65], v[82:83] op_sel_hi:[1,0]
	v_cvt_pk_bf16_f32 v64, v68, v69
	v_cvt_pk_bf16_f32 v65, v70, v71
	s_mov_b64 s[2:3], s[30:31]
	v_cvt_pk_bf16_f32 v66, v66, v67
	v_mul_f32_e32 v67, 0x4b800000, v167
	v_cndmask_b32_e32 v67, v167, v67, vcc
	v_rsq_f32_e32 v68, v67
	v_cvt_pk_bf16_f32 v67, v72, v73
	global_store_dwordx4 v[80:81], v[64:67], off offset:256
	s_nop 1
	v_mul_f32_e32 v66, 0x45800000, v68
	v_cndmask_b32_e32 v66, v68, v66, vcc
	v_mul_f32_e32 v66, 0x3e0293ee, v66
	v_pk_mul_f32 v[60:61], v[60:61], v[66:67] op_sel_hi:[1,0]
	v_pk_mul_f32 v[68:69], v[58:59], v[66:67] op_sel_hi:[1,0]
	v_pk_mul_f32 v[58:59], v[56:57], v[66:67] op_sel_hi:[1,0]
	v_cvt_pk_bf16_f32 v56, v60, v61
	v_add_co_u32_e32 v60, vcc, s59, v144
	v_pk_mul_f32 v[62:63], v[62:63], v[66:67] op_sel_hi:[1,0]
	s_nop 0
	v_addc_co_u32_e32 v61, vcc, 0, v145, vcc
	v_cvt_pk_bf16_f32 v57, v62, v63
	v_cvt_pk_bf16_f32 v58, v58, v59
	v_cvt_pk_bf16_f32 v59, v68, v69
	global_store_dwordx4 v[60:61], v[56:59], off
	v_pk_mul_f32 v[54:55], v[54:55], v[66:67] op_sel_hi:[1,0]
	v_pk_mul_f32 v[52:53], v[52:53], v[66:67] op_sel_hi:[1,0]
	v_pk_mul_f32 v[56:57], v[50:51], v[66:67] op_sel_hi:[1,0]
	v_pk_mul_f32 v[50:51], v[48:49], v[66:67] op_sel_hi:[1,0]
	v_cvt_pk_bf16_f32 v48, v52, v53
	v_cvt_pk_bf16_f32 v49, v54, v55
	v_cmp_gt_f32_e32 vcc, s58, v168
	v_cvt_pk_bf16_f32 v50, v50, v51
	v_mul_f32_e32 v51, 0x4b800000, v168
	v_lshl_add_u64 v[64:65], v[144:145], 0, s[14:15]
	v_cndmask_b32_e32 v51, v168, v51, vcc
	v_rsq_f32_e32 v52, v51
	v_cvt_pk_bf16_f32 v51, v56, v57
	global_store_dwordx4 v[64:65], v[48:51], off offset:256
	s_nop 1
	v_mul_f32_e32 v50, 0x45800000, v52
	v_cndmask_b32_e32 v50, v52, v50, vcc
	v_mul_f32_e32 v50, 0x3e0293ee, v50
	v_pk_mul_f32 v[44:45], v[44:45], v[50:51] op_sel_hi:[1,0]
	v_pk_mul_f32 v[52:53], v[42:43], v[50:51] op_sel_hi:[1,0]
	v_pk_mul_f32 v[42:43], v[40:41], v[50:51] op_sel_hi:[1,0]
	v_cvt_pk_bf16_f32 v40, v44, v45
	v_add_co_u32_e32 v44, vcc, s60, v144
	v_pk_mul_f32 v[46:47], v[46:47], v[50:51] op_sel_hi:[1,0]
	s_nop 0
	v_addc_co_u32_e32 v45, vcc, 0, v145, vcc
	v_cvt_pk_bf16_f32 v41, v46, v47
	v_cvt_pk_bf16_f32 v42, v42, v43
	v_cvt_pk_bf16_f32 v43, v52, v53
	global_store_dwordx4 v[44:45], v[40:43], off
	v_pk_mul_f32 v[38:39], v[38:39], v[50:51] op_sel_hi:[1,0]
	v_pk_mul_f32 v[36:37], v[36:37], v[50:51] op_sel_hi:[1,0]
	v_pk_mul_f32 v[40:41], v[34:35], v[50:51] op_sel_hi:[1,0]
	v_pk_mul_f32 v[34:35], v[32:33], v[50:51] op_sel_hi:[1,0]
	v_cvt_pk_bf16_f32 v32, v36, v37
	v_cvt_pk_bf16_f32 v33, v38, v39
	v_cmp_gt_f32_e32 vcc, s58, v169
	v_cvt_pk_bf16_f32 v34, v34, v35
	v_mul_f32_e32 v35, 0x4b800000, v169
	v_lshl_add_u64 v[48:49], v[144:145], 0, s[20:21]
	v_cndmask_b32_e32 v35, v169, v35, vcc
	v_rsq_f32_e32 v36, v35
	v_cvt_pk_bf16_f32 v35, v40, v41
	global_store_dwordx4 v[48:49], v[32:35], off offset:256
	s_nop 1
	v_mul_f32_e32 v34, 0x45800000, v36
	v_cndmask_b32_e32 v34, v36, v34, vcc
	v_mul_f32_e32 v34, 0x3e0293ee, v34
	v_pk_mul_f32 v[28:29], v[28:29], v[34:35] op_sel_hi:[1,0]
	v_pk_mul_f32 v[36:37], v[26:27], v[34:35] op_sel_hi:[1,0]
	v_pk_mul_f32 v[26:27], v[24:25], v[34:35] op_sel_hi:[1,0]
	v_cvt_pk_bf16_f32 v24, v28, v29
	v_add_co_u32_e32 v28, vcc, s61, v144
	v_pk_mul_f32 v[30:31], v[30:31], v[34:35] op_sel_hi:[1,0]
	s_nop 0
	v_addc_co_u32_e32 v29, vcc, 0, v145, vcc
	v_cvt_pk_bf16_f32 v25, v30, v31
	v_cvt_pk_bf16_f32 v26, v26, v27
	v_cvt_pk_bf16_f32 v27, v36, v37
	global_store_dwordx4 v[28:29], v[24:27], off
	v_pk_mul_f32 v[22:23], v[22:23], v[34:35] op_sel_hi:[1,0]
	v_pk_mul_f32 v[20:21], v[20:21], v[34:35] op_sel_hi:[1,0]
	v_pk_mul_f32 v[24:25], v[18:19], v[34:35] op_sel_hi:[1,0]
	v_pk_mul_f32 v[18:19], v[16:17], v[34:35] op_sel_hi:[1,0]
	v_cvt_pk_bf16_f32 v16, v20, v21
	v_cvt_pk_bf16_f32 v17, v22, v23
	v_cmp_gt_f32_e32 vcc, s58, v170
	v_cvt_pk_bf16_f32 v18, v18, v19
	v_mul_f32_e32 v19, 0x4b800000, v170
	v_lshl_add_u64 v[32:33], v[144:145], 0, s[22:23]
	v_cndmask_b32_e32 v19, v170, v19, vcc
	v_rsq_f32_e32 v20, v19
	v_cvt_pk_bf16_f32 v19, v24, v25
	global_store_dwordx4 v[32:33], v[16:19], off offset:256
	s_nop 1
	v_mul_f32_e32 v18, 0x45800000, v20
	v_cndmask_b32_e32 v18, v20, v18, vcc
	v_mul_f32_e32 v18, 0x3e0293ee, v18
	v_pk_mul_f32 v[12:13], v[12:13], v[18:19] op_sel_hi:[1,0]
	v_pk_mul_f32 v[20:21], v[10:11], v[18:19] op_sel_hi:[1,0]
	v_pk_mul_f32 v[10:11], v[8:9], v[18:19] op_sel_hi:[1,0]
	v_cvt_pk_bf16_f32 v8, v12, v13
	v_add_co_u32_e32 v12, vcc, s62, v144
	v_pk_mul_f32 v[14:15], v[14:15], v[18:19] op_sel_hi:[1,0]
	s_nop 0
	v_addc_co_u32_e32 v13, vcc, 0, v145, vcc
	v_cvt_pk_bf16_f32 v9, v14, v15
	v_lshl_add_u64 v[16:17], v[144:145], 0, s[24:25]
	v_cvt_pk_bf16_f32 v10, v10, v11
	v_cvt_pk_bf16_f32 v11, v20, v21
	global_store_dwordx4 v[12:13], v[8:11], off
	s_and_b64 vcc, exec, s[6:7]
	v_pk_mul_f32 v[6:7], v[6:7], v[18:19] op_sel_hi:[1,0]
	v_pk_mul_f32 v[8:9], v[2:3], v[18:19] op_sel_hi:[1,0]
	v_pk_mul_f32 v[2:3], v[0:1], v[18:19] op_sel_hi:[1,0]
	v_pk_mul_f32 v[4:5], v[4:5], v[18:19] op_sel_hi:[1,0]
	s_nop 0
	v_cvt_pk_bf16_f32 v0, v4, v5
	v_cvt_pk_bf16_f32 v1, v6, v7
	v_cvt_pk_bf16_f32 v2, v2, v3
	v_cvt_pk_bf16_f32 v3, v8, v9
	global_store_dwordx4 v[16:17], v[0:3], off offset:256
	s_cbranch_vccz .LBB0_1073
	s_waitcnt vmcnt(0)
	s_cmpk_gt_u32 s33, 0xff
	s_cbranch_scc1 .LBB0_1084
	s_barrier

.LBB0_1160:
	ds_read_b128 v[144:147], v178
	ds_read_b128 v[148:151], v178 offset:1024
	ds_read_b128 v[152:155], v178 offset:2048
	ds_read_b128 v[156:159], v178 offset:3072
	s_add_u32 s38, s36, 0xfffe0080
	s_addc_u32 s39, s37, -1
	s_cmp_eq_u32 s62, 4
	s_cselect_b32 s41, s25, s39
	s_cselect_b32 s40, s31, s38
	s_cselect_b32 s39, s23, s61
	s_cselect_b32 s38, s59, s60
	v_lshl_add_u64 v[172:173], s[36:37], 0, v[136:137]
	s_add_i32 m0, s35, 0xc000
	ds_read_b128 v[160:163], v179
	ds_read_b128 v[164:167], v179 offset:1024
	ds_read_b128 v[168:171], v179 offset:2048
	ds_read_b128 v[182:185], v179 offset:3072
	ds_read_b128 v[186:189], v179 offset:4096
	ds_read_b128 v[190:193], v179 offset:5120
	ds_read_b128 v[194:197], v179 offset:6144
	ds_read_b128 v[198:201], v179 offset:7168
	global_load_lds_dwordx4 v[172:173], off
	v_lshl_add_u64 v[172:173], s[36:37], 0, v[138:139]
	s_add_i32 m0, s35, 0xe000
	s_nop 0
	global_load_lds_dwordx4 v[172:173], off
	s_waitcnt lgkmcnt(8)
	s_barrier
	s_waitcnt lgkmcnt(0)
	s_setprio 1
	v_mfma_f32_16x16x32_bf16 v[124:127], v[144:147], v[160:163], v[124:127]
	v_mfma_f32_16x16x32_bf16 v[120:123], v[152:155], v[160:163], v[120:123]
	v_mfma_f32_16x16x32_bf16 v[108:111], v[144:147], v[168:171], v[108:111]
	v_mfma_f32_16x16x32_bf16 v[104:107], v[152:155], v[168:171], v[104:107]
	v_mfma_f32_16x16x32_bf16 v[96:99], v[144:147], v[186:189], v[96:99]
	v_mfma_f32_16x16x32_bf16 v[88:91], v[152:155], v[186:189], v[88:91]
	v_mfma_f32_16x16x32_bf16 v[80:83], v[144:147], v[194:197], v[80:83]
	v_mfma_f32_16x16x32_bf16 v[72:75], v[152:155], v[194:197], v[72:75]
	v_mfma_f32_16x16x32_bf16 v[124:127], v[148:151], v[164:167], v[124:127]
	v_mfma_f32_16x16x32_bf16 v[120:123], v[156:159], v[164:167], v[120:123]
	v_mfma_f32_16x16x32_bf16 v[108:111], v[148:151], v[182:185], v[108:111]
	v_mfma_f32_16x16x32_bf16 v[104:107], v[156:159], v[182:185], v[104:107]
	v_mfma_f32_16x16x32_bf16 v[96:99], v[148:151], v[190:193], v[96:99]
	v_mfma_f32_16x16x32_bf16 v[88:91], v[156:159], v[190:193], v[88:91]
	v_mfma_f32_16x16x32_bf16 v[80:83], v[148:151], v[198:201], v[80:83]
	v_mfma_f32_16x16x32_bf16 v[72:75], v[156:159], v[198:201], v[72:75]
	s_setprio 0
	s_barrier
	s_add_i32 s63, s57, s48
	v_lshl_add_u64 v[172:173], s[38:39], 0, v[130:131]
	s_mov_b32 m0, s63
	ds_read_b128 v[202:205], v180
	ds_read_b128 v[206:209], v180 offset:1024
	ds_read_b128 v[212:215], v180 offset:2048
	ds_read_b128 v[216:219], v180 offset:3072
	global_load_lds_dwordx4 v[172:173], off
	v_lshl_add_u64 v[220:221], s[38:39], 0, v[134:135]
	s_add_i32 m0, s63, 0x2000
	s_nop 0
	global_load_lds_dwordx4 v[220:221], off
	s_barrier
	s_waitcnt lgkmcnt(0)
	s_setprio 1
	v_mfma_f32_16x16x32_bf16 v[116:119], v[202:205], v[160:163], v[116:119]
	v_mfma_f32_16x16x32_bf16 v[112:115], v[212:215], v[160:163], v[112:115]
	v_mfma_f32_16x16x32_bf16 v[100:103], v[202:205], v[168:171], v[100:103]
	v_mfma_f32_16x16x32_bf16 v[92:95], v[212:215], v[168:171], v[92:95]
	v_mfma_f32_16x16x32_bf16 v[84:87], v[202:205], v[186:189], v[84:87]
	v_mfma_f32_16x16x32_bf16 v[76:79], v[212:215], v[186:189], v[76:79]
	v_mfma_f32_16x16x32_bf16 v[68:71], v[202:205], v[194:197], v[68:71]
	v_mfma_f32_16x16x32_bf16 v[64:67], v[212:215], v[194:197], v[64:67]
	v_mfma_f32_16x16x32_bf16 v[116:119], v[206:209], v[164:167], v[116:119]
	v_mfma_f32_16x16x32_bf16 v[112:115], v[216:219], v[164:167], v[112:115]
	v_mfma_f32_16x16x32_bf16 v[100:103], v[206:209], v[182:185], v[100:103]
	v_mfma_f32_16x16x32_bf16 v[92:95], v[216:219], v[182:185], v[92:95]
	v_mfma_f32_16x16x32_bf16 v[84:87], v[206:209], v[190:193], v[84:87]
	v_mfma_f32_16x16x32_bf16 v[76:79], v[216:219], v[190:193], v[76:79]
	v_mfma_f32_16x16x32_bf16 v[68:71], v[206:209], v[198:201], v[68:71]
	v_mfma_f32_16x16x32_bf16 v[64:67], v[216:219], v[198:201], v[64:67]
	s_setprio 0
	s_mov_b32 m0, s35
	v_lshl_add_u64 v[222:223], s[40:41], 0, v[128:129]
	s_barrier
	ds_read_b128 v[160:163], v179 offset:16384
	ds_read_b128 v[164:167], v179 offset:17408
	ds_read_b128 v[168:171], v179 offset:18432
	ds_read_b128 v[182:185], v179 offset:19456
	ds_read_b128 v[186:189], v179 offset:20480
	ds_read_b128 v[190:193], v179 offset:21504
	ds_read_b128 v[194:197], v179 offset:22528
	ds_read_b128 v[198:201], v179 offset:23552
	global_load_lds_dwordx4 v[222:223], off
	v_lshl_add_u64 v[224:225], s[40:41], 0, v[132:133]
	s_mov_b32 m0, s49
	s_nop 0
	global_load_lds_dwordx4 v[224:225], off
	s_barrier
	s_waitcnt lgkmcnt(0)
	s_setprio 1
	v_mfma_f32_16x16x32_bf16 v[60:63], v[144:147], v[160:163], v[60:63]
	v_mfma_f32_16x16x32_bf16 v[56:59], v[152:155], v[160:163], v[56:59]
	v_mfma_f32_16x16x32_bf16 v[44:47], v[144:147], v[168:171], v[44:47]
	v_mfma_f32_16x16x32_bf16 v[40:43], v[152:155], v[168:171], v[40:43]
	v_mfma_f32_16x16x32_bf16 v[32:35], v[144:147], v[186:189], v[32:35]
	v_mfma_f32_16x16x32_bf16 v[24:27], v[152:155], v[186:189], v[24:27]
	v_mfma_f32_16x16x32_bf16 v[16:19], v[144:147], v[194:197], v[16:19]
	v_mfma_f32_16x16x32_bf16 v[8:11], v[152:155], v[194:197], v[8:11]
	v_mfma_f32_16x16x32_bf16 v[60:63], v[148:151], v[164:167], v[60:63]
	v_mfma_f32_16x16x32_bf16 v[56:59], v[156:159], v[164:167], v[56:59]
	v_mfma_f32_16x16x32_bf16 v[44:47], v[148:151], v[182:185], v[44:47]
	v_mfma_f32_16x16x32_bf16 v[40:43], v[156:159], v[182:185], v[40:43]
	v_mfma_f32_16x16x32_bf16 v[32:35], v[148:151], v[190:193], v[32:35]
	v_mfma_f32_16x16x32_bf16 v[24:27], v[156:159], v[190:193], v[24:27]
	v_mfma_f32_16x16x32_bf16 v[16:19], v[148:151], v[198:201], v[16:19]
	v_mfma_f32_16x16x32_bf16 v[8:11], v[156:159], v[198:201], v[8:11]
	s_setprio 0
	s_barrier
	s_add_u32 s64, s38, 0x20000
	s_addc_u32 s65, s39, 0
	s_add_i32 s63, s58, s48
	v_lshl_add_u64 v[144:145], s[64:65], 0, v[130:131]
	s_mov_b32 m0, s63
	s_nop 0
	global_load_lds_dwordx4 v[144:145], off
	v_lshl_add_u64 v[144:145], s[64:65], 0, v[134:135]
	s_add_i32 m0, s63, 0x2000
	s_nop 0
	global_load_lds_dwordx4 v[144:145], off
	s_waitcnt vmcnt(6)
	s_barrier
	s_setprio 1
	v_mfma_f32_16x16x32_bf16 v[52:55], v[202:205], v[160:163], v[52:55]
	v_mfma_f32_16x16x32_bf16 v[48:51], v[212:215], v[160:163], v[48:51]
	v_mfma_f32_16x16x32_bf16 v[36:39], v[202:205], v[168:171], v[36:39]
	v_mfma_f32_16x16x32_bf16 v[28:31], v[212:215], v[168:171], v[28:31]
	v_mfma_f32_16x16x32_bf16 v[20:23], v[202:205], v[186:189], v[20:23]
	v_mfma_f32_16x16x32_bf16 v[12:15], v[212:215], v[186:189], v[12:15]
	v_mfma_f32_16x16x32_bf16 v[4:7], v[202:205], v[194:197], v[4:7]
	v_mfma_f32_16x16x32_bf16 v[0:3], v[212:215], v[194:197], v[0:3]
	v_mfma_f32_16x16x32_bf16 v[52:55], v[206:209], v[164:167], v[52:55]
	v_mfma_f32_16x16x32_bf16 v[48:51], v[216:219], v[164:167], v[48:51]
	v_mfma_f32_16x16x32_bf16 v[36:39], v[206:209], v[182:185], v[36:39]
	v_mfma_f32_16x16x32_bf16 v[28:31], v[216:219], v[182:185], v[28:31]
	v_mfma_f32_16x16x32_bf16 v[20:23], v[206:209], v[190:193], v[20:23]
	v_mfma_f32_16x16x32_bf16 v[12:15], v[216:219], v[190:193], v[12:15]
	v_mfma_f32_16x16x32_bf16 v[4:7], v[206:209], v[198:201], v[4:7]
	v_mfma_f32_16x16x32_bf16 v[0:3], v[216:219], v[198:201], v[0:3]
	s_setprio 0
	s_add_i32 s63, 0, 0x18000
	v_add_u32_e32 v156, s63, v176
	s_barrier
	ds_read_b128 v[144:147], v156
	ds_read_b128 v[148:151], v156 offset:1024
	ds_read_b128 v[152:155], v156 offset:2048
	ds_read_b128 v[156:159], v156 offset:3072
	s_add_u32 s40, s40, 0x20000
	s_addc_u32 s41, s41, 0
	s_mov_b32 m0, s50
	v_lshl_add_u64 v[202:203], s[40:41], 0, v[128:129]
	ds_read_b128 v[160:163], v179 offset:32768
	ds_read_b128 v[164:167], v179 offset:33792
	ds_read_b128 v[168:171], v179 offset:34816
	ds_read_b128 v[182:185], v179 offset:35840
	ds_read_b128 v[186:189], v179 offset:36864
	ds_read_b128 v[190:193], v179 offset:37888
	ds_read_b128 v[194:197], v179 offset:38912
	ds_read_b128 v[198:201], v179 offset:39936
	global_load_lds_dwordx4 v[202:203], off
	v_lshl_add_u64 v[202:203], s[40:41], 0, v[132:133]
	s_mov_b32 m0, s51
	s_nop 0
	global_load_lds_dwordx4 v[202:203], off
	s_waitcnt lgkmcnt(8)
	s_barrier
	s_waitcnt lgkmcnt(0)
	s_setprio 1
	v_mfma_f32_16x16x32_bf16 v[124:127], v[144:147], v[160:163], v[124:127]
	v_mfma_f32_16x16x32_bf16 v[120:123], v[152:155], v[160:163], v[120:123]
	v_mfma_f32_16x16x32_bf16 v[108:111], v[144:147], v[168:171], v[108:111]
	v_mfma_f32_16x16x32_bf16 v[104:107], v[152:155], v[168:171], v[104:107]
	v_mfma_f32_16x16x32_bf16 v[96:99], v[144:147], v[186:189], v[96:99]
	v_mfma_f32_16x16x32_bf16 v[88:91], v[152:155], v[186:189], v[88:91]
	v_mfma_f32_16x16x32_bf16 v[80:83], v[144:147], v[194:197], v[80:83]
	v_mfma_f32_16x16x32_bf16 v[72:75], v[152:155], v[194:197], v[72:75]
	v_mfma_f32_16x16x32_bf16 v[124:127], v[148:151], v[164:167], v[124:127]
	v_mfma_f32_16x16x32_bf16 v[120:123], v[156:159], v[164:167], v[120:123]
	v_mfma_f32_16x16x32_bf16 v[108:111], v[148:151], v[182:185], v[108:111]
	v_mfma_f32_16x16x32_bf16 v[104:107], v[156:159], v[182:185], v[104:107]
	v_mfma_f32_16x16x32_bf16 v[96:99], v[148:151], v[190:193], v[96:99]
	v_mfma_f32_16x16x32_bf16 v[88:91], v[156:159], v[190:193], v[88:91]
	v_mfma_f32_16x16x32_bf16 v[80:83], v[148:151], v[198:201], v[80:83]
	v_mfma_f32_16x16x32_bf16 v[72:75], v[156:159], v[198:201], v[72:75]
	s_setprio 0
	s_barrier
	s_add_i32 s40, 0, 0x1c000
	s_add_i32 s41, s63, s48
	v_add_u32_e32 v181, s40, v176
	v_lshl_add_u64 v[172:173], v[172:173], 0, s[0:1]
	s_mov_b32 m0, s41
	ds_read_b128 v[202:205], v181
	ds_read_b128 v[206:209], v181 offset:1024
	ds_read_b128 v[212:215], v181 offset:2048
	ds_read_b128 v[216:219], v181 offset:3072
	global_load_lds_dwordx4 v[172:173], off
	v_lshl_add_u64 v[172:173], v[220:221], 0, s[0:1]
	s_add_i32 m0, s41, 0x2000
	s_nop 0
	global_load_lds_dwordx4 v[172:173], off
	s_barrier
	s_waitcnt lgkmcnt(0)
	s_setprio 1
	v_mfma_f32_16x16x32_bf16 v[116:119], v[202:205], v[160:163], v[116:119]
	v_mfma_f32_16x16x32_bf16 v[112:115], v[212:215], v[160:163], v[112:115]
	v_mfma_f32_16x16x32_bf16 v[100:103], v[202:205], v[168:171], v[100:103]
	v_mfma_f32_16x16x32_bf16 v[92:95], v[212:215], v[168:171], v[92:95]
	v_mfma_f32_16x16x32_bf16 v[84:87], v[202:205], v[186:189], v[84:87]
	v_mfma_f32_16x16x32_bf16 v[76:79], v[212:215], v[186:189], v[76:79]
	v_mfma_f32_16x16x32_bf16 v[68:71], v[202:205], v[194:197], v[68:71]
	v_mfma_f32_16x16x32_bf16 v[64:67], v[212:215], v[194:197], v[64:67]
	v_mfma_f32_16x16x32_bf16 v[116:119], v[206:209], v[164:167], v[116:119]
	v_mfma_f32_16x16x32_bf16 v[112:115], v[216:219], v[164:167], v[112:115]
	v_mfma_f32_16x16x32_bf16 v[100:103], v[206:209], v[182:185], v[100:103]
	v_mfma_f32_16x16x32_bf16 v[92:95], v[216:219], v[182:185], v[92:95]
	v_mfma_f32_16x16x32_bf16 v[84:87], v[206:209], v[190:193], v[84:87]
	v_mfma_f32_16x16x32_bf16 v[76:79], v[216:219], v[190:193], v[76:79]
	v_mfma_f32_16x16x32_bf16 v[68:71], v[206:209], v[198:201], v[68:71]
	v_mfma_f32_16x16x32_bf16 v[64:67], v[216:219], v[198:201], v[64:67]
	s_setprio 0
	s_mov_b32 m0, s53
	v_lshl_add_u64 v[172:173], v[222:223], 0, s[0:1]
	s_barrier
	ds_read_b128 v[160:163], v179 offset:49152
	ds_read_b128 v[164:167], v179 offset:50176
	ds_read_b128 v[168:171], v179 offset:51200
	ds_read_b128 v[182:185], v179 offset:52224
	ds_read_b128 v[186:189], v179 offset:53248
	ds_read_b128 v[190:193], v179 offset:54272
	ds_read_b128 v[194:197], v179 offset:55296
	ds_read_b128 v[198:201], v179 offset:56320
	global_load_lds_dwordx4 v[172:173], off
	v_lshl_add_u64 v[172:173], v[224:225], 0, s[0:1]
	s_mov_b32 m0, s54
	s_nop 0
	global_load_lds_dwordx4 v[172:173], off
	s_barrier
	s_waitcnt lgkmcnt(0)
	s_setprio 1
	v_mfma_f32_16x16x32_bf16 v[60:63], v[144:147], v[160:163], v[60:63]
	v_mfma_f32_16x16x32_bf16 v[56:59], v[152:155], v[160:163], v[56:59]
	v_mfma_f32_16x16x32_bf16 v[44:47], v[144:147], v[168:171], v[44:47]
	v_mfma_f32_16x16x32_bf16 v[40:43], v[152:155], v[168:171], v[40:43]
	v_mfma_f32_16x16x32_bf16 v[32:35], v[144:147], v[186:189], v[32:35]
	v_mfma_f32_16x16x32_bf16 v[24:27], v[152:155], v[186:189], v[24:27]
	v_mfma_f32_16x16x32_bf16 v[16:19], v[144:147], v[194:197], v[16:19]
	v_mfma_f32_16x16x32_bf16 v[8:11], v[152:155], v[194:197], v[8:11]
	v_mfma_f32_16x16x32_bf16 v[60:63], v[148:151], v[164:167], v[60:63]
	v_mfma_f32_16x16x32_bf16 v[56:59], v[156:159], v[164:167], v[56:59]
	v_mfma_f32_16x16x32_bf16 v[44:47], v[148:151], v[182:185], v[44:47]
	v_mfma_f32_16x16x32_bf16 v[40:43], v[156:159], v[182:185], v[40:43]
	v_mfma_f32_16x16x32_bf16 v[32:35], v[148:151], v[190:193], v[32:35]
	v_mfma_f32_16x16x32_bf16 v[24:27], v[156:159], v[190:193], v[24:27]
	v_mfma_f32_16x16x32_bf16 v[16:19], v[148:151], v[198:201], v[16:19]
	v_mfma_f32_16x16x32_bf16 v[8:11], v[156:159], v[198:201], v[8:11]
	s_setprio 0
	s_barrier
	s_add_u32 s38, s38, 0x20080
	s_addc_u32 s39, s39, 0
	s_add_i32 s40, s40, s48
	v_lshl_add_u64 v[144:145], s[38:39], 0, v[130:131]
	s_mov_b32 m0, s40
	s_nop 0
	global_load_lds_dwordx4 v[144:145], off
	v_lshl_add_u64 v[144:145], s[38:39], 0, v[134:135]
	s_add_i32 m0, s40, 0x2000
	s_nop 0
	global_load_lds_dwordx4 v[144:145], off
	s_waitcnt vmcnt(6)
	s_barrier
	s_setprio 1
	v_mfma_f32_16x16x32_bf16 v[52:55], v[202:205], v[160:163], v[52:55]
	v_mfma_f32_16x16x32_bf16 v[48:51], v[212:215], v[160:163], v[48:51]
	v_mfma_f32_16x16x32_bf16 v[36:39], v[202:205], v[168:171], v[36:39]
	v_mfma_f32_16x16x32_bf16 v[28:31], v[212:215], v[168:171], v[28:31]
	v_mfma_f32_16x16x32_bf16 v[20:23], v[202:205], v[186:189], v[20:23]
	v_mfma_f32_16x16x32_bf16 v[12:15], v[212:215], v[186:189], v[12:15]
	v_mfma_f32_16x16x32_bf16 v[4:7], v[202:205], v[194:197], v[4:7]
	v_mfma_f32_16x16x32_bf16 v[0:3], v[212:215], v[194:197], v[0:3]
	v_mfma_f32_16x16x32_bf16 v[52:55], v[206:209], v[164:167], v[52:55]
	v_mfma_f32_16x16x32_bf16 v[48:51], v[216:219], v[164:167], v[48:51]
	v_mfma_f32_16x16x32_bf16 v[36:39], v[206:209], v[182:185], v[36:39]
	v_mfma_f32_16x16x32_bf16 v[28:31], v[216:219], v[182:185], v[28:31]
	v_mfma_f32_16x16x32_bf16 v[20:23], v[206:209], v[190:193], v[20:23]
	v_mfma_f32_16x16x32_bf16 v[12:15], v[216:219], v[190:193], v[12:15]
	v_mfma_f32_16x16x32_bf16 v[4:7], v[206:209], v[198:201], v[4:7]
	v_mfma_f32_16x16x32_bf16 v[0:3], v[216:219], v[198:201], v[0:3]
	s_setprio 0
	s_add_i32 s62, s62, 2
	s_add_u32 s36, s36, 0x100
	s_addc_u32 s37, s37, 0
	s_add_u32 s60, s60, 0x100
	s_addc_u32 s61, s61, 0
	s_cmp_gt_u32 s62, 5
	s_barrier
	s_cbranch_scc0 .LBB0_1160
	v_lshl_or_b32 v144, s34, 8, v177
	v_lshl_add_u32 v150, s30, 8, v175
	v_ashrrev_i32_e32 v145, 31, v144
	v_ashrrev_i32_e32 v151, 31, v150
	v_lshlrev_b64 v[144:145], 1, v[144:145]
	v_lshl_add_u64 v[146:147], s[10:11], 0, v[144:145]
	v_lshlrev_b64 v[148:149], 11, v[150:151]
	v_lshl_add_u64 v[152:153], v[146:147], 0, v[148:149]
	global_load_dwordx4 v[156:159], v[152:153], off
	global_load_dwordx4 v[160:163], v[152:153], off offset:256
	v_or_b32_e32 v152, 16, v150
	v_ashrrev_i32_e32 v153, 31, v152
	v_lshlrev_b64 v[170:171], 11, v[152:153]
	v_lshl_add_u64 v[152:153], v[146:147], 0, v[170:171]
	global_load_dwordx4 v[164:167], v[152:153], off
	global_load_dwordx4 v[182:185], v[152:153], off offset:256
	v_or_b32_e32 v152, 32, v150
	v_ashrrev_i32_e32 v153, 31, v152
	v_lshlrev_b64 v[154:155], 11, v[152:153]
	v_lshl_add_u64 v[152:153], v[146:147], 0, v[154:155]
	global_load_dwordx4 v[186:189], v[152:153], off
	global_load_dwordx4 v[190:193], v[152:153], off offset:256
	v_or_b32_e32 v152, 48, v150
	v_ashrrev_i32_e32 v153, 31, v152
	v_lshlrev_b64 v[152:153], 11, v[152:153]
	v_lshl_add_u64 v[168:169], v[146:147], 0, v[152:153]
	global_load_dwordx4 v[194:197], v[168:169], off
	global_load_dwordx4 v[198:201], v[168:169], off offset:256
	s_waitcnt vmcnt(0)
	v_lshlrev_b32_e32 v202, 16, v156
	v_and_b32_e32 v203, 0xffff0000, v156
	v_lshlrev_b32_e32 v204, 16, v157
	v_and_b32_e32 v205, 0xffff0000, v157
	v_lshlrev_b32_e32 v206, 16, v158
	v_and_b32_e32 v207, 0xffff0000, v158
	v_lshlrev_b32_e32 v208, 16, v159
	v_and_b32_e32 v209, 0xffff0000, v159
	v_pk_add_f32 v[126:127], v[126:127], v[204:205]
	v_pk_add_f32 v[124:125], v[124:125], v[202:203]
	v_lshlrev_b32_e32 v224, 16, v166
	v_and_b32_e32 v225, 0xffff0000, v166
	v_lshlrev_b32_e32 v226, 16, v167
	v_and_b32_e32 v227, 0xffff0000, v167
	v_lshlrev_b32_e32 v212, 16, v160
	v_lshlrev_b32_e32 v166, 16, v194
	v_and_b32_e32 v167, 0xffff0000, v194
	v_lshlrev_b32_e32 v172, 16, v195
	v_and_b32_e32 v173, 0xffff0000, v195
	v_pk_add_f32 v[194:195], v[122:123], v[208:209]
	v_pk_add_f32 v[122:123], v[120:121], v[206:207]
	v_mul_f32_e32 v120, v125, v125
	v_mul_f32_e32 v121, v127, v127
	v_fmac_f32_e32 v120, v124, v124
	v_fmac_f32_e32 v121, v126, v126
	v_add_f32_e32 v120, v120, v121
	v_mul_f32_e32 v121, v123, v123
	v_fmac_f32_e32 v121, v122, v122
	v_add_f32_e32 v120, v121, v120
	v_mul_f32_e32 v121, v195, v195
	v_fmac_f32_e32 v121, v194, v194
	v_and_b32_e32 v213, 0xffff0000, v160
	v_lshlrev_b32_e32 v214, 16, v161
	v_and_b32_e32 v215, 0xffff0000, v161
	v_add_f32_e32 v181, v121, v120
	v_cvt_pk_bf16_f32 v120, v124, v125
	v_lshl_add_u64 v[124:125], s[90:91], 0, v[148:149]
	v_lshlrev_b32_e32 v216, 16, v162
	v_and_b32_e32 v217, 0xffff0000, v162
	v_lshlrev_b32_e32 v218, 16, v163
	v_and_b32_e32 v219, 0xffff0000, v163
	v_cvt_pk_bf16_f32 v121, v126, v127
	v_lshl_add_u64 v[124:125], v[124:125], 0, v[144:145]
	v_pk_add_f32 v[118:119], v[118:119], v[214:215]
	v_pk_add_f32 v[116:117], v[116:117], v[212:213]
	v_cvt_pk_bf16_f32 v122, v122, v123
	v_cvt_pk_bf16_f32 v123, v194, v195
	global_store_dwordx4 v[124:125], v[120:123], off
	v_lshlrev_b32_e32 v220, 16, v164
	v_and_b32_e32 v221, 0xffff0000, v164
	v_pk_add_f32 v[120:121], v[114:115], v[218:219]
	v_pk_add_f32 v[114:115], v[112:113], v[216:217]
	v_mul_f32_e32 v112, v117, v117
	v_mul_f32_e32 v113, v119, v119
	v_fmac_f32_e32 v112, v116, v116
	v_fmac_f32_e32 v113, v118, v118
	v_add_f32_e32 v112, v112, v113
	v_mul_f32_e32 v113, v115, v115
	v_fmac_f32_e32 v113, v114, v114
	v_add_f32_e32 v112, v113, v112
	v_mul_f32_e32 v113, v121, v121
	v_fmac_f32_e32 v113, v120, v120
	v_add_f32_e32 v112, v113, v112
	v_lshlrev_b32_e32 v222, 16, v165
	v_and_b32_e32 v223, 0xffff0000, v165
	v_add_f32_e32 v126, v181, v112
	v_cvt_pk_bf16_f32 v112, v116, v117
	v_cvt_pk_bf16_f32 v113, v118, v119
	v_lshl_add_u64 v[116:117], s[90:91], 0, v[170:171]
	v_lshlrev_b32_e32 v230, 16, v184
	v_and_b32_e32 v231, 0xffff0000, v184
	v_lshlrev_b32_e32 v232, 16, v186
	v_and_b32_e32 v233, 0xffff0000, v186
	v_lshlrev_b32_e32 v186, 16, v187
	v_and_b32_e32 v187, 0xffff0000, v187
	v_cvt_pk_bf16_f32 v114, v114, v115
	v_cvt_pk_bf16_f32 v115, v120, v121
	global_store_dwordx4 v[124:125], v[112:115], off offset:256
	v_pk_add_f32 v[110:111], v[110:111], v[222:223]
	v_pk_add_f32 v[108:109], v[108:109], v[220:221]
	v_lshl_add_u64 v[118:119], v[116:117], 0, v[144:145]
	v_cvt_pk_bf16_f32 v112, v108, v109
	v_cvt_pk_bf16_f32 v113, v110, v111
	v_lshlrev_b32_e32 v228, 16, v182
	v_and_b32_e32 v229, 0xffff0000, v182
	v_lshlrev_b32_e32 v182, 16, v183
	v_and_b32_e32 v183, 0xffff0000, v183
	v_lshlrev_b32_e32 v184, 16, v185
	v_and_b32_e32 v185, 0xffff0000, v185
	v_lshlrev_b32_e32 v238, 16, v192
	v_and_b32_e32 v239, 0xffff0000, v192
	v_pk_add_f32 v[106:107], v[106:107], v[226:227]
	v_pk_add_f32 v[104:105], v[104:105], v[224:225]
	v_lshlrev_b32_e32 v156, 16, v200
	v_cvt_pk_bf16_f32 v114, v104, v105
	v_cvt_pk_bf16_f32 v115, v106, v107
	global_store_dwordx4 v[118:119], v[112:115], off
	v_and_b32_e32 v157, 0xffff0000, v200
	v_pk_add_f32 v[102:103], v[102:103], v[182:183]
	v_pk_add_f32 v[112:113], v[92:93], v[230:231]
	v_pk_add_f32 v[92:93], v[98:99], v[186:187]
	v_lshl_add_u64 v[98:99], s[90:91], 0, v[154:155]
	v_pk_add_f32 v[100:101], v[100:101], v[228:229]
	v_pk_add_f32 v[94:95], v[94:95], v[184:185]
	v_cvt_pk_bf16_f32 v114, v100, v101
	v_cvt_pk_bf16_f32 v115, v102, v103
	v_cvt_pk_bf16_f32 v116, v112, v113
	v_lshlrev_b32_e32 v234, 16, v188
	v_cvt_pk_bf16_f32 v117, v94, v95
	global_store_dwordx4 v[118:119], v[114:117], off offset:256
	v_lshl_add_u64 v[118:119], v[98:99], 0, v[144:145]
	v_pk_add_f32 v[98:99], v[76:77], v[238:239]
	v_pk_add_f32 v[76:77], v[82:83], v[172:173]
	v_lshl_add_u64 v[82:83], s[90:91], 0, v[152:153]
	v_lshl_add_u64 v[122:123], v[82:83], 0, v[144:145]
	v_pk_add_f32 v[82:83], v[64:65], v[156:157]
	v_and_b32_e32 v65, 64, v174
	v_and_b32_e32 v235, 0xffff0000, v188
	v_lshlrev_b32_e32 v188, 16, v189
	v_and_b32_e32 v189, 0xffff0000, v189
	v_lshlrev_b32_e32 v236, 16, v190
	v_and_b32_e32 v237, 0xffff0000, v190
	v_pk_add_f32 v[96:97], v[96:97], v[232:233]
	v_xor_b32_e32 v64, 16, v174
	v_cvt_pk_bf16_f32 v114, v96, v97
	v_add_u32_e32 v65, 64, v65
	v_lshlrev_b32_e32 v190, 16, v191
	v_and_b32_e32 v191, 0xffff0000, v191
	v_lshlrev_b32_e32 v192, 16, v193
	v_and_b32_e32 v193, 0xffff0000, v193
	v_pk_add_f32 v[90:91], v[90:91], v[188:189]
	v_pk_add_f32 v[88:89], v[88:89], v[234:235]
	v_cvt_pk_bf16_f32 v115, v92, v93
	v_pk_add_f32 v[84:85], v[84:85], v[236:237]
	v_cvt_pk_bf16_f32 v116, v88, v89
	v_cvt_pk_bf16_f32 v117, v90, v91
	global_store_dwordx4 v[118:119], v[114:117], off
	v_cmp_lt_i32_e32 vcc, v64, v65
	v_lshlrev_b32_e32 v164, 16, v196
	v_cvt_pk_bf16_f32 v114, v84, v85
	v_and_b32_e32 v165, 0xffff0000, v196
	v_lshlrev_b32_e32 v168, 16, v197
	v_and_b32_e32 v169, 0xffff0000, v197
	v_pk_add_f32 v[86:87], v[86:87], v[190:191]
	v_pk_add_f32 v[78:79], v[78:79], v[192:193]
	v_cvt_pk_bf16_f32 v115, v86, v87
	v_cvt_pk_bf16_f32 v116, v98, v99
	v_pk_add_f32 v[80:81], v[80:81], v[166:167]
	v_cvt_pk_bf16_f32 v117, v78, v79
	global_store_dwordx4 v[118:119], v[114:117], off offset:256
	v_cndmask_b32_e32 v64, v174, v64, vcc
	v_pk_add_f32 v[74:75], v[74:75], v[168:169]
	v_cvt_pk_bf16_f32 v114, v80, v81
	v_pk_add_f32 v[72:73], v[72:73], v[164:165]
	v_cvt_pk_bf16_f32 v115, v76, v77
	v_lshlrev_b32_e32 v158, 16, v198
	v_cvt_pk_bf16_f32 v116, v72, v73
	v_cvt_pk_bf16_f32 v117, v74, v75
	global_store_dwordx4 v[122:123], v[114:117], off
	v_and_b32_e32 v159, 0xffff0000, v198
	v_lshlrev_b32_e32 v162, 16, v199
	v_lshlrev_b32_e32 v114, 2, v64
	ds_bpermute_b32 v64, v114, v126
	v_xor_b32_e32 v115, 32, v174
	v_cmp_lt_i32_e32 vcc, v115, v65
	v_and_b32_e32 v163, 0xffff0000, v199
	v_lshlrev_b32_e32 v160, 16, v201
	v_cndmask_b32_e32 v65, v174, v115, vcc
	v_lshlrev_b32_e32 v115, 2, v65
	s_waitcnt lgkmcnt(0)
	v_add_f32_e32 v116, v126, v64
	ds_bpermute_b32 v117, v115, v116
	v_and_b32_e32 v161, 0xffff0000, v201
	v_pk_add_f32 v[70:71], v[70:71], v[162:163]
	v_pk_add_f32 v[68:69], v[68:69], v[158:159]
	v_pk_add_f32 v[66:67], v[66:67], v[160:161]
	v_lshl_add_u64 v[64:65], v[150:151], 2, s[8:9]
	v_cvt_pk_bf16_f32 v118, v68, v69
	v_cvt_pk_bf16_f32 v119, v70, v71
	v_cvt_pk_bf16_f32 v120, v82, v83
	v_cvt_pk_bf16_f32 v121, v66, v67
	global_store_dwordx4 v[122:123], v[118:121], off offset:256
	s_and_saveexec_b64 s[30:31], s[2:3]
	s_cbranch_execz .LBB0_1163
	s_waitcnt lgkmcnt(0)
	v_add_f32_e32 v116, v116, v117
	global_atomic_add_f32 v[64:65], v116, off

.LBB0_1218:
	ds_read_b128 v[144:147], v151
	ds_read_b128 v[156:159], v151 offset:1024
	ds_read_b128 v[160:163], v151 offset:2048
	ds_read_b128 v[164:167], v151 offset:3072
	s_add_u32 s30, s28, 0xfffc0080
	s_addc_u32 s31, s29, -1
	s_cmp_eq_u32 s63, 12
	s_cselect_b32 s35, s23, s31
	s_cselect_b32 s34, s59, s30
	s_cselect_b32 s31, s21, s62
	s_cselect_b32 s30, s60, s61
	v_lshl_add_u64 v[172:173], s[28:29], 0, v[136:137]
	s_add_i32 m0, s40, 0xc000
	ds_read_b128 v[168:171], v152
	ds_read_b128 v[176:179], v152 offset:1024
	ds_read_b128 v[180:183], v152 offset:2048
	ds_read_b128 v[184:187], v152 offset:3072
	ds_read_b128 v[188:191], v152 offset:4096
	ds_read_b128 v[192:195], v152 offset:5120
	ds_read_b128 v[196:199], v152 offset:6144
	ds_read_b128 v[200:203], v152 offset:7168
	global_load_lds_dwordx4 v[172:173], off
	v_lshl_add_u64 v[172:173], s[28:29], 0, v[138:139]
	s_add_i32 m0, s40, 0xe000
	s_nop 0
	global_load_lds_dwordx4 v[172:173], off
	s_waitcnt lgkmcnt(8)
	s_barrier
	s_waitcnt lgkmcnt(0)
	s_setprio 1
	v_mfma_f32_16x16x32_bf16 v[124:127], v[144:147], v[168:171], v[124:127]
	v_mfma_f32_16x16x32_bf16 v[120:123], v[160:163], v[168:171], v[120:123]
	v_mfma_f32_16x16x32_bf16 v[116:119], v[144:147], v[180:183], v[116:119]
	v_mfma_f32_16x16x32_bf16 v[112:115], v[160:163], v[180:183], v[112:115]
	v_mfma_f32_16x16x32_bf16 v[92:95], v[144:147], v[188:191], v[92:95]
	v_mfma_f32_16x16x32_bf16 v[88:91], v[160:163], v[188:191], v[88:91]
	v_mfma_f32_16x16x32_bf16 v[76:79], v[144:147], v[196:199], v[76:79]
	v_mfma_f32_16x16x32_bf16 v[72:75], v[160:163], v[196:199], v[72:75]
	v_mfma_f32_16x16x32_bf16 v[124:127], v[156:159], v[176:179], v[124:127]
	v_mfma_f32_16x16x32_bf16 v[120:123], v[164:167], v[176:179], v[120:123]
	v_mfma_f32_16x16x32_bf16 v[116:119], v[156:159], v[184:187], v[116:119]
	v_mfma_f32_16x16x32_bf16 v[112:115], v[164:167], v[184:187], v[112:115]
	v_mfma_f32_16x16x32_bf16 v[92:95], v[156:159], v[192:195], v[92:95]
	v_mfma_f32_16x16x32_bf16 v[88:91], v[164:167], v[192:195], v[88:91]
	v_mfma_f32_16x16x32_bf16 v[76:79], v[156:159], v[200:203], v[76:79]
	v_mfma_f32_16x16x32_bf16 v[72:75], v[164:167], v[200:203], v[72:75]
	s_setprio 0
	s_barrier
	s_add_i32 s64, s52, s39
	v_lshl_add_u64 v[172:173], s[30:31], 0, v[130:131]
	s_mov_b32 m0, s64
	ds_read_b128 v[204:207], v153
	ds_read_b128 v[212:215], v153 offset:1024
	ds_read_b128 v[216:219], v153 offset:2048
	ds_read_b128 v[220:223], v153 offset:3072
	global_load_lds_dwordx4 v[172:173], off
	v_lshl_add_u64 v[208:209], s[30:31], 0, v[134:135]
	s_add_i32 m0, s64, 0x2000
	s_nop 0
	global_load_lds_dwordx4 v[208:209], off
	s_barrier
	s_waitcnt lgkmcnt(0)
	s_setprio 1
	v_mfma_f32_16x16x32_bf16 v[108:111], v[204:207], v[168:171], v[108:111]
	v_mfma_f32_16x16x32_bf16 v[104:107], v[216:219], v[168:171], v[104:107]
	v_mfma_f32_16x16x32_bf16 v[100:103], v[204:207], v[180:183], v[100:103]
	v_mfma_f32_16x16x32_bf16 v[96:99], v[216:219], v[180:183], v[96:99]
	v_mfma_f32_16x16x32_bf16 v[84:87], v[204:207], v[188:191], v[84:87]
	v_mfma_f32_16x16x32_bf16 v[80:83], v[216:219], v[188:191], v[80:83]
	v_mfma_f32_16x16x32_bf16 v[68:71], v[204:207], v[196:199], v[68:71]
	v_mfma_f32_16x16x32_bf16 v[64:67], v[216:219], v[196:199], v[64:67]
	v_mfma_f32_16x16x32_bf16 v[108:111], v[212:215], v[176:179], v[108:111]
	v_mfma_f32_16x16x32_bf16 v[104:107], v[220:223], v[176:179], v[104:107]
	v_mfma_f32_16x16x32_bf16 v[100:103], v[212:215], v[184:187], v[100:103]
	v_mfma_f32_16x16x32_bf16 v[96:99], v[220:223], v[184:187], v[96:99]
	v_mfma_f32_16x16x32_bf16 v[84:87], v[212:215], v[192:195], v[84:87]
	v_mfma_f32_16x16x32_bf16 v[80:83], v[220:223], v[192:195], v[80:83]
	v_mfma_f32_16x16x32_bf16 v[68:71], v[212:215], v[200:203], v[68:71]
	v_mfma_f32_16x16x32_bf16 v[64:67], v[220:223], v[200:203], v[64:67]
	s_setprio 0
	s_mov_b32 m0, s40
	v_lshl_add_u64 v[224:225], s[34:35], 0, v[128:129]
	s_barrier
	ds_read_b128 v[168:171], v152 offset:16384
	ds_read_b128 v[176:179], v152 offset:17408
	ds_read_b128 v[180:183], v152 offset:18432
	ds_read_b128 v[184:187], v152 offset:19456
	ds_read_b128 v[188:191], v152 offset:20480
	ds_read_b128 v[192:195], v152 offset:21504
	ds_read_b128 v[196:199], v152 offset:22528
	ds_read_b128 v[200:203], v152 offset:23552
	global_load_lds_dwordx4 v[224:225], off
	v_lshl_add_u64 v[226:227], s[34:35], 0, v[132:133]
	s_mov_b32 m0, s41
	s_nop 0
	global_load_lds_dwordx4 v[226:227], off
	s_barrier
	s_waitcnt lgkmcnt(0)
	s_setprio 1
	v_mfma_f32_16x16x32_bf16 v[60:63], v[144:147], v[168:171], v[60:63]
	v_mfma_f32_16x16x32_bf16 v[56:59], v[160:163], v[168:171], v[56:59]
	v_mfma_f32_16x16x32_bf16 v[44:47], v[144:147], v[180:183], v[44:47]
	v_mfma_f32_16x16x32_bf16 v[40:43], v[160:163], v[180:183], v[40:43]
	v_mfma_f32_16x16x32_bf16 v[28:31], v[144:147], v[188:191], v[28:31]
	v_mfma_f32_16x16x32_bf16 v[24:27], v[160:163], v[188:191], v[24:27]
	v_mfma_f32_16x16x32_bf16 v[12:15], v[144:147], v[196:199], v[12:15]
	v_mfma_f32_16x16x32_bf16 v[8:11], v[160:163], v[196:199], v[8:11]
	v_mfma_f32_16x16x32_bf16 v[60:63], v[156:159], v[176:179], v[60:63]
	v_mfma_f32_16x16x32_bf16 v[56:59], v[164:167], v[176:179], v[56:59]
	v_mfma_f32_16x16x32_bf16 v[44:47], v[156:159], v[184:187], v[44:47]
	v_mfma_f32_16x16x32_bf16 v[40:43], v[164:167], v[184:187], v[40:43]
	v_mfma_f32_16x16x32_bf16 v[28:31], v[156:159], v[192:195], v[28:31]
	v_mfma_f32_16x16x32_bf16 v[24:27], v[164:167], v[192:195], v[24:27]
	v_mfma_f32_16x16x32_bf16 v[12:15], v[156:159], v[200:203], v[12:15]
	v_mfma_f32_16x16x32_bf16 v[8:11], v[164:167], v[200:203], v[8:11]
	s_setprio 0
	s_barrier
	s_add_u32 s64, s30, 0x40000
	s_addc_u32 s65, s31, 0
	s_add_i32 s66, s53, s39
	v_lshl_add_u64 v[144:145], s[64:65], 0, v[130:131]
	s_mov_b32 m0, s66
	s_nop 0
	global_load_lds_dwordx4 v[144:145], off
	v_lshl_add_u64 v[144:145], s[64:65], 0, v[134:135]
	s_add_i32 m0, s66, 0x2000
	s_nop 0
	global_load_lds_dwordx4 v[144:145], off
	s_waitcnt vmcnt(6)
	s_barrier
	s_setprio 1
	v_mfma_f32_16x16x32_bf16 v[52:55], v[204:207], v[168:171], v[52:55]
	v_mfma_f32_16x16x32_bf16 v[48:51], v[216:219], v[168:171], v[48:51]
	v_mfma_f32_16x16x32_bf16 v[36:39], v[204:207], v[180:183], v[36:39]
	v_mfma_f32_16x16x32_bf16 v[32:35], v[216:219], v[180:183], v[32:35]
	v_mfma_f32_16x16x32_bf16 v[20:23], v[204:207], v[188:191], v[20:23]
	v_mfma_f32_16x16x32_bf16 v[16:19], v[216:219], v[188:191], v[16:19]
	v_mfma_f32_16x16x32_bf16 v[4:7], v[204:207], v[196:199], v[4:7]
	v_mfma_f32_16x16x32_bf16 v[0:3], v[216:219], v[196:199], v[0:3]
	v_mfma_f32_16x16x32_bf16 v[52:55], v[212:215], v[176:179], v[52:55]
	v_mfma_f32_16x16x32_bf16 v[48:51], v[220:223], v[176:179], v[48:51]
	v_mfma_f32_16x16x32_bf16 v[36:39], v[212:215], v[184:187], v[36:39]
	v_mfma_f32_16x16x32_bf16 v[32:35], v[220:223], v[184:187], v[32:35]
	v_mfma_f32_16x16x32_bf16 v[20:23], v[212:215], v[192:195], v[20:23]
	v_mfma_f32_16x16x32_bf16 v[16:19], v[220:223], v[192:195], v[16:19]
	v_mfma_f32_16x16x32_bf16 v[4:7], v[212:215], v[200:203], v[4:7]
	v_mfma_f32_16x16x32_bf16 v[0:3], v[220:223], v[200:203], v[0:3]
	s_setprio 0
	s_add_i32 s64, 0, 0x18000
	v_add_u32_e32 v155, s64, v149
	s_barrier
	ds_read_b128 v[144:147], v155
	ds_read_b128 v[156:159], v155 offset:1024
	ds_read_b128 v[160:163], v155 offset:2048
	ds_read_b128 v[164:167], v155 offset:3072
	s_add_u32 s34, s34, 0x40000
	s_addc_u32 s35, s35, 0
	s_mov_b32 m0, s42
	v_lshl_add_u64 v[204:205], s[34:35], 0, v[128:129]
	ds_read_b128 v[168:171], v152 offset:32768
	ds_read_b128 v[176:179], v152 offset:33792
	ds_read_b128 v[180:183], v152 offset:34816
	ds_read_b128 v[184:187], v152 offset:35840
	ds_read_b128 v[188:191], v152 offset:36864
	ds_read_b128 v[192:195], v152 offset:37888
	ds_read_b128 v[196:199], v152 offset:38912
	ds_read_b128 v[200:203], v152 offset:39936
	global_load_lds_dwordx4 v[204:205], off
	v_lshl_add_u64 v[204:205], s[34:35], 0, v[132:133]
	s_mov_b32 m0, s43
	s_nop 0
	global_load_lds_dwordx4 v[204:205], off
	s_waitcnt lgkmcnt(8)
	s_barrier
	s_waitcnt lgkmcnt(0)
	s_setprio 1
	v_mfma_f32_16x16x32_bf16 v[124:127], v[144:147], v[168:171], v[124:127]
	v_mfma_f32_16x16x32_bf16 v[120:123], v[160:163], v[168:171], v[120:123]
	v_mfma_f32_16x16x32_bf16 v[116:119], v[144:147], v[180:183], v[116:119]
	v_mfma_f32_16x16x32_bf16 v[112:115], v[160:163], v[180:183], v[112:115]
	v_mfma_f32_16x16x32_bf16 v[92:95], v[144:147], v[188:191], v[92:95]
	v_mfma_f32_16x16x32_bf16 v[88:91], v[160:163], v[188:191], v[88:91]
	v_mfma_f32_16x16x32_bf16 v[76:79], v[144:147], v[196:199], v[76:79]
	v_mfma_f32_16x16x32_bf16 v[72:75], v[160:163], v[196:199], v[72:75]
	v_mfma_f32_16x16x32_bf16 v[124:127], v[156:159], v[176:179], v[124:127]
	v_mfma_f32_16x16x32_bf16 v[120:123], v[164:167], v[176:179], v[120:123]
	v_mfma_f32_16x16x32_bf16 v[116:119], v[156:159], v[184:187], v[116:119]
	v_mfma_f32_16x16x32_bf16 v[112:115], v[164:167], v[184:187], v[112:115]
	v_mfma_f32_16x16x32_bf16 v[92:95], v[156:159], v[192:195], v[92:95]
	v_mfma_f32_16x16x32_bf16 v[88:91], v[164:167], v[192:195], v[88:91]
	v_mfma_f32_16x16x32_bf16 v[76:79], v[156:159], v[200:203], v[76:79]
	v_mfma_f32_16x16x32_bf16 v[72:75], v[164:167], v[200:203], v[72:75]
	s_setprio 0
	s_barrier
	s_add_i32 s34, 0, 0x1c000
	s_add_i32 s35, s64, s39
	v_add_u32_e32 v155, s34, v149
	v_lshl_add_u64 v[172:173], v[172:173], 0, s[6:7]
	s_mov_b32 m0, s35
	ds_read_b128 v[204:207], v155
	ds_read_b128 v[212:215], v155 offset:1024
	ds_read_b128 v[216:219], v155 offset:2048
	ds_read_b128 v[220:223], v155 offset:3072
	global_load_lds_dwordx4 v[172:173], off
	v_lshl_add_u64 v[172:173], v[208:209], 0, s[6:7]
	s_add_i32 m0, s35, 0x2000
	s_nop 0
	global_load_lds_dwordx4 v[172:173], off
	s_barrier
	s_waitcnt lgkmcnt(0)
	s_setprio 1
	v_mfma_f32_16x16x32_bf16 v[108:111], v[204:207], v[168:171], v[108:111]
	v_mfma_f32_16x16x32_bf16 v[104:107], v[216:219], v[168:171], v[104:107]
	v_mfma_f32_16x16x32_bf16 v[100:103], v[204:207], v[180:183], v[100:103]
	v_mfma_f32_16x16x32_bf16 v[96:99], v[216:219], v[180:183], v[96:99]
	v_mfma_f32_16x16x32_bf16 v[84:87], v[204:207], v[188:191], v[84:87]
	v_mfma_f32_16x16x32_bf16 v[80:83], v[216:219], v[188:191], v[80:83]
	v_mfma_f32_16x16x32_bf16 v[68:71], v[204:207], v[196:199], v[68:71]
	v_mfma_f32_16x16x32_bf16 v[64:67], v[216:219], v[196:199], v[64:67]
	v_mfma_f32_16x16x32_bf16 v[108:111], v[212:215], v[176:179], v[108:111]
	v_mfma_f32_16x16x32_bf16 v[104:107], v[220:223], v[176:179], v[104:107]
	v_mfma_f32_16x16x32_bf16 v[100:103], v[212:215], v[184:187], v[100:103]
	v_mfma_f32_16x16x32_bf16 v[96:99], v[220:223], v[184:187], v[96:99]
	v_mfma_f32_16x16x32_bf16 v[84:87], v[212:215], v[192:195], v[84:87]
	v_mfma_f32_16x16x32_bf16 v[80:83], v[220:223], v[192:195], v[80:83]
	v_mfma_f32_16x16x32_bf16 v[68:71], v[212:215], v[200:203], v[68:71]
	v_mfma_f32_16x16x32_bf16 v[64:67], v[220:223], v[200:203], v[64:67]
	s_setprio 0
	s_mov_b32 m0, s49
	v_lshl_add_u64 v[172:173], v[224:225], 0, s[6:7]
	s_barrier
	ds_read_b128 v[168:171], v152 offset:49152
	ds_read_b128 v[176:179], v152 offset:50176
	ds_read_b128 v[180:183], v152 offset:51200
	ds_read_b128 v[184:187], v152 offset:52224
	ds_read_b128 v[188:191], v152 offset:53248
	ds_read_b128 v[192:195], v152 offset:54272
	ds_read_b128 v[196:199], v152 offset:55296
	ds_read_b128 v[200:203], v152 offset:56320
	global_load_lds_dwordx4 v[172:173], off
	v_lshl_add_u64 v[172:173], v[226:227], 0, s[6:7]
	s_mov_b32 m0, s50
	s_nop 0
	global_load_lds_dwordx4 v[172:173], off
	s_barrier
	s_waitcnt lgkmcnt(0)
	s_setprio 1
	v_mfma_f32_16x16x32_bf16 v[60:63], v[144:147], v[168:171], v[60:63]
	v_mfma_f32_16x16x32_bf16 v[56:59], v[160:163], v[168:171], v[56:59]
	v_mfma_f32_16x16x32_bf16 v[44:47], v[144:147], v[180:183], v[44:47]
	v_mfma_f32_16x16x32_bf16 v[40:43], v[160:163], v[180:183], v[40:43]
	v_mfma_f32_16x16x32_bf16 v[28:31], v[144:147], v[188:191], v[28:31]
	v_mfma_f32_16x16x32_bf16 v[24:27], v[160:163], v[188:191], v[24:27]
	v_mfma_f32_16x16x32_bf16 v[12:15], v[144:147], v[196:199], v[12:15]
	v_mfma_f32_16x16x32_bf16 v[8:11], v[160:163], v[196:199], v[8:11]
	v_mfma_f32_16x16x32_bf16 v[60:63], v[156:159], v[176:179], v[60:63]
	v_mfma_f32_16x16x32_bf16 v[56:59], v[164:167], v[176:179], v[56:59]
	v_mfma_f32_16x16x32_bf16 v[44:47], v[156:159], v[184:187], v[44:47]
	v_mfma_f32_16x16x32_bf16 v[40:43], v[164:167], v[184:187], v[40:43]
	v_mfma_f32_16x16x32_bf16 v[28:31], v[156:159], v[192:195], v[28:31]
	v_mfma_f32_16x16x32_bf16 v[24:27], v[164:167], v[192:195], v[24:27]
	v_mfma_f32_16x16x32_bf16 v[12:15], v[156:159], v[200:203], v[12:15]
	v_mfma_f32_16x16x32_bf16 v[8:11], v[164:167], v[200:203], v[8:11]
	s_setprio 0
	s_barrier
	s_add_u32 s30, s30, 0x40080
	s_addc_u32 s31, s31, 0
	s_add_i32 s34, s34, s39
	v_lshl_add_u64 v[144:145], s[30:31], 0, v[130:131]
	s_mov_b32 m0, s34
	s_nop 0
	global_load_lds_dwordx4 v[144:145], off
	v_lshl_add_u64 v[144:145], s[30:31], 0, v[134:135]
	s_add_i32 m0, s34, 0x2000
	s_nop 0
	global_load_lds_dwordx4 v[144:145], off
	s_waitcnt vmcnt(6)
	s_barrier
	s_setprio 1
	v_mfma_f32_16x16x32_bf16 v[52:55], v[204:207], v[168:171], v[52:55]
	v_mfma_f32_16x16x32_bf16 v[48:51], v[216:219], v[168:171], v[48:51]
	v_mfma_f32_16x16x32_bf16 v[36:39], v[204:207], v[180:183], v[36:39]
	v_mfma_f32_16x16x32_bf16 v[32:35], v[216:219], v[180:183], v[32:35]
	v_mfma_f32_16x16x32_bf16 v[20:23], v[204:207], v[188:191], v[20:23]
	v_mfma_f32_16x16x32_bf16 v[16:19], v[216:219], v[188:191], v[16:19]
	v_mfma_f32_16x16x32_bf16 v[4:7], v[204:207], v[196:199], v[4:7]
	v_mfma_f32_16x16x32_bf16 v[0:3], v[216:219], v[196:199], v[0:3]
	v_mfma_f32_16x16x32_bf16 v[52:55], v[212:215], v[176:179], v[52:55]
	v_mfma_f32_16x16x32_bf16 v[48:51], v[220:223], v[176:179], v[48:51]
	v_mfma_f32_16x16x32_bf16 v[36:39], v[212:215], v[184:187], v[36:39]
	v_mfma_f32_16x16x32_bf16 v[32:35], v[220:223], v[184:187], v[32:35]
	v_mfma_f32_16x16x32_bf16 v[20:23], v[212:215], v[192:195], v[20:23]
	v_mfma_f32_16x16x32_bf16 v[16:19], v[220:223], v[192:195], v[16:19]
	v_mfma_f32_16x16x32_bf16 v[4:7], v[212:215], v[200:203], v[4:7]
	v_mfma_f32_16x16x32_bf16 v[0:3], v[220:223], v[200:203], v[0:3]
	s_setprio 0
	s_add_i32 s63, s63, 2
	s_add_u32 s28, s28, 0x100
	s_addc_u32 s29, s29, 0
	s_add_u32 s61, s61, 0x100
	s_addc_u32 s62, s62, 0
	s_cmp_gt_u32 s63, 13
	s_barrier
	s_cbranch_scc0 .LBB0_1218
	v_lshl_add_u32 v146, s0, 8, v148
	v_ashrrev_i32_e32 v147, 31, v146
	v_lshl_add_u64 v[144:145], v[146:147], 2, s[8:9]
	global_load_dword v155, v[144:145], off
	global_load_dword v162, v[144:145], off offset:64
	global_load_dword v163, v[144:145], off offset:128
	global_load_dword v164, v[144:145], off offset:192
	global_load_dword v165, v[144:145], off offset:512
	global_load_dword v166, v[144:145], off offset:576
	global_load_dword v167, v[144:145], off offset:640
	global_load_dword v168, v[144:145], off offset:704
	v_lshl_or_b32 v144, s1, 8, v150
	v_ashrrev_i32_e32 v145, 31, v144
	v_lshlrev_b64 v[158:159], 13, v[146:147]
	v_lshlrev_b64 v[160:161], 1, v[144:145]
	v_lshl_add_u64 v[144:145], s[92:93], 0, v[158:159]
	v_lshl_add_u64 v[144:145], v[144:145], 0, v[160:161]
	v_or_b32_e32 v156, 16, v146
	v_ashrrev_i32_e32 v157, 31, v156
	v_lshlrev_b64 v[156:157], 13, v[156:157]
	v_lshl_add_u64 v[156:157], s[92:93], 0, v[156:157]
	v_lshl_add_u64 v[156:157], v[156:157], 0, v[160:161]
	s_mov_b64 s[30:31], s[26:27]
	s_mov_b64 s[28:29], s[24:25]
	s_waitcnt vmcnt(0)
	v_fmamk_f32 v147, v155, 0x3a800000, v154
	v_mul_f32_e32 v158, 0x4b800000, v147
	v_cmp_gt_f32_e32 vcc, s54, v147
	v_fmamk_f32 v155, v162, 0x3a800000, v154
	v_mul_f32_e32 v162, 0x4b800000, v155
	v_cndmask_b32_e32 v147, v147, v158, vcc
	v_rsq_f32_e32 v158, v147
	v_cmp_gt_f32_e64 s[0:1], s54, v155
	v_fmamk_f32 v159, v163, 0x3a800000, v154
	v_fmamk_f32 v163, v164, 0x3a800000, v154
	v_cndmask_b32_e64 v155, v155, v162, s[0:1]
	v_rsq_f32_e32 v155, v155
	v_mul_f32_e32 v162, 0x45800000, v158
	v_cndmask_b32_e32 v158, v158, v162, vcc
	v_pk_mul_f32 v[124:125], v[124:125], v[158:159] op_sel_hi:[1,0]
	v_pk_mul_f32 v[104:105], v[104:105], v[158:159] op_sel_hi:[1,0]
	v_fmamk_f32 v164, v165, 0x3a800000, v154
	v_fmamk_f32 v165, v166, 0x3a800000, v154
	v_fmamk_f32 v166, v167, 0x3a800000, v154
	v_mul_f32_e32 v167, 0x45800000, v155
	v_pk_mul_f32 v[126:127], v[126:127], v[158:159] op_sel_hi:[1,0]
	v_pk_mul_f32 v[122:123], v[122:123], v[158:159] op_sel_hi:[1,0]
	v_pk_mul_f32 v[120:121], v[120:121], v[158:159] op_sel_hi:[1,0]
	v_pk_mul_f32 v[108:109], v[108:109], v[158:159] op_sel_hi:[1,0]
	v_pk_mul_f32 v[106:107], v[106:107], v[158:159] op_sel_hi:[1,0]
	v_max_f32_e32 v124, 0, v124
	v_max_f32_e32 v125, 0, v125
	v_max_f32_e32 v104, 0, v104
	v_cndmask_b32_e64 v162, v155, v167, s[0:1]
	v_pk_mul_f32 v[110:111], v[110:111], v[158:159] op_sel_hi:[1,0]
	v_max_f32_e32 v120, 0, v120
	v_max_f32_e32 v121, 0, v121
	v_max_f32_e32 v126, 0, v126
	v_max_f32_e32 v122, 0, v122
	v_max_f32_e32 v127, 0, v127
	v_max_f32_e32 v123, 0, v123
	v_max_f32_e32 v108, 0, v108
	v_max_f32_e32 v109, 0, v109
	v_max_f32_e32 v105, 0, v105
	v_max_f32_e32 v106, 0, v106
	v_max_f32_e32 v107, 0, v107
	v_mul_f32_e32 v124, v124, v124
	v_mul_f32_e32 v125, v125, v125
	v_mul_f32_e32 v155, v104, v104
	v_cvt_pk_bf16_f32 v104, v124, v125
	v_fmamk_f32 v147, v168, 0x3a800000, v154
	v_pk_mul_f32 v[112:113], v[112:113], v[162:163] op_sel_hi:[1,0]
	v_max_f32_e32 v110, 0, v110
	v_max_f32_e32 v111, 0, v111
	v_mul_f32_e32 v120, v120, v120
	v_mul_f32_e32 v121, v121, v121
	v_mul_f32_e32 v126, v126, v126
	v_mul_f32_e32 v122, v122, v122
	v_mul_f32_e32 v127, v127, v127
	v_mul_f32_e32 v123, v123, v123
	v_mul_f32_e32 v108, v108, v108
	v_mul_f32_e32 v109, v109, v109
	v_mul_f32_e32 v158, v105, v105
	v_mul_f32_e32 v167, v106, v106
	v_mul_f32_e32 v168, v107, v107
	v_cvt_pk_bf16_f32 v105, v126, v127
	v_cvt_pk_bf16_f32 v106, v120, v121
	v_cvt_pk_bf16_f32 v107, v122, v123
	global_store_dwordx4 v[144:145], v[104:107], off nt
	v_pk_mul_f32 v[116:117], v[116:117], v[162:163] op_sel_hi:[1,0]
	v_mul_f32_e32 v110, v110, v110
	v_cvt_pk_bf16_f32 v104, v108, v109
	v_mul_f32_e32 v111, v111, v111
	v_cvt_pk_bf16_f32 v105, v110, v111
	v_cvt_pk_bf16_f32 v106, v155, v158
	v_cvt_pk_bf16_f32 v107, v167, v168
	global_store_dwordx4 v[144:145], v[104:107], off offset:256 nt
	v_pk_mul_f32 v[118:119], v[118:119], v[162:163] op_sel_hi:[1,0]
	v_pk_mul_f32 v[114:115], v[114:115], v[162:163] op_sel_hi:[1,0]
	v_max_f32_e32 v104, 0, v112
	v_mul_f32_e32 v106, v104, v104
	v_max_f32_e32 v104, 0, v117
	v_max_f32_e32 v116, 0, v116
	v_max_f32_e32 v107, 0, v113
	v_mul_f32_e32 v104, v104, v104
	v_pk_mul_f32 v[98:99], v[98:99], v[162:163] op_sel_hi:[1,0]
	v_pk_mul_f32 v[96:97], v[96:97], v[162:163] op_sel_hi:[1,0]
	v_mul_f32_e32 v105, v116, v116
	v_mul_f32_e32 v107, v107, v107
	v_max_f32_e32 v108, 0, v118
	v_max_f32_e32 v109, 0, v114
	v_max_f32_e32 v110, 0, v119
	v_max_f32_e32 v111, 0, v115
	v_cvt_pk_bf16_f32 v104, v105, v104
	v_pk_mul_f32 v[102:103], v[102:103], v[162:163] op_sel_hi:[1,0]
	v_pk_mul_f32 v[100:101], v[100:101], v[162:163] op_sel_hi:[1,0]
	v_max_f32_e32 v96, 0, v96
	v_max_f32_e32 v97, 0, v97
	v_max_f32_e32 v98, 0, v98
	v_mul_f32_e32 v108, v108, v108
	v_mul_f32_e32 v109, v109, v109
	v_mul_f32_e32 v110, v110, v110
	v_mul_f32_e32 v111, v111, v111
	v_cvt_pk_bf16_f32 v105, v108, v110
	v_cvt_pk_bf16_f32 v106, v106, v107
	v_cvt_pk_bf16_f32 v107, v109, v111
	global_store_dwordx4 v[156:157], v[104:107], off nt
	v_max_f32_e32 v100, 0, v100
	v_max_f32_e32 v99, 0, v99
	v_mul_f32_e32 v104, v96, v96
	v_max_f32_e32 v96, 0, v101
	v_mul_f32_e32 v101, v97, v97
	v_max_f32_e32 v97, 0, v102
	v_mul_f32_e32 v102, v98, v98
	v_max_f32_e32 v98, 0, v103
	v_mul_f32_e32 v96, v96, v96
	v_mul_f32_e32 v97, v97, v97
	v_mul_f32_e32 v98, v98, v98
	v_mul_f32_e32 v100, v100, v100
	v_mul_f32_e32 v99, v99, v99
	v_cvt_pk_bf16_f32 v96, v100, v96
	v_cvt_pk_bf16_f32 v97, v97, v98
	v_cvt_pk_bf16_f32 v98, v104, v101
	v_cvt_pk_bf16_f32 v99, v102, v99
	global_store_dwordx4 v[156:157], v[96:99], off offset:256 nt
	v_cmp_gt_f32_e32 vcc, s54, v159
	s_mov_b32 s1, s20
	v_mul_f32_e32 v98, 0x4b800000, v159
	v_cndmask_b32_e32 v98, v159, v98, vcc
	v_rsq_f32_e32 v98, v98
	v_or_b32_e32 v96, 32, v146
	v_ashrrev_i32_e32 v97, 31, v96
	v_lshlrev_b64 v[96:97], 13, v[96:97]
	v_mul_f32_e32 v99, 0x45800000, v98
	v_cndmask_b32_e32 v98, v98, v99, vcc
	v_pk_mul_f32 v[88:89], v[88:89], v[98:99] op_sel_hi:[1,0]
	v_pk_mul_f32 v[92:93], v[92:93], v[98:99] op_sel_hi:[1,0]
	v_pk_mul_f32 v[90:91], v[90:91], v[98:99] op_sel_hi:[1,0]
	v_max_f32_e32 v88, 0, v88
	v_pk_mul_f32 v[94:95], v[94:95], v[98:99] op_sel_hi:[1,0]
	v_mul_f32_e32 v99, v88, v88
	v_max_f32_e32 v88, 0, v93
	v_max_f32_e32 v89, 0, v89
	v_max_f32_e32 v90, 0, v90
	v_lshl_add_u64 v[96:97], s[92:93], 0, v[96:97]
	v_max_f32_e32 v92, 0, v92
	v_mul_f32_e32 v88, v88, v88
	v_mul_f32_e32 v93, v89, v89
	v_max_f32_e32 v89, 0, v94
	v_mul_f32_e32 v94, v90, v90
	v_max_f32_e32 v90, 0, v95
	v_max_f32_e32 v91, 0, v91
	v_pk_mul_f32 v[82:83], v[82:83], v[98:99] op_sel_hi:[1,0]
	v_pk_mul_f32 v[80:81], v[80:81], v[98:99] op_sel_hi:[1,0]
	v_lshl_add_u64 v[96:97], v[96:97], 0, v[160:161]
	v_mul_f32_e32 v92, v92, v92
	v_mul_f32_e32 v89, v89, v89
	v_mul_f32_e32 v90, v90, v90
	v_mul_f32_e32 v91, v91, v91
	v_cvt_pk_bf16_f32 v88, v92, v88
	v_pk_mul_f32 v[86:87], v[86:87], v[98:99] op_sel_hi:[1,0]
	v_pk_mul_f32 v[84:85], v[84:85], v[98:99] op_sel_hi:[1,0]
	v_max_f32_e32 v80, 0, v80
	v_max_f32_e32 v81, 0, v81
	v_max_f32_e32 v82, 0, v82
	v_cvt_pk_bf16_f32 v89, v89, v90
	v_cvt_pk_bf16_f32 v90, v99, v93
	v_cvt_pk_bf16_f32 v91, v94, v91
	global_store_dwordx4 v[96:97], v[88:91], off nt
	v_max_f32_e32 v84, 0, v84
	v_max_f32_e32 v83, 0, v83
	v_mul_f32_e32 v88, v80, v80
	v_max_f32_e32 v80, 0, v85
	v_mul_f32_e32 v85, v81, v81
	v_max_f32_e32 v81, 0, v86
	v_mul_f32_e32 v86, v82, v82
	v_max_f32_e32 v82, 0, v87
	v_mul_f32_e32 v80, v80, v80
	v_mul_f32_e32 v81, v81, v81
	v_mul_f32_e32 v82, v82, v82
	v_mul_f32_e32 v84, v84, v84
	v_mul_f32_e32 v83, v83, v83
	v_cvt_pk_bf16_f32 v80, v84, v80
	v_cvt_pk_bf16_f32 v81, v81, v82
	v_cvt_pk_bf16_f32 v82, v88, v85
	v_cvt_pk_bf16_f32 v83, v86, v83
	global_store_dwordx4 v[96:97], v[80:83], off offset:256 nt
	v_cmp_gt_f32_e32 vcc, s54, v163
	s_mov_b32 s0, s22
	v_mul_f32_e32 v82, 0x4b800000, v163
	v_cndmask_b32_e32 v82, v163, v82, vcc
	v_rsq_f32_e32 v82, v82
	v_or_b32_e32 v80, 48, v146
	v_ashrrev_i32_e32 v81, 31, v80
	v_lshlrev_b64 v[80:81], 13, v[80:81]
	v_mul_f32_e32 v83, 0x45800000, v82
	v_cndmask_b32_e32 v82, v82, v83, vcc
	v_pk_mul_f32 v[72:73], v[72:73], v[82:83] op_sel_hi:[1,0]
	v_pk_mul_f32 v[76:77], v[76:77], v[82:83] op_sel_hi:[1,0]
	v_pk_mul_f32 v[74:75], v[74:75], v[82:83] op_sel_hi:[1,0]
	v_max_f32_e32 v72, 0, v72
	v_pk_mul_f32 v[78:79], v[78:79], v[82:83] op_sel_hi:[1,0]
	v_mul_f32_e32 v83, v72, v72
	v_max_f32_e32 v72, 0, v77
	v_max_f32_e32 v73, 0, v73
	v_max_f32_e32 v74, 0, v74
	v_lshl_add_u64 v[80:81], s[92:93], 0, v[80:81]
	v_max_f32_e32 v76, 0, v76
	v_mul_f32_e32 v72, v72, v72
	v_mul_f32_e32 v77, v73, v73
	v_max_f32_e32 v73, 0, v78
	v_mul_f32_e32 v78, v74, v74
	v_max_f32_e32 v74, 0, v79
	v_max_f32_e32 v75, 0, v75
	v_pk_mul_f32 v[64:65], v[64:65], v[82:83] op_sel_hi:[1,0]
	v_lshl_add_u64 v[80:81], v[80:81], 0, v[160:161]
	v_mul_f32_e32 v76, v76, v76
	v_mul_f32_e32 v73, v73, v73
	v_mul_f32_e32 v74, v74, v74
	v_mul_f32_e32 v75, v75, v75
	v_cvt_pk_bf16_f32 v72, v76, v72
	v_pk_mul_f32 v[68:69], v[68:69], v[82:83] op_sel_hi:[1,0]
	v_max_f32_e32 v64, 0, v64
	v_cvt_pk_bf16_f32 v73, v73, v74
	v_cvt_pk_bf16_f32 v74, v83, v77
	v_cvt_pk_bf16_f32 v75, v78, v75
	global_store_dwordx4 v[80:81], v[72:75], off nt
	v_max_f32_e32 v68, 0, v68
	v_mul_f32_e32 v68, v68, v68
	v_mul_f32_e32 v72, v64, v64
	v_max_f32_e32 v64, 0, v69
	v_mul_f32_e32 v64, v64, v64
	v_cvt_pk_bf16_f32 v64, v68, v64
	v_mul_f32_e32 v68, 0x4b800000, v164
	v_cmp_gt_f32_e32 vcc, s54, v164
	v_pk_mul_f32 v[66:67], v[66:67], v[82:83] op_sel_hi:[1,0]
	v_pk_mul_f32 v[70:71], v[70:71], v[82:83] op_sel_hi:[1,0]
	v_cndmask_b32_e32 v68, v164, v68, vcc
	v_max_f32_e32 v65, 0, v65
	v_max_f32_e32 v66, 0, v66
	v_rsq_f32_e32 v68, v68
	v_mul_f32_e32 v69, v65, v65
	v_max_f32_e32 v65, 0, v70
	v_mul_f32_e32 v70, v66, v66
	v_max_f32_e32 v66, 0, v71
	v_mul_f32_e32 v65, v65, v65
	v_max_f32_e32 v67, 0, v67
	v_mul_f32_e32 v66, v66, v66
	v_mul_f32_e32 v67, v67, v67
	v_cvt_pk_bf16_f32 v65, v65, v66
	v_cvt_pk_bf16_f32 v66, v72, v69
	v_cvt_pk_bf16_f32 v67, v70, v67
	global_store_dwordx4 v[80:81], v[64:67], off offset:256 nt
	s_nop 1
	v_mul_f32_e32 v66, 0x45800000, v68
	v_cndmask_b32_e32 v66, v68, v66, vcc
	v_pk_mul_f32 v[56:57], v[56:57], v[66:67] op_sel_hi:[1,0]
	v_pk_mul_f32 v[60:61], v[60:61], v[66:67] op_sel_hi:[1,0]
	v_pk_mul_f32 v[58:59], v[58:59], v[66:67] op_sel_hi:[1,0]
	v_max_f32_e32 v56, 0, v56
	v_pk_mul_f32 v[62:63], v[62:63], v[66:67] op_sel_hi:[1,0]
	v_max_f32_e32 v60, 0, v60
	v_mul_f32_e32 v67, v56, v56
	v_max_f32_e32 v56, 0, v61
	v_max_f32_e32 v57, 0, v57
	v_max_f32_e32 v58, 0, v58
	v_mul_f32_e32 v60, v60, v60
	v_mul_f32_e32 v56, v56, v56
	v_mul_f32_e32 v61, v57, v57
	v_max_f32_e32 v57, 0, v62
	v_mul_f32_e32 v62, v58, v58
	v_max_f32_e32 v58, 0, v63
	v_mul_f32_e32 v57, v57, v57
	v_max_f32_e32 v59, 0, v59
	v_mul_f32_e32 v58, v58, v58
	v_cvt_pk_bf16_f32 v56, v60, v56
	v_add_co_u32_e32 v60, vcc, s55, v144
	v_pk_mul_f32 v[48:49], v[48:49], v[66:67] op_sel_hi:[1,0]
	v_mul_f32_e32 v59, v59, v59
	v_cvt_pk_bf16_f32 v57, v57, v58
	v_cvt_pk_bf16_f32 v58, v67, v61
	v_addc_co_u32_e32 v61, vcc, 0, v145, vcc
	v_pk_mul_f32 v[52:53], v[52:53], v[66:67] op_sel_hi:[1,0]
	v_max_f32_e32 v48, 0, v48
	v_cvt_pk_bf16_f32 v59, v62, v59
	global_store_dwordx4 v[60:61], v[56:59], off nt
	v_max_f32_e32 v52, 0, v52
	v_mul_f32_e32 v52, v52, v52
	v_mul_f32_e32 v56, v48, v48
	v_max_f32_e32 v48, 0, v53
	v_mul_f32_e32 v48, v48, v48
	v_cvt_pk_bf16_f32 v48, v52, v48
	v_mul_f32_e32 v52, 0x4b800000, v165
	v_cmp_gt_f32_e32 vcc, s54, v165
	v_pk_mul_f32 v[50:51], v[50:51], v[66:67] op_sel_hi:[1,0]
	v_pk_mul_f32 v[54:55], v[54:55], v[66:67] op_sel_hi:[1,0]
	v_cndmask_b32_e32 v52, v165, v52, vcc
	v_max_f32_e32 v49, 0, v49
	v_max_f32_e32 v50, 0, v50
	v_rsq_f32_e32 v52, v52
	v_mul_f32_e32 v53, v49, v49
	v_max_f32_e32 v49, 0, v54
	v_mul_f32_e32 v54, v50, v50
	v_max_f32_e32 v50, 0, v55
	v_mul_f32_e32 v49, v49, v49
	v_max_f32_e32 v51, 0, v51
	v_mul_f32_e32 v50, v50, v50
	v_lshl_add_u64 v[64:65], v[144:145], 0, s[12:13]
	v_mul_f32_e32 v51, v51, v51
	v_cvt_pk_bf16_f32 v49, v49, v50
	v_cvt_pk_bf16_f32 v50, v56, v53
	v_cvt_pk_bf16_f32 v51, v54, v51
	global_store_dwordx4 v[64:65], v[48:51], off offset:256 nt
	s_nop 1
	v_mul_f32_e32 v50, 0x45800000, v52
	v_cndmask_b32_e32 v50, v52, v50, vcc
	v_pk_mul_f32 v[40:41], v[40:41], v[50:51] op_sel_hi:[1,0]
	v_pk_mul_f32 v[44:45], v[44:45], v[50:51] op_sel_hi:[1,0]
	v_pk_mul_f32 v[42:43], v[42:43], v[50:51] op_sel_hi:[1,0]
	v_max_f32_e32 v40, 0, v40
	v_pk_mul_f32 v[46:47], v[46:47], v[50:51] op_sel_hi:[1,0]
	v_max_f32_e32 v44, 0, v44
	v_mul_f32_e32 v51, v40, v40
	v_max_f32_e32 v40, 0, v45
	v_max_f32_e32 v41, 0, v41
	v_max_f32_e32 v42, 0, v42
	v_mul_f32_e32 v44, v44, v44
	v_mul_f32_e32 v40, v40, v40
	v_mul_f32_e32 v45, v41, v41
	v_max_f32_e32 v41, 0, v46
	v_mul_f32_e32 v46, v42, v42
	v_max_f32_e32 v42, 0, v47
	v_mul_f32_e32 v41, v41, v41
	v_max_f32_e32 v43, 0, v43
	v_mul_f32_e32 v42, v42, v42
	v_cvt_pk_bf16_f32 v40, v44, v40
	v_add_co_u32_e32 v44, vcc, s56, v144
	v_pk_mul_f32 v[32:33], v[32:33], v[50:51] op_sel_hi:[1,0]
	v_mul_f32_e32 v43, v43, v43
	v_cvt_pk_bf16_f32 v41, v41, v42
	v_cvt_pk_bf16_f32 v42, v51, v45
	v_addc_co_u32_e32 v45, vcc, 0, v145, vcc
	v_pk_mul_f32 v[36:37], v[36:37], v[50:51] op_sel_hi:[1,0]
	v_max_f32_e32 v32, 0, v32
	v_cvt_pk_bf16_f32 v43, v46, v43
	global_store_dwordx4 v[44:45], v[40:43], off nt
	v_max_f32_e32 v36, 0, v36
	v_mul_f32_e32 v36, v36, v36
	v_mul_f32_e32 v40, v32, v32
	v_max_f32_e32 v32, 0, v37
	v_mul_f32_e32 v32, v32, v32
	v_cvt_pk_bf16_f32 v32, v36, v32
	v_mul_f32_e32 v36, 0x4b800000, v166
	v_cmp_gt_f32_e32 vcc, s54, v166
	v_pk_mul_f32 v[34:35], v[34:35], v[50:51] op_sel_hi:[1,0]
	v_pk_mul_f32 v[38:39], v[38:39], v[50:51] op_sel_hi:[1,0]
	v_cndmask_b32_e32 v36, v166, v36, vcc
	v_max_f32_e32 v33, 0, v33
	v_max_f32_e32 v34, 0, v34
	v_rsq_f32_e32 v36, v36
	v_mul_f32_e32 v37, v33, v33
	v_max_f32_e32 v33, 0, v38
	v_mul_f32_e32 v38, v34, v34
	v_max_f32_e32 v34, 0, v39
	v_mul_f32_e32 v33, v33, v33
	v_max_f32_e32 v35, 0, v35
	v_mul_f32_e32 v34, v34, v34
	v_lshl_add_u64 v[48:49], v[144:145], 0, s[14:15]
	v_mul_f32_e32 v35, v35, v35
	v_cvt_pk_bf16_f32 v33, v33, v34
	v_cvt_pk_bf16_f32 v34, v40, v37
	v_cvt_pk_bf16_f32 v35, v38, v35
	global_store_dwordx4 v[48:49], v[32:35], off offset:256 nt
	s_nop 1
	v_mul_f32_e32 v34, 0x45800000, v36
	v_cndmask_b32_e32 v34, v36, v34, vcc
	v_pk_mul_f32 v[24:25], v[24:25], v[34:35] op_sel_hi:[1,0]
	v_pk_mul_f32 v[28:29], v[28:29], v[34:35] op_sel_hi:[1,0]
	v_pk_mul_f32 v[26:27], v[26:27], v[34:35] op_sel_hi:[1,0]
	v_max_f32_e32 v24, 0, v24
	v_pk_mul_f32 v[30:31], v[30:31], v[34:35] op_sel_hi:[1,0]
	v_max_f32_e32 v28, 0, v28
	v_mul_f32_e32 v35, v24, v24
	v_max_f32_e32 v24, 0, v29
	v_max_f32_e32 v25, 0, v25
	v_max_f32_e32 v26, 0, v26
	v_mul_f32_e32 v28, v28, v28
	v_mul_f32_e32 v24, v24, v24
	v_mul_f32_e32 v29, v25, v25
	v_max_f32_e32 v25, 0, v30
	v_mul_f32_e32 v30, v26, v26
	v_max_f32_e32 v26, 0, v31
	v_mul_f32_e32 v25, v25, v25
	v_max_f32_e32 v27, 0, v27
	v_mul_f32_e32 v26, v26, v26
	v_cvt_pk_bf16_f32 v24, v28, v24
	v_add_co_u32_e32 v28, vcc, s57, v144
	v_pk_mul_f32 v[16:17], v[16:17], v[34:35] op_sel_hi:[1,0]
	v_mul_f32_e32 v27, v27, v27
	v_cvt_pk_bf16_f32 v25, v25, v26
	v_cvt_pk_bf16_f32 v26, v35, v29
	v_addc_co_u32_e32 v29, vcc, 0, v145, vcc
	v_pk_mul_f32 v[20:21], v[20:21], v[34:35] op_sel_hi:[1,0]
	v_max_f32_e32 v16, 0, v16
	v_cvt_pk_bf16_f32 v27, v30, v27
	global_store_dwordx4 v[28:29], v[24:27], off nt
	v_max_f32_e32 v20, 0, v20
	v_mul_f32_e32 v20, v20, v20
	v_mul_f32_e32 v24, v16, v16
	v_max_f32_e32 v16, 0, v21
	v_mul_f32_e32 v16, v16, v16
	v_cvt_pk_bf16_f32 v16, v20, v16
	v_mul_f32_e32 v20, 0x4b800000, v147
	v_cmp_gt_f32_e32 vcc, s54, v147
	v_pk_mul_f32 v[18:19], v[18:19], v[34:35] op_sel_hi:[1,0]
	v_pk_mul_f32 v[22:23], v[22:23], v[34:35] op_sel_hi:[1,0]
	v_cndmask_b32_e32 v20, v147, v20, vcc
	v_max_f32_e32 v17, 0, v17
	v_max_f32_e32 v18, 0, v18
	v_rsq_f32_e32 v20, v20
	v_mul_f32_e32 v21, v17, v17
	v_max_f32_e32 v17, 0, v22
	v_mul_f32_e32 v22, v18, v18
	v_max_f32_e32 v18, 0, v23
	v_mul_f32_e32 v17, v17, v17
	v_max_f32_e32 v19, 0, v19
	v_mul_f32_e32 v18, v18, v18
	v_lshl_add_u64 v[32:33], v[144:145], 0, s[16:17]
	v_mul_f32_e32 v19, v19, v19
	v_cvt_pk_bf16_f32 v17, v17, v18
	v_cvt_pk_bf16_f32 v18, v24, v21
	v_cvt_pk_bf16_f32 v19, v22, v19
	global_store_dwordx4 v[32:33], v[16:19], off offset:256 nt
	s_nop 1
	v_mul_f32_e32 v18, 0x45800000, v20
	v_cndmask_b32_e32 v18, v20, v18, vcc
	v_pk_mul_f32 v[8:9], v[8:9], v[18:19] op_sel_hi:[1,0]
	v_pk_mul_f32 v[12:13], v[12:13], v[18:19] op_sel_hi:[1,0]
	v_pk_mul_f32 v[10:11], v[10:11], v[18:19] op_sel_hi:[1,0]
	v_max_f32_e32 v8, 0, v8
	v_pk_mul_f32 v[14:15], v[14:15], v[18:19] op_sel_hi:[1,0]
	v_max_f32_e32 v12, 0, v12
	v_mul_f32_e32 v19, v8, v8
	v_max_f32_e32 v8, 0, v13
	v_max_f32_e32 v9, 0, v9
	v_max_f32_e32 v10, 0, v10
	v_mul_f32_e32 v12, v12, v12
	v_mul_f32_e32 v8, v8, v8
	v_mul_f32_e32 v13, v9, v9
	v_max_f32_e32 v9, 0, v14
	v_mul_f32_e32 v14, v10, v10
	v_max_f32_e32 v10, 0, v15
	v_mul_f32_e32 v9, v9, v9
	v_max_f32_e32 v11, 0, v11
	v_mul_f32_e32 v10, v10, v10
	v_cvt_pk_bf16_f32 v8, v12, v8
	v_add_co_u32_e32 v12, vcc, s58, v144
	v_pk_mul_f32 v[2:3], v[2:3], v[18:19] op_sel_hi:[1,0]
	v_pk_mul_f32 v[0:1], v[0:1], v[18:19] op_sel_hi:[1,0]
	v_mul_f32_e32 v11, v11, v11
	v_cvt_pk_bf16_f32 v9, v9, v10
	v_cvt_pk_bf16_f32 v10, v19, v13
	v_addc_co_u32_e32 v13, vcc, 0, v145, vcc
	v_pk_mul_f32 v[6:7], v[6:7], v[18:19] op_sel_hi:[1,0]
	v_pk_mul_f32 v[4:5], v[4:5], v[18:19] op_sel_hi:[1,0]
	v_max_f32_e32 v0, 0, v0
	v_max_f32_e32 v1, 0, v1
	v_max_f32_e32 v2, 0, v2
	v_cvt_pk_bf16_f32 v11, v14, v11
	global_store_dwordx4 v[12:13], v[8:11], off nt
	v_max_f32_e32 v3, 0, v3
	v_lshl_add_u64 v[16:17], v[144:145], 0, s[18:19]
	v_mul_f32_e32 v8, v0, v0
	v_max_f32_e32 v0, 0, v5
	v_mul_f32_e32 v5, v1, v1
	v_max_f32_e32 v1, 0, v6
	v_mul_f32_e32 v6, v2, v2
	v_max_f32_e32 v2, 0, v7
	v_max_f32_e32 v4, 0, v4
	v_mul_f32_e32 v0, v0, v0
	v_mul_f32_e32 v1, v1, v1
	v_mul_f32_e32 v2, v2, v2
	v_mul_f32_e32 v3, v3, v3
	s_and_b64 vcc, exec, s[2:3]
	v_mul_f32_e32 v4, v4, v4
	v_cvt_pk_bf16_f32 v0, v4, v0
	v_cvt_pk_bf16_f32 v1, v1, v2
	v_cvt_pk_bf16_f32 v2, v8, v5
	v_cvt_pk_bf16_f32 v3, v6, v3
	global_store_dwordx4 v[16:17], v[0:3], off offset:256 nt
	s_cbranch_vccz .LBB0_1211
	s_waitcnt vmcnt(0)
	s_cmpk_gt_u32 s33, 0xff
	s_cbranch_scc1 .LBB0_1222
	s_barrier

.LBB0_1264:
	ds_read_b128 v[144:147], v178
	ds_read_b128 v[148:151], v178 offset:1024
	ds_read_b128 v[152:155], v178 offset:2048
	ds_read_b128 v[156:159], v178 offset:3072
	s_add_u32 s34, s30, 0xfff00080
	s_addc_u32 s35, s31, -1
	s_cmp_eq_u32 s58, 60
	s_cselect_b32 s37, s21, s35
	s_cselect_b32 s36, s27, s34
	s_cselect_b32 s35, s19, s57
	s_cselect_b32 s34, s55, s56
	v_lshl_add_u64 v[172:173], s[30:31], 0, v[136:137]
	s_add_i32 m0, s29, 0xc000
	ds_read_b128 v[160:163], v179
	ds_read_b128 v[164:167], v179 offset:1024
	ds_read_b128 v[168:171], v179 offset:2048
	ds_read_b128 v[182:185], v179 offset:3072
	ds_read_b128 v[186:189], v179 offset:4096
	ds_read_b128 v[190:193], v179 offset:5120
	ds_read_b128 v[194:197], v179 offset:6144
	ds_read_b128 v[198:201], v179 offset:7168
	global_load_lds_dwordx4 v[172:173], off
	v_lshl_add_u64 v[172:173], s[30:31], 0, v[138:139]
	s_add_i32 m0, s29, 0xe000
	s_nop 0
	global_load_lds_dwordx4 v[172:173], off
	s_waitcnt lgkmcnt(8)
	s_barrier
	s_waitcnt lgkmcnt(0)
	s_setprio 1
	v_mfma_f32_16x16x32_bf16 v[124:127], v[144:147], v[160:163], v[124:127]
	v_mfma_f32_16x16x32_bf16 v[120:123], v[152:155], v[160:163], v[120:123]
	v_mfma_f32_16x16x32_bf16 v[108:111], v[144:147], v[168:171], v[108:111]
	v_mfma_f32_16x16x32_bf16 v[104:107], v[152:155], v[168:171], v[104:107]
	v_mfma_f32_16x16x32_bf16 v[96:99], v[144:147], v[186:189], v[96:99]
	v_mfma_f32_16x16x32_bf16 v[88:91], v[152:155], v[186:189], v[88:91]
	v_mfma_f32_16x16x32_bf16 v[80:83], v[144:147], v[194:197], v[80:83]
	v_mfma_f32_16x16x32_bf16 v[72:75], v[152:155], v[194:197], v[72:75]
	v_mfma_f32_16x16x32_bf16 v[124:127], v[148:151], v[164:167], v[124:127]
	v_mfma_f32_16x16x32_bf16 v[120:123], v[156:159], v[164:167], v[120:123]
	v_mfma_f32_16x16x32_bf16 v[108:111], v[148:151], v[182:185], v[108:111]
	v_mfma_f32_16x16x32_bf16 v[104:107], v[156:159], v[182:185], v[104:107]
	v_mfma_f32_16x16x32_bf16 v[96:99], v[148:151], v[190:193], v[96:99]
	v_mfma_f32_16x16x32_bf16 v[88:91], v[156:159], v[190:193], v[88:91]
	v_mfma_f32_16x16x32_bf16 v[80:83], v[148:151], v[198:201], v[80:83]
	v_mfma_f32_16x16x32_bf16 v[72:75], v[156:159], v[198:201], v[72:75]
	s_setprio 0
	s_barrier
	s_add_i32 s59, s53, s40
	v_lshl_add_u64 v[172:173], s[34:35], 0, v[130:131]
	s_mov_b32 m0, s59
	ds_read_b128 v[202:205], v180
	ds_read_b128 v[206:209], v180 offset:1024
	ds_read_b128 v[212:215], v180 offset:2048
	ds_read_b128 v[216:219], v180 offset:3072
	global_load_lds_dwordx4 v[172:173], off
	v_lshl_add_u64 v[220:221], s[34:35], 0, v[134:135]
	s_add_i32 m0, s59, 0x2000
	s_nop 0
	global_load_lds_dwordx4 v[220:221], off
	s_barrier
	s_waitcnt lgkmcnt(0)
	s_setprio 1
	v_mfma_f32_16x16x32_bf16 v[116:119], v[202:205], v[160:163], v[116:119]
	v_mfma_f32_16x16x32_bf16 v[112:115], v[212:215], v[160:163], v[112:115]
	v_mfma_f32_16x16x32_bf16 v[100:103], v[202:205], v[168:171], v[100:103]
	v_mfma_f32_16x16x32_bf16 v[92:95], v[212:215], v[168:171], v[92:95]
	v_mfma_f32_16x16x32_bf16 v[84:87], v[202:205], v[186:189], v[84:87]
	v_mfma_f32_16x16x32_bf16 v[76:79], v[212:215], v[186:189], v[76:79]
	v_mfma_f32_16x16x32_bf16 v[68:71], v[202:205], v[194:197], v[68:71]
	v_mfma_f32_16x16x32_bf16 v[64:67], v[212:215], v[194:197], v[64:67]
	v_mfma_f32_16x16x32_bf16 v[116:119], v[206:209], v[164:167], v[116:119]
	v_mfma_f32_16x16x32_bf16 v[112:115], v[216:219], v[164:167], v[112:115]
	v_mfma_f32_16x16x32_bf16 v[100:103], v[206:209], v[182:185], v[100:103]
	v_mfma_f32_16x16x32_bf16 v[92:95], v[216:219], v[182:185], v[92:95]
	v_mfma_f32_16x16x32_bf16 v[84:87], v[206:209], v[190:193], v[84:87]
	v_mfma_f32_16x16x32_bf16 v[76:79], v[216:219], v[190:193], v[76:79]
	v_mfma_f32_16x16x32_bf16 v[68:71], v[206:209], v[198:201], v[68:71]
	v_mfma_f32_16x16x32_bf16 v[64:67], v[216:219], v[198:201], v[64:67]
	s_setprio 0
	s_mov_b32 m0, s29
	v_lshl_add_u64 v[222:223], s[36:37], 0, v[128:129]
	s_barrier
	ds_read_b128 v[160:163], v179 offset:16384
	ds_read_b128 v[164:167], v179 offset:17408
	ds_read_b128 v[168:171], v179 offset:18432
	ds_read_b128 v[182:185], v179 offset:19456
	ds_read_b128 v[186:189], v179 offset:20480
	ds_read_b128 v[190:193], v179 offset:21504
	ds_read_b128 v[194:197], v179 offset:22528
	ds_read_b128 v[198:201], v179 offset:23552
	global_load_lds_dwordx4 v[222:223], off
	v_lshl_add_u64 v[224:225], s[36:37], 0, v[132:133]
	s_mov_b32 m0, s41
	s_nop 0
	global_load_lds_dwordx4 v[224:225], off
	s_barrier
	s_waitcnt lgkmcnt(0)
	s_setprio 1
	v_mfma_f32_16x16x32_bf16 v[60:63], v[144:147], v[160:163], v[60:63]
	v_mfma_f32_16x16x32_bf16 v[56:59], v[152:155], v[160:163], v[56:59]
	v_mfma_f32_16x16x32_bf16 v[44:47], v[144:147], v[168:171], v[44:47]
	v_mfma_f32_16x16x32_bf16 v[40:43], v[152:155], v[168:171], v[40:43]
	v_mfma_f32_16x16x32_bf16 v[32:35], v[144:147], v[186:189], v[32:35]
	v_mfma_f32_16x16x32_bf16 v[24:27], v[152:155], v[186:189], v[24:27]
	v_mfma_f32_16x16x32_bf16 v[16:19], v[144:147], v[194:197], v[16:19]
	v_mfma_f32_16x16x32_bf16 v[8:11], v[152:155], v[194:197], v[8:11]
	v_mfma_f32_16x16x32_bf16 v[60:63], v[148:151], v[164:167], v[60:63]
	v_mfma_f32_16x16x32_bf16 v[56:59], v[156:159], v[164:167], v[56:59]
	v_mfma_f32_16x16x32_bf16 v[44:47], v[148:151], v[182:185], v[44:47]
	v_mfma_f32_16x16x32_bf16 v[40:43], v[156:159], v[182:185], v[40:43]
	v_mfma_f32_16x16x32_bf16 v[32:35], v[148:151], v[190:193], v[32:35]
	v_mfma_f32_16x16x32_bf16 v[24:27], v[156:159], v[190:193], v[24:27]
	v_mfma_f32_16x16x32_bf16 v[16:19], v[148:151], v[198:201], v[16:19]
	v_mfma_f32_16x16x32_bf16 v[8:11], v[156:159], v[198:201], v[8:11]
	s_setprio 0
	s_barrier
	s_add_u32 s60, s34, 0x100000
	s_addc_u32 s61, s35, 0
	s_add_i32 s59, s54, s40
	v_lshl_add_u64 v[144:145], s[60:61], 0, v[130:131]
	s_mov_b32 m0, s59
	s_nop 0
	global_load_lds_dwordx4 v[144:145], off
	v_lshl_add_u64 v[144:145], s[60:61], 0, v[134:135]
	s_add_i32 m0, s59, 0x2000
	s_nop 0
	global_load_lds_dwordx4 v[144:145], off
	s_waitcnt vmcnt(6)
	s_barrier
	s_setprio 1
	v_mfma_f32_16x16x32_bf16 v[52:55], v[202:205], v[160:163], v[52:55]
	v_mfma_f32_16x16x32_bf16 v[48:51], v[212:215], v[160:163], v[48:51]
	v_mfma_f32_16x16x32_bf16 v[36:39], v[202:205], v[168:171], v[36:39]
	v_mfma_f32_16x16x32_bf16 v[28:31], v[212:215], v[168:171], v[28:31]
	v_mfma_f32_16x16x32_bf16 v[20:23], v[202:205], v[186:189], v[20:23]
	v_mfma_f32_16x16x32_bf16 v[12:15], v[212:215], v[186:189], v[12:15]
	v_mfma_f32_16x16x32_bf16 v[4:7], v[202:205], v[194:197], v[4:7]
	v_mfma_f32_16x16x32_bf16 v[0:3], v[212:215], v[194:197], v[0:3]
	v_mfma_f32_16x16x32_bf16 v[52:55], v[206:209], v[164:167], v[52:55]
	v_mfma_f32_16x16x32_bf16 v[48:51], v[216:219], v[164:167], v[48:51]
	v_mfma_f32_16x16x32_bf16 v[36:39], v[206:209], v[182:185], v[36:39]
	v_mfma_f32_16x16x32_bf16 v[28:31], v[216:219], v[182:185], v[28:31]
	v_mfma_f32_16x16x32_bf16 v[20:23], v[206:209], v[190:193], v[20:23]
	v_mfma_f32_16x16x32_bf16 v[12:15], v[216:219], v[190:193], v[12:15]
	v_mfma_f32_16x16x32_bf16 v[4:7], v[206:209], v[198:201], v[4:7]
	v_mfma_f32_16x16x32_bf16 v[0:3], v[216:219], v[198:201], v[0:3]
	s_setprio 0
	s_add_i32 s59, 0, 0x18000
	v_add_u32_e32 v156, s59, v176
	s_barrier
	ds_read_b128 v[144:147], v156
	ds_read_b128 v[148:151], v156 offset:1024
	ds_read_b128 v[152:155], v156 offset:2048
	ds_read_b128 v[156:159], v156 offset:3072
	s_add_u32 s36, s36, 0x100000
	s_addc_u32 s37, s37, 0
	s_mov_b32 m0, s42
	v_lshl_add_u64 v[202:203], s[36:37], 0, v[128:129]
	ds_read_b128 v[160:163], v179 offset:32768
	ds_read_b128 v[164:167], v179 offset:33792
	ds_read_b128 v[168:171], v179 offset:34816
	ds_read_b128 v[182:185], v179 offset:35840
	ds_read_b128 v[186:189], v179 offset:36864
	ds_read_b128 v[190:193], v179 offset:37888
	ds_read_b128 v[194:197], v179 offset:38912
	ds_read_b128 v[198:201], v179 offset:39936
	global_load_lds_dwordx4 v[202:203], off
	v_lshl_add_u64 v[202:203], s[36:37], 0, v[132:133]
	s_mov_b32 m0, s43
	s_nop 0
	global_load_lds_dwordx4 v[202:203], off
	s_waitcnt lgkmcnt(8)
	s_barrier
	s_waitcnt lgkmcnt(0)
	s_setprio 1
	v_mfma_f32_16x16x32_bf16 v[124:127], v[144:147], v[160:163], v[124:127]
	v_mfma_f32_16x16x32_bf16 v[120:123], v[152:155], v[160:163], v[120:123]
	v_mfma_f32_16x16x32_bf16 v[108:111], v[144:147], v[168:171], v[108:111]
	v_mfma_f32_16x16x32_bf16 v[104:107], v[152:155], v[168:171], v[104:107]
	v_mfma_f32_16x16x32_bf16 v[96:99], v[144:147], v[186:189], v[96:99]
	v_mfma_f32_16x16x32_bf16 v[88:91], v[152:155], v[186:189], v[88:91]
	v_mfma_f32_16x16x32_bf16 v[80:83], v[144:147], v[194:197], v[80:83]
	v_mfma_f32_16x16x32_bf16 v[72:75], v[152:155], v[194:197], v[72:75]
	v_mfma_f32_16x16x32_bf16 v[124:127], v[148:151], v[164:167], v[124:127]
	v_mfma_f32_16x16x32_bf16 v[120:123], v[156:159], v[164:167], v[120:123]
	v_mfma_f32_16x16x32_bf16 v[108:111], v[148:151], v[182:185], v[108:111]
	v_mfma_f32_16x16x32_bf16 v[104:107], v[156:159], v[182:185], v[104:107]
	v_mfma_f32_16x16x32_bf16 v[96:99], v[148:151], v[190:193], v[96:99]
	v_mfma_f32_16x16x32_bf16 v[88:91], v[156:159], v[190:193], v[88:91]
	v_mfma_f32_16x16x32_bf16 v[80:83], v[148:151], v[198:201], v[80:83]
	v_mfma_f32_16x16x32_bf16 v[72:75], v[156:159], v[198:201], v[72:75]
	s_setprio 0
	s_barrier
	s_add_i32 s36, 0, 0x1c000
	s_add_i32 s37, s59, s40
	v_add_u32_e32 v181, s36, v176
	v_lshl_add_u64 v[172:173], v[172:173], 0, s[0:1]
	s_mov_b32 m0, s37
	ds_read_b128 v[202:205], v181
	ds_read_b128 v[206:209], v181 offset:1024
	ds_read_b128 v[212:215], v181 offset:2048
	ds_read_b128 v[216:219], v181 offset:3072
	global_load_lds_dwordx4 v[172:173], off
	v_lshl_add_u64 v[172:173], v[220:221], 0, s[0:1]
	s_add_i32 m0, s37, 0x2000
	s_nop 0
	global_load_lds_dwordx4 v[172:173], off
	s_barrier
	s_waitcnt lgkmcnt(0)
	s_setprio 1
	v_mfma_f32_16x16x32_bf16 v[116:119], v[202:205], v[160:163], v[116:119]
	v_mfma_f32_16x16x32_bf16 v[112:115], v[212:215], v[160:163], v[112:115]
	v_mfma_f32_16x16x32_bf16 v[100:103], v[202:205], v[168:171], v[100:103]
	v_mfma_f32_16x16x32_bf16 v[92:95], v[212:215], v[168:171], v[92:95]
	v_mfma_f32_16x16x32_bf16 v[84:87], v[202:205], v[186:189], v[84:87]
	v_mfma_f32_16x16x32_bf16 v[76:79], v[212:215], v[186:189], v[76:79]
	v_mfma_f32_16x16x32_bf16 v[68:71], v[202:205], v[194:197], v[68:71]
	v_mfma_f32_16x16x32_bf16 v[64:67], v[212:215], v[194:197], v[64:67]
	v_mfma_f32_16x16x32_bf16 v[116:119], v[206:209], v[164:167], v[116:119]
	v_mfma_f32_16x16x32_bf16 v[112:115], v[216:219], v[164:167], v[112:115]
	v_mfma_f32_16x16x32_bf16 v[100:103], v[206:209], v[182:185], v[100:103]
	v_mfma_f32_16x16x32_bf16 v[92:95], v[216:219], v[182:185], v[92:95]
	v_mfma_f32_16x16x32_bf16 v[84:87], v[206:209], v[190:193], v[84:87]
	v_mfma_f32_16x16x32_bf16 v[76:79], v[216:219], v[190:193], v[76:79]
	v_mfma_f32_16x16x32_bf16 v[68:71], v[206:209], v[198:201], v[68:71]
	v_mfma_f32_16x16x32_bf16 v[64:67], v[216:219], v[198:201], v[64:67]
	s_setprio 0
	s_mov_b32 m0, s49
	v_lshl_add_u64 v[172:173], v[222:223], 0, s[0:1]
	s_barrier
	ds_read_b128 v[160:163], v179 offset:49152
	ds_read_b128 v[164:167], v179 offset:50176
	ds_read_b128 v[168:171], v179 offset:51200
	ds_read_b128 v[182:185], v179 offset:52224
	ds_read_b128 v[186:189], v179 offset:53248
	ds_read_b128 v[190:193], v179 offset:54272
	ds_read_b128 v[194:197], v179 offset:55296
	ds_read_b128 v[198:201], v179 offset:56320
	global_load_lds_dwordx4 v[172:173], off
	v_lshl_add_u64 v[172:173], v[224:225], 0, s[0:1]
	s_mov_b32 m0, s50
	s_nop 0
	global_load_lds_dwordx4 v[172:173], off
	s_barrier
	s_waitcnt lgkmcnt(0)
	s_setprio 1
	v_mfma_f32_16x16x32_bf16 v[60:63], v[144:147], v[160:163], v[60:63]
	v_mfma_f32_16x16x32_bf16 v[56:59], v[152:155], v[160:163], v[56:59]
	v_mfma_f32_16x16x32_bf16 v[44:47], v[144:147], v[168:171], v[44:47]
	v_mfma_f32_16x16x32_bf16 v[40:43], v[152:155], v[168:171], v[40:43]
	v_mfma_f32_16x16x32_bf16 v[32:35], v[144:147], v[186:189], v[32:35]
	v_mfma_f32_16x16x32_bf16 v[24:27], v[152:155], v[186:189], v[24:27]
	v_mfma_f32_16x16x32_bf16 v[16:19], v[144:147], v[194:197], v[16:19]
	v_mfma_f32_16x16x32_bf16 v[8:11], v[152:155], v[194:197], v[8:11]
	v_mfma_f32_16x16x32_bf16 v[60:63], v[148:151], v[164:167], v[60:63]
	v_mfma_f32_16x16x32_bf16 v[56:59], v[156:159], v[164:167], v[56:59]
	v_mfma_f32_16x16x32_bf16 v[44:47], v[148:151], v[182:185], v[44:47]
	v_mfma_f32_16x16x32_bf16 v[40:43], v[156:159], v[182:185], v[40:43]
	v_mfma_f32_16x16x32_bf16 v[32:35], v[148:151], v[190:193], v[32:35]
	v_mfma_f32_16x16x32_bf16 v[24:27], v[156:159], v[190:193], v[24:27]
	v_mfma_f32_16x16x32_bf16 v[16:19], v[148:151], v[198:201], v[16:19]
	v_mfma_f32_16x16x32_bf16 v[8:11], v[156:159], v[198:201], v[8:11]
	s_setprio 0
	s_barrier
	s_add_u32 s34, s34, 0x100080
	s_addc_u32 s35, s35, 0
	s_add_i32 s36, s36, s40
	v_lshl_add_u64 v[144:145], s[34:35], 0, v[130:131]
	s_mov_b32 m0, s36
	s_nop 0
	global_load_lds_dwordx4 v[144:145], off
	v_lshl_add_u64 v[144:145], s[34:35], 0, v[134:135]
	s_add_i32 m0, s36, 0x2000
	s_nop 0
	global_load_lds_dwordx4 v[144:145], off
	s_waitcnt vmcnt(6)
	s_barrier
	s_setprio 1
	v_mfma_f32_16x16x32_bf16 v[52:55], v[202:205], v[160:163], v[52:55]
	v_mfma_f32_16x16x32_bf16 v[48:51], v[212:215], v[160:163], v[48:51]
	v_mfma_f32_16x16x32_bf16 v[36:39], v[202:205], v[168:171], v[36:39]
	v_mfma_f32_16x16x32_bf16 v[28:31], v[212:215], v[168:171], v[28:31]
	v_mfma_f32_16x16x32_bf16 v[20:23], v[202:205], v[186:189], v[20:23]
	v_mfma_f32_16x16x32_bf16 v[12:15], v[212:215], v[186:189], v[12:15]
	v_mfma_f32_16x16x32_bf16 v[4:7], v[202:205], v[194:197], v[4:7]
	v_mfma_f32_16x16x32_bf16 v[0:3], v[212:215], v[194:197], v[0:3]
	v_mfma_f32_16x16x32_bf16 v[52:55], v[206:209], v[164:167], v[52:55]
	v_mfma_f32_16x16x32_bf16 v[48:51], v[216:219], v[164:167], v[48:51]
	v_mfma_f32_16x16x32_bf16 v[36:39], v[206:209], v[182:185], v[36:39]
	v_mfma_f32_16x16x32_bf16 v[28:31], v[216:219], v[182:185], v[28:31]
	v_mfma_f32_16x16x32_bf16 v[20:23], v[206:209], v[190:193], v[20:23]
	v_mfma_f32_16x16x32_bf16 v[12:15], v[216:219], v[190:193], v[12:15]
	v_mfma_f32_16x16x32_bf16 v[4:7], v[206:209], v[198:201], v[4:7]
	v_mfma_f32_16x16x32_bf16 v[0:3], v[216:219], v[198:201], v[0:3]
	s_setprio 0
	s_add_i32 s58, s58, 2
	s_add_u32 s30, s30, 0x100
	s_addc_u32 s31, s31, 0
	s_add_u32 s56, s56, 0x100
	s_addc_u32 s57, s57, 0
	s_cmp_gt_u32 s58, 61
	s_barrier
	s_cbranch_scc0 .LBB0_1264
	v_lshl_or_b32 v144, s28, 8, v177
	v_lshl_add_u32 v150, s26, 8, v175
	v_ashrrev_i32_e32 v145, 31, v144
	v_ashrrev_i32_e32 v151, 31, v150
	v_lshlrev_b64 v[144:145], 1, v[144:145]
	v_lshl_add_u64 v[146:147], s[90:91], 0, v[144:145]
	v_lshlrev_b64 v[148:149], 11, v[150:151]
	v_lshl_add_u64 v[152:153], v[146:147], 0, v[148:149]
	global_load_dwordx4 v[156:159], v[152:153], off
	global_load_dwordx4 v[160:163], v[152:153], off offset:256
	v_or_b32_e32 v152, 16, v150
	v_ashrrev_i32_e32 v153, 31, v152
	v_lshlrev_b64 v[170:171], 11, v[152:153]
	v_lshl_add_u64 v[152:153], v[146:147], 0, v[170:171]
	global_load_dwordx4 v[164:167], v[152:153], off
	global_load_dwordx4 v[182:185], v[152:153], off offset:256
	v_or_b32_e32 v152, 32, v150
	v_ashrrev_i32_e32 v153, 31, v152
	v_lshlrev_b64 v[154:155], 11, v[152:153]
	v_lshl_add_u64 v[152:153], v[146:147], 0, v[154:155]
	global_load_dwordx4 v[186:189], v[152:153], off
	global_load_dwordx4 v[190:193], v[152:153], off offset:256
	v_or_b32_e32 v152, 48, v150
	v_ashrrev_i32_e32 v153, 31, v152
	v_lshlrev_b64 v[152:153], 11, v[152:153]
	v_lshl_add_u64 v[168:169], v[146:147], 0, v[152:153]
	global_load_dwordx4 v[194:197], v[168:169], off
	global_load_dwordx4 v[198:201], v[168:169], off offset:256
	s_waitcnt vmcnt(0)
	v_lshlrev_b32_e32 v202, 16, v156
	v_and_b32_e32 v203, 0xffff0000, v156
	v_lshlrev_b32_e32 v204, 16, v157
	v_and_b32_e32 v205, 0xffff0000, v157
	v_lshlrev_b32_e32 v206, 16, v158
	v_and_b32_e32 v207, 0xffff0000, v158
	v_lshlrev_b32_e32 v208, 16, v159
	v_and_b32_e32 v209, 0xffff0000, v159
	v_pk_add_f32 v[126:127], v[126:127], v[204:205]
	v_pk_add_f32 v[124:125], v[124:125], v[202:203]
	v_lshlrev_b32_e32 v224, 16, v166
	v_and_b32_e32 v225, 0xffff0000, v166
	v_lshlrev_b32_e32 v226, 16, v167
	v_and_b32_e32 v227, 0xffff0000, v167
	v_lshlrev_b32_e32 v212, 16, v160
	v_lshlrev_b32_e32 v166, 16, v194
	v_and_b32_e32 v167, 0xffff0000, v194
	v_lshlrev_b32_e32 v172, 16, v195
	v_and_b32_e32 v173, 0xffff0000, v195
	v_pk_add_f32 v[194:195], v[122:123], v[208:209]
	v_pk_add_f32 v[122:123], v[120:121], v[206:207]
	v_mul_f32_e32 v120, v125, v125
	v_mul_f32_e32 v121, v127, v127
	v_fmac_f32_e32 v120, v124, v124
	v_fmac_f32_e32 v121, v126, v126
	v_add_f32_e32 v120, v120, v121
	v_mul_f32_e32 v121, v123, v123
	v_fmac_f32_e32 v121, v122, v122
	v_add_f32_e32 v120, v121, v120
	v_mul_f32_e32 v121, v195, v195
	v_fmac_f32_e32 v121, v194, v194
	v_and_b32_e32 v213, 0xffff0000, v160
	v_lshlrev_b32_e32 v214, 16, v161
	v_and_b32_e32 v215, 0xffff0000, v161
	v_add_f32_e32 v181, v121, v120
	v_cvt_pk_bf16_f32 v120, v124, v125
	v_lshl_add_u64 v[124:125], s[10:11], 0, v[148:149]
	v_lshlrev_b32_e32 v216, 16, v162
	v_and_b32_e32 v217, 0xffff0000, v162
	v_lshlrev_b32_e32 v218, 16, v163
	v_and_b32_e32 v219, 0xffff0000, v163
	v_cvt_pk_bf16_f32 v121, v126, v127
	v_lshl_add_u64 v[124:125], v[124:125], 0, v[144:145]
	v_pk_add_f32 v[118:119], v[118:119], v[214:215]
	v_pk_add_f32 v[116:117], v[116:117], v[212:213]
	v_cvt_pk_bf16_f32 v122, v122, v123
	v_cvt_pk_bf16_f32 v123, v194, v195
	global_store_dwordx4 v[124:125], v[120:123], off
	v_lshlrev_b32_e32 v220, 16, v164
	v_and_b32_e32 v221, 0xffff0000, v164
	v_pk_add_f32 v[120:121], v[114:115], v[218:219]
	v_pk_add_f32 v[114:115], v[112:113], v[216:217]
	v_mul_f32_e32 v112, v117, v117
	v_mul_f32_e32 v113, v119, v119
	v_fmac_f32_e32 v112, v116, v116
	v_fmac_f32_e32 v113, v118, v118
	v_add_f32_e32 v112, v112, v113
	v_mul_f32_e32 v113, v115, v115
	v_fmac_f32_e32 v113, v114, v114
	v_add_f32_e32 v112, v113, v112
	v_mul_f32_e32 v113, v121, v121
	v_fmac_f32_e32 v113, v120, v120
	v_add_f32_e32 v112, v113, v112
	v_lshlrev_b32_e32 v222, 16, v165
	v_and_b32_e32 v223, 0xffff0000, v165
	v_add_f32_e32 v126, v181, v112
	v_cvt_pk_bf16_f32 v112, v116, v117
	v_cvt_pk_bf16_f32 v113, v118, v119
	v_lshl_add_u64 v[116:117], s[10:11], 0, v[170:171]
	v_lshlrev_b32_e32 v230, 16, v184
	v_and_b32_e32 v231, 0xffff0000, v184
	v_lshlrev_b32_e32 v232, 16, v186
	v_and_b32_e32 v233, 0xffff0000, v186
	v_lshlrev_b32_e32 v186, 16, v187
	v_and_b32_e32 v187, 0xffff0000, v187
	v_cvt_pk_bf16_f32 v114, v114, v115
	v_cvt_pk_bf16_f32 v115, v120, v121
	global_store_dwordx4 v[124:125], v[112:115], off offset:256
	v_pk_add_f32 v[110:111], v[110:111], v[222:223]
	v_pk_add_f32 v[108:109], v[108:109], v[220:221]
	v_lshl_add_u64 v[118:119], v[116:117], 0, v[144:145]
	v_cvt_pk_bf16_f32 v112, v108, v109
	v_cvt_pk_bf16_f32 v113, v110, v111
	v_lshlrev_b32_e32 v228, 16, v182
	v_and_b32_e32 v229, 0xffff0000, v182
	v_lshlrev_b32_e32 v182, 16, v183
	v_and_b32_e32 v183, 0xffff0000, v183
	v_lshlrev_b32_e32 v184, 16, v185
	v_and_b32_e32 v185, 0xffff0000, v185
	v_lshlrev_b32_e32 v238, 16, v192
	v_and_b32_e32 v239, 0xffff0000, v192
	v_pk_add_f32 v[106:107], v[106:107], v[226:227]
	v_pk_add_f32 v[104:105], v[104:105], v[224:225]
	v_lshlrev_b32_e32 v156, 16, v200
	v_cvt_pk_bf16_f32 v114, v104, v105
	v_cvt_pk_bf16_f32 v115, v106, v107
	global_store_dwordx4 v[118:119], v[112:115], off
	v_and_b32_e32 v157, 0xffff0000, v200
	v_pk_add_f32 v[102:103], v[102:103], v[182:183]
	v_pk_add_f32 v[112:113], v[92:93], v[230:231]
	v_pk_add_f32 v[92:93], v[98:99], v[186:187]
	v_lshl_add_u64 v[98:99], s[10:11], 0, v[154:155]
	v_pk_add_f32 v[100:101], v[100:101], v[228:229]
	v_pk_add_f32 v[94:95], v[94:95], v[184:185]
	v_cvt_pk_bf16_f32 v114, v100, v101
	v_cvt_pk_bf16_f32 v115, v102, v103
	v_cvt_pk_bf16_f32 v116, v112, v113
	v_lshlrev_b32_e32 v234, 16, v188
	v_cvt_pk_bf16_f32 v117, v94, v95
	global_store_dwordx4 v[118:119], v[114:117], off offset:256
	v_lshl_add_u64 v[118:119], v[98:99], 0, v[144:145]
	v_pk_add_f32 v[98:99], v[76:77], v[238:239]
	v_pk_add_f32 v[76:77], v[82:83], v[172:173]
	v_lshl_add_u64 v[82:83], s[10:11], 0, v[152:153]
	v_lshl_add_u64 v[122:123], v[82:83], 0, v[144:145]
	v_pk_add_f32 v[82:83], v[64:65], v[156:157]
	v_and_b32_e32 v65, 64, v174
	v_and_b32_e32 v235, 0xffff0000, v188
	v_lshlrev_b32_e32 v188, 16, v189
	v_and_b32_e32 v189, 0xffff0000, v189
	v_lshlrev_b32_e32 v236, 16, v190
	v_and_b32_e32 v237, 0xffff0000, v190
	v_pk_add_f32 v[96:97], v[96:97], v[232:233]
	v_xor_b32_e32 v64, 16, v174
	v_cvt_pk_bf16_f32 v114, v96, v97
	v_add_u32_e32 v65, 64, v65
	v_lshlrev_b32_e32 v190, 16, v191
	v_and_b32_e32 v191, 0xffff0000, v191
	v_lshlrev_b32_e32 v192, 16, v193
	v_and_b32_e32 v193, 0xffff0000, v193
	v_pk_add_f32 v[90:91], v[90:91], v[188:189]
	v_pk_add_f32 v[88:89], v[88:89], v[234:235]
	v_cvt_pk_bf16_f32 v115, v92, v93
	v_pk_add_f32 v[84:85], v[84:85], v[236:237]
	v_cvt_pk_bf16_f32 v116, v88, v89
	v_cvt_pk_bf16_f32 v117, v90, v91
	global_store_dwordx4 v[118:119], v[114:117], off
	v_cmp_lt_i32_e32 vcc, v64, v65
	v_lshlrev_b32_e32 v164, 16, v196
	v_cvt_pk_bf16_f32 v114, v84, v85
	v_and_b32_e32 v165, 0xffff0000, v196
	v_lshlrev_b32_e32 v168, 16, v197
	v_and_b32_e32 v169, 0xffff0000, v197
	v_pk_add_f32 v[86:87], v[86:87], v[190:191]
	v_pk_add_f32 v[78:79], v[78:79], v[192:193]
	v_cvt_pk_bf16_f32 v115, v86, v87
	v_cvt_pk_bf16_f32 v116, v98, v99
	v_pk_add_f32 v[80:81], v[80:81], v[166:167]
	v_cvt_pk_bf16_f32 v117, v78, v79
	global_store_dwordx4 v[118:119], v[114:117], off offset:256
	v_cndmask_b32_e32 v64, v174, v64, vcc
	v_pk_add_f32 v[74:75], v[74:75], v[168:169]
	v_cvt_pk_bf16_f32 v114, v80, v81
	v_pk_add_f32 v[72:73], v[72:73], v[164:165]
	v_cvt_pk_bf16_f32 v115, v76, v77
	v_lshlrev_b32_e32 v158, 16, v198
	v_cvt_pk_bf16_f32 v116, v72, v73
	v_cvt_pk_bf16_f32 v117, v74, v75
	global_store_dwordx4 v[122:123], v[114:117], off
	v_and_b32_e32 v159, 0xffff0000, v198
	v_lshlrev_b32_e32 v162, 16, v199
	v_lshlrev_b32_e32 v114, 2, v64
	ds_bpermute_b32 v64, v114, v126
	v_xor_b32_e32 v115, 32, v174
	v_cmp_lt_i32_e32 vcc, v115, v65
	v_and_b32_e32 v163, 0xffff0000, v199
	v_lshlrev_b32_e32 v160, 16, v201
	v_cndmask_b32_e32 v65, v174, v115, vcc
	v_lshlrev_b32_e32 v115, 2, v65
	s_waitcnt lgkmcnt(0)
	v_add_f32_e32 v116, v126, v64
	ds_bpermute_b32 v117, v115, v116
	v_and_b32_e32 v161, 0xffff0000, v201
	v_pk_add_f32 v[70:71], v[70:71], v[162:163]
	v_pk_add_f32 v[68:69], v[68:69], v[158:159]
	v_pk_add_f32 v[66:67], v[66:67], v[160:161]
	v_lshl_add_u64 v[64:65], v[150:151], 2, s[6:7]
	v_cvt_pk_bf16_f32 v118, v68, v69
	v_cvt_pk_bf16_f32 v119, v70, v71
	v_cvt_pk_bf16_f32 v120, v82, v83
	v_cvt_pk_bf16_f32 v121, v66, v67
	global_store_dwordx4 v[122:123], v[118:121], off offset:256
	s_and_saveexec_b64 s[26:27], s[2:3]
	s_cbranch_execz .LBB0_1267
	s_waitcnt lgkmcnt(0)
	v_add_f32_e32 v116, v116, v117
	global_atomic_add_f32 v[64:65], v116, off
